# write-through (sc1) global stores in the 9 phases that end at a cross-XCD grid seam, so the seam's L2 write-back has little left to flush
# baseline (speedup 1.0000x reference)
; #define LAS __attribute__((address_space(3)))
; __device__ __forceinline__ unsigned cvt_pk_bf16(float lo, float hi) { unsigned r; asm volatile("v_cvt_pk_bf16_f32 %0, %1, %2" : "=v"(r) : "v"(lo), "v"(hi)); return r; }
; __device__ __forceinline__ void p0_emit(const P0Item& p, LAS float* scr, int lane, const f32x4 (&v)[8], const float (&gk)[8]) {
;     const int r8 = lane >> 3, c4 = lane & 7;
; #pragma unroll
;     for (int i = 0; i < 8; ++i) { const int kk = 8 * i + r8; LAS float* d = scr + kk * 33 + 4 * c4; d[0] = v[i][0] * gk[i]; d[1] = v[i][1] * gk[i]; d[2] = v[i][2] * gk[i]; d[3] = v[i][3] * gk[i]; }
;     asm volatile("s_waitcnt lgkmcnt(0)" ::: "memory");
;     const int c = lane & 7;
; #pragma unroll
;     for (int j = 0; j < 4; ++j) { const int n = (lane >> 3) + 8 * j; const LAS float* sp = scr + (8 * c) * 33 + n;
;         u32x4 o; o.x = cvt_pk_bf16(sp[0 * 33], sp[1 * 33]); o.y = cvt_pk_bf16(sp[2 * 33], sp[3 * 33]); o.z = cvt_pk_bf16(sp[4 * 33], sp[5 * 33]); o.w = cvt_pk_bf16(sp[6 * 33], sp[7 * 33]);
;         *(u32x4*)(p.dst + (size_t)n * p.K + 8 * c) = o; }
;     asm volatile("s_waitcnt lgkmcnt(0)" ::: "memory");
; }
; __global__ void __launch_bounds__(512, 2) mk_fwd(Args args) {
;     ...
;             for (; it < args.nitems; it += NGW) {
;                 const bool more = it + NGW < args.nitems;
;                 if (more) { p0_decode(args, it + NGW, pn, Nn); p0_load(pn, Nn, lane, vn, gkn); }
;                 p0_emit(pc, scr, lane, v, gk);
;                 if (more) { pc = pn; Nc = Nn;
; #pragma unroll
;                     for (int i = 0; i < 8; ++i) { v[i] = vn[i]; gk[i] = gkn[i]; } }
;             }
.LBB0_124:
	s_waitcnt vmcnt(7)
	v_pk_mul_f32 v[102:103], v[66:67], v[0:1] op_sel_hi:[0,1]
	ds_write2_b32 v71, v102, v103 offset1:1
	v_pk_mul_f32 v[102:103], v[66:67], v[2:3] op_sel_hi:[0,1]
	ds_write2_b32 v71, v102, v103 offset0:2 offset1:3
	s_waitcnt vmcnt(6)
	v_pk_mul_f32 v[102:103], v[64:65], v[4:5] op_sel_hi:[0,1]
	v_add_u32_e32 v84, 0x420, v71
	ds_write2_b32 v84, v102, v103 offset1:1
	v_pk_mul_f32 v[102:103], v[64:65], v[6:7] op_sel_hi:[0,1]
	v_add_u32_e32 v84, 0x428, v71
	ds_write2_b32 v84, v102, v103 offset1:1
	s_waitcnt vmcnt(5)
	v_pk_mul_f32 v[102:103], v[70:71], v[8:9] op_sel_hi:[0,1]
	v_add_u32_e32 v84, 0x840, v71
	ds_write2_b32 v84, v102, v103 offset1:1
	v_pk_mul_f32 v[102:103], v[70:71], v[10:11] op_sel_hi:[0,1]
	v_add_u32_e32 v84, 0x848, v71
	ds_write2_b32 v84, v102, v103 offset1:1
	s_waitcnt vmcnt(4)
	v_pk_mul_f32 v[102:103], v[68:69], v[12:13] op_sel_hi:[0,1]
	v_add_u32_e32 v84, 0xc60, v71
	ds_write2_b32 v84, v102, v103 offset1:1
	v_pk_mul_f32 v[102:103], v[68:69], v[14:15] op_sel_hi:[0,1]
	v_add_u32_e32 v84, 0xc68, v71
	ds_write2_b32 v84, v102, v103 offset1:1
	s_waitcnt vmcnt(3)
	v_pk_mul_f32 v[102:103], v[74:75], v[16:17] op_sel_hi:[0,1]
	v_add_u32_e32 v84, 0x1080, v71
	ds_write2_b32 v84, v102, v103 offset1:1
	v_pk_mul_f32 v[102:103], v[74:75], v[18:19] op_sel_hi:[0,1]
	v_add_u32_e32 v84, 0x1088, v71
	ds_write2_b32 v84, v102, v103 offset1:1
	s_waitcnt vmcnt(2)
	v_pk_mul_f32 v[102:103], v[72:73], v[20:21] op_sel_hi:[0,1]
	v_add_u32_e32 v84, 0x14a0, v71
	ds_write2_b32 v84, v102, v103 offset1:1
	v_pk_mul_f32 v[102:103], v[72:73], v[22:23] op_sel_hi:[0,1]
	v_add_u32_e32 v84, 0x14a8, v71
	ds_write2_b32 v84, v102, v103 offset1:1
	s_waitcnt vmcnt(1)
	v_pk_mul_f32 v[102:103], v[78:79], v[24:25] op_sel_hi:[0,1]
	v_add_u32_e32 v84, 0x18c0, v71
	ds_write2_b32 v84, v102, v103 offset1:1
	v_pk_mul_f32 v[102:103], v[78:79], v[26:27] op_sel_hi:[0,1]
	v_add_u32_e32 v84, 0x18c8, v71
	ds_write2_b32 v84, v102, v103 offset1:1
	s_waitcnt vmcnt(0)
	v_pk_mul_f32 v[102:103], v[76:77], v[28:29] op_sel_hi:[0,1]
	v_add_u32_e32 v84, 0x1ce0, v71
	ds_write2_b32 v84, v102, v103 offset1:1
	v_pk_mul_f32 v[102:103], v[76:77], v[30:31] op_sel_hi:[0,1]
	v_add_u32_e32 v84, 0x1ce8, v71
	ds_write2_b32 v84, v102, v103 offset1:1
	s_waitcnt lgkmcnt(0)
	ds_read2_b32 v[102:103], v69 offset1:33
	s_waitcnt lgkmcnt(0)
	v_cvt_pk_bf16_f32 v102, v102, v103
	ds_read2_b32 v[104:105], v69 offset0:66 offset1:99
	v_mov_b32_e32 v101, v85
	s_waitcnt lgkmcnt(0)
	v_cvt_pk_bf16_f32 v103, v104, v105
	ds_read2_b32 v[104:105], v69 offset0:132 offset1:165
	v_lshl_add_u64 v[110:111], s[6:7], 0, v[100:101]
	v_mad_i64_i32 v[112:113], s[10:11], s4, v80, 0
	s_waitcnt lgkmcnt(0)
	v_cvt_pk_bf16_f32 v104, v104, v105
	ds_read2_b32 v[106:107], v69 offset0:198 offset1:231
	s_waitcnt lgkmcnt(0)
	v_cvt_pk_bf16_f32 v105, v106, v107
	v_lshl_add_u64 v[112:113], v[112:113], 1, v[110:111]
	ds_read2_b32 v[106:107], v69 offset0:8 offset1:41
	global_store_dwordx4 v[112:113], v[102:105], off sc1
	v_mad_i64_i32 v[112:113], s[10:11], s4, v86, 0
	s_waitcnt lgkmcnt(0)
	v_cvt_pk_bf16_f32 v102, v106, v107
	ds_read2_b32 v[104:105], v69 offset0:74 offset1:107
	s_waitcnt lgkmcnt(0)
	v_cvt_pk_bf16_f32 v103, v104, v105
	ds_read2_b32 v[104:105], v69 offset0:140 offset1:173
	s_waitcnt lgkmcnt(0)
	v_cvt_pk_bf16_f32 v104, v104, v105
	ds_read2_b32 v[106:107], v69 offset0:206 offset1:239
	s_waitcnt lgkmcnt(0)
	v_cvt_pk_bf16_f32 v105, v106, v107
	v_lshl_add_u64 v[112:113], v[112:113], 1, v[110:111]
	ds_read2_b32 v[106:107], v69 offset0:16 offset1:49
	global_store_dwordx4 v[112:113], v[102:105], off sc1
	v_mad_i64_i32 v[112:113], s[10:11], s4, v88, 0
	s_waitcnt lgkmcnt(0)
	v_cvt_pk_bf16_f32 v102, v106, v107
	ds_read2_b32 v[104:105], v69 offset0:82 offset1:115
	s_waitcnt lgkmcnt(0)
	v_cvt_pk_bf16_f32 v103, v104, v105
	ds_read2_b32 v[104:105], v69 offset0:148 offset1:181
	s_waitcnt lgkmcnt(0)
	v_cvt_pk_bf16_f32 v104, v104, v105
	ds_read2_b32 v[106:107], v69 offset0:214 offset1:247
	s_waitcnt lgkmcnt(0)
	v_cvt_pk_bf16_f32 v105, v106, v107
	v_lshl_add_u64 v[112:113], v[112:113], 1, v[110:111]
	ds_read2_b32 v[106:107], v69 offset0:24 offset1:57
	global_store_dwordx4 v[112:113], v[102:105], off sc1
	s_andn2_b64 vcc, exec, s[22:23]
	s_waitcnt lgkmcnt(0)
	v_cvt_pk_bf16_f32 v102, v106, v107
	ds_read2_b32 v[104:105], v69 offset0:90 offset1:123
	s_waitcnt lgkmcnt(0)
	v_cvt_pk_bf16_f32 v103, v104, v105
	ds_read2_b32 v[104:105], v69 offset0:156 offset1:189
	s_waitcnt lgkmcnt(0)
	v_cvt_pk_bf16_f32 v104, v104, v105
	ds_read2_b32 v[106:107], v69 offset0:222 offset1:255
	s_waitcnt lgkmcnt(0)
	v_cvt_pk_bf16_f32 v105, v106, v107
	v_mad_i64_i32 v[106:107], s[10:11], s4, v90, 0
	v_lshl_add_u64 v[106:107], v[106:107], 1, v[110:111]
	global_store_dwordx4 v[106:107], v[102:105], off sc1
	s_waitcnt lgkmcnt(0)
	s_cbranch_vccnz .LBB0_79
	s_mov_b32 s4, s8
	s_mov_b64 s[6:7], s[2:3]
	v_mov_b32_e32 v66, v75
	v_mov_b32_e32 v64, v77
	v_mov_b32_e32 v70, v73
	v_mov_b32_e32 v68, v79
	v_mov_b32_e32 v74, v81
	v_mov_b32_e32 v72, v87
	v_mov_b32_e32 v78, v83
	v_mov_b32_e32 v76, v89
	v_mov_b32_e32 v0, v32
	v_mov_b32_e32 v1, v33
	v_mov_b32_e32 v2, v34
	v_mov_b32_e32 v3, v35
	v_mov_b32_e32 v4, v36
	v_mov_b32_e32 v5, v37
	v_mov_b32_e32 v6, v38
	v_mov_b32_e32 v7, v39
	v_mov_b32_e32 v8, v40
	v_mov_b32_e32 v9, v41
	v_mov_b32_e32 v10, v42
	v_mov_b32_e32 v11, v43
	v_mov_b32_e32 v12, v44
	v_mov_b32_e32 v13, v45
	v_mov_b32_e32 v14, v46
	v_mov_b32_e32 v15, v47
	v_mov_b32_e32 v16, v48
	v_mov_b32_e32 v17, v49
	v_mov_b32_e32 v18, v50
	v_mov_b32_e32 v19, v51
	v_mov_b32_e32 v20, v52
	v_mov_b32_e32 v21, v53
	v_mov_b32_e32 v22, v54
	v_mov_b32_e32 v23, v55
	v_mov_b32_e32 v24, v56
	v_mov_b32_e32 v25, v57
	v_mov_b32_e32 v26, v58
	v_mov_b32_e32 v27, v59
	v_mov_b32_e32 v28, v60
	v_mov_b32_e32 v29, v61
	v_mov_b32_e32 v30, v62
	v_mov_b32_e32 v31, v63
	s_branch .LBB0_79

; __device__ __forceinline__ unsigned cvt_pk_bf16(float lo, float hi) { unsigned r; asm volatile("v_cvt_pk_bf16_f32 %0, %1, %2" : "=v"(r) : "v"(lo), "v"(hi)); return r; }
; __global__ void __launch_bounds__(512, 2) mk_fwd(Args args) {
;     ...
;         for (int m0 = gw * 8; m0 < T; m0 += NGW * 8) {
;             f32x4 v[8][4]; float sq[8];
; #pragma unroll
;             for (int r = 0; r < 8; ++r) { const f32x4* xr = (const f32x4*)(x + (size_t)(m0 + r) * D) + lane;
; #pragma unroll
;                 for (int j = 0; j < 4; ++j) v[r][j] = __builtin_nontemporal_load(xr + 64 * j); }
; #pragma unroll
;             for (int r = 0; r < 8; ++r) { float s_ = 0.f;
; #pragma unroll
;                 for (int j = 0; j < 4; ++j) s_ += (v[r][j][0] * v[r][j][0] + v[r][j][1] * v[r][j][1]) + (v[r][j][2] * v[r][j][2] + v[r][j][3] * v[r][j][3]);
;                 sq[r] = wave_sum(s_);
;                 u32x2* o8 = (u32x2*)(HB0 + (size_t)(m0 + r) * D) + lane;
; #pragma unroll
;                 for (int j = 0; j < 4; ++j) { u32x2 wv; wv.x = cvt_pk_bf16(v[r][j][0], v[r][j][1]); wv.y = cvt_pk_bf16(v[r][j][2], v[r][j][3]); o8[64 * j] = wv; } }
; #pragma unroll
;             for (int h = 0; h < 2; ++h) { const int r = lane >> 4, c = lane & 15; const float sv = r == 0 ? sq[4 * h] : r == 1 ? sq[4 * h + 1] : r == 2 ? sq[4 * h + 2] : sq[4 * h + 3]; SS0[(size_t)(m0 + 4 * h + r) * 16 + c] = c == 0 ? sv : 0.f; }
;         }
.LBB0_129:
	s_or_b64 exec, exec, s[20:21]
	v_add_u32_e32 v0, 4, v0
	v_ashrrev_i32_e32 v1, 31, v0
	v_lshlrev_b64 v[0:1], 6, v[0:1]
	s_add_i32 s10, s10, s12
	v_cndmask_b32_e64 v2, 0, v2, s[4:5]
	v_lshl_add_u64 v[0:1], v[110:111], 0, v[0:1]
	v_lshl_add_u64 v[112:113], v[112:113], 0, s[16:17]
	s_cmpk_gt_i32 s10, 0x7fff
	v_lshl_add_u64 v[114:115], v[114:115], 0, s[18:19]
	global_store_dword v[0:1], v2, off sc1
	s_cbranch_scc1 .LBB0_151
.LBB0_130:
	global_load_dwordx4 v[122:125], v[114:115], off nt
	global_load_dwordx4 v[126:129], v[114:115], off offset:1024 nt
	global_load_dwordx4 v[130:133], v[114:115], off offset:2048 nt
	global_load_dwordx4 v[134:137], v[114:115], off offset:3072 nt
	v_add_co_u32_e32 v0, vcc, 0x1000, v114
	s_waitcnt vmcnt(3)
	v_mul_f32_e32 v144, v123, v123
	v_addc_co_u32_e32 v1, vcc, 0, v115, vcc
	global_load_dwordx4 v[138:141], v[0:1], off nt
	global_load_dwordx4 v[104:107], v[0:1], off offset:1024 nt
	global_load_dwordx4 v[100:103], v[0:1], off offset:2048 nt
	global_load_dwordx4 v[92:95], v[0:1], off offset:3072 nt
	v_add_co_u32_e32 v2, vcc, 0x2000, v114
	s_waitcnt vmcnt(6)
	v_mul_f32_e32 v145, v127, v127
	v_addc_co_u32_e32 v3, vcc, 0, v115, vcc
	global_load_dwordx4 v[96:99], v[2:3], off nt
	global_load_dwordx4 v[88:91], v[2:3], off offset:1024 nt
	global_load_dwordx4 v[84:87], v[2:3], off offset:2048 nt
	global_load_dwordx4 v[80:83], v[2:3], off offset:3072 nt
	v_add_co_u32_e32 v0, vcc, 0x3000, v114
	v_mul_f32_e32 v146, v129, v129
	s_nop 0
	v_addc_co_u32_e32 v1, vcc, 0, v115, vcc
	global_load_dwordx4 v[76:79], v[0:1], off nt
	global_load_dwordx4 v[72:75], v[0:1], off offset:1024 nt
	global_load_dwordx4 v[68:71], v[0:1], off offset:2048 nt
	global_load_dwordx4 v[64:67], v[0:1], off offset:3072 nt
	v_add_co_u32_e32 v2, vcc, 0x4000, v114
	v_fmac_f32_e32 v144, v122, v122
	s_nop 0
	v_addc_co_u32_e32 v3, vcc, 0, v115, vcc
	v_add_co_u32_e32 v0, vcc, 0x5000, v114
	global_load_dwordx4 v[60:63], v[2:3], off nt
	global_load_dwordx4 v[56:59], v[2:3], off offset:1024 nt
	global_load_dwordx4 v[52:55], v[2:3], off offset:2048 nt
	s_waitcnt lgkmcnt(2)
	global_load_dwordx4 v[48:51], v[2:3], off offset:3072 nt
	v_addc_co_u32_e32 v1, vcc, 0, v115, vcc
	global_load_dwordx4 v[44:47], v[0:1], off nt
	global_load_dwordx4 v[40:43], v[0:1], off offset:1024 nt
	global_load_dwordx4 v[36:39], v[0:1], off offset:2048 nt
	s_waitcnt lgkmcnt(1)
	global_load_dwordx4 v[32:35], v[0:1], off offset:3072 nt
	v_add_co_u32_e32 v2, vcc, 0x6000, v114
	s_waitcnt vmcnt(21)
	v_mul_f32_e32 v147, v131, v131
	v_addc_co_u32_e32 v3, vcc, 0, v115, vcc
	v_add_co_u32_e32 v0, vcc, 0x7000, v114
	global_load_dwordx4 v[28:31], v[2:3], off nt
	global_load_dwordx4 v[24:27], v[2:3], off offset:1024 nt
	global_load_dwordx4 v[20:23], v[2:3], off offset:2048 nt
	s_waitcnt lgkmcnt(0)
	global_load_dwordx4 v[16:19], v[2:3], off offset:3072 nt
	v_addc_co_u32_e32 v1, vcc, 0, v115, vcc
	global_load_dwordx4 v[12:15], v[0:1], off nt
	global_load_dwordx4 v[8:11], v[0:1], off offset:1024 nt
	global_load_dwordx4 v[4:7], v[0:1], off offset:2048 nt
	s_nop 0
	global_load_dwordx4 v[0:3], v[0:1], off offset:3072 nt
	v_cvt_pk_bf16_f32 v142, v122, v123
	v_cvt_pk_bf16_f32 v143, v124, v125
	v_mul_f32_e32 v125, v125, v125
	global_store_dwordx2 v[112:113], v[142:143], off sc1
	v_cvt_pk_bf16_f32 v122, v126, v127
	v_cvt_pk_bf16_f32 v123, v128, v129
	v_fmac_f32_e32 v125, v124, v124
	v_fmac_f32_e32 v145, v126, v126
	v_fmac_f32_e32 v146, v128, v128
	global_store_dwordx2 v[112:113], v[122:123], off offset:512 sc1
	v_mul_f32_e32 v124, v133, v133
	v_cvt_pk_bf16_f32 v122, v130, v131
	v_cvt_pk_bf16_f32 v123, v132, v133
	v_fmac_f32_e32 v147, v130, v130
	v_fmac_f32_e32 v124, v132, v132
	global_store_dwordx2 v[112:113], v[122:123], off offset:1024 sc1
	s_waitcnt vmcnt(31)
	v_mul_f32_e32 v123, v135, v135
	v_mul_f32_e32 v126, v137, v137
	v_add_f32_e32 v125, v144, v125
	v_add_f32_e32 v129, v145, v146
	v_fmac_f32_e32 v123, v134, v134
	v_fmac_f32_e32 v126, v136, v136
	v_add_f32_e32 v125, v125, v129
	v_add_f32_e32 v124, v147, v124
	v_add_f32_e32 v124, v125, v124
	v_add_f32_e32 v123, v123, v126
	v_add_f32_e32 v124, v124, v123
	v_cvt_pk_bf16_f32 v122, v134, v135
	s_waitcnt vmcnt(30)
	v_mul_f32_e32 v127, v139, v139
	v_mul_f32_e32 v128, v141, v141
	s_waitcnt vmcnt(29)
	v_mul_f32_e32 v125, v105, v105
	v_mul_f32_e32 v126, v107, v107
	v_fmac_f32_e32 v127, v138, v138
	v_fmac_f32_e32 v128, v140, v140
	v_fmac_f32_e32 v125, v104, v104
	v_fmac_f32_e32 v126, v106, v106
	v_add_f32_e32 v123, v127, v128
	v_add_f32_e32 v125, v125, v126
	v_add_f32_e32 v123, v123, v125
	s_waitcnt vmcnt(28)
	v_mul_f32_e32 v125, v101, v101
	v_mul_f32_e32 v126, v103, v103
	v_fmac_f32_e32 v125, v100, v100
	v_fmac_f32_e32 v126, v102, v102
	v_add_f32_e32 v125, v125, v126
	v_add_f32_e32 v123, v123, v125
	s_waitcnt vmcnt(27)
	v_mul_f32_e32 v125, v93, v93
	v_mul_f32_e32 v126, v95, v95
	v_fmac_f32_e32 v125, v92, v92
	v_fmac_f32_e32 v126, v94, v94
	v_add_f32_e32 v125, v125, v126
	ds_bpermute_b32 v126, v109, v124
	v_add_f32_e32 v125, v123, v125
	v_cvt_pk_bf16_f32 v123, v136, v137
	global_store_dwordx2 v[112:113], v[122:123], off offset:1536 sc1
	v_cvt_pk_bf16_f32 v122, v138, v139
	s_waitcnt lgkmcnt(0)
	v_add_f32_e32 v124, v124, v126
	ds_bpermute_b32 v126, v116, v124
	v_cvt_pk_bf16_f32 v123, v140, v141
	global_store_dwordx2 v[112:113], v[122:123], off offset:2048 sc1
	v_cvt_pk_bf16_f32 v122, v104, v105
	s_waitcnt vmcnt(28)
	v_mul_f32_e32 v104, v97, v97
	v_mul_f32_e32 v105, v99, v99
	v_fmac_f32_e32 v104, v96, v96
	v_fmac_f32_e32 v105, v98, v98
	v_add_f32_e32 v104, v104, v105
	s_waitcnt vmcnt(27)
; __device__ __forceinline__ unsigned cvt_pk_bf16(float lo, float hi) { unsigned r; asm volatile("v_cvt_pk_bf16_f32 %0, %1, %2" : "=v"(r) : "v"(lo), "v"(hi)); return r; }
; __global__ void __launch_bounds__(512, 2) mk_fwd(Args args) {
;     ...
;             for (int r = 0; r < 8; ++r) { const f32x4* xr = (const f32x4*)(x + (size_t)(m0 + r) * D) + lane;
; #pragma unroll
;                 for (int j = 0; j < 4; ++j) v[r][j] = __builtin_nontemporal_load(xr + 64 * j); }
; #pragma unroll
;             for (int r = 0; r < 8; ++r) { float s_ = 0.f;
; #pragma unroll
;                 for (int j = 0; j < 4; ++j) s_ += (v[r][j][0] * v[r][j][0] + v[r][j][1] * v[r][j][1]) + (v[r][j][2] * v[r][j][2] + v[r][j][3] * v[r][j][3]);
;                 sq[r] = wave_sum(s_);
;                 u32x2* o8 = (u32x2*)(HB0 + (size_t)(m0 + r) * D) + lane;
; #pragma unroll
;                 for (int j = 0; j < 4; ++j) { u32x2 wv; wv.x = cvt_pk_bf16(v[r][j][0], v[r][j][1]); wv.y = cvt_pk_bf16(v[r][j][2], v[r][j][3]); o8[64 * j] = wv; } }
	v_mul_f32_e32 v105, v89, v89
	v_mul_f32_e32 v123, v91, v91
	v_fmac_f32_e32 v105, v88, v88
	v_fmac_f32_e32 v123, v90, v90
	s_waitcnt lgkmcnt(0)
	v_add_f32_e32 v124, v124, v126
	v_add_f32_e32 v105, v105, v123
	ds_bpermute_b32 v126, v117, v124
	v_add_f32_e32 v104, v104, v105
	s_waitcnt vmcnt(26)
	v_mul_f32_e32 v105, v85, v85
	v_mul_f32_e32 v123, v87, v87
	v_fmac_f32_e32 v105, v84, v84
	v_fmac_f32_e32 v123, v86, v86
	v_add_f32_e32 v105, v105, v123
	v_add_f32_e32 v104, v104, v105
	s_waitcnt vmcnt(25)
	v_mul_f32_e32 v105, v81, v81
	v_mul_f32_e32 v123, v83, v83
	v_fmac_f32_e32 v105, v80, v80
	v_fmac_f32_e32 v123, v82, v82
	v_add_f32_e32 v105, v105, v123
	s_waitcnt lgkmcnt(0)
	v_add_f32_e32 v123, v124, v126
	ds_bpermute_b32 v124, v118, v123
	ds_bpermute_b32 v127, v109, v125
	v_add_f32_e32 v104, v104, v105
	ds_bpermute_b32 v105, v109, v104
	s_waitcnt lgkmcnt(2)
	v_add_f32_e32 v124, v123, v124
	v_cvt_pk_bf16_f32 v123, v106, v107
	global_store_dwordx2 v[112:113], v[122:123], off offset:2560 sc1
	v_cvt_pk_bf16_f32 v100, v100, v101
	v_cvt_pk_bf16_f32 v101, v102, v103
	global_store_dwordx2 v[112:113], v[100:101], off offset:3072 sc1
	v_cvt_pk_bf16_f32 v92, v92, v93
	v_cvt_pk_bf16_f32 v93, v94, v95
	global_store_dwordx2 v[112:113], v[92:93], off offset:3584 sc1
	s_waitcnt vmcnt(27)
	v_mul_f32_e32 v92, v77, v77
	v_mul_f32_e32 v93, v79, v79
	v_fmac_f32_e32 v92, v76, v76
	v_fmac_f32_e32 v93, v78, v78
	v_cvt_pk_bf16_f32 v96, v96, v97
	v_cvt_pk_bf16_f32 v97, v98, v99
	v_add_f32_e32 v92, v92, v93
	s_waitcnt vmcnt(26)
	v_mul_f32_e32 v93, v73, v73
	v_mul_f32_e32 v98, v75, v75
	v_fmac_f32_e32 v93, v72, v72
	v_fmac_f32_e32 v98, v74, v74
	v_add_f32_e32 v93, v93, v98
	v_add_f32_e32 v92, v92, v93
	s_waitcnt vmcnt(25)
	v_mul_f32_e32 v93, v69, v69
	v_mul_f32_e32 v98, v71, v71
	v_fmac_f32_e32 v93, v68, v68
	v_fmac_f32_e32 v98, v70, v70
	v_add_f32_e32 v93, v93, v98
	v_add_f32_e32 v92, v92, v93
	s_waitcnt vmcnt(24)
	v_mul_f32_e32 v93, v65, v65
	v_mul_f32_e32 v98, v67, v67
	v_fmac_f32_e32 v93, v64, v64
	v_fmac_f32_e32 v98, v66, v66
	v_add_f32_e32 v93, v93, v98
	v_add_f32_e32 v98, v92, v93
	ds_bpermute_b32 v99, v109, v98
	v_add_co_u32_e32 v94, vcc, s11, v112
	s_waitcnt lgkmcnt(2)
	v_add_f32_e32 v125, v125, v127
	v_addc_co_u32_e32 v95, vcc, 0, v113, vcc
	s_waitcnt lgkmcnt(0)
	v_add_f32_e32 v98, v98, v99
	ds_bpermute_b32 v99, v116, v98
	v_add_co_u32_e32 v92, vcc, s13, v112
	ds_bpermute_b32 v127, v116, v125
	s_nop 0
	v_addc_co_u32_e32 v93, vcc, 0, v113, vcc
	global_store_dwordx2 v[92:93], v[96:97], off offset:-4096 sc1
	v_cvt_pk_bf16_f32 v88, v88, v89
	v_cvt_pk_bf16_f32 v89, v90, v91
	global_store_dwordx2 v[94:95], v[88:89], off offset:512 sc1
	s_waitcnt lgkmcnt(1)
	v_add_f32_e32 v88, v98, v99
	ds_bpermute_b32 v89, v117, v88
	v_cvt_pk_bf16_f32 v84, v84, v85
	v_cvt_pk_bf16_f32 v85, v86, v87
	global_store_dwordx2 v[94:95], v[84:85], off offset:1024 sc1
	v_cvt_pk_bf16_f32 v80, v80, v81
	s_waitcnt lgkmcnt(0)
	v_add_f32_e32 v81, v88, v89
	ds_bpermute_b32 v84, v118, v81
	s_waitcnt vmcnt(26)
	v_mul_f32_e32 v85, v61, v61
	v_mul_f32_e32 v86, v63, v63
	v_fmac_f32_e32 v85, v60, v60
	v_fmac_f32_e32 v86, v62, v62
	s_waitcnt lgkmcnt(0)
	v_add_f32_e32 v84, v81, v84
	v_cvt_pk_bf16_f32 v81, v82, v83
	global_store_dwordx2 v[94:95], v[80:81], off offset:1536 sc1
	v_cvt_pk_bf16_f32 v76, v76, v77
	v_cvt_pk_bf16_f32 v77, v78, v79
	global_store_dwordx2 v[94:95], v[76:77], off offset:2048 sc1
	v_cvt_pk_bf16_f32 v72, v72, v73
	v_cvt_pk_bf16_f32 v73, v74, v75
	global_store_dwordx2 v[94:95], v[72:73], off offset:2560 sc1
	v_cvt_pk_bf16_f32 v68, v68, v69
	v_cvt_pk_bf16_f32 v69, v70, v71
	global_store_dwordx2 v[94:95], v[68:69], off offset:3072 sc1
	v_cvt_pk_bf16_f32 v64, v64, v65
	s_waitcnt vmcnt(26)
	v_mul_f32_e32 v65, v45, v45
	v_mul_f32_e32 v70, v47, v47
	v_fmac_f32_e32 v65, v44, v44
	v_fmac_f32_e32 v70, v46, v46
	v_add_f32_e32 v65, v65, v70
	s_waitcnt vmcnt(25)
	v_mul_f32_e32 v70, v41, v41
	v_mul_f32_e32 v71, v43, v43
	v_fmac_f32_e32 v70, v40, v40
	v_fmac_f32_e32 v71, v42, v42
	v_add_f32_e32 v85, v85, v86
	v_mul_f32_e32 v86, v57, v57
	v_mul_f32_e32 v87, v59, v59
	v_add_f32_e32 v70, v70, v71
	v_fmac_f32_e32 v86, v56, v56
	v_fmac_f32_e32 v87, v58, v58
	v_add_f32_e32 v65, v65, v70
	s_waitcnt vmcnt(24)
	v_mul_f32_e32 v70, v37, v37
	v_mul_f32_e32 v71, v39, v39
	v_add_f32_e32 v86, v86, v87
	v_fmac_f32_e32 v70, v36, v36
	v_fmac_f32_e32 v71, v38, v38
	v_add_f32_e32 v85, v85, v86
	v_mul_f32_e32 v86, v53, v53
	v_mul_f32_e32 v87, v55, v55
	v_add_f32_e32 v70, v70, v71
	v_fmac_f32_e32 v86, v52, v52
	v_fmac_f32_e32 v87, v54, v54
	v_add_f32_e32 v65, v65, v70
	s_waitcnt vmcnt(23)
	v_mul_f32_e32 v70, v33, v33
	v_mul_f32_e32 v71, v35, v35
	v_add_f32_e32 v86, v86, v87
	v_fmac_f32_e32 v70, v32, v32
	v_fmac_f32_e32 v71, v34, v34
	v_add_f32_e32 v85, v85, v86
	v_mul_f32_e32 v86, v49, v49
	v_mul_f32_e32 v87, v51, v51
	v_add_f32_e32 v70, v70, v71
	v_fmac_f32_e32 v86, v48, v48
	v_fmac_f32_e32 v87, v50, v50
	v_add_f32_e32 v70, v65, v70
	v_cvt_pk_bf16_f32 v65, v66, v67
	global_store_dwordx2 v[94:95], v[64:65], off offset:3584 sc1
	v_cvt_pk_bf16_f32 v60, v60, v61
	v_cvt_pk_bf16_f32 v61, v62, v63
	global_store_dwordx2 v[92:93], v[60:61], off sc1
	v_cvt_pk_bf16_f32 v56, v56, v57
	v_cvt_pk_bf16_f32 v57, v58, v59
	global_store_dwordx2 v[92:93], v[56:57], off offset:512 sc1
	v_cvt_pk_bf16_f32 v52, v52, v53
	v_cvt_pk_bf16_f32 v53, v54, v55
	global_store_dwordx2 v[92:93], v[52:53], off offset:1024 sc1
	v_cvt_pk_bf16_f32 v48, v48, v49
	v_cvt_pk_bf16_f32 v49, v50, v51
	s_waitcnt vmcnt(26)
	v_mul_f32_e32 v50, v29, v29
	v_mul_f32_e32 v51, v31, v31
	v_fmac_f32_e32 v50, v28, v28
	v_fmac_f32_e32 v51, v30, v30
	v_add_f32_e32 v50, v50, v51
	s_waitcnt vmcnt(25)
; __device__ __forceinline__ unsigned cvt_pk_bf16(float lo, float hi) { unsigned r; asm volatile("v_cvt_pk_bf16_f32 %0, %1, %2" : "=v"(r) : "v"(lo), "v"(hi)); return r; }
; __global__ void __launch_bounds__(512, 2) mk_fwd(Args args) {
;     ...
;             for (int r = 0; r < 8; ++r) { float s_ = 0.f;
; #pragma unroll
;                 for (int j = 0; j < 4; ++j) s_ += (v[r][j][0] * v[r][j][0] + v[r][j][1] * v[r][j][1]) + (v[r][j][2] * v[r][j][2] + v[r][j][3] * v[r][j][3]);
;                 sq[r] = wave_sum(s_);
;                 u32x2* o8 = (u32x2*)(HB0 + (size_t)(m0 + r) * D) + lane;
; #pragma unroll
;                 for (int j = 0; j < 4; ++j) { u32x2 wv; wv.x = cvt_pk_bf16(v[r][j][0], v[r][j][1]); wv.y = cvt_pk_bf16(v[r][j][2], v[r][j][3]); o8[64 * j] = wv; } }
; #pragma unroll
;             for (int h = 0; h < 2; ++h) { const int r = lane >> 4, c = lane & 15; const float sv = r == 0 ? sq[4 * h] : r == 1 ? sq[4 * h + 1] : r == 2 ? sq[4 * h + 2] : sq[4 * h + 3]; SS0[(size_t)(m0 + 4 * h + r) * 16 + c] = c == 0 ? sv : 0.f; }
	v_mul_f32_e32 v51, v25, v25
	v_mul_f32_e32 v52, v27, v27
	v_fmac_f32_e32 v51, v24, v24
	v_fmac_f32_e32 v52, v26, v26
	v_add_f32_e32 v51, v51, v52
	v_add_f32_e32 v50, v50, v51
	s_waitcnt vmcnt(24)
	v_mul_f32_e32 v51, v21, v21
	v_mul_f32_e32 v52, v23, v23
	v_fmac_f32_e32 v51, v20, v20
	v_fmac_f32_e32 v52, v22, v22
	v_add_f32_e32 v51, v51, v52
	v_add_f32_e32 v50, v50, v51
	s_waitcnt vmcnt(23)
	v_mul_f32_e32 v51, v17, v17
	v_mul_f32_e32 v52, v19, v19
	v_fmac_f32_e32 v51, v16, v16
	v_fmac_f32_e32 v52, v18, v18
	v_add_f32_e32 v51, v51, v52
	v_add_f32_e32 v50, v50, v51
	ds_bpermute_b32 v51, v109, v50
	global_store_dwordx2 v[92:93], v[48:49], off offset:1536 sc1
	v_cvt_pk_bf16_f32 v44, v44, v45
	v_cvt_pk_bf16_f32 v45, v46, v47
	global_store_dwordx2 v[92:93], v[44:45], off offset:2048 sc1
	s_waitcnt lgkmcnt(0)
	v_add_f32_e32 v46, v50, v51
	v_cvt_pk_bf16_f32 v40, v40, v41
	v_cvt_pk_bf16_f32 v41, v42, v43
	global_store_dwordx2 v[92:93], v[40:41], off offset:2560 sc1
	v_cvt_pk_bf16_f32 v36, v36, v37
	v_cvt_pk_bf16_f32 v37, v38, v39
	ds_bpermute_b32 v47, v116, v46
	global_store_dwordx2 v[92:93], v[36:37], off offset:3072 sc1
	s_waitcnt vmcnt(26)
	v_mul_f32_e32 v37, v13, v13
	v_mul_f32_e32 v38, v15, v15
	v_fmac_f32_e32 v37, v12, v12
	v_fmac_f32_e32 v38, v14, v14
	v_add_f32_e32 v37, v37, v38
	s_waitcnt vmcnt(25)
	v_mul_f32_e32 v38, v9, v9
	v_mul_f32_e32 v39, v11, v11
	v_fmac_f32_e32 v38, v8, v8
	v_fmac_f32_e32 v39, v10, v10
	v_add_f32_e32 v38, v38, v39
	s_waitcnt lgkmcnt(0)
	v_add_f32_e32 v40, v46, v47
	v_add_f32_e32 v37, v37, v38
	s_waitcnt vmcnt(24)
	v_mul_f32_e32 v38, v5, v5
	v_mul_f32_e32 v39, v7, v7
	ds_bpermute_b32 v41, v117, v40
	v_fmac_f32_e32 v38, v4, v4
	v_fmac_f32_e32 v39, v6, v6
	v_add_f32_e32 v38, v38, v39
	v_add_f32_e32 v37, v37, v38
	s_waitcnt vmcnt(23)
	v_mul_f32_e32 v38, v1, v1
	v_mul_f32_e32 v39, v3, v3
	v_fmac_f32_e32 v38, v0, v0
	v_fmac_f32_e32 v39, v2, v2
	v_add_f32_e32 v86, v86, v87
	v_add_f32_e32 v38, v38, v39
	v_add_f32_e32 v85, v85, v86
	v_cvt_pk_bf16_f32 v32, v32, v33
	s_waitcnt lgkmcnt(0)
	v_add_f32_e32 v33, v40, v41
	v_add_f32_e32 v37, v37, v38
	v_add_f32_e32 v125, v125, v127
	ds_bpermute_b32 v86, v109, v85
	ds_bpermute_b32 v71, v109, v70
	ds_bpermute_b32 v36, v118, v33
	ds_bpermute_b32 v38, v109, v37
	ds_bpermute_b32 v127, v117, v125
	v_add_f32_e32 v104, v104, v105
	s_waitcnt lgkmcnt(4)
	v_add_f32_e32 v82, v85, v86
	s_waitcnt lgkmcnt(3)
	v_add_f32_e32 v66, v70, v71
	s_waitcnt lgkmcnt(2)
	v_add_f32_e32 v36, v33, v36
	v_cvt_pk_bf16_f32 v33, v34, v35
	s_waitcnt lgkmcnt(1)
	v_add_f32_e32 v34, v37, v38
	s_waitcnt lgkmcnt(0)
	v_add_f32_e32 v125, v125, v127
	ds_bpermute_b32 v105, v116, v104
	ds_bpermute_b32 v83, v116, v82
	ds_bpermute_b32 v67, v116, v66
	ds_bpermute_b32 v35, v116, v34
	ds_bpermute_b32 v126, v118, v125
	s_waitcnt lgkmcnt(4)
	v_add_f32_e32 v105, v104, v105
	s_waitcnt lgkmcnt(3)
	v_add_f32_e32 v78, v82, v83
	s_waitcnt lgkmcnt(2)
	v_add_f32_e32 v60, v66, v67
	s_waitcnt lgkmcnt(1)
	v_add_f32_e32 v34, v34, v35
	ds_bpermute_b32 v127, v119, v124
	s_waitcnt lgkmcnt(1)
	v_add_f32_e32 v125, v125, v126
	ds_bpermute_b32 v128, v117, v105
	ds_bpermute_b32 v79, v117, v78
	ds_bpermute_b32 v61, v117, v60
	ds_bpermute_b32 v35, v117, v34
	ds_bpermute_b32 v126, v119, v125
	global_store_dwordx2 v[92:93], v[32:33], off offset:3584 sc1
	v_cvt_pk_bf16_f32 v28, v28, v29
	v_cvt_pk_bf16_f32 v29, v30, v31
	v_add_co_u32_e32 v30, vcc, s28, v112
	s_waitcnt lgkmcnt(5)
	v_add_f32_e32 v106, v124, v127
	v_addc_co_u32_e32 v31, vcc, 0, v113, vcc
	s_waitcnt lgkmcnt(4)
	v_add_f32_e32 v124, v105, v128
	s_waitcnt lgkmcnt(3)
	v_add_f32_e32 v72, v78, v79
	s_waitcnt lgkmcnt(2)
	v_add_f32_e32 v54, v60, v61
	global_store_dwordx2 v[30:31], v[28:29], off sc1
	s_waitcnt lgkmcnt(1)
	v_add_f32_e32 v28, v34, v35
	s_waitcnt lgkmcnt(0)
	v_add_f32_e32 v104, v125, v126
	ds_bpermute_b32 v125, v118, v124
	ds_bpermute_b32 v73, v118, v72
	ds_bpermute_b32 v55, v118, v54
	ds_bpermute_b32 v29, v118, v28
	v_cvt_pk_bf16_f32 v24, v24, v25
	s_waitcnt lgkmcnt(3)
	v_add_f32_e32 v102, v124, v125
	s_waitcnt lgkmcnt(2)
	v_add_f32_e32 v68, v72, v73
	s_waitcnt lgkmcnt(1)
	v_add_f32_e32 v48, v54, v55
	v_cvt_pk_bf16_f32 v25, v26, v27
	global_store_dwordx2 v[30:31], v[24:25], off offset:512 sc1
	v_cvt_pk_bf16_f32 v20, v20, v21
	v_cvt_pk_bf16_f32 v21, v22, v23
	s_waitcnt lgkmcnt(0)
	v_add_f32_e32 v22, v28, v29
	ds_bpermute_b32 v103, v119, v102
	ds_bpermute_b32 v87, v119, v84
	ds_bpermute_b32 v69, v119, v68
	ds_bpermute_b32 v49, v119, v48
	ds_bpermute_b32 v39, v119, v36
	ds_bpermute_b32 v23, v119, v22
	global_store_dwordx2 v[30:31], v[20:21], off offset:1024 sc1
	v_cvt_pk_bf16_f32 v16, v16, v17
	s_waitcnt lgkmcnt(5)
	v_add_f32_e32 v100, v102, v103
	s_waitcnt lgkmcnt(4)
	v_add_f32_e32 v80, v84, v87
	s_waitcnt lgkmcnt(3)
	v_add_f32_e32 v64, v68, v69
	s_waitcnt lgkmcnt(2)
	v_add_f32_e32 v48, v48, v49
	s_waitcnt lgkmcnt(1)
	v_add_f32_e32 v32, v36, v39
	v_cvt_pk_bf16_f32 v17, v18, v19
	global_store_dwordx2 v[30:31], v[16:17], off offset:1536 sc1
	s_waitcnt lgkmcnt(0)
	v_add_f32_e32 v16, v22, v23
	ds_bpermute_b32 v107, v120, v106
	ds_bpermute_b32 v105, v120, v104
	ds_bpermute_b32 v101, v120, v100
	ds_bpermute_b32 v81, v120, v80
	ds_bpermute_b32 v65, v120, v64
	ds_bpermute_b32 v49, v120, v48
	ds_bpermute_b32 v33, v120, v32
	ds_bpermute_b32 v17, v120, v16
	v_cvt_pk_bf16_f32 v12, v12, v13
	v_cvt_pk_bf16_f32 v13, v14, v15
	global_store_dwordx2 v[30:31], v[12:13], off offset:2048 sc1
	v_cvt_pk_bf16_f32 v8, v8, v9
	v_cvt_pk_bf16_f32 v9, v10, v11
	global_store_dwordx2 v[30:31], v[8:9], off offset:2560 sc1
	v_cvt_pk_bf16_f32 v4, v4, v5
	v_cvt_pk_bf16_f32 v5, v6, v7
	global_store_dwordx2 v[30:31], v[4:5], off offset:3072 sc1
	v_cvt_pk_bf16_f32 v0, v0, v1
	v_cvt_pk_bf16_f32 v1, v2, v3
	global_store_dwordx2 v[30:31], v[0:1], off offset:3584 sc1
	s_and_saveexec_b64 s[20:21], s[2:3]
	s_xor_b64 s[20:21], exec, s[20:21]
	s_cbranch_execz .LBB0_136
	v_cmp_lt_i32_e32 vcc, 1, v121
	s_mov_b64 s[22:23], 0
	s_and_saveexec_b64 s[24:25], vcc
	s_xor_b64 s[24:25], exec, s[24:25]
	s_cbranch_execnz .LBB0_143
	s_andn2_saveexec_b64 s[24:25], s[24:25]
	s_cbranch_execnz .LBB0_146

; __global__ void __launch_bounds__(512, 2) mk_fwd(Args args) {
;     ...
;             for (int h = 0; h < 2; ++h) { const int r = lane >> 4, c = lane & 15; const float sv = r == 0 ? sq[4 * h] : r == 1 ? sq[4 * h + 1] : r == 2 ? sq[4 * h + 2] : sq[4 * h + 3]; SS0[(size_t)(m0 + 4 * h + r) * 16 + c] = c == 0 ? sv : 0.f; }
.LBB0_138:
	s_or_b64 exec, exec, s[20:21]
	v_add_u32_e32 v0, s10, v121
	v_cndmask_b32_e64 v3, 0, v1, s[4:5]
	v_ashrrev_i32_e32 v1, 31, v0
	v_lshlrev_b64 v[4:5], 6, v[0:1]
	s_waitcnt lgkmcnt(3)
	v_add_f32_e32 v2, v64, v65
	v_lshl_add_u64 v[4:5], v[110:111], 0, v[4:5]
	global_store_dword v[4:5], v3, off sc1
	s_and_saveexec_b64 s[20:21], s[2:3]
	s_cbranch_execz .LBB0_129
	v_cmp_lt_i32_e32 vcc, 1, v121
	s_mov_b64 s[22:23], 0
	s_mov_b64 s[24:25], 0
	s_and_saveexec_b64 s[26:27], vcc
	s_xor_b64 s[26:27], exec, s[26:27]
	s_cbranch_execnz .LBB0_147
	s_andn2_saveexec_b64 s[26:27], s[26:27]
	s_cbranch_execnz .LBB0_148

; __global__ void __launch_bounds__(512, 2) mk_fwd(Args args) {
;     ...
;             for (size_t i = (size_t)(vcu * 512 + tid); i < NV; i += 8 * st) {
;                 f32x4 a[8], b[8];
; #pragma unroll
;                 for (int q = 0; q < 8; ++q) if (i + q * st < NV) { a[q] = __builtin_nontemporal_load((const f32x4*)(p + (i + q * st) * 8)); b[q] = __builtin_nontemporal_load((const f32x4*)(p + (i + q * st) * 8 + 4)); }
; #pragma unroll
;                 for (int q = 0; q < 8; ++q) if (i + q * st < NV) *(u32x4*)(PB + (i + q * st) * 8) = pack8(a[q], b[q]);
.LBB0_168:
	s_or_b64 exec, exec, s[56:57]
	s_waitcnt vmcnt(0)
	v_cvt_pk_bf16_f32 v60, v60, v61
	v_cvt_pk_bf16_f32 v61, v62, v63
	v_cvt_pk_bf16_f32 v62, v56, v57
	v_cvt_pk_bf16_f32 v63, v58, v59
	global_store_dwordx4 v[64:65], v[60:63], off sc1
	s_and_saveexec_b64 s[56:57], vcc
	s_cbranch_execnz .LBB0_175
	s_or_b64 exec, exec, s[56:57]
	s_and_saveexec_b64 s[56:57], s[2:3]
	s_cbranch_execnz .LBB0_176

; __global__ void __launch_bounds__(512, 2) mk_fwd(Args args) {
;     ...
;                 for (int q = 0; q < 8; ++q) if (i + q * st < NV) { a[q] = __builtin_nontemporal_load((const f32x4*)(p + (i + q * st) * 8)); b[q] = __builtin_nontemporal_load((const f32x4*)(p + (i + q * st) * 8 + 4)); }
; #pragma unroll
;                 for (int q = 0; q < 8; ++q) if (i + q * st < NV) *(u32x4*)(PB + (i + q * st) * 8) = pack8(a[q], b[q]);
.LBB0_175:
	v_lshl_add_u64 v[60:61], v[64:65], 0, s[30:31]
	v_cvt_pk_bf16_f32 v56, v24, v25
	v_cvt_pk_bf16_f32 v57, v26, v27
	v_cvt_pk_bf16_f32 v58, v52, v53
	v_cvt_pk_bf16_f32 v59, v54, v55
	global_store_dwordx4 v[60:61], v[56:59], off sc1
	s_or_b64 exec, exec, s[56:57]
	s_and_saveexec_b64 s[56:57], s[2:3]
	s_cbranch_execz .LBB0_170
.LBB0_176:
	v_lshl_add_u64 v[60:61], v[64:65], 0, s[26:27]
	v_cvt_pk_bf16_f32 v56, v20, v21
	v_cvt_pk_bf16_f32 v57, v22, v23
	v_cvt_pk_bf16_f32 v58, v48, v49
	v_cvt_pk_bf16_f32 v59, v50, v51
	global_store_dwordx4 v[60:61], v[56:59], off sc1
	s_or_b64 exec, exec, s[56:57]
	s_and_saveexec_b64 s[2:3], s[4:5]
	s_cbranch_execz .LBB0_171
.LBB0_177:
	v_lshl_add_u64 v[60:61], v[64:65], 0, s[36:37]
	v_cvt_pk_bf16_f32 v56, v16, v17
	v_cvt_pk_bf16_f32 v57, v18, v19
	v_cvt_pk_bf16_f32 v58, v44, v45
	v_cvt_pk_bf16_f32 v59, v46, v47
	global_store_dwordx4 v[60:61], v[56:59], off sc1
	s_or_b64 exec, exec, s[2:3]
	s_and_saveexec_b64 s[2:3], s[6:7]
	s_cbranch_execz .LBB0_172
.LBB0_178:
	v_lshl_add_u64 v[60:61], v[64:65], 0, s[28:29]
	v_cvt_pk_bf16_f32 v56, v12, v13
	v_cvt_pk_bf16_f32 v57, v14, v15
	v_cvt_pk_bf16_f32 v58, v40, v41
	v_cvt_pk_bf16_f32 v59, v42, v43
	global_store_dwordx4 v[60:61], v[56:59], off sc1
	s_or_b64 exec, exec, s[2:3]
	s_and_saveexec_b64 s[2:3], s[8:9]
	s_cbranch_execz .LBB0_173
.LBB0_179:
	v_lshl_add_u64 v[60:61], v[64:65], 0, s[46:47]
	v_cvt_pk_bf16_f32 v56, v8, v9
	v_cvt_pk_bf16_f32 v57, v10, v11
	v_cvt_pk_bf16_f32 v58, v36, v37
	v_cvt_pk_bf16_f32 v59, v38, v39
	global_store_dwordx4 v[60:61], v[56:59], off sc1
	s_or_b64 exec, exec, s[2:3]
	s_and_saveexec_b64 s[2:3], s[10:11]
	s_cbranch_execz .LBB0_174
.LBB0_180:
	v_lshl_add_u64 v[60:61], v[64:65], 0, s[34:35]
	v_cvt_pk_bf16_f32 v56, v4, v5
	v_cvt_pk_bf16_f32 v57, v6, v7
	v_cvt_pk_bf16_f32 v58, v32, v33
	v_cvt_pk_bf16_f32 v59, v34, v35
	global_store_dwordx4 v[60:61], v[56:59], off sc1
	s_or_b64 exec, exec, s[2:3]
	s_and_saveexec_b64 s[2:3], s[12:13]
	s_cbranch_execz .LBB0_153
.LBB0_181:
	v_lshl_add_u64 v[60:61], v[64:65], 0, s[38:39]
	v_cvt_pk_bf16_f32 v56, v0, v1
	v_cvt_pk_bf16_f32 v57, v2, v3
	v_cvt_pk_bf16_f32 v58, v28, v29
	v_cvt_pk_bf16_f32 v59, v30, v31
	global_store_dwordx4 v[60:61], v[56:59], off sc1
	s_branch .LBB0_153

; __global__ void __launch_bounds__(512, 2) mk_fwd(Args args) {
;     ...
;         if (bxp == 1) { const float* lam = args.in[20]; float* SP8 = PF32(WS_SP8);
;             for (int i = tid; i < D; i += 512) SP8[i] = 8.0f * log1pf(expf(-lam[i])); }
.LBB0_186:
	global_load_dword v5, v[0:1], off
	v_add_u32_e32 v6, 0x200, v6
	v_cmp_lt_i32_e32 vcc, s17, v6
	s_or_b64 s[4:5], vcc, s[4:5]
	v_lshl_add_u64 v[0:1], v[0:1], 0, s[6:7]
	s_waitcnt vmcnt(0)
	v_mul_f32_e32 v9, 0xbfb8aa3b, v5
	v_rndne_f32_e32 v10, v9
	v_fma_f32 v11, v5, s8, -v9
	v_sub_f32_e32 v9, v9, v10
	v_fmac_f32_e32 v11, 0xb2a5705f, v5
	v_add_f32_e32 v9, v9, v11
	v_cvt_i32_f32_e32 v10, v10
	v_exp_f32_e32 v9, v9
	v_cmp_nlt_f32_e32 vcc, s9, v5
	v_ldexp_f32 v9, v9, v10
	s_nop 0
	v_cndmask_b32_e32 v9, 0, v9, vcc
	v_cmp_ngt_f32_e32 vcc, s10, v5
	s_nop 1
	v_cndmask_b32_e32 v9, v7, v9, vcc
	v_add_f32_e32 v5, 1.0, v9
	v_add_f32_e32 v12, -1.0, v5
	v_frexp_mant_f32_e32 v13, v5
	v_cvt_f64_f32_e32 v[10:11], v5
	v_sub_f32_e32 v14, v12, v5
	v_frexp_exp_i32_f64_e32 v10, v[10:11]
	v_cmp_gt_f32_e32 vcc, s12, v13
	v_sub_f32_e32 v12, v9, v12
	v_add_f32_e32 v11, 1.0, v14
	v_subbrev_co_u32_e32 v10, vcc, 0, v10, vcc
	v_add_f32_e32 v11, v12, v11
	v_sub_u32_e32 v12, 0, v10
	v_ldexp_f32 v5, v5, v12
	v_ldexp_f32 v11, v11, v12
	v_add_f32_e32 v12, -1.0, v5
	v_add_f32_e32 v14, 1.0, v5
	v_add_f32_e32 v13, 1.0, v12
	v_add_f32_e32 v15, -1.0, v14
	v_sub_f32_e32 v13, v5, v13
	v_sub_f32_e32 v5, v5, v15
	v_add_f32_e32 v5, v11, v5
	v_add_f32_e32 v15, v11, v13
	v_add_f32_e32 v11, v14, v5
	v_rcp_f32_e32 v18, v11
	v_add_f32_e32 v13, v12, v15
	v_sub_f32_e32 v14, v14, v11
	v_add_f32_e32 v5, v5, v14
	v_mul_f32_e32 v20, v13, v18
	v_mul_f32_e32 v14, v11, v20
	v_fma_f32 v16, v20, v11, -v14
	v_sub_f32_e32 v12, v12, v13
	v_fmac_f32_e32 v16, v20, v5
	v_add_f32_e32 v19, v15, v12
	v_add_f32_e32 v12, v14, v16
	v_sub_f32_e32 v15, v13, v12
	v_mov_b32_e32 v17, v12
	v_pk_add_f32 v[12:13], v[12:13], v[14:15] neg_lo:[0,1] neg_hi:[0,1]
	v_cvt_f32_i32_e32 v10, v10
	v_pk_add_f32 v[12:13], v[12:13], v[16:17] neg_lo:[0,1] neg_hi:[0,1]
	v_cmp_neq_f32_e32 vcc, s11, v9
	v_add_f32_e32 v13, v19, v13
	v_add_f32_e32 v12, v12, v13
	v_add_f32_e32 v13, v15, v12
	v_mul_f32_e32 v17, v18, v13
	v_mul_f32_e32 v14, v11, v17
	v_fma_f32 v16, v17, v11, -v14
	v_sub_f32_e32 v15, v15, v13
	v_fmac_f32_e32 v16, v17, v5
	v_add_f32_e32 v19, v12, v15
	v_add_f32_e32 v21, v20, v17
	v_add_f32_e32 v12, v14, v16
	v_sub_f32_e32 v11, v21, v20
	v_sub_f32_e32 v15, v13, v12
	v_sub_f32_e32 v5, v17, v11
	v_mov_b32_e32 v17, v12
	v_pk_add_f32 v[12:13], v[12:13], v[14:15] neg_lo:[0,1] neg_hi:[0,1]
	s_nop 0
	v_pk_add_f32 v[12:13], v[12:13], v[16:17] neg_lo:[0,1] neg_hi:[0,1]
	s_nop 0
	v_add_f32_e32 v11, v19, v13
	v_add_f32_e32 v11, v12, v11
	v_add_f32_e32 v11, v15, v11
	v_mul_f32_e32 v11, v18, v11
	v_add_f32_e32 v5, v5, v11
	v_add_f32_e32 v11, v21, v5
	v_mul_f32_e32 v12, v11, v11
	v_sub_f32_e32 v14, v11, v21
	v_fmamk_f32 v15, v12, 0x3e9b6dac, v8
	v_ldexp_f32 v13, v11, 1
	v_sub_f32_e32 v14, v5, v14
	v_mul_f32_e32 v11, v11, v12
	v_fmaak_f32 v5, v12, v15, 0x3f2aaada
	v_ldexp_f32 v17, v14, 1
	v_pk_mul_f32 v[14:15], v[10:11], v[4:5]
	s_nop 0
	v_fma_f32 v12, v10, s13, -v14
	v_fmac_f32_e32 v12, 0xb102e308, v10
	v_pk_add_f32 v[10:11], v[14:15], v[12:13]
	v_mov_b32_e32 v16, v14
	v_sub_f32_e32 v5, v11, v13
	v_sub_f32_e32 v5, v15, v5
	v_add_f32_e32 v17, v17, v5
	v_pk_add_f32 v[18:19], v[10:11], v[14:15] neg_lo:[0,1] neg_hi:[0,1]
	v_pk_add_f32 v[14:15], v[10:11], v[16:17]
	v_mov_b32_e32 v13, v10
	v_mov_b32_e32 v19, v15
	v_pk_add_f32 v[22:23], v[12:13], v[18:19] neg_lo:[0,1] neg_hi:[0,1]
	v_pk_add_f32 v[12:13], v[12:13], v[18:19]
	v_mov_b32_e32 v21, v10
	v_pk_add_f32 v[18:19], v[12:13], v[10:11] op_sel:[1,0] op_sel_hi:[0,1] neg_lo:[0,1] neg_hi:[0,1]
	v_mov_b32_e32 v20, v17
	v_mov_b32_e32 v16, v15
	v_mov_b32_e32 v17, v13
	v_pk_mov_b32 v[10:11], v[10:11], v[18:19] op_sel:[1,0]
	v_pk_add_f32 v[14:15], v[14:15], v[18:19] op_sel_hi:[1,0] neg_lo:[0,1] neg_hi:[0,1]
	v_pk_add_f32 v[10:11], v[16:17], v[10:11] neg_lo:[0,1] neg_hi:[0,1]
	v_mov_b32_e32 v14, v22
	v_pk_add_f32 v[10:11], v[20:21], v[10:11] neg_lo:[0,1] neg_hi:[0,1]
	v_mov_b32_e32 v23, v13
	v_pk_add_f32 v[14:15], v[14:15], v[10:11]
	s_nop 0
	v_pk_add_f32 v[16:17], v[14:15], v[14:15] op_sel:[0,1] op_sel_hi:[1,0]
	s_nop 0
	v_pk_add_f32 v[12:13], v[12:13], v[16:17] op_sel:[1,0] op_sel_hi:[0,1]
	v_mov_b32_e32 v15, v12
	v_mov_b32_e32 v11, v16
	v_pk_add_f32 v[16:17], v[14:15], v[22:23] neg_lo:[0,1] neg_hi:[0,1]
	s_nop 0
	v_sub_f32_e32 v5, v14, v16
	v_pk_add_f32 v[10:11], v[10:11], v[16:17] neg_lo:[0,1] neg_hi:[0,1]
	v_sub_f32_e32 v5, v22, v5
	v_add_f32_e32 v5, v10, v5
	v_add_f32_e32 v5, v5, v11
	v_add_f32_e32 v5, v12, v5
	v_cndmask_b32_e32 v5, v7, v5, vcc
	v_cmp_lt_f32_e64 vcc, |v9|, s16
	s_nop 1
	v_cndmask_b32_e32 v5, v5, v9, vcc
	v_mul_f32_e32 v5, 0x41000000, v5
	global_store_dword v[2:3], v5, off sc1
	v_lshl_add_u64 v[2:3], v[2:3], 0, s[6:7]
	s_andn2_b64 exec, exec, s[4:5]
	s_cbranch_execnz .LBB0_186

; __global__ void __launch_bounds__(512, 2) mk_fwd(Args args) {
;     ...
;         if (bxp == 0) { const float* rb = args.in[2]; float* BIAS = PF32(WS_BIAS);
;             for (int i = tid; i < 3 * NH * 129; i += 512) { const int g = i / (NH * 129), h = (i / 129) % NH, dist = i % 129; BIAS[i] = rb[rel_bucket(dist << (2 * g)) * NH + h] * LOG2E; } }
.LBB0_193:
	s_or_b64 exec, exec, s[10:11]
	v_lshrrev_b32_e32 v5, 29, v3
	v_add_u32_e32 v5, v3, v5
	v_and_b32_e32 v5, -8, v5
	v_sub_u32_e32 v3, v3, v5
	v_lshl_add_u32 v4, v4, 3, v3
	v_ashrrev_i32_e32 v5, 31, v4
	s_waitcnt lgkmcnt(0)
	v_lshl_add_u64 v[4:5], v[4:5], 2, s[4:5]
	global_load_dword v3, v[4:5], off
	v_add_u32_e32 v4, 0x200, v108
	v_cmp_lt_i32_e32 vcc, s18, v108
	s_or_b64 s[6:7], vcc, s[6:7]
	v_mov_b32_e32 v108, v4
	s_waitcnt vmcnt(0)
	v_mul_f32_e32 v3, 0x3fb8aa3b, v3
	global_store_dword v[0:1], v3, off sc1
	v_lshl_add_u64 v[0:1], v[0:1], 0, s[8:9]
	s_andn2_b64 exec, exec, s[6:7]
	s_cbranch_execz .LBB0_196

; __device__ __forceinline__ f32x4 bf4_lo(const u32x4 w) { return (f32x4){bf_lo(w.x), bf_hi(w.x), bf_lo(w.y), bf_hi(w.y)}; }
; __device__ __forceinline__ f32x4 bf4_hi(const u32x4 w) { return (f32x4){bf_lo(w.z), bf_hi(w.z), bf_lo(w.w), bf_hi(w.w)}; }
;     __device__ __forceinline__ void operator()(const Acc& acc, const Unit& u, int wr, int wc, int fr, int fq) const {
;     ...
;             if constexpr (BASE_F32) {
; #pragma unroll
;                 for (int m = 0; m < 4; ++m)
; #pragma unroll
;                     for (int bj = 0; bj < 2; ++bj) { const size_t off = (size_t)ROW_OF(u, ai, m) * D + colb + bj * 128; hv[m][bj][0] = *(const f32x4*)((const float*)base + off); hv[m][bj][1] = *(const f32x4*)((const float*)base + off + 4); }
;             } else {
;                 u32x4 hw[4][2];
; #pragma unroll
;                 for (int m = 0; m < 4; ++m)
; #pragma unroll
;                     for (int bj = 0; bj < 2; ++bj) hw[m][bj] = *(const u32x4*)((const bf16_t*)base + (size_t)ROW_OF(u, ai, m) * D + colb + bj * 128);
; #pragma unroll
;                 for (int m = 0; m < 4; ++m)
; #pragma unroll
;                     for (int bj = 0; bj < 2; ++bj) { hv[m][bj][0] = bf4_lo(hw[m][bj]); hv[m][bj][1] = bf4_hi(hw[m][bj]); }
;             }
; #pragma unroll
;             for (int m = 0; m < 4; ++m) {
;                 const int row = ROW_OF(u, ai, m); float sq = 0.f;
; #pragma unroll
;                 for (int bj = 0; bj < 2; ++bj) {
;                     const size_t off = (size_t)row * D + colb + bj * 128;
;                     const f32x4 h0 = hv[m][bj][0] + acc[ai][bj][m][0] * scale, h1 = hv[m][bj][1] + acc[ai][bj][m][1] * scale;
;                     *(u32x4*)(hb + off) = pack8(h0, h1);
;                     sq += (h0[0] * h0[0] + h0[1] * h0[1]) + (h0[2] * h0[2] + h0[3] * h0[3]) + (h1[0] * h1[0] + h1[1] * h1[1]) + (h1[2] * h1[2] + h1[3] * h1[3]);
;                 }
;                 sq = red4_sum(sq);
;                 if (fq == 0) ss_out[(size_t)row * 16 + u.pn * 4 + wc] = sq;
;             }
.LBB0_356:
	v_lshl_or_b32 v112, s10, 8, v206
	v_lshl_add_u32 v196, s57, 8, v204
	v_ashrrev_i32_e32 v113, 31, v112
	v_ashrrev_i32_e32 v197, 31, v196
	v_lshl_add_u64 v[194:195], v[112:113], 2, s[8:9]
	v_lshlrev_b64 v[0:1], 12, v[196:197]
	v_or_b32_e32 v202, 16, v196
	v_or_b32_e32 v200, 32, v196
	v_or_b32_e32 v198, 48, v196
	v_lshl_add_u64 v[0:1], v[194:195], 0, v[0:1]
	v_ashrrev_i32_e32 v203, 31, v202
	v_ashrrev_i32_e32 v201, 31, v200
	v_ashrrev_i32_e32 v199, 31, v198
	global_load_dwordx4 v[210:213], v[0:1], off
	global_load_dwordx4 v[214:217], v[0:1], off offset:16
	global_load_dwordx4 v[218:221], v[0:1], off offset:512
	global_load_dwordx4 v[222:225], v[0:1], off offset:528
	v_lshlrev_b64 v[0:1], 12, v[202:203]
	v_lshlrev_b64 v[2:3], 12, v[200:201]
	v_lshlrev_b64 v[4:5], 12, v[198:199]
	v_lshl_add_u64 v[0:1], v[194:195], 0, v[0:1]
	v_lshl_add_u64 v[2:3], v[194:195], 0, v[2:3]
	v_lshl_add_u64 v[4:5], v[194:195], 0, v[4:5]
	global_load_dwordx4 v[40:43], v[0:1], off offset:16
	global_load_dwordx4 v[44:47], v[0:1], off
	global_load_dwordx4 v[32:35], v[0:1], off offset:528
	global_load_dwordx4 v[36:39], v[0:1], off offset:512
	global_load_dwordx4 v[24:27], v[2:3], off offset:16
	global_load_dwordx4 v[28:31], v[2:3], off
	global_load_dwordx4 v[16:19], v[2:3], off offset:528
	global_load_dwordx4 v[20:23], v[2:3], off offset:512
	global_load_dwordx4 v[8:11], v[4:5], off offset:16
	global_load_dwordx4 v[12:15], v[4:5], off
	s_nop 0
	global_load_dwordx4 v[0:3], v[4:5], off offset:528
	s_nop 0
	global_load_dwordx4 v[4:7], v[4:5], off offset:512
	v_lshlrev_b64 v[226:227], 11, v[196:197]
	v_lshl_add_u64 v[226:227], s[14:15], 0, v[226:227]
	v_lshl_add_u64 v[226:227], v[112:113], 1, v[226:227]
	s_lshl_b32 s26, s10, 2
	s_ashr_i32 s27, s26, 31
	s_waitcnt vmcnt(0)
	v_pk_add_f32 v[212:213], v[178:179], v[212:213]
	v_pk_add_f32 v[210:211], v[180:181], v[210:211]
	v_pk_add_f32 v[192:193], v[192:193], v[220:221]
	v_pk_add_f32 v[190:191], v[190:191], v[218:219]
	v_pk_add_f32 v[182:183], v[182:183], v[216:217]
	v_pk_add_f32 v[184:185], v[184:185], v[214:215]
	v_pk_add_f32 v[186:187], v[186:187], v[222:223]
	v_cvt_pk_bf16_f32 v178, v210, v211
	v_cvt_pk_bf16_f32 v179, v212, v213
	v_mul_f32_e32 v211, v211, v211
	v_mul_f32_e32 v213, v213, v213
	v_mul_f32_e32 v214, v191, v191
	v_mul_f32_e32 v215, v193, v193
	v_pk_add_f32 v[188:189], v[188:189], v[224:225]
	v_cvt_pk_bf16_f32 v180, v184, v185
	v_cvt_pk_bf16_f32 v181, v182, v183
	v_mul_f32_e32 v185, v185, v185
	v_mul_f32_e32 v183, v183, v183
	v_mul_f32_e32 v216, v187, v187
	global_store_dwordx4 v[226:227], v[178:181], off sc1
	v_fmac_f32_e32 v211, v210, v210
	v_fmac_f32_e32 v213, v212, v212
	v_cvt_pk_bf16_f32 v178, v190, v191
	v_fmac_f32_e32 v214, v190, v190
	v_fmac_f32_e32 v215, v192, v192
	v_mul_f32_e32 v217, v189, v189
	v_fmac_f32_e32 v185, v184, v184
	v_fmac_f32_e32 v183, v182, v182
	v_cvt_pk_bf16_f32 v179, v192, v193
	v_cvt_pk_bf16_f32 v180, v186, v187
	v_cvt_pk_bf16_f32 v181, v188, v189
	v_fmac_f32_e32 v216, v186, v186
	v_add_f32_e32 v182, v211, v213
	global_store_dwordx4 v[226:227], v[178:181], off offset:256 sc1
	v_fmac_f32_e32 v217, v188, v188
	s_nop 0
	v_add_f32_e32 v178, v214, v215
	v_add_f32_e32 v179, v185, v182
	v_add_f32_e32 v178, v216, v178
	v_add_f32_e32 v179, v183, v179
	v_add_f32_e32 v178, v217, v178
	v_add_f32_e32 v178, v179, v178
	v_mov_b32_e32 v179, v178
	s_nop 1
	v_permlane16_swap_b32_e32 v178, v179
	v_add_f32_e32 v178, v178, v179
	v_mov_b32_e32 v179, v178
	s_nop 1
	v_permlane32_swap_b32_e32 v178, v179
	s_and_saveexec_b64 s[28:29], s[2:3]
	s_cbranch_execz .LBB0_358
	v_add_f32_e32 v180, v178, v179
	v_lshlrev_b64 v[178:179], 6, v[196:197]
	v_lshl_add_u64 v[178:179], s[16:17], 0, v[178:179]
	v_lshl_add_u64 v[178:179], s[26:27], 2, v[178:179]
	s_lshl_b32 s10, s45, 2
	v_lshl_add_u64 v[178:179], v[178:179], 0, s[10:11]
	global_store_dword v[178:179], v180, off sc1
.LBB0_358:
	s_or_b64 exec, exec, s[28:29]
	v_lshlrev_b64 v[178:179], 11, v[202:203]
	v_pk_add_f32 v[44:45], v[174:175], v[44:45]
	v_lshl_add_u64 v[174:175], s[14:15], 0, v[178:179]
	v_pk_add_f32 v[46:47], v[176:177], v[46:47]
	v_pk_add_f32 v[170:171], v[170:171], v[40:41]
	v_cvt_pk_bf16_f32 v40, v44, v45
	v_cvt_pk_bf16_f32 v41, v46, v47
	v_lshl_add_u64 v[174:175], v[112:113], 1, v[174:175]
	v_pk_add_f32 v[172:173], v[172:173], v[42:43]
	v_cvt_pk_bf16_f32 v42, v170, v171
	v_pk_add_f32 v[38:39], v[168:169], v[38:39]
	v_cvt_pk_bf16_f32 v43, v172, v173
	global_store_dwordx4 v[174:175], v[40:43], off sc1
	v_pk_add_f32 v[36:37], v[166:167], v[36:37]
	s_nop 0
	v_mul_f32_e32 v40, v45, v45
	v_mul_f32_e32 v41, v47, v47
	v_fmac_f32_e32 v40, v44, v44
	v_fmac_f32_e32 v41, v46, v46
	v_add_f32_e32 v40, v40, v41
	v_mul_f32_e32 v41, v171, v171
	v_fmac_f32_e32 v41, v170, v170
	v_add_f32_e32 v40, v41, v40
	v_mul_f32_e32 v41, v173, v173
	v_fmac_f32_e32 v41, v172, v172
	v_pk_add_f32 v[42:43], v[162:163], v[32:33]
	v_cvt_pk_bf16_f32 v32, v36, v37
	v_cvt_pk_bf16_f32 v33, v38, v39
	v_add_f32_e32 v44, v41, v40
	v_pk_add_f32 v[40:41], v[164:165], v[34:35]
	v_cvt_pk_bf16_f32 v34, v42, v43
	s_nop 0
	v_cvt_pk_bf16_f32 v35, v40, v41
	global_store_dwordx4 v[174:175], v[32:35], off offset:256 sc1
	s_nop 1
	v_mul_f32_e32 v32, v37, v37
	v_mul_f32_e32 v33, v39, v39
	v_fmac_f32_e32 v32, v36, v36
	v_fmac_f32_e32 v33, v38, v38
	v_add_f32_e32 v32, v32, v33
	v_mul_f32_e32 v33, v43, v43
	v_fmac_f32_e32 v33, v42, v42
	v_add_f32_e32 v32, v33, v32
	v_mul_f32_e32 v33, v41, v41
	v_fmac_f32_e32 v33, v40, v40
	v_add_f32_e32 v32, v33, v32
	v_add_f32_e32 v32, v44, v32
	v_mov_b32_e32 v33, v32
	s_nop 1
	v_permlane16_swap_b32_e32 v32, v33
	v_add_f32_e32 v32, v32, v33
	v_mov_b32_e32 v33, v32
	s_nop 1
	v_permlane32_swap_b32_e32 v32, v33
	s_and_saveexec_b64 s[28:29], s[2:3]
	s_cbranch_execz .LBB0_360
	v_add_f32_e32 v34, v32, v33
	v_lshlrev_b64 v[32:33], 6, v[202:203]
	v_lshl_add_u64 v[32:33], s[16:17], 0, v[32:33]
	v_lshl_add_u64 v[32:33], s[26:27], 2, v[32:33]
	s_lshl_b32 s10, s45, 2
	v_lshl_add_u64 v[32:33], v[32:33], 0, s[10:11]
	global_store_dword v[32:33], v34, off sc1
; __device__ __forceinline__ f32x4 bf4_lo(const u32x4 w) { return (f32x4){bf_lo(w.x), bf_hi(w.x), bf_lo(w.y), bf_hi(w.y)}; }
; __device__ __forceinline__ f32x4 bf4_hi(const u32x4 w) { return (f32x4){bf_lo(w.z), bf_hi(w.z), bf_lo(w.w), bf_hi(w.w)}; }
;     __device__ __forceinline__ void operator()(const Acc& acc, const Unit& u, int wr, int wc, int fr, int fq) const {
;     ...
;             if constexpr (BASE_F32) {
; #pragma unroll
;                 for (int m = 0; m < 4; ++m)
; #pragma unroll
;                     for (int bj = 0; bj < 2; ++bj) { const size_t off = (size_t)ROW_OF(u, ai, m) * D + colb + bj * 128; hv[m][bj][0] = *(const f32x4*)((const float*)base + off); hv[m][bj][1] = *(const f32x4*)((const float*)base + off + 4); }
;             } else {
;                 u32x4 hw[4][2];
; #pragma unroll
;                 for (int m = 0; m < 4; ++m)
; #pragma unroll
;                     for (int bj = 0; bj < 2; ++bj) hw[m][bj] = *(const u32x4*)((const bf16_t*)base + (size_t)ROW_OF(u, ai, m) * D + colb + bj * 128);
; #pragma unroll
;                 for (int m = 0; m < 4; ++m)
; #pragma unroll
;                     for (int bj = 0; bj < 2; ++bj) { hv[m][bj][0] = bf4_lo(hw[m][bj]); hv[m][bj][1] = bf4_hi(hw[m][bj]); }
;             }
; #pragma unroll
;             for (int m = 0; m < 4; ++m) {
;                 const int row = ROW_OF(u, ai, m); float sq = 0.f;
; #pragma unroll
;                 for (int bj = 0; bj < 2; ++bj) {
;                     const size_t off = (size_t)row * D + colb + bj * 128;
;                     const f32x4 h0 = hv[m][bj][0] + acc[ai][bj][m][0] * scale, h1 = hv[m][bj][1] + acc[ai][bj][m][1] * scale;
;                     *(u32x4*)(hb + off) = pack8(h0, h1);
;                     sq += (h0[0] * h0[0] + h0[1] * h0[1]) + (h0[2] * h0[2] + h0[3] * h0[3]) + (h1[0] * h1[0] + h1[1] * h1[1]) + (h1[2] * h1[2] + h1[3] * h1[3]);
;                 }
;                 sq = red4_sum(sq);
;                 if (fq == 0) ss_out[(size_t)row * 16 + u.pn * 4 + wc] = sq;
;             }
.LBB0_360:
	s_or_b64 exec, exec, s[28:29]
	v_lshlrev_b64 v[32:33], 11, v[200:201]
	v_lshl_add_u64 v[32:33], s[14:15], 0, v[32:33]
	v_pk_add_f32 v[30:31], v[160:161], v[30:31]
	v_pk_add_f32 v[28:29], v[158:159], v[28:29]
	v_pk_add_f32 v[36:37], v[154:155], v[24:25]
	v_cvt_pk_bf16_f32 v24, v28, v29
	v_cvt_pk_bf16_f32 v25, v30, v31
	v_lshl_add_u64 v[32:33], v[112:113], 1, v[32:33]
	v_pk_add_f32 v[34:35], v[156:157], v[26:27]
	v_cvt_pk_bf16_f32 v26, v36, v37
	v_pk_add_f32 v[22:23], v[152:153], v[22:23]
	v_cvt_pk_bf16_f32 v27, v34, v35
	global_store_dwordx4 v[32:33], v[24:27], off sc1
	v_pk_add_f32 v[20:21], v[150:151], v[20:21]
	s_nop 0
	v_mul_f32_e32 v24, v29, v29
	v_mul_f32_e32 v25, v31, v31
	v_fmac_f32_e32 v24, v28, v28
	v_fmac_f32_e32 v25, v30, v30
	v_add_f32_e32 v24, v24, v25
	v_mul_f32_e32 v25, v37, v37
	v_fmac_f32_e32 v25, v36, v36
	v_add_f32_e32 v24, v25, v24
	v_mul_f32_e32 v25, v35, v35
	v_fmac_f32_e32 v25, v34, v34
	v_pk_add_f32 v[26:27], v[146:147], v[16:17]
	v_cvt_pk_bf16_f32 v16, v20, v21
	v_cvt_pk_bf16_f32 v17, v22, v23
	v_add_f32_e32 v28, v25, v24
	v_pk_add_f32 v[24:25], v[148:149], v[18:19]
	v_cvt_pk_bf16_f32 v18, v26, v27
	s_nop 0
	v_cvt_pk_bf16_f32 v19, v24, v25
	global_store_dwordx4 v[32:33], v[16:19], off offset:256 sc1
	s_nop 1
	v_mul_f32_e32 v16, v21, v21
	v_mul_f32_e32 v17, v23, v23
	v_fmac_f32_e32 v16, v20, v20
	v_fmac_f32_e32 v17, v22, v22
	v_add_f32_e32 v16, v16, v17
	v_mul_f32_e32 v17, v27, v27
	v_fmac_f32_e32 v17, v26, v26
	v_add_f32_e32 v16, v17, v16
	v_mul_f32_e32 v17, v25, v25
	v_fmac_f32_e32 v17, v24, v24
	v_add_f32_e32 v16, v17, v16
	v_add_f32_e32 v16, v28, v16
	v_mov_b32_e32 v17, v16
	s_nop 1
	v_permlane16_swap_b32_e32 v16, v17
	v_add_f32_e32 v16, v16, v17
	v_mov_b32_e32 v17, v16
	s_nop 1
	v_permlane32_swap_b32_e32 v16, v17
	s_and_saveexec_b64 s[28:29], s[2:3]
	s_cbranch_execz .LBB0_362
	v_add_f32_e32 v18, v16, v17
	v_lshlrev_b64 v[16:17], 6, v[200:201]
	v_lshl_add_u64 v[16:17], s[16:17], 0, v[16:17]
	v_lshl_add_u64 v[16:17], s[26:27], 2, v[16:17]
	s_lshl_b32 s10, s45, 2
	v_lshl_add_u64 v[16:17], v[16:17], 0, s[10:11]
	global_store_dword v[16:17], v18, off sc1
.LBB0_362:
	s_or_b64 exec, exec, s[28:29]
	v_lshlrev_b64 v[16:17], 11, v[198:199]
	v_lshl_add_u64 v[16:17], s[14:15], 0, v[16:17]
	v_pk_add_f32 v[14:15], v[144:145], v[14:15]
	v_pk_add_f32 v[12:13], v[126:127], v[12:13]
	v_pk_add_f32 v[20:21], v[122:123], v[8:9]
	v_cvt_pk_bf16_f32 v8, v12, v13
	v_cvt_pk_bf16_f32 v9, v14, v15
	v_lshl_add_u64 v[16:17], v[112:113], 1, v[16:17]
	v_pk_add_f32 v[18:19], v[124:125], v[10:11]
	v_cvt_pk_bf16_f32 v10, v20, v21
	v_pk_add_f32 v[6:7], v[120:121], v[6:7]
	v_cvt_pk_bf16_f32 v11, v18, v19
	global_store_dwordx4 v[16:17], v[8:11], off sc1
	v_pk_add_f32 v[4:5], v[118:119], v[4:5]
	s_nop 0
	v_mul_f32_e32 v8, v13, v13
	v_mul_f32_e32 v9, v15, v15
	v_fmac_f32_e32 v8, v12, v12
	v_fmac_f32_e32 v9, v14, v14
	v_add_f32_e32 v8, v8, v9
	v_mul_f32_e32 v9, v21, v21
	v_fmac_f32_e32 v9, v20, v20
	v_add_f32_e32 v8, v9, v8
	v_mul_f32_e32 v9, v19, v19
	v_fmac_f32_e32 v9, v18, v18
	v_pk_add_f32 v[10:11], v[114:115], v[0:1]
	v_cvt_pk_bf16_f32 v0, v4, v5
	v_cvt_pk_bf16_f32 v1, v6, v7
	v_add_f32_e32 v12, v9, v8
	v_pk_add_f32 v[8:9], v[116:117], v[2:3]
	v_cvt_pk_bf16_f32 v2, v10, v11
	s_nop 0
	v_cvt_pk_bf16_f32 v3, v8, v9
	global_store_dwordx4 v[16:17], v[0:3], off offset:256 sc1
	s_nop 1
	v_mul_f32_e32 v0, v5, v5
	v_mul_f32_e32 v1, v7, v7
	v_fmac_f32_e32 v0, v4, v4
	v_fmac_f32_e32 v1, v6, v6
	v_add_f32_e32 v0, v0, v1
	v_mul_f32_e32 v1, v11, v11
	v_fmac_f32_e32 v1, v10, v10
	v_add_f32_e32 v0, v1, v0
	v_mul_f32_e32 v1, v9, v9
	v_fmac_f32_e32 v1, v8, v8
	v_add_f32_e32 v0, v1, v0
	v_add_f32_e32 v0, v12, v0
	v_mov_b32_e32 v1, v0
	s_nop 1
	v_permlane16_swap_b32_e32 v0, v1
	v_add_f32_e32 v0, v0, v1
	v_mov_b32_e32 v1, v0
	s_nop 1
	v_permlane32_swap_b32_e32 v0, v1
	s_and_saveexec_b64 s[28:29], s[2:3]
	s_cbranch_execz .LBB0_364
	v_add_f32_e32 v2, v0, v1
	v_lshlrev_b64 v[0:1], 6, v[198:199]
	v_lshl_add_u64 v[0:1], s[16:17], 0, v[0:1]
	v_lshl_add_u64 v[0:1], s[26:27], 2, v[0:1]
	s_lshl_b32 s10, s45, 2
	v_lshl_add_u64 v[0:1], v[0:1], 0, s[10:11]
	global_store_dword v[0:1], v2, off sc1
.LBB0_364:
	s_or_b64 exec, exec, s[28:29]
	v_add_u32_e32 v120, 0x80, v196
	v_ashrrev_i32_e32 v121, 31, v120
	v_lshlrev_b64 v[0:1], 12, v[120:121]
	v_add_u32_e32 v118, 0x90, v196
	v_add_u32_e32 v116, 0xa0, v196
	v_add_u32_e32 v114, 0xb0, v196
	v_lshl_add_u64 v[0:1], v[194:195], 0, v[0:1]
	v_ashrrev_i32_e32 v119, 31, v118
	v_ashrrev_i32_e32 v117, 31, v116
	v_ashrrev_i32_e32 v115, 31, v114
	global_load_dwordx4 v[122:125], v[0:1], off
	global_load_dwordx4 v[144:147], v[0:1], off offset:16
	global_load_dwordx4 v[148:151], v[0:1], off offset:512
	global_load_dwordx4 v[152:155], v[0:1], off offset:528
	v_lshlrev_b64 v[0:1], 12, v[118:119]
	v_lshlrev_b64 v[2:3], 12, v[116:117]
	v_lshlrev_b64 v[4:5], 12, v[114:115]
	v_lshl_add_u64 v[0:1], v[194:195], 0, v[0:1]
	v_lshl_add_u64 v[2:3], v[194:195], 0, v[2:3]
	v_lshl_add_u64 v[4:5], v[194:195], 0, v[4:5]
	global_load_dwordx4 v[40:43], v[0:1], off offset:16
	global_load_dwordx4 v[44:47], v[0:1], off
	global_load_dwordx4 v[32:35], v[0:1], off offset:528
	global_load_dwordx4 v[36:39], v[0:1], off offset:512
	global_load_dwordx4 v[24:27], v[2:3], off offset:16
	global_load_dwordx4 v[28:31], v[2:3], off
	global_load_dwordx4 v[16:19], v[2:3], off offset:528
	global_load_dwordx4 v[20:23], v[2:3], off offset:512
	global_load_dwordx4 v[8:11], v[4:5], off offset:16
	global_load_dwordx4 v[12:15], v[4:5], off
	s_nop 0
	global_load_dwordx4 v[0:3], v[4:5], off offset:528
	s_nop 0
	global_load_dwordx4 v[4:7], v[4:5], off offset:512
	v_lshlrev_b64 v[126:127], 11, v[120:121]
	v_lshl_add_u64 v[126:127], s[14:15], 0, v[126:127]
	v_lshl_add_u64 v[126:127], v[112:113], 1, v[126:127]
	s_waitcnt vmcnt(0)
;     __device__ __forceinline__ void operator()(const Acc& acc, const Unit& u, int wr, int wc, int fr, int fq) const {
;     ...
; #pragma unroll
;             for (int m = 0; m < 4; ++m) {
;                 const int row = ROW_OF(u, ai, m); float sq = 0.f;
; #pragma unroll
;                 for (int bj = 0; bj < 2; ++bj) {
;                     const size_t off = (size_t)row * D + colb + bj * 128;
;                     const f32x4 h0 = hv[m][bj][0] + acc[ai][bj][m][0] * scale, h1 = hv[m][bj][1] + acc[ai][bj][m][1] * scale;
;                     *(u32x4*)(hb + off) = pack8(h0, h1);
;                     sq += (h0[0] * h0[0] + h0[1] * h0[1]) + (h0[2] * h0[2] + h0[3] * h0[3]) + (h1[0] * h1[0] + h1[1] * h1[1]) + (h1[2] * h1[2] + h1[3] * h1[3]);
;                 }
;                 sq = red4_sum(sq);
;                 if (fq == 0) ss_out[(size_t)row * 16 + u.pn * 4 + wc] = sq;
;             }
	v_pk_add_f32 v[124:125], v[96:97], v[124:125]
	v_pk_add_f32 v[122:123], v[98:99], v[122:123]
	v_pk_add_f32 v[110:111], v[110:111], v[150:151]
	v_pk_add_f32 v[108:109], v[108:109], v[148:149]
	v_pk_add_f32 v[100:101], v[100:101], v[146:147]
	v_pk_add_f32 v[102:103], v[102:103], v[144:145]
	v_pk_add_f32 v[104:105], v[104:105], v[152:153]
	v_cvt_pk_bf16_f32 v96, v122, v123
	v_cvt_pk_bf16_f32 v97, v124, v125
	v_mul_f32_e32 v123, v123, v123
	v_mul_f32_e32 v125, v125, v125
	v_mul_f32_e32 v144, v109, v109
	v_mul_f32_e32 v145, v111, v111
	v_pk_add_f32 v[106:107], v[106:107], v[154:155]
	v_cvt_pk_bf16_f32 v98, v102, v103
	v_cvt_pk_bf16_f32 v99, v100, v101
	v_mul_f32_e32 v103, v103, v103
	v_mul_f32_e32 v101, v101, v101
	v_mul_f32_e32 v146, v105, v105
	global_store_dwordx4 v[126:127], v[96:99], off sc1
	v_fmac_f32_e32 v123, v122, v122
	v_fmac_f32_e32 v125, v124, v124
	v_cvt_pk_bf16_f32 v96, v108, v109
	v_fmac_f32_e32 v144, v108, v108
	v_fmac_f32_e32 v145, v110, v110
	v_mul_f32_e32 v147, v107, v107
	v_fmac_f32_e32 v103, v102, v102
	v_fmac_f32_e32 v101, v100, v100
	v_cvt_pk_bf16_f32 v97, v110, v111
	v_cvt_pk_bf16_f32 v98, v104, v105
	v_cvt_pk_bf16_f32 v99, v106, v107
	v_fmac_f32_e32 v146, v104, v104
	v_add_f32_e32 v100, v123, v125
	global_store_dwordx4 v[126:127], v[96:99], off offset:256 sc1
	v_fmac_f32_e32 v147, v106, v106
	s_nop 0
	v_add_f32_e32 v96, v144, v145
	v_add_f32_e32 v97, v103, v100
	v_add_f32_e32 v96, v146, v96
	v_add_f32_e32 v97, v101, v97
	v_add_f32_e32 v96, v147, v96
	v_add_f32_e32 v96, v97, v96
	v_mov_b32_e32 v97, v96
	s_nop 1
	v_permlane16_swap_b32_e32 v96, v97
	v_add_f32_e32 v96, v96, v97
	v_mov_b32_e32 v97, v96
	s_nop 1
	v_permlane32_swap_b32_e32 v96, v97
	s_and_saveexec_b64 s[28:29], s[2:3]
	s_cbranch_execz .LBB0_366
	v_add_f32_e32 v98, v96, v97
	v_lshlrev_b64 v[96:97], 6, v[120:121]
	v_lshl_add_u64 v[96:97], s[16:17], 0, v[96:97]
	v_lshl_add_u64 v[96:97], s[26:27], 2, v[96:97]
	s_lshl_b32 s10, s45, 2
	v_lshl_add_u64 v[96:97], v[96:97], 0, s[10:11]
	global_store_dword v[96:97], v98, off sc1
.LBB0_366:
	s_or_b64 exec, exec, s[28:29]
	v_lshlrev_b64 v[96:97], 11, v[118:119]
	v_pk_add_f32 v[44:45], v[92:93], v[44:45]
	v_lshl_add_u64 v[92:93], s[14:15], 0, v[96:97]
	v_pk_add_f32 v[46:47], v[94:95], v[46:47]
	v_pk_add_f32 v[88:89], v[88:89], v[40:41]
	v_cvt_pk_bf16_f32 v40, v44, v45
	v_cvt_pk_bf16_f32 v41, v46, v47
	v_lshl_add_u64 v[92:93], v[112:113], 1, v[92:93]
	v_pk_add_f32 v[90:91], v[90:91], v[42:43]
	v_cvt_pk_bf16_f32 v42, v88, v89
	v_pk_add_f32 v[38:39], v[86:87], v[38:39]
	v_cvt_pk_bf16_f32 v43, v90, v91
	global_store_dwordx4 v[92:93], v[40:43], off sc1
	v_pk_add_f32 v[36:37], v[84:85], v[36:37]
	s_nop 0
	v_mul_f32_e32 v40, v45, v45
	v_mul_f32_e32 v41, v47, v47
	v_fmac_f32_e32 v40, v44, v44
	v_fmac_f32_e32 v41, v46, v46
	v_add_f32_e32 v40, v40, v41
	v_mul_f32_e32 v41, v89, v89
	v_fmac_f32_e32 v41, v88, v88
	v_add_f32_e32 v40, v41, v40
	v_mul_f32_e32 v41, v91, v91
	v_fmac_f32_e32 v41, v90, v90
	v_pk_add_f32 v[42:43], v[80:81], v[32:33]
	v_cvt_pk_bf16_f32 v32, v36, v37
	v_cvt_pk_bf16_f32 v33, v38, v39
	v_add_f32_e32 v44, v41, v40
	v_pk_add_f32 v[40:41], v[82:83], v[34:35]
	v_cvt_pk_bf16_f32 v34, v42, v43
	s_nop 0
	v_cvt_pk_bf16_f32 v35, v40, v41
	global_store_dwordx4 v[92:93], v[32:35], off offset:256 sc1
	s_nop 1
	v_mul_f32_e32 v32, v37, v37
	v_mul_f32_e32 v33, v39, v39
	v_fmac_f32_e32 v32, v36, v36
	v_fmac_f32_e32 v33, v38, v38
	v_add_f32_e32 v32, v32, v33
	v_mul_f32_e32 v33, v43, v43
	v_fmac_f32_e32 v33, v42, v42
	v_add_f32_e32 v32, v33, v32
	v_mul_f32_e32 v33, v41, v41
	v_fmac_f32_e32 v33, v40, v40
	v_add_f32_e32 v32, v33, v32
	v_add_f32_e32 v32, v44, v32
	v_mov_b32_e32 v33, v32
	s_nop 1
	v_permlane16_swap_b32_e32 v32, v33
	v_add_f32_e32 v32, v32, v33
	v_mov_b32_e32 v33, v32
	s_nop 1
	v_permlane32_swap_b32_e32 v32, v33
	s_and_saveexec_b64 s[28:29], s[2:3]
	s_cbranch_execz .LBB0_368
	v_add_f32_e32 v34, v32, v33
	v_lshlrev_b64 v[32:33], 6, v[118:119]
	v_lshl_add_u64 v[32:33], s[16:17], 0, v[32:33]
	v_lshl_add_u64 v[32:33], s[26:27], 2, v[32:33]
	s_lshl_b32 s10, s45, 2
	v_lshl_add_u64 v[32:33], v[32:33], 0, s[10:11]
	global_store_dword v[32:33], v34, off sc1
;     __device__ __forceinline__ void operator()(const Acc& acc, const Unit& u, int wr, int wc, int fr, int fq) const {
;     ...
; #pragma unroll
;             for (int m = 0; m < 4; ++m) {
;                 const int row = ROW_OF(u, ai, m); float sq = 0.f;
; #pragma unroll
;                 for (int bj = 0; bj < 2; ++bj) {
;                     const size_t off = (size_t)row * D + colb + bj * 128;
;                     const f32x4 h0 = hv[m][bj][0] + acc[ai][bj][m][0] * scale, h1 = hv[m][bj][1] + acc[ai][bj][m][1] * scale;
;                     *(u32x4*)(hb + off) = pack8(h0, h1);
;                     sq += (h0[0] * h0[0] + h0[1] * h0[1]) + (h0[2] * h0[2] + h0[3] * h0[3]) + (h1[0] * h1[0] + h1[1] * h1[1]) + (h1[2] * h1[2] + h1[3] * h1[3]);
;                 }
;                 sq = red4_sum(sq);
;                 if (fq == 0) ss_out[(size_t)row * 16 + u.pn * 4 + wc] = sq;
;             }
.LBB0_368:
	s_or_b64 exec, exec, s[28:29]
	v_lshlrev_b64 v[32:33], 11, v[116:117]
	v_lshl_add_u64 v[32:33], s[14:15], 0, v[32:33]
	v_pk_add_f32 v[30:31], v[78:79], v[30:31]
	v_pk_add_f32 v[28:29], v[76:77], v[28:29]
	v_pk_add_f32 v[36:37], v[72:73], v[24:25]
	v_cvt_pk_bf16_f32 v24, v28, v29
	v_cvt_pk_bf16_f32 v25, v30, v31
	v_lshl_add_u64 v[32:33], v[112:113], 1, v[32:33]
	v_pk_add_f32 v[34:35], v[74:75], v[26:27]
	v_cvt_pk_bf16_f32 v26, v36, v37
	v_pk_add_f32 v[22:23], v[70:71], v[22:23]
	v_cvt_pk_bf16_f32 v27, v34, v35
	global_store_dwordx4 v[32:33], v[24:27], off sc1
	v_pk_add_f32 v[20:21], v[68:69], v[20:21]
	s_nop 0
	v_mul_f32_e32 v24, v29, v29
	v_mul_f32_e32 v25, v31, v31
	v_fmac_f32_e32 v24, v28, v28
	v_fmac_f32_e32 v25, v30, v30
	v_add_f32_e32 v24, v24, v25
	v_mul_f32_e32 v25, v37, v37
	v_fmac_f32_e32 v25, v36, v36
	v_add_f32_e32 v24, v25, v24
	v_mul_f32_e32 v25, v35, v35
	v_fmac_f32_e32 v25, v34, v34
	v_pk_add_f32 v[26:27], v[64:65], v[16:17]
	v_cvt_pk_bf16_f32 v16, v20, v21
	v_cvt_pk_bf16_f32 v17, v22, v23
	v_add_f32_e32 v28, v25, v24
	v_pk_add_f32 v[24:25], v[66:67], v[18:19]
	v_cvt_pk_bf16_f32 v18, v26, v27
	s_nop 0
	v_cvt_pk_bf16_f32 v19, v24, v25
	global_store_dwordx4 v[32:33], v[16:19], off offset:256 sc1
	s_nop 1
	v_mul_f32_e32 v16, v21, v21
	v_mul_f32_e32 v17, v23, v23
	v_fmac_f32_e32 v16, v20, v20
	v_fmac_f32_e32 v17, v22, v22
	v_add_f32_e32 v16, v16, v17
	v_mul_f32_e32 v17, v27, v27
	v_fmac_f32_e32 v17, v26, v26
	v_add_f32_e32 v16, v17, v16
	v_mul_f32_e32 v17, v25, v25
	v_fmac_f32_e32 v17, v24, v24
	v_add_f32_e32 v16, v17, v16
	v_add_f32_e32 v16, v28, v16
	v_mov_b32_e32 v17, v16
	s_nop 1
	v_permlane16_swap_b32_e32 v16, v17
	v_add_f32_e32 v16, v16, v17
	v_mov_b32_e32 v17, v16
	s_nop 1
	v_permlane32_swap_b32_e32 v16, v17
	s_and_saveexec_b64 s[28:29], s[2:3]
	s_cbranch_execz .LBB0_370
	v_add_f32_e32 v18, v16, v17
	v_lshlrev_b64 v[16:17], 6, v[116:117]
	v_lshl_add_u64 v[16:17], s[16:17], 0, v[16:17]
	v_lshl_add_u64 v[16:17], s[26:27], 2, v[16:17]
	s_lshl_b32 s10, s45, 2
	v_lshl_add_u64 v[16:17], v[16:17], 0, s[10:11]
	global_store_dword v[16:17], v18, off sc1
.LBB0_370:
	s_or_b64 exec, exec, s[28:29]
	v_lshlrev_b64 v[16:17], 11, v[114:115]
	v_lshl_add_u64 v[16:17], s[14:15], 0, v[16:17]
	v_pk_add_f32 v[14:15], v[62:63], v[14:15]
	v_pk_add_f32 v[12:13], v[60:61], v[12:13]
	v_pk_add_f32 v[20:21], v[56:57], v[8:9]
	v_cvt_pk_bf16_f32 v8, v12, v13
	v_cvt_pk_bf16_f32 v9, v14, v15
	v_lshl_add_u64 v[16:17], v[112:113], 1, v[16:17]
	v_pk_add_f32 v[18:19], v[58:59], v[10:11]
	v_cvt_pk_bf16_f32 v10, v20, v21
	v_pk_add_f32 v[6:7], v[54:55], v[6:7]
	v_cvt_pk_bf16_f32 v11, v18, v19
	global_store_dwordx4 v[16:17], v[8:11], off sc1
	v_pk_add_f32 v[4:5], v[52:53], v[4:5]
	s_nop 0
	v_mul_f32_e32 v8, v13, v13
	v_mul_f32_e32 v9, v15, v15
	v_fmac_f32_e32 v8, v12, v12
	v_fmac_f32_e32 v9, v14, v14
	v_add_f32_e32 v8, v8, v9
	v_mul_f32_e32 v9, v21, v21
	v_fmac_f32_e32 v9, v20, v20
	v_add_f32_e32 v8, v9, v8
	v_mul_f32_e32 v9, v19, v19
	v_fmac_f32_e32 v9, v18, v18
	v_pk_add_f32 v[10:11], v[48:49], v[0:1]
	v_cvt_pk_bf16_f32 v0, v4, v5
	v_cvt_pk_bf16_f32 v1, v6, v7
	v_add_f32_e32 v12, v9, v8
	v_pk_add_f32 v[8:9], v[50:51], v[2:3]
	v_cvt_pk_bf16_f32 v2, v10, v11
	s_nop 0
	v_cvt_pk_bf16_f32 v3, v8, v9
	global_store_dwordx4 v[16:17], v[0:3], off offset:256 sc1
	s_nop 1
	v_mul_f32_e32 v0, v5, v5
	v_mul_f32_e32 v1, v7, v7
	v_fmac_f32_e32 v0, v4, v4
	v_fmac_f32_e32 v1, v6, v6
	v_add_f32_e32 v0, v0, v1
	v_mul_f32_e32 v1, v11, v11
	v_fmac_f32_e32 v1, v10, v10
	v_add_f32_e32 v0, v1, v0
	v_mul_f32_e32 v1, v9, v9
	v_fmac_f32_e32 v1, v8, v8
	v_add_f32_e32 v0, v1, v0
	v_add_f32_e32 v0, v12, v0
	v_mov_b32_e32 v1, v0
	s_nop 1
	v_permlane16_swap_b32_e32 v0, v1
	v_add_f32_e32 v0, v0, v1
	v_mov_b32_e32 v1, v0
	s_nop 1
	v_permlane32_swap_b32_e32 v0, v1
	s_and_saveexec_b64 s[28:29], s[2:3]
	s_cbranch_execz .LBB0_372
	v_add_f32_e32 v2, v0, v1
	v_lshlrev_b64 v[0:1], 6, v[114:115]
	v_lshl_add_u64 v[0:1], s[16:17], 0, v[0:1]
	v_lshl_add_u64 v[0:1], s[26:27], 2, v[0:1]
	s_lshl_b32 s10, s45, 2
	v_lshl_add_u64 v[0:1], v[0:1], 0, s[10:11]
	global_store_dword v[0:1], v2, off sc1

; #define ROW_RS(u, ai, m) row_rs_lds((ai) * 128 + wr * 64 + (m) * 16 + fr, fq)
; #define ROWLOOP for (int ai = 0; ai < 2; ++ai) _Pragma("unroll") for (int m = 0; m < 4; ++m)
;     __device__ __forceinline__ void operator()(const Acc& acc, const Unit& u, int wr, int wc, int fr, int fq) const {
;     ...
;         } else {
;             const bool isq = pn < 8; bf16_t* o = isq ? Q : Kb; const float* gp = isq ? qg : kg; const float sc = isq ? QSCALE : 1.0f;
;             const int head = 4 * (pn & 1) + wc;
;             f32x4 gn[2][2];
; #pragma unroll
;             for (int bj = 0; bj < 2; ++bj)
; #pragma unroll
;                 for (int n = 0; n < 2; ++n) gn[bj][n] = *(const f32x4*)(gp + bj * 32 + fq * 8 + n * 4) * sc;
; #pragma unroll
;             ROWLOOP { const int row = ROW_OF(u, ai, m); const float rs = ROW_RS(u, ai, m);
;                 f32x4 v[2][2]; float sq = 0.f;
; #pragma unroll
;                 for (int bj = 0; bj < 2; ++bj)
; #pragma unroll
;                     for (int n = 0; n < 2; ++n) { v[bj][n] = acc[ai][bj][m][n] * rs; sq += (v[bj][n][0] * v[bj][n][0] + v[bj][n][1] * v[bj][n][1]) + (v[bj][n][2] * v[bj][n][2] + v[bj][n][3] * v[bj][n][3]); }
;                 sq = red4_sum(sq);
;                 const float rr = __builtin_amdgcn_rsqf(sq * (1.0f / HD) + EPS);
; #pragma unroll
;                 for (int bj = 0; bj < 2; ++bj) *(u32x4*)(o + (size_t)row * CW + head * 64 + bj * 32 + fq * 8) = pack8(v[bj][0] * rr * gn[bj][0], v[bj][1] * rr * gn[bj][1]);
;             }
.LBB0_450:
	s_cmp_gt_u32 s33, 5
	s_cbranch_scc0 .LBB0_452
	s_cmp_lt_u32 s33, 8
	s_cselect_b64 vcc, -1, 0
	s_and_b64 s[36:37], vcc, exec
	s_cselect_b32 s4, s63, 0x14100000
	s_add_u32 s4, s6, s4
	s_addc_u32 s25, s7, 0
	s_and_b64 s[36:37], vcc, exec
	s_waitcnt lgkmcnt(0)
	s_cselect_b32 s37, s9, s11
	s_cselect_b32 s36, s8, s10
	v_lshlrev_b32_e32 v136, 2, v138
	global_load_dwordx4 v[154:157], v136, s[36:37]
	global_load_dwordx4 v[158:161], v136, s[36:37] offset:16
	global_load_dwordx4 v[178:181], v136, s[36:37] offset:128
	global_load_dwordx4 v[182:185], v136, s[36:37] offset:144
	v_add_u32_e32 v176, v172, v170
	ds_read_b128 v[162:165], v176
	s_lshl_b32 s27, s33, 2
	s_and_b32 s27, s27, 4
	s_or_b32 s27, s27, s54
	s_lshl_b32 s27, s27, 7
	s_waitcnt lgkmcnt(0)
	v_add_f32_e32 v152, v162, v163
	v_add_f32_e32 v153, v164, v165
	v_add_f32_e32 v152, v152, v153
	v_mov_b32_e32 v153, v152
	s_nop 1
	v_permlane16_swap_b32_e32 v152, v153
	v_add_f32_e32 v152, v152, v153
	v_mov_b32_e32 v153, v152
	s_nop 1
	v_permlane32_swap_b32_e32 v152, v153
	v_add_f32_e32 v152, v152, v153
	v_fmamk_f32 v152, v152, 0x3a800000, v174
	v_rsq_f32_e32 v162, v152
	s_add_u32 s36, s4, s27
	v_lshlrev_b32_e32 v136, 1, v138
	s_addc_u32 s37, s25, 0
	v_pk_mul_f32 v[188:189], v[126:127], v[162:163] op_sel_hi:[1,0]
	v_pk_mul_f32 v[190:191], v[124:125], v[162:163] op_sel_hi:[1,0]
	v_pk_mul_f32 v[192:193], v[122:123], v[162:163] op_sel_hi:[1,0]
	v_pk_mul_f32 v[194:195], v[120:121], v[162:163] op_sel_hi:[1,0]
	v_lshl_add_u64 v[152:153], s[36:37], 0, v[136:137]
	v_pk_mul_f32 v[196:197], v[118:119], v[162:163] op_sel_hi:[1,0]
	v_pk_mul_f32 v[198:199], v[116:117], v[162:163] op_sel_hi:[1,0]
	v_pk_mul_f32 v[200:201], v[114:115], v[162:163] op_sel_hi:[1,0]
	v_pk_mul_f32 v[202:203], v[112:113], v[162:163] op_sel_hi:[1,0]
	v_mul_f32_e32 v136, v191, v191
	v_mul_f32_e32 v162, v189, v189
	v_mul_f32_e32 v163, v195, v195
	v_mul_f32_e32 v164, v193, v193
	v_mul_f32_e32 v165, v199, v199
	v_mul_f32_e32 v166, v197, v197
	v_fmac_f32_e32 v136, v190, v190
	v_fmac_f32_e32 v162, v188, v188
	v_fmac_f32_e32 v163, v194, v194
	v_fmac_f32_e32 v164, v192, v192
	v_mul_f32_e32 v167, v203, v203
	v_mul_f32_e32 v168, v201, v201
	v_fmac_f32_e32 v165, v198, v198
	v_fmac_f32_e32 v166, v196, v196
	v_add_f32_e32 v136, v136, v162
	v_add_f32_e32 v162, v163, v164
	v_fmac_f32_e32 v167, v202, v202
	v_fmac_f32_e32 v168, v200, v200
	v_add_f32_e32 v163, v165, v166
	v_add_f32_e32 v136, v136, v162
	v_add_f32_e32 v164, v167, v168
	v_add_f32_e32 v136, v163, v136
	v_add_f32_e32 v136, v164, v136
	v_mov_b32_e32 v162, v136
	s_nop 1
	v_permlane16_swap_b32_e32 v136, v162
	v_add_f32_e32 v136, v136, v162
	v_mov_b32_e32 v162, v136
	s_nop 1
	v_permlane32_swap_b32_e32 v136, v162
	v_add_f32_e32 v136, v136, v162
	v_fmamk_f32 v136, v136, 0x3c800000, v174
	v_rsq_f32_e32 v136, v136
	v_lshl_add_u32 v150, s34, 8, v139
	v_cndmask_b32_e32 v186, 1.0, v175, vcc
	v_ashrrev_i32_e32 v151, 31, v150
	s_mov_b64 s[36:37], 0
	s_waitcnt vmcnt(0)
	v_pk_mul_f32 v[166:167], v[186:187], v[156:157] op_sel_hi:[0,1]
	v_pk_mul_f32 v[162:163], v[186:187], v[160:161] op_sel_hi:[0,1]
	v_pk_mul_f32 v[160:161], v[186:187], v[178:179] op_sel_hi:[0,1]
	v_lshlrev_b64 v[178:179], 10, v[150:151]
	v_pk_mul_f32 v[168:169], v[186:187], v[154:155] op_sel_hi:[0,1]
	v_pk_mul_f32 v[164:165], v[186:187], v[158:159] op_sel_hi:[0,1]
	v_pk_mul_f32 v[158:159], v[186:187], v[180:181] op_sel_hi:[0,1]
	v_pk_mul_f32 v[154:155], v[186:187], v[184:185] op_sel_hi:[0,1]
	v_pk_mul_f32 v[156:157], v[186:187], v[182:183] op_sel_hi:[0,1]
	v_lshl_add_u64 v[186:187], v[152:153], 0, v[178:179]
	v_pk_mul_f32 v[178:179], v[190:191], v[136:137] op_sel_hi:[1,0]
	v_pk_mul_f32 v[180:181], v[188:189], v[136:137] op_sel_hi:[1,0]
	v_pk_mul_f32 v[178:179], v[168:169], v[178:179]
	v_pk_mul_f32 v[180:181], v[166:167], v[180:181]
	v_pk_mul_f32 v[182:183], v[194:195], v[136:137] op_sel_hi:[1,0]
	v_pk_mul_f32 v[184:185], v[192:193], v[136:137] op_sel_hi:[1,0]
	v_pk_mul_f32 v[182:183], v[164:165], v[182:183]
	v_pk_mul_f32 v[184:185], v[162:163], v[184:185]
	v_cvt_pk_bf16_f32 v178, v178, v179
	v_cvt_pk_bf16_f32 v179, v180, v181
	v_cvt_pk_bf16_f32 v180, v182, v183
	v_pk_mul_f32 v[182:183], v[202:203], v[136:137] op_sel_hi:[1,0]
	v_cvt_pk_bf16_f32 v181, v184, v185
	global_store_dwordx4 v[186:187], v[178:181], off sc1
	v_pk_mul_f32 v[184:185], v[200:201], v[136:137] op_sel_hi:[1,0]
	v_pk_mul_f32 v[182:183], v[156:157], v[182:183]
	v_pk_mul_f32 v[178:179], v[198:199], v[136:137] op_sel_hi:[1,0]
	v_pk_mul_f32 v[180:181], v[196:197], v[136:137] op_sel_hi:[1,0]
	v_pk_mul_f32 v[178:179], v[160:161], v[178:179]
	v_pk_mul_f32 v[180:181], v[158:159], v[180:181]
	v_pk_mul_f32 v[184:185], v[154:155], v[184:185]
	v_cvt_pk_bf16_f32 v178, v178, v179
	v_cvt_pk_bf16_f32 v179, v180, v181
	v_cvt_pk_bf16_f32 v180, v182, v183
	v_or_b32_e32 v194, 16, v150
	v_cvt_pk_bf16_f32 v181, v184, v185
	ds_read_b128 v[182:185], v176 offset:1024
	global_store_dwordx4 v[186:187], v[178:181], off offset:64 sc1
	v_ashrrev_i32_e32 v195, 31, v194
	v_lshlrev_b64 v[194:195], 10, v[194:195]
	v_lshl_add_u64 v[194:195], v[152:153], 0, v[194:195]
	s_waitcnt lgkmcnt(0)
; #define LAS __attribute__((address_space(3)))
; #define ROW_RS(u, ai, m) row_rs_lds((ai) * 128 + wr * 64 + (m) * 16 + fr, fq)
; #define ROWLOOP for (int ai = 0; ai < 2; ++ai) _Pragma("unroll") for (int m = 0; m < 4; ++m)
; __device__ __forceinline__ float row_rs_lds(int rt, int fq) {
;     extern __shared__ __attribute__((aligned(16))) unsigned char lds_raw_[];
;     const f32x4 v = *(const LAS f32x4*)((LAS unsigned char*)lds_raw_ + RS_OFF + rt * 64 + fq * 16);
;     float s = (v[0] + v[1]) + (v[2] + v[3]);
;     s = red4_sum(s);
;     return __builtin_amdgcn_rsqf(s * (1.0f / D) + EPS);
;     __device__ __forceinline__ void operator()(const Acc& acc, const Unit& u, int wr, int wc, int fr, int fq) const {
;     ...
;             ROWLOOP { const int row = ROW_OF(u, ai, m); const float rs = ROW_RS(u, ai, m);
;                 f32x4 v[2][2]; float sq = 0.f;
; #pragma unroll
;                 for (int bj = 0; bj < 2; ++bj)
; #pragma unroll
;                     for (int n = 0; n < 2; ++n) { v[bj][n] = acc[ai][bj][m][n] * rs; sq += (v[bj][n][0] * v[bj][n][0] + v[bj][n][1] * v[bj][n][1]) + (v[bj][n][2] * v[bj][n][2] + v[bj][n][3] * v[bj][n][3]); }
;                 sq = red4_sum(sq);
;                 const float rr = __builtin_amdgcn_rsqf(sq * (1.0f / HD) + EPS);
; #pragma unroll
;                 for (int bj = 0; bj < 2; ++bj) *(u32x4*)(o + (size_t)row * CW + head * 64 + bj * 32 + fq * 8) = pack8(v[bj][0] * rr * gn[bj][0], v[bj][1] * rr * gn[bj][1]);
;             }
	v_add_f32_e32 v136, v182, v183
	v_add_f32_e32 v151, v184, v185
	v_add_f32_e32 v136, v136, v151
	v_mov_b32_e32 v151, v136
	s_nop 1
	v_permlane16_swap_b32_e32 v136, v151
	v_add_f32_e32 v136, v136, v151
	v_mov_b32_e32 v151, v136
	s_nop 1
	v_permlane32_swap_b32_e32 v136, v151
	v_add_f32_e32 v136, v136, v151
	v_fmamk_f32 v136, v136, 0x3a800000, v174
	v_rsq_f32_e32 v136, v136
	s_nop 0
	v_pk_mul_f32 v[178:179], v[110:111], v[136:137] op_sel_hi:[1,0]
	v_pk_mul_f32 v[180:181], v[108:109], v[136:137] op_sel_hi:[1,0]
	v_mul_f32_e32 v177, v179, v179
	v_mul_f32_e32 v151, v181, v181
	v_fmac_f32_e32 v151, v180, v180
	v_fmac_f32_e32 v177, v178, v178
	v_pk_mul_f32 v[182:183], v[106:107], v[136:137] op_sel_hi:[1,0]
	v_pk_mul_f32 v[184:185], v[104:105], v[136:137] op_sel_hi:[1,0]
	v_add_f32_e32 v151, v151, v177
	v_mul_f32_e32 v177, v185, v185
	v_mul_f32_e32 v186, v183, v183
	v_fmac_f32_e32 v177, v184, v184
	v_fmac_f32_e32 v186, v182, v182
	v_add_f32_e32 v177, v177, v186
	v_pk_mul_f32 v[186:187], v[102:103], v[136:137] op_sel_hi:[1,0]
	v_pk_mul_f32 v[188:189], v[100:101], v[136:137] op_sel_hi:[1,0]
	v_add_f32_e32 v151, v151, v177
	v_mul_f32_e32 v177, v189, v189
	v_mul_f32_e32 v190, v187, v187
	v_fmac_f32_e32 v177, v188, v188
	v_fmac_f32_e32 v190, v186, v186
	v_add_f32_e32 v177, v177, v190
	v_pk_mul_f32 v[190:191], v[98:99], v[136:137] op_sel_hi:[1,0]
	v_pk_mul_f32 v[192:193], v[96:97], v[136:137] op_sel_hi:[1,0]
	v_add_f32_e32 v151, v177, v151
	v_mul_f32_e32 v136, v193, v193
	v_mul_f32_e32 v177, v191, v191
	v_fmac_f32_e32 v136, v192, v192
	v_fmac_f32_e32 v177, v190, v190
	v_add_f32_e32 v136, v136, v177
	v_add_f32_e32 v136, v136, v151
	v_mov_b32_e32 v151, v136
	s_nop 1
	v_permlane16_swap_b32_e32 v136, v151
	v_add_f32_e32 v136, v136, v151
	v_mov_b32_e32 v151, v136
	s_nop 1
	v_permlane32_swap_b32_e32 v136, v151
	v_add_f32_e32 v136, v136, v151
	v_fmamk_f32 v136, v136, 0x3c800000, v174
	v_rsq_f32_e32 v136, v136
	s_nop 0
	v_pk_mul_f32 v[180:181], v[180:181], v[136:137] op_sel_hi:[1,0]
	v_pk_mul_f32 v[178:179], v[178:179], v[136:137] op_sel_hi:[1,0]
	v_pk_mul_f32 v[182:183], v[182:183], v[136:137] op_sel_hi:[1,0]
	v_pk_mul_f32 v[196:197], v[166:167], v[178:179]
	v_pk_mul_f32 v[178:179], v[168:169], v[180:181]
	v_pk_mul_f32 v[180:181], v[184:185], v[136:137] op_sel_hi:[1,0]
	v_pk_mul_f32 v[182:183], v[162:163], v[182:183]
	v_pk_mul_f32 v[180:181], v[164:165], v[180:181]
	v_cvt_pk_bf16_f32 v178, v178, v179
	v_cvt_pk_bf16_f32 v179, v196, v197
	v_pk_mul_f32 v[184:185], v[190:191], v[136:137] op_sel_hi:[1,0]
	v_cvt_pk_bf16_f32 v180, v180, v181
	v_cvt_pk_bf16_f32 v181, v182, v183
	global_store_dwordx4 v[194:195], v[178:181], off sc1
	v_pk_mul_f32 v[182:183], v[192:193], v[136:137] op_sel_hi:[1,0]
	v_pk_mul_f32 v[184:185], v[154:155], v[184:185]
	v_pk_mul_f32 v[178:179], v[188:189], v[136:137] op_sel_hi:[1,0]
	v_pk_mul_f32 v[180:181], v[186:187], v[136:137] op_sel_hi:[1,0]
	v_pk_mul_f32 v[178:179], v[160:161], v[178:179]
	v_pk_mul_f32 v[180:181], v[158:159], v[180:181]
	v_pk_mul_f32 v[182:183], v[156:157], v[182:183]
	v_cvt_pk_bf16_f32 v178, v178, v179
	v_cvt_pk_bf16_f32 v179, v180, v181
	s_nop 0
	v_cvt_pk_bf16_f32 v180, v182, v183
	v_cvt_pk_bf16_f32 v181, v184, v185
	ds_read_b128 v[182:185], v176 offset:2048
	global_store_dwordx4 v[194:195], v[178:181], off offset:64 sc1
	v_or_b32_e32 v194, 32, v150
	v_ashrrev_i32_e32 v195, 31, v194
	v_lshlrev_b64 v[194:195], 10, v[194:195]
	s_waitcnt lgkmcnt(0)
	v_add_f32_e32 v136, v182, v183
	v_add_f32_e32 v151, v184, v185
	v_add_f32_e32 v136, v136, v151
	v_mov_b32_e32 v151, v136
	s_nop 1
	v_permlane16_swap_b32_e32 v136, v151
	v_add_f32_e32 v136, v136, v151
	v_mov_b32_e32 v151, v136
	s_nop 1
	v_permlane32_swap_b32_e32 v136, v151
	v_add_f32_e32 v136, v136, v151
	v_fmamk_f32 v136, v136, 0x3a800000, v174
	v_rsq_f32_e32 v136, v136
	v_lshl_add_u64 v[194:195], v[152:153], 0, v[194:195]
	v_pk_mul_f32 v[178:179], v[94:95], v[136:137] op_sel_hi:[1,0]
	v_pk_mul_f32 v[180:181], v[92:93], v[136:137] op_sel_hi:[1,0]
	v_mul_f32_e32 v177, v179, v179
	v_mul_f32_e32 v151, v181, v181
	v_fmac_f32_e32 v151, v180, v180
	v_fmac_f32_e32 v177, v178, v178
	v_pk_mul_f32 v[182:183], v[90:91], v[136:137] op_sel_hi:[1,0]
	v_pk_mul_f32 v[184:185], v[88:89], v[136:137] op_sel_hi:[1,0]
	v_add_f32_e32 v151, v151, v177
	v_mul_f32_e32 v177, v185, v185
	v_mul_f32_e32 v186, v183, v183
	v_fmac_f32_e32 v177, v184, v184
	v_fmac_f32_e32 v186, v182, v182
	v_add_f32_e32 v177, v177, v186
	v_pk_mul_f32 v[186:187], v[86:87], v[136:137] op_sel_hi:[1,0]
	v_pk_mul_f32 v[188:189], v[84:85], v[136:137] op_sel_hi:[1,0]
	v_add_f32_e32 v151, v151, v177
	v_mul_f32_e32 v177, v189, v189
	v_mul_f32_e32 v190, v187, v187
	v_fmac_f32_e32 v177, v188, v188
	v_fmac_f32_e32 v190, v186, v186
	v_add_f32_e32 v177, v177, v190
	v_pk_mul_f32 v[190:191], v[82:83], v[136:137] op_sel_hi:[1,0]
	v_pk_mul_f32 v[192:193], v[80:81], v[136:137] op_sel_hi:[1,0]
	v_add_f32_e32 v151, v177, v151
	v_mul_f32_e32 v136, v193, v193
	v_mul_f32_e32 v177, v191, v191
	v_fmac_f32_e32 v136, v192, v192
	v_fmac_f32_e32 v177, v190, v190
	v_add_f32_e32 v136, v136, v177
	v_add_f32_e32 v136, v136, v151
	v_mov_b32_e32 v151, v136
	s_nop 1
	v_permlane16_swap_b32_e32 v136, v151
	v_add_f32_e32 v136, v136, v151
	v_mov_b32_e32 v151, v136
	s_nop 1
	v_permlane32_swap_b32_e32 v136, v151
	v_add_f32_e32 v136, v136, v151
	v_fmamk_f32 v136, v136, 0x3c800000, v174
	v_rsq_f32_e32 v136, v136
	s_nop 0
	v_pk_mul_f32 v[180:181], v[180:181], v[136:137] op_sel_hi:[1,0]
	v_pk_mul_f32 v[178:179], v[178:179], v[136:137] op_sel_hi:[1,0]
	v_pk_mul_f32 v[182:183], v[182:183], v[136:137] op_sel_hi:[1,0]
	v_pk_mul_f32 v[196:197], v[166:167], v[178:179]
	v_pk_mul_f32 v[178:179], v[168:169], v[180:181]
	v_pk_mul_f32 v[180:181], v[184:185], v[136:137] op_sel_hi:[1,0]
	v_pk_mul_f32 v[182:183], v[162:163], v[182:183]
	v_pk_mul_f32 v[180:181], v[164:165], v[180:181]
	v_cvt_pk_bf16_f32 v178, v178, v179
	v_cvt_pk_bf16_f32 v179, v196, v197
	v_pk_mul_f32 v[184:185], v[190:191], v[136:137] op_sel_hi:[1,0]
	v_cvt_pk_bf16_f32 v180, v180, v181
	v_cvt_pk_bf16_f32 v181, v182, v183
	global_store_dwordx4 v[194:195], v[178:181], off sc1
	v_pk_mul_f32 v[182:183], v[192:193], v[136:137] op_sel_hi:[1,0]
	v_pk_mul_f32 v[184:185], v[154:155], v[184:185]
	v_pk_mul_f32 v[178:179], v[188:189], v[136:137] op_sel_hi:[1,0]
	v_pk_mul_f32 v[180:181], v[186:187], v[136:137] op_sel_hi:[1,0]
	v_pk_mul_f32 v[178:179], v[160:161], v[178:179]
	v_pk_mul_f32 v[180:181], v[158:159], v[180:181]
	v_pk_mul_f32 v[182:183], v[156:157], v[182:183]
	v_cvt_pk_bf16_f32 v178, v178, v179
	v_cvt_pk_bf16_f32 v179, v180, v181
	s_nop 0
	v_cvt_pk_bf16_f32 v180, v182, v183
	v_cvt_pk_bf16_f32 v181, v184, v185
	ds_read_b128 v[182:185], v176 offset:3072
	global_store_dwordx4 v[194:195], v[178:181], off offset:64 sc1
	v_or_b32_e32 v194, 48, v150
	v_ashrrev_i32_e32 v195, 31, v194
	v_lshlrev_b64 v[194:195], 10, v[194:195]
	s_waitcnt lgkmcnt(0)
; #define LAS __attribute__((address_space(3)))
; #define ROW_RS(u, ai, m) row_rs_lds((ai) * 128 + wr * 64 + (m) * 16 + fr, fq)
; #define ROWLOOP for (int ai = 0; ai < 2; ++ai) _Pragma("unroll") for (int m = 0; m < 4; ++m)
; __device__ __forceinline__ float row_rs_lds(int rt, int fq) {
;     extern __shared__ __attribute__((aligned(16))) unsigned char lds_raw_[];
;     const f32x4 v = *(const LAS f32x4*)((LAS unsigned char*)lds_raw_ + RS_OFF + rt * 64 + fq * 16);
;     float s = (v[0] + v[1]) + (v[2] + v[3]);
;     s = red4_sum(s);
;     return __builtin_amdgcn_rsqf(s * (1.0f / D) + EPS);
;     __device__ __forceinline__ void operator()(const Acc& acc, const Unit& u, int wr, int wc, int fr, int fq) const {
;     ...
;             ROWLOOP { const int row = ROW_OF(u, ai, m); const float rs = ROW_RS(u, ai, m);
;                 f32x4 v[2][2]; float sq = 0.f;
; #pragma unroll
;                 for (int bj = 0; bj < 2; ++bj)
; #pragma unroll
;                     for (int n = 0; n < 2; ++n) { v[bj][n] = acc[ai][bj][m][n] * rs; sq += (v[bj][n][0] * v[bj][n][0] + v[bj][n][1] * v[bj][n][1]) + (v[bj][n][2] * v[bj][n][2] + v[bj][n][3] * v[bj][n][3]); }
;                 sq = red4_sum(sq);
;                 const float rr = __builtin_amdgcn_rsqf(sq * (1.0f / HD) + EPS);
; #pragma unroll
;                 for (int bj = 0; bj < 2; ++bj) *(u32x4*)(o + (size_t)row * CW + head * 64 + bj * 32 + fq * 8) = pack8(v[bj][0] * rr * gn[bj][0], v[bj][1] * rr * gn[bj][1]);
;             }
	v_add_f32_e32 v136, v182, v183
	v_add_f32_e32 v151, v184, v185
	v_add_f32_e32 v136, v136, v151
	v_mov_b32_e32 v151, v136
	s_nop 1
	v_permlane16_swap_b32_e32 v136, v151
	v_add_f32_e32 v136, v136, v151
	v_mov_b32_e32 v151, v136
	s_nop 1
	v_permlane32_swap_b32_e32 v136, v151
	v_add_f32_e32 v136, v136, v151
	v_fmamk_f32 v136, v136, 0x3a800000, v174
	v_rsq_f32_e32 v136, v136
	v_lshl_add_u64 v[194:195], v[152:153], 0, v[194:195]
	v_pk_mul_f32 v[178:179], v[78:79], v[136:137] op_sel_hi:[1,0]
	v_pk_mul_f32 v[180:181], v[76:77], v[136:137] op_sel_hi:[1,0]
	v_mul_f32_e32 v177, v179, v179
	v_mul_f32_e32 v151, v181, v181
	v_fmac_f32_e32 v151, v180, v180
	v_fmac_f32_e32 v177, v178, v178
	v_pk_mul_f32 v[182:183], v[74:75], v[136:137] op_sel_hi:[1,0]
	v_pk_mul_f32 v[184:185], v[72:73], v[136:137] op_sel_hi:[1,0]
	v_add_f32_e32 v151, v151, v177
	v_mul_f32_e32 v177, v185, v185
	v_mul_f32_e32 v186, v183, v183
	v_fmac_f32_e32 v177, v184, v184
	v_fmac_f32_e32 v186, v182, v182
	v_add_f32_e32 v177, v177, v186
	v_pk_mul_f32 v[186:187], v[70:71], v[136:137] op_sel_hi:[1,0]
	v_pk_mul_f32 v[188:189], v[68:69], v[136:137] op_sel_hi:[1,0]
	v_add_f32_e32 v151, v151, v177
	v_mul_f32_e32 v177, v189, v189
	v_mul_f32_e32 v190, v187, v187
	v_fmac_f32_e32 v177, v188, v188
	v_fmac_f32_e32 v190, v186, v186
	v_add_f32_e32 v177, v177, v190
	v_pk_mul_f32 v[190:191], v[66:67], v[136:137] op_sel_hi:[1,0]
	v_pk_mul_f32 v[192:193], v[64:65], v[136:137] op_sel_hi:[1,0]
	v_add_f32_e32 v151, v177, v151
	v_mul_f32_e32 v136, v193, v193
	v_mul_f32_e32 v177, v191, v191
	v_fmac_f32_e32 v136, v192, v192
	v_fmac_f32_e32 v177, v190, v190
	v_add_f32_e32 v136, v136, v177
	v_add_f32_e32 v136, v136, v151
	v_mov_b32_e32 v151, v136
	s_nop 1
	v_permlane16_swap_b32_e32 v136, v151
	v_add_f32_e32 v136, v136, v151
	v_mov_b32_e32 v151, v136
	s_nop 1
	v_permlane32_swap_b32_e32 v136, v151
	v_add_f32_e32 v136, v136, v151
	v_fmamk_f32 v136, v136, 0x3c800000, v174
	v_rsq_f32_e32 v136, v136
	s_nop 0
	v_pk_mul_f32 v[180:181], v[180:181], v[136:137] op_sel_hi:[1,0]
	v_pk_mul_f32 v[178:179], v[178:179], v[136:137] op_sel_hi:[1,0]
	v_pk_mul_f32 v[182:183], v[182:183], v[136:137] op_sel_hi:[1,0]
	v_pk_mul_f32 v[196:197], v[166:167], v[178:179]
	v_pk_mul_f32 v[178:179], v[168:169], v[180:181]
	v_pk_mul_f32 v[180:181], v[184:185], v[136:137] op_sel_hi:[1,0]
	v_pk_mul_f32 v[182:183], v[162:163], v[182:183]
	v_pk_mul_f32 v[180:181], v[164:165], v[180:181]
	v_cvt_pk_bf16_f32 v178, v178, v179
	v_cvt_pk_bf16_f32 v179, v196, v197
	v_pk_mul_f32 v[184:185], v[190:191], v[136:137] op_sel_hi:[1,0]
	v_cvt_pk_bf16_f32 v180, v180, v181
	v_cvt_pk_bf16_f32 v181, v182, v183
	global_store_dwordx4 v[194:195], v[178:181], off sc1
	v_pk_mul_f32 v[182:183], v[192:193], v[136:137] op_sel_hi:[1,0]
	v_pk_mul_f32 v[184:185], v[154:155], v[184:185]
	v_pk_mul_f32 v[178:179], v[188:189], v[136:137] op_sel_hi:[1,0]
	v_pk_mul_f32 v[180:181], v[186:187], v[136:137] op_sel_hi:[1,0]
	v_pk_mul_f32 v[178:179], v[160:161], v[178:179]
	v_pk_mul_f32 v[180:181], v[158:159], v[180:181]
	v_pk_mul_f32 v[182:183], v[156:157], v[182:183]
	v_cvt_pk_bf16_f32 v178, v178, v179
	v_cvt_pk_bf16_f32 v179, v180, v181
	s_nop 0
	v_cvt_pk_bf16_f32 v180, v182, v183
	v_cvt_pk_bf16_f32 v181, v184, v185
	ds_read_b128 v[182:185], v176 offset:8192
	global_store_dwordx4 v[194:195], v[178:181], off offset:64 sc1
	s_waitcnt lgkmcnt(0)
	v_add_f32_e32 v136, v182, v183
	v_add_f32_e32 v151, v184, v185
	v_add_f32_e32 v136, v136, v151
	v_mov_b32_e32 v151, v136
	s_nop 1
	v_permlane16_swap_b32_e32 v136, v151
	v_add_f32_e32 v136, v136, v151
	v_mov_b32_e32 v151, v136
	s_nop 1
	v_permlane32_swap_b32_e32 v136, v151
	v_add_f32_e32 v136, v136, v151
	v_fmamk_f32 v136, v136, 0x3a800000, v174
	v_rsq_f32_e32 v136, v136
	v_add_u32_e32 v178, 0x80, v150
	v_pk_mul_f32 v[180:181], v[62:63], v[136:137] op_sel_hi:[1,0]
	v_pk_mul_f32 v[182:183], v[60:61], v[136:137] op_sel_hi:[1,0]
	v_mul_f32_e32 v177, v181, v181
	v_mul_f32_e32 v151, v183, v183
	v_fmac_f32_e32 v151, v182, v182
	v_fmac_f32_e32 v177, v180, v180
	v_pk_mul_f32 v[184:185], v[58:59], v[136:137] op_sel_hi:[1,0]
	v_pk_mul_f32 v[186:187], v[56:57], v[136:137] op_sel_hi:[1,0]
	v_add_f32_e32 v151, v151, v177
	v_mul_f32_e32 v177, v187, v187
	v_mul_f32_e32 v179, v185, v185
	v_fmac_f32_e32 v177, v186, v186
	v_fmac_f32_e32 v179, v184, v184
	v_add_f32_e32 v177, v177, v179
	v_pk_mul_f32 v[188:189], v[54:55], v[136:137] op_sel_hi:[1,0]
	v_pk_mul_f32 v[190:191], v[52:53], v[136:137] op_sel_hi:[1,0]
	v_add_f32_e32 v151, v151, v177
	v_mul_f32_e32 v177, v191, v191
	v_mul_f32_e32 v179, v189, v189
	v_fmac_f32_e32 v177, v190, v190
	v_fmac_f32_e32 v179, v188, v188
	v_add_f32_e32 v177, v177, v179
	v_pk_mul_f32 v[192:193], v[50:51], v[136:137] op_sel_hi:[1,0]
	v_pk_mul_f32 v[194:195], v[48:49], v[136:137] op_sel_hi:[1,0]
	v_add_f32_e32 v151, v177, v151
	v_mul_f32_e32 v136, v195, v195
	v_mul_f32_e32 v177, v193, v193
	v_fmac_f32_e32 v136, v194, v194
	v_fmac_f32_e32 v177, v192, v192
	v_add_f32_e32 v136, v136, v177
	v_add_f32_e32 v136, v136, v151
	v_mov_b32_e32 v151, v136
	s_nop 1
	v_permlane16_swap_b32_e32 v136, v151
	v_add_f32_e32 v136, v136, v151
	v_mov_b32_e32 v151, v136
	s_nop 1
	v_permlane32_swap_b32_e32 v136, v151
	v_add_f32_e32 v136, v136, v151
	v_fmamk_f32 v136, v136, 0x3c800000, v174
	v_rsq_f32_e32 v136, v136
	v_ashrrev_i32_e32 v179, 31, v178
	v_lshlrev_b64 v[178:179], 10, v[178:179]
	v_lshl_add_u64 v[196:197], v[152:153], 0, v[178:179]
	v_pk_mul_f32 v[178:179], v[182:183], v[136:137] op_sel_hi:[1,0]
	v_pk_mul_f32 v[180:181], v[180:181], v[136:137] op_sel_hi:[1,0]
	v_pk_mul_f32 v[178:179], v[168:169], v[178:179]
	v_pk_mul_f32 v[180:181], v[166:167], v[180:181]
	v_pk_mul_f32 v[182:183], v[186:187], v[136:137] op_sel_hi:[1,0]
	v_pk_mul_f32 v[184:185], v[184:185], v[136:137] op_sel_hi:[1,0]
	v_pk_mul_f32 v[182:183], v[164:165], v[182:183]
	v_pk_mul_f32 v[184:185], v[162:163], v[184:185]
	v_cvt_pk_bf16_f32 v178, v178, v179
	v_cvt_pk_bf16_f32 v179, v180, v181
	v_cvt_pk_bf16_f32 v180, v182, v183
	v_pk_mul_f32 v[182:183], v[194:195], v[136:137] op_sel_hi:[1,0]
	v_cvt_pk_bf16_f32 v181, v184, v185
	global_store_dwordx4 v[196:197], v[178:181], off sc1
	v_pk_mul_f32 v[184:185], v[192:193], v[136:137] op_sel_hi:[1,0]
	v_pk_mul_f32 v[182:183], v[156:157], v[182:183]
	v_pk_mul_f32 v[178:179], v[190:191], v[136:137] op_sel_hi:[1,0]
	v_pk_mul_f32 v[180:181], v[188:189], v[136:137] op_sel_hi:[1,0]
	v_pk_mul_f32 v[178:179], v[160:161], v[178:179]
	v_pk_mul_f32 v[180:181], v[158:159], v[180:181]
	v_pk_mul_f32 v[184:185], v[154:155], v[184:185]
	v_cvt_pk_bf16_f32 v178, v178, v179
	v_cvt_pk_bf16_f32 v179, v180, v181
	v_cvt_pk_bf16_f32 v180, v182, v183
	v_add_u32_e32 v194, 0x90, v150
	v_cvt_pk_bf16_f32 v181, v184, v185
	ds_read_b128 v[182:185], v176 offset:9216
	global_store_dwordx4 v[196:197], v[178:181], off offset:64 sc1
	v_ashrrev_i32_e32 v195, 31, v194
	v_lshlrev_b64 v[194:195], 10, v[194:195]
	v_lshl_add_u64 v[194:195], v[152:153], 0, v[194:195]
	s_waitcnt lgkmcnt(0)
; #define LAS __attribute__((address_space(3)))
; #define ROW_RS(u, ai, m) row_rs_lds((ai) * 128 + wr * 64 + (m) * 16 + fr, fq)
; #define ROWLOOP for (int ai = 0; ai < 2; ++ai) _Pragma("unroll") for (int m = 0; m < 4; ++m)
; __device__ __forceinline__ float row_rs_lds(int rt, int fq) {
;     extern __shared__ __attribute__((aligned(16))) unsigned char lds_raw_[];
;     const f32x4 v = *(const LAS f32x4*)((LAS unsigned char*)lds_raw_ + RS_OFF + rt * 64 + fq * 16);
;     float s = (v[0] + v[1]) + (v[2] + v[3]);
;     s = red4_sum(s);
;     return __builtin_amdgcn_rsqf(s * (1.0f / D) + EPS);
;     __device__ __forceinline__ void operator()(const Acc& acc, const Unit& u, int wr, int wc, int fr, int fq) const {
;     ...
;             ROWLOOP { const int row = ROW_OF(u, ai, m); const float rs = ROW_RS(u, ai, m);
;                 f32x4 v[2][2]; float sq = 0.f;
; #pragma unroll
;                 for (int bj = 0; bj < 2; ++bj)
; #pragma unroll
;                     for (int n = 0; n < 2; ++n) { v[bj][n] = acc[ai][bj][m][n] * rs; sq += (v[bj][n][0] * v[bj][n][0] + v[bj][n][1] * v[bj][n][1]) + (v[bj][n][2] * v[bj][n][2] + v[bj][n][3] * v[bj][n][3]); }
;                 sq = red4_sum(sq);
;                 const float rr = __builtin_amdgcn_rsqf(sq * (1.0f / HD) + EPS);
; #pragma unroll
;                 for (int bj = 0; bj < 2; ++bj) *(u32x4*)(o + (size_t)row * CW + head * 64 + bj * 32 + fq * 8) = pack8(v[bj][0] * rr * gn[bj][0], v[bj][1] * rr * gn[bj][1]);
;             }
	v_add_f32_e32 v136, v182, v183
	v_add_f32_e32 v151, v184, v185
	v_add_f32_e32 v136, v136, v151
	v_mov_b32_e32 v151, v136
	s_nop 1
	v_permlane16_swap_b32_e32 v136, v151
	v_add_f32_e32 v136, v136, v151
	v_mov_b32_e32 v151, v136
	s_nop 1
	v_permlane32_swap_b32_e32 v136, v151
	v_add_f32_e32 v136, v136, v151
	v_fmamk_f32 v136, v136, 0x3a800000, v174
	v_rsq_f32_e32 v136, v136
	s_nop 0
	v_pk_mul_f32 v[178:179], v[46:47], v[136:137] op_sel_hi:[1,0]
	v_pk_mul_f32 v[180:181], v[44:45], v[136:137] op_sel_hi:[1,0]
	v_mul_f32_e32 v177, v179, v179
	v_mul_f32_e32 v151, v181, v181
	v_fmac_f32_e32 v151, v180, v180
	v_fmac_f32_e32 v177, v178, v178
	v_pk_mul_f32 v[182:183], v[42:43], v[136:137] op_sel_hi:[1,0]
	v_pk_mul_f32 v[184:185], v[40:41], v[136:137] op_sel_hi:[1,0]
	v_add_f32_e32 v151, v151, v177
	v_mul_f32_e32 v177, v185, v185
	v_mul_f32_e32 v186, v183, v183
	v_fmac_f32_e32 v177, v184, v184
	v_fmac_f32_e32 v186, v182, v182
	v_add_f32_e32 v177, v177, v186
	v_pk_mul_f32 v[186:187], v[38:39], v[136:137] op_sel_hi:[1,0]
	v_pk_mul_f32 v[188:189], v[36:37], v[136:137] op_sel_hi:[1,0]
	v_add_f32_e32 v151, v151, v177
	v_mul_f32_e32 v177, v189, v189
	v_mul_f32_e32 v190, v187, v187
	v_fmac_f32_e32 v177, v188, v188
	v_fmac_f32_e32 v190, v186, v186
	v_add_f32_e32 v177, v177, v190
	v_pk_mul_f32 v[190:191], v[34:35], v[136:137] op_sel_hi:[1,0]
	v_pk_mul_f32 v[192:193], v[32:33], v[136:137] op_sel_hi:[1,0]
	v_add_f32_e32 v151, v177, v151
	v_mul_f32_e32 v136, v193, v193
	v_mul_f32_e32 v177, v191, v191
	v_fmac_f32_e32 v136, v192, v192
	v_fmac_f32_e32 v177, v190, v190
	v_add_f32_e32 v136, v136, v177
	v_add_f32_e32 v136, v136, v151
	v_mov_b32_e32 v151, v136
	s_nop 1
	v_permlane16_swap_b32_e32 v136, v151
	v_add_f32_e32 v136, v136, v151
	v_mov_b32_e32 v151, v136
	s_nop 1
	v_permlane32_swap_b32_e32 v136, v151
	v_add_f32_e32 v136, v136, v151
	v_fmamk_f32 v136, v136, 0x3c800000, v174
	v_rsq_f32_e32 v136, v136
	s_nop 0
	v_pk_mul_f32 v[180:181], v[180:181], v[136:137] op_sel_hi:[1,0]
	v_pk_mul_f32 v[178:179], v[178:179], v[136:137] op_sel_hi:[1,0]
	v_pk_mul_f32 v[182:183], v[182:183], v[136:137] op_sel_hi:[1,0]
	v_pk_mul_f32 v[196:197], v[166:167], v[178:179]
	v_pk_mul_f32 v[178:179], v[168:169], v[180:181]
	v_pk_mul_f32 v[180:181], v[184:185], v[136:137] op_sel_hi:[1,0]
	v_pk_mul_f32 v[182:183], v[162:163], v[182:183]
	v_pk_mul_f32 v[180:181], v[164:165], v[180:181]
	v_cvt_pk_bf16_f32 v178, v178, v179
	v_cvt_pk_bf16_f32 v179, v196, v197
	v_pk_mul_f32 v[184:185], v[190:191], v[136:137] op_sel_hi:[1,0]
	v_cvt_pk_bf16_f32 v180, v180, v181
	v_cvt_pk_bf16_f32 v181, v182, v183
	global_store_dwordx4 v[194:195], v[178:181], off sc1
	v_pk_mul_f32 v[182:183], v[192:193], v[136:137] op_sel_hi:[1,0]
	v_pk_mul_f32 v[184:185], v[154:155], v[184:185]
	v_pk_mul_f32 v[178:179], v[188:189], v[136:137] op_sel_hi:[1,0]
	v_pk_mul_f32 v[180:181], v[186:187], v[136:137] op_sel_hi:[1,0]
	v_pk_mul_f32 v[178:179], v[160:161], v[178:179]
	v_pk_mul_f32 v[180:181], v[158:159], v[180:181]
	v_pk_mul_f32 v[182:183], v[156:157], v[182:183]
	v_cvt_pk_bf16_f32 v178, v178, v179
	v_cvt_pk_bf16_f32 v179, v180, v181
	s_nop 0
	v_cvt_pk_bf16_f32 v180, v182, v183
	v_cvt_pk_bf16_f32 v181, v184, v185
	ds_read_b128 v[182:185], v176 offset:10240
	global_store_dwordx4 v[194:195], v[178:181], off offset:64 sc1
	v_add_u32_e32 v194, 0xa0, v150
	v_ashrrev_i32_e32 v195, 31, v194
	v_lshlrev_b64 v[194:195], 10, v[194:195]
	s_waitcnt lgkmcnt(0)
	v_add_f32_e32 v136, v182, v183
	v_add_f32_e32 v151, v184, v185
	v_add_f32_e32 v136, v136, v151
	v_mov_b32_e32 v151, v136
	s_nop 1
	v_permlane16_swap_b32_e32 v136, v151
	v_add_f32_e32 v136, v136, v151
	v_mov_b32_e32 v151, v136
	s_nop 1
	v_permlane32_swap_b32_e32 v136, v151
	v_add_f32_e32 v136, v136, v151
	v_fmamk_f32 v136, v136, 0x3a800000, v174
	v_rsq_f32_e32 v136, v136
	v_lshl_add_u64 v[194:195], v[152:153], 0, v[194:195]
	v_add_u32_e32 v150, 0xb0, v150
	v_pk_mul_f32 v[178:179], v[30:31], v[136:137] op_sel_hi:[1,0]
	v_pk_mul_f32 v[180:181], v[28:29], v[136:137] op_sel_hi:[1,0]
	v_mul_f32_e32 v177, v179, v179
	v_mul_f32_e32 v151, v181, v181
	v_fmac_f32_e32 v151, v180, v180
	v_fmac_f32_e32 v177, v178, v178
	v_pk_mul_f32 v[182:183], v[26:27], v[136:137] op_sel_hi:[1,0]
	v_pk_mul_f32 v[184:185], v[24:25], v[136:137] op_sel_hi:[1,0]
	v_add_f32_e32 v151, v151, v177
	v_mul_f32_e32 v177, v185, v185
	v_mul_f32_e32 v186, v183, v183
	v_fmac_f32_e32 v177, v184, v184
	v_fmac_f32_e32 v186, v182, v182
	v_add_f32_e32 v177, v177, v186
	v_pk_mul_f32 v[186:187], v[22:23], v[136:137] op_sel_hi:[1,0]
	v_pk_mul_f32 v[188:189], v[20:21], v[136:137] op_sel_hi:[1,0]
	v_add_f32_e32 v151, v151, v177
	v_mul_f32_e32 v177, v189, v189
	v_mul_f32_e32 v190, v187, v187
	v_fmac_f32_e32 v177, v188, v188
	v_fmac_f32_e32 v190, v186, v186
	v_add_f32_e32 v177, v177, v190
	v_pk_mul_f32 v[190:191], v[18:19], v[136:137] op_sel_hi:[1,0]
	v_pk_mul_f32 v[192:193], v[16:17], v[136:137] op_sel_hi:[1,0]
	v_add_f32_e32 v151, v177, v151
	v_mul_f32_e32 v136, v193, v193
	v_mul_f32_e32 v177, v191, v191
	v_fmac_f32_e32 v136, v192, v192
	v_fmac_f32_e32 v177, v190, v190
	v_add_f32_e32 v136, v136, v177
	v_add_f32_e32 v136, v136, v151
	v_mov_b32_e32 v151, v136
	s_nop 1
	v_permlane16_swap_b32_e32 v136, v151
	v_add_f32_e32 v136, v136, v151
	v_mov_b32_e32 v151, v136
	s_nop 1
	v_permlane32_swap_b32_e32 v136, v151
	v_add_f32_e32 v136, v136, v151
	v_fmamk_f32 v136, v136, 0x3c800000, v174
	v_rsq_f32_e32 v136, v136
	s_nop 0
	v_pk_mul_f32 v[180:181], v[180:181], v[136:137] op_sel_hi:[1,0]
	v_pk_mul_f32 v[178:179], v[178:179], v[136:137] op_sel_hi:[1,0]
	v_pk_mul_f32 v[182:183], v[182:183], v[136:137] op_sel_hi:[1,0]
	v_pk_mul_f32 v[196:197], v[166:167], v[178:179]
	v_pk_mul_f32 v[178:179], v[168:169], v[180:181]
	v_pk_mul_f32 v[180:181], v[184:185], v[136:137] op_sel_hi:[1,0]
	v_pk_mul_f32 v[182:183], v[162:163], v[182:183]
	v_pk_mul_f32 v[180:181], v[164:165], v[180:181]
	v_cvt_pk_bf16_f32 v178, v178, v179
	v_cvt_pk_bf16_f32 v179, v196, v197
	v_pk_mul_f32 v[184:185], v[190:191], v[136:137] op_sel_hi:[1,0]
	v_cvt_pk_bf16_f32 v180, v180, v181
	v_cvt_pk_bf16_f32 v181, v182, v183
	global_store_dwordx4 v[194:195], v[178:181], off sc1
	v_pk_mul_f32 v[182:183], v[192:193], v[136:137] op_sel_hi:[1,0]
	v_pk_mul_f32 v[184:185], v[154:155], v[184:185]
	v_pk_mul_f32 v[178:179], v[188:189], v[136:137] op_sel_hi:[1,0]
	v_pk_mul_f32 v[180:181], v[186:187], v[136:137] op_sel_hi:[1,0]
	v_pk_mul_f32 v[178:179], v[160:161], v[178:179]
	v_pk_mul_f32 v[180:181], v[158:159], v[180:181]
	v_pk_mul_f32 v[182:183], v[156:157], v[182:183]
	v_cvt_pk_bf16_f32 v178, v178, v179
	v_cvt_pk_bf16_f32 v179, v180, v181
	s_nop 0
	v_cvt_pk_bf16_f32 v180, v182, v183
	v_cvt_pk_bf16_f32 v181, v184, v185
	ds_read_b128 v[182:185], v176 offset:11264
	global_store_dwordx4 v[194:195], v[178:181], off offset:64 sc1
	s_waitcnt lgkmcnt(0)
; #define ROW_RS(u, ai, m) row_rs_lds((ai) * 128 + wr * 64 + (m) * 16 + fr, fq)
; #define ROWLOOP for (int ai = 0; ai < 2; ++ai) _Pragma("unroll") for (int m = 0; m < 4; ++m)
;     __device__ __forceinline__ void operator()(const Acc& acc, const Unit& u, int wr, int wc, int fr, int fq) const {
;     ...
;         } else if (pn < 6) {
;             const int ct = (pn - 2) * 128;
; #pragma unroll
;             ROWLOOP { const int row = ROW_OF(u, ai, m); const float rs = ROW_RS(u, ai, m); const float r2 = rs * rs;
;                 *(u32x4*)(U + (size_t)row * CW + ct + wc * 32 + fq * 8) = pack8(acc[ai][0][m][0] * acc[ai][1][m][0] * r2, acc[ai][0][m][1] * acc[ai][1][m][1] * r2); }
;     ...
;             ROWLOOP { const int row = ROW_OF(u, ai, m); const float rs = ROW_RS(u, ai, m);
;                 f32x4 v[2][2]; float sq = 0.f;
; #pragma unroll
;                 for (int bj = 0; bj < 2; ++bj)
; #pragma unroll
;                     for (int n = 0; n < 2; ++n) { v[bj][n] = acc[ai][bj][m][n] * rs; sq += (v[bj][n][0] * v[bj][n][0] + v[bj][n][1] * v[bj][n][1]) + (v[bj][n][2] * v[bj][n][2] + v[bj][n][3] * v[bj][n][3]); }
;                 sq = red4_sum(sq);
;                 const float rr = __builtin_amdgcn_rsqf(sq * (1.0f / HD) + EPS);
; #pragma unroll
;                 for (int bj = 0; bj < 2; ++bj) *(u32x4*)(o + (size_t)row * CW + head * 64 + bj * 32 + fq * 8) = pack8(v[bj][0] * rr * gn[bj][0], v[bj][1] * rr * gn[bj][1]);
;             }
	v_add_f32_e32 v136, v182, v183
	v_add_f32_e32 v151, v184, v185
	v_add_f32_e32 v136, v136, v151
	v_mov_b32_e32 v151, v136
	s_nop 1
	v_permlane16_swap_b32_e32 v136, v151
	v_add_f32_e32 v136, v136, v151
	v_mov_b32_e32 v151, v136
	s_nop 1
	v_permlane32_swap_b32_e32 v136, v151
	v_add_f32_e32 v136, v136, v151
	v_fmamk_f32 v136, v136, 0x3a800000, v174
	v_rsq_f32_e32 v136, v136
	s_nop 0
	v_pk_mul_f32 v[176:177], v[14:15], v[136:137] op_sel_hi:[1,0]
	v_pk_mul_f32 v[178:179], v[12:13], v[136:137] op_sel_hi:[1,0]
	v_mul_f32_e32 v180, v177, v177
	v_mul_f32_e32 v151, v179, v179
	v_fmac_f32_e32 v151, v178, v178
	v_fmac_f32_e32 v180, v176, v176
	v_add_f32_e32 v151, v151, v180
	v_pk_mul_f32 v[180:181], v[10:11], v[136:137] op_sel_hi:[1,0]
	v_pk_mul_f32 v[182:183], v[8:9], v[136:137] op_sel_hi:[1,0]
	v_mul_f32_e32 v185, v181, v181
	v_mul_f32_e32 v184, v183, v183
	v_fmac_f32_e32 v184, v182, v182
	v_fmac_f32_e32 v185, v180, v180
	v_add_f32_e32 v184, v184, v185
	v_add_f32_e32 v151, v151, v184
	v_pk_mul_f32 v[184:185], v[6:7], v[136:137] op_sel_hi:[1,0]
	v_pk_mul_f32 v[186:187], v[4:5], v[136:137] op_sel_hi:[1,0]
	v_mul_f32_e32 v189, v185, v185
	v_mul_f32_e32 v188, v187, v187
	v_fmac_f32_e32 v188, v186, v186
	v_fmac_f32_e32 v189, v184, v184
	v_add_f32_e32 v188, v188, v189
	v_add_f32_e32 v151, v188, v151
	v_pk_mul_f32 v[188:189], v[2:3], v[136:137] op_sel_hi:[1,0]
	v_pk_mul_f32 v[190:191], v[0:1], v[136:137] op_sel_hi:[1,0]
	v_mul_f32_e32 v192, v189, v189
	v_mul_f32_e32 v136, v191, v191
	v_fmac_f32_e32 v136, v190, v190
	v_fmac_f32_e32 v192, v188, v188
	v_add_f32_e32 v136, v136, v192
	v_add_f32_e32 v136, v136, v151
	v_mov_b32_e32 v151, v136
	s_nop 1
	v_permlane16_swap_b32_e32 v136, v151
	v_add_f32_e32 v136, v136, v151
	v_mov_b32_e32 v151, v136
	s_nop 1
	v_permlane32_swap_b32_e32 v136, v151
	v_add_f32_e32 v136, v136, v151
	v_fmamk_f32 v136, v136, 0x3c800000, v174
	v_rsq_f32_e32 v136, v136
	v_ashrrev_i32_e32 v151, 31, v150
	v_lshlrev_b64 v[150:151], 10, v[150:151]
	v_lshl_add_u64 v[192:193], v[152:153], 0, v[150:151]
	v_pk_mul_f32 v[150:151], v[178:179], v[136:137] op_sel_hi:[1,0]
	v_pk_mul_f32 v[152:153], v[176:177], v[136:137] op_sel_hi:[1,0]
	v_pk_mul_f32 v[150:151], v[168:169], v[150:151]
	v_pk_mul_f32 v[152:153], v[166:167], v[152:153]
	v_pk_mul_f32 v[166:167], v[182:183], v[136:137] op_sel_hi:[1,0]
	v_pk_mul_f32 v[168:169], v[180:181], v[136:137] op_sel_hi:[1,0]
	v_pk_mul_f32 v[164:165], v[164:165], v[166:167]
	v_pk_mul_f32 v[162:163], v[162:163], v[168:169]
	v_cvt_pk_bf16_f32 v150, v150, v151
	v_cvt_pk_bf16_f32 v151, v152, v153
	v_cvt_pk_bf16_f32 v152, v164, v165
	s_nop 0
	v_cvt_pk_bf16_f32 v153, v162, v163
	global_store_dwordx4 v[192:193], v[150:153], off sc1
	s_nop 1
	v_pk_mul_f32 v[150:151], v[186:187], v[136:137] op_sel_hi:[1,0]
	v_pk_mul_f32 v[152:153], v[184:185], v[136:137] op_sel_hi:[1,0]
	v_pk_mul_f32 v[150:151], v[160:161], v[150:151]
	v_pk_mul_f32 v[152:153], v[158:159], v[152:153]
	v_pk_mul_f32 v[158:159], v[190:191], v[136:137] op_sel_hi:[1,0]
	v_pk_mul_f32 v[160:161], v[188:189], v[136:137] op_sel_hi:[1,0]
	v_pk_mul_f32 v[156:157], v[156:157], v[158:159]
	v_pk_mul_f32 v[154:155], v[154:155], v[160:161]
	v_cvt_pk_bf16_f32 v150, v150, v151
	v_cvt_pk_bf16_f32 v151, v152, v153
	v_cvt_pk_bf16_f32 v152, v156, v157
	s_nop 0
	v_cvt_pk_bf16_f32 v153, v154, v155
	global_store_dwordx4 v[192:193], v[150:153], off offset:64 sc1
.LBB0_452:
	s_andn2_b64 vcc, exec, s[36:37]
	s_cbranch_vccnz .LBB0_454
	v_add_u32_e32 v164, v172, v170
	ds_read_b128 v[150:153], v164
	v_pk_mul_f32 v[154:155], v[116:117], v[124:125]
	v_pk_mul_f32 v[158:159], v[112:113], v[120:121]
	s_lshl_b32 s4, s33, 8
	s_lshl_b32 s36, s56, 1
	s_waitcnt lgkmcnt(0)
	v_add_f32_e32 v136, v150, v151
	v_add_f32_e32 v150, v152, v153
	v_add_f32_e32 v136, v136, v150
	v_mov_b32_e32 v150, v136
	s_nop 1
	v_permlane16_swap_b32_e32 v136, v150
	v_add_f32_e32 v136, v136, v150
	v_mov_b32_e32 v150, v136
	s_nop 1
	v_permlane32_swap_b32_e32 v136, v150
	v_add_f32_e32 v136, v136, v150
	v_fmamk_f32 v136, v136, 0x3a800000, v174
	v_rsq_f32_e32 v136, v136
	v_lshl_add_u32 v150, s34, 8, v139
	v_pk_mul_f32 v[152:153], v[118:119], v[126:127]
	v_ashrrev_i32_e32 v151, 31, v150
	v_mul_f32_e32 v136, v136, v136
	v_pk_mul_f32 v[156:157], v[152:153], v[136:137] op_sel_hi:[1,0]
	v_pk_mul_f32 v[152:153], v[154:155], v[136:137] op_sel_hi:[1,0]
	v_pk_mul_f32 v[154:155], v[114:115], v[122:123]
	v_cvt_pk_bf16_f32 v152, v152, v153
	v_cvt_pk_bf16_f32 v153, v156, v157
	v_lshlrev_b64 v[156:157], 10, v[150:151]
	v_pk_mul_f32 v[160:161], v[154:155], v[136:137] op_sel_hi:[1,0]
	v_pk_mul_f32 v[154:155], v[158:159], v[136:137] op_sel_hi:[1,0]
	v_lshl_add_u64 v[156:157], s[14:15], 0, v[156:157]
	v_cvt_pk_bf16_f32 v154, v154, v155
	v_cvt_pk_bf16_f32 v155, v160, v161
	v_lshl_add_u64 v[160:161], v[156:157], 0, s[4:5]
	ds_read_b128 v[156:159], v164 offset:1024
	s_mov_b32 s37, s5
	v_lshl_add_u64 v[160:161], v[160:161], 0, s[36:37]
	v_lshlrev_b32_e32 v136, 1, v138
	v_pk_mul_f32 v[162:163], v[96:97], v[104:105]
	s_waitcnt lgkmcnt(0)
; #define LAS __attribute__((address_space(3)))
; #define ROW_RS(u, ai, m) row_rs_lds((ai) * 128 + wr * 64 + (m) * 16 + fr, fq)
; #define ROWLOOP for (int ai = 0; ai < 2; ++ai) _Pragma("unroll") for (int m = 0; m < 4; ++m)
; __device__ __forceinline__ float row_rs_lds(int rt, int fq) {
;     extern __shared__ __attribute__((aligned(16))) unsigned char lds_raw_[];
;     const f32x4 v = *(const LAS f32x4*)((LAS unsigned char*)lds_raw_ + RS_OFF + rt * 64 + fq * 16);
;     float s = (v[0] + v[1]) + (v[2] + v[3]);
;     s = red4_sum(s);
;     return __builtin_amdgcn_rsqf(s * (1.0f / D) + EPS);
;     __device__ __forceinline__ void operator()(const Acc& acc, const Unit& u, int wr, int wc, int fr, int fq) const {
;     ...
;         } else if (pn < 6) {
;             const int ct = (pn - 2) * 128;
; #pragma unroll
;             ROWLOOP { const int row = ROW_OF(u, ai, m); const float rs = ROW_RS(u, ai, m); const float r2 = rs * rs;
;                 *(u32x4*)(U + (size_t)row * CW + ct + wc * 32 + fq * 8) = pack8(acc[ai][0][m][0] * acc[ai][1][m][0] * r2, acc[ai][0][m][1] * acc[ai][1][m][1] * r2); }
	v_add_f32_e32 v151, v156, v157
	v_add_f32_e32 v156, v158, v159
	v_add_f32_e32 v151, v151, v156
	v_mov_b32_e32 v156, v151
	s_nop 1
	v_permlane16_swap_b32_e32 v151, v156
	v_add_f32_e32 v151, v151, v156
	v_mov_b32_e32 v156, v151
	s_nop 1
	v_permlane32_swap_b32_e32 v151, v156
	v_add_f32_e32 v151, v151, v156
	v_fmamk_f32 v151, v151, 0x3a800000, v174
	v_rsq_f32_e32 v151, v151
	v_lshl_add_u64 v[156:157], v[160:161], 0, v[136:137]
	global_store_dwordx4 v[156:157], v[152:155], off offset:-512 sc1
	v_pk_mul_f32 v[156:157], v[100:101], v[108:109]
	v_pk_mul_f32 v[158:159], v[98:99], v[106:107]
	v_mul_f32_e32 v152, v151, v151
	v_pk_mul_f32 v[154:155], v[102:103], v[110:111]
	v_pk_mul_f32 v[156:157], v[156:157], v[152:153] op_sel_hi:[1,0]
	v_pk_mul_f32 v[154:155], v[154:155], v[152:153] op_sel_hi:[1,0]
	v_pk_mul_f32 v[158:159], v[158:159], v[152:153] op_sel_hi:[1,0]
	v_pk_mul_f32 v[162:163], v[162:163], v[152:153] op_sel_hi:[1,0]
	v_cvt_pk_bf16_f32 v152, v156, v157
	v_cvt_pk_bf16_f32 v153, v154, v155
	v_or_b32_e32 v160, 16, v150
	v_cvt_pk_bf16_f32 v154, v162, v163
	v_cvt_pk_bf16_f32 v155, v158, v159
	ds_read_b128 v[156:159], v164 offset:2048
	v_ashrrev_i32_e32 v161, 31, v160
	v_lshlrev_b64 v[160:161], 10, v[160:161]
	v_lshl_add_u64 v[160:161], s[14:15], 0, v[160:161]
	v_lshl_add_u64 v[160:161], v[160:161], 0, s[4:5]
	s_waitcnt lgkmcnt(0)
	v_add_f32_e32 v151, v156, v157
	v_add_f32_e32 v156, v158, v159
	v_add_f32_e32 v151, v151, v156
	v_mov_b32_e32 v156, v151
	s_nop 1
	v_permlane16_swap_b32_e32 v151, v156
	v_add_f32_e32 v151, v151, v156
	v_mov_b32_e32 v156, v151
	s_nop 1
	v_permlane32_swap_b32_e32 v151, v156
	v_add_f32_e32 v151, v151, v156
	v_fmamk_f32 v151, v151, 0x3a800000, v174
	v_rsq_f32_e32 v151, v151
	v_lshl_add_u64 v[160:161], v[160:161], 0, s[36:37]
	v_lshl_add_u64 v[156:157], v[160:161], 0, v[136:137]
	global_store_dwordx4 v[156:157], v[152:155], off offset:-512 sc1
	v_pk_mul_f32 v[156:157], v[84:85], v[92:93]
	v_pk_mul_f32 v[158:159], v[82:83], v[90:91]
	v_mul_f32_e32 v152, v151, v151
	v_pk_mul_f32 v[154:155], v[86:87], v[94:95]
	v_pk_mul_f32 v[156:157], v[156:157], v[152:153] op_sel_hi:[1,0]
	v_pk_mul_f32 v[154:155], v[154:155], v[152:153] op_sel_hi:[1,0]
	v_pk_mul_f32 v[162:163], v[80:81], v[88:89]
	v_pk_mul_f32 v[158:159], v[158:159], v[152:153] op_sel_hi:[1,0]
	v_pk_mul_f32 v[162:163], v[162:163], v[152:153] op_sel_hi:[1,0]
	v_cvt_pk_bf16_f32 v152, v156, v157
	v_cvt_pk_bf16_f32 v153, v154, v155
	v_or_b32_e32 v160, 32, v150
	v_cvt_pk_bf16_f32 v154, v162, v163
	v_cvt_pk_bf16_f32 v155, v158, v159
	ds_read_b128 v[156:159], v164 offset:3072
	v_ashrrev_i32_e32 v161, 31, v160
	v_lshlrev_b64 v[160:161], 10, v[160:161]
	v_lshl_add_u64 v[160:161], s[14:15], 0, v[160:161]
	v_lshl_add_u64 v[160:161], v[160:161], 0, s[4:5]
	s_waitcnt lgkmcnt(0)
	v_add_f32_e32 v151, v156, v157
	v_add_f32_e32 v156, v158, v159
	v_add_f32_e32 v151, v151, v156
	v_mov_b32_e32 v156, v151
	s_nop 1
	v_permlane16_swap_b32_e32 v151, v156
	v_add_f32_e32 v151, v151, v156
	v_mov_b32_e32 v156, v151
	s_nop 1
	v_permlane32_swap_b32_e32 v151, v156
	v_add_f32_e32 v151, v151, v156
	v_fmamk_f32 v151, v151, 0x3a800000, v174
	v_rsq_f32_e32 v151, v151
	v_lshl_add_u64 v[160:161], v[160:161], 0, s[36:37]
	v_lshl_add_u64 v[156:157], v[160:161], 0, v[136:137]
	global_store_dwordx4 v[156:157], v[152:155], off offset:-512 sc1
	v_pk_mul_f32 v[156:157], v[68:69], v[76:77]
	v_pk_mul_f32 v[158:159], v[66:67], v[74:75]
	v_mul_f32_e32 v152, v151, v151
	v_pk_mul_f32 v[154:155], v[70:71], v[78:79]
	v_pk_mul_f32 v[156:157], v[156:157], v[152:153] op_sel_hi:[1,0]
	v_pk_mul_f32 v[154:155], v[154:155], v[152:153] op_sel_hi:[1,0]
	v_pk_mul_f32 v[162:163], v[64:65], v[72:73]
	v_pk_mul_f32 v[158:159], v[158:159], v[152:153] op_sel_hi:[1,0]
	v_pk_mul_f32 v[162:163], v[162:163], v[152:153] op_sel_hi:[1,0]
	v_cvt_pk_bf16_f32 v152, v156, v157
	v_cvt_pk_bf16_f32 v153, v154, v155
	v_or_b32_e32 v160, 48, v150
	v_cvt_pk_bf16_f32 v154, v162, v163
	v_cvt_pk_bf16_f32 v155, v158, v159
	ds_read_b128 v[156:159], v164 offset:8192
	v_ashrrev_i32_e32 v161, 31, v160
	v_lshlrev_b64 v[160:161], 10, v[160:161]
	v_lshl_add_u64 v[160:161], s[14:15], 0, v[160:161]
	v_lshl_add_u64 v[160:161], v[160:161], 0, s[4:5]
	s_waitcnt lgkmcnt(0)
	v_add_f32_e32 v151, v156, v157
	v_add_f32_e32 v156, v158, v159
	v_add_f32_e32 v151, v151, v156
	v_mov_b32_e32 v156, v151
	s_nop 1
	v_permlane16_swap_b32_e32 v151, v156
	v_add_f32_e32 v151, v151, v156
	v_mov_b32_e32 v156, v151
	s_nop 1
	v_permlane32_swap_b32_e32 v151, v156
	v_add_f32_e32 v151, v151, v156
	v_fmamk_f32 v151, v151, 0x3a800000, v174
	v_rsq_f32_e32 v151, v151
	v_lshl_add_u64 v[160:161], v[160:161], 0, s[36:37]
	v_lshl_add_u64 v[156:157], v[160:161], 0, v[136:137]
	global_store_dwordx4 v[156:157], v[152:155], off offset:-512 sc1
	v_pk_mul_f32 v[156:157], v[52:53], v[60:61]
	v_pk_mul_f32 v[158:159], v[50:51], v[58:59]
	v_mul_f32_e32 v152, v151, v151
	v_pk_mul_f32 v[154:155], v[54:55], v[62:63]
	v_pk_mul_f32 v[156:157], v[156:157], v[152:153] op_sel_hi:[1,0]
	v_pk_mul_f32 v[154:155], v[154:155], v[152:153] op_sel_hi:[1,0]
	v_pk_mul_f32 v[162:163], v[48:49], v[56:57]
	v_pk_mul_f32 v[158:159], v[158:159], v[152:153] op_sel_hi:[1,0]
	v_pk_mul_f32 v[162:163], v[162:163], v[152:153] op_sel_hi:[1,0]
	v_cvt_pk_bf16_f32 v152, v156, v157
	v_cvt_pk_bf16_f32 v153, v154, v155
	v_add_u32_e32 v160, 0x80, v150
	v_cvt_pk_bf16_f32 v154, v162, v163
	v_cvt_pk_bf16_f32 v155, v158, v159
	ds_read_b128 v[156:159], v164 offset:9216
	v_ashrrev_i32_e32 v161, 31, v160
	v_lshlrev_b64 v[160:161], 10, v[160:161]
	v_lshl_add_u64 v[160:161], s[14:15], 0, v[160:161]
	v_lshl_add_u64 v[160:161], v[160:161], 0, s[4:5]
	s_waitcnt lgkmcnt(0)
; #define ROW_RS(u, ai, m) row_rs_lds((ai) * 128 + wr * 64 + (m) * 16 + fr, fq)
; #define ROWLOOP for (int ai = 0; ai < 2; ++ai) _Pragma("unroll") for (int m = 0; m < 4; ++m)
;     __device__ __forceinline__ void operator()(const Acc& acc, const Unit& u, int wr, int wc, int fr, int fq) const {
;     ...
;         } else if (pn < 6) {
;             const int ct = (pn - 2) * 128;
; #pragma unroll
;             ROWLOOP { const int row = ROW_OF(u, ai, m); const float rs = ROW_RS(u, ai, m); const float r2 = rs * rs;
;                 *(u32x4*)(U + (size_t)row * CW + ct + wc * 32 + fq * 8) = pack8(acc[ai][0][m][0] * acc[ai][1][m][0] * r2, acc[ai][0][m][1] * acc[ai][1][m][1] * r2); }
	v_add_f32_e32 v151, v156, v157
	v_add_f32_e32 v156, v158, v159
	v_add_f32_e32 v151, v151, v156
	v_mov_b32_e32 v156, v151
	s_nop 1
	v_permlane16_swap_b32_e32 v151, v156
	v_add_f32_e32 v151, v151, v156
	v_mov_b32_e32 v156, v151
	s_nop 1
	v_permlane32_swap_b32_e32 v151, v156
	v_add_f32_e32 v151, v151, v156
	v_fmamk_f32 v151, v151, 0x3a800000, v174
	v_rsq_f32_e32 v151, v151
	v_lshl_add_u64 v[160:161], v[160:161], 0, s[36:37]
	v_lshl_add_u64 v[156:157], v[160:161], 0, v[136:137]
	global_store_dwordx4 v[156:157], v[152:155], off offset:-512 sc1
	v_pk_mul_f32 v[156:157], v[36:37], v[44:45]
	v_pk_mul_f32 v[158:159], v[34:35], v[42:43]
	v_mul_f32_e32 v152, v151, v151
	v_pk_mul_f32 v[154:155], v[38:39], v[46:47]
	v_pk_mul_f32 v[156:157], v[156:157], v[152:153] op_sel_hi:[1,0]
	v_pk_mul_f32 v[154:155], v[154:155], v[152:153] op_sel_hi:[1,0]
	v_pk_mul_f32 v[162:163], v[32:33], v[40:41]
	v_pk_mul_f32 v[158:159], v[158:159], v[152:153] op_sel_hi:[1,0]
	v_pk_mul_f32 v[162:163], v[162:163], v[152:153] op_sel_hi:[1,0]
	v_cvt_pk_bf16_f32 v152, v156, v157
	v_cvt_pk_bf16_f32 v153, v154, v155
	v_add_u32_e32 v160, 0x90, v150
	v_cvt_pk_bf16_f32 v154, v162, v163
	v_cvt_pk_bf16_f32 v155, v158, v159
	ds_read_b128 v[156:159], v164 offset:10240
	v_ashrrev_i32_e32 v161, 31, v160
	v_lshlrev_b64 v[160:161], 10, v[160:161]
	v_lshl_add_u64 v[160:161], s[14:15], 0, v[160:161]
	v_lshl_add_u64 v[160:161], v[160:161], 0, s[4:5]
	s_waitcnt lgkmcnt(0)
	v_add_f32_e32 v151, v156, v157
	v_add_f32_e32 v156, v158, v159
	v_add_f32_e32 v151, v151, v156
	v_mov_b32_e32 v156, v151
	s_nop 1
	v_permlane16_swap_b32_e32 v151, v156
	v_add_f32_e32 v151, v151, v156
	v_mov_b32_e32 v156, v151
	s_nop 1
	v_permlane32_swap_b32_e32 v151, v156
	v_add_f32_e32 v151, v151, v156
	v_fmamk_f32 v151, v151, 0x3a800000, v174
	v_rsq_f32_e32 v151, v151
	v_lshl_add_u64 v[160:161], v[160:161], 0, s[36:37]
	v_lshl_add_u64 v[156:157], v[160:161], 0, v[136:137]
	global_store_dwordx4 v[156:157], v[152:155], off offset:-512 sc1
	v_pk_mul_f32 v[156:157], v[20:21], v[28:29]
	v_pk_mul_f32 v[158:159], v[18:19], v[26:27]
	v_mul_f32_e32 v152, v151, v151
	v_pk_mul_f32 v[154:155], v[22:23], v[30:31]
	v_pk_mul_f32 v[156:157], v[156:157], v[152:153] op_sel_hi:[1,0]
	v_pk_mul_f32 v[154:155], v[154:155], v[152:153] op_sel_hi:[1,0]
	v_pk_mul_f32 v[162:163], v[16:17], v[24:25]
	v_pk_mul_f32 v[158:159], v[158:159], v[152:153] op_sel_hi:[1,0]
	v_pk_mul_f32 v[162:163], v[162:163], v[152:153] op_sel_hi:[1,0]
	v_cvt_pk_bf16_f32 v152, v156, v157
	v_cvt_pk_bf16_f32 v153, v154, v155
	v_add_u32_e32 v160, 0xa0, v150
	v_cvt_pk_bf16_f32 v154, v162, v163
	v_cvt_pk_bf16_f32 v155, v158, v159
	ds_read_b128 v[156:159], v164 offset:11264
	v_ashrrev_i32_e32 v161, 31, v160
	v_lshlrev_b64 v[160:161], 10, v[160:161]
	v_lshl_add_u64 v[160:161], s[14:15], 0, v[160:161]
	v_lshl_add_u64 v[160:161], v[160:161], 0, s[4:5]
	s_waitcnt lgkmcnt(0)
	v_add_f32_e32 v151, v156, v157
	v_add_f32_e32 v156, v158, v159
	v_add_f32_e32 v151, v151, v156
	v_mov_b32_e32 v156, v151
	s_nop 1
	v_permlane16_swap_b32_e32 v151, v156
	v_add_f32_e32 v151, v151, v156
	v_mov_b32_e32 v156, v151
	v_lshl_add_u64 v[160:161], v[160:161], 0, s[36:37]
	s_nop 0
	v_permlane32_swap_b32_e32 v151, v156
	v_add_f32_e32 v151, v151, v156
	v_lshl_add_u64 v[156:157], v[160:161], 0, v[136:137]
	v_fmamk_f32 v151, v151, 0x3a800000, v174
	global_store_dwordx4 v[156:157], v[152:155], off offset:-512 sc1
	v_rsq_f32_e32 v151, v151
	v_pk_mul_f32 v[156:157], v[4:5], v[12:13]
	v_add_u32_e32 v154, 0xb0, v150
	v_ashrrev_i32_e32 v155, 31, v154
	v_lshlrev_b64 v[154:155], 10, v[154:155]
	v_lshl_add_u64 v[154:155], s[14:15], 0, v[154:155]
	v_lshl_add_u64 v[154:155], v[154:155], 0, s[4:5]
	v_mul_f32_e32 v150, v151, v151
	v_pk_mul_f32 v[152:153], v[6:7], v[14:15]
	v_lshl_add_u64 v[154:155], v[154:155], 0, s[36:37]
	v_pk_mul_f32 v[152:153], v[152:153], v[150:151] op_sel_hi:[1,0]
	v_pk_mul_f32 v[158:159], v[2:3], v[10:11]
	v_pk_mul_f32 v[160:161], v[0:1], v[8:9]
	v_lshl_add_u64 v[154:155], v[154:155], 0, v[136:137]
	v_pk_mul_f32 v[156:157], v[156:157], v[150:151] op_sel_hi:[1,0]
	v_pk_mul_f32 v[158:159], v[158:159], v[150:151] op_sel_hi:[1,0]
	v_pk_mul_f32 v[160:161], v[160:161], v[150:151] op_sel_hi:[1,0]
	v_cvt_pk_bf16_f32 v150, v156, v157
	v_cvt_pk_bf16_f32 v151, v152, v153
	s_nop 0
	v_cvt_pk_bf16_f32 v152, v160, v161
	v_cvt_pk_bf16_f32 v153, v158, v159
	global_store_dwordx4 v[154:155], v[150:153], off offset:-512 sc1

; #define LAS __attribute__((address_space(3)))
; #define ROW_RS(u, ai, m) row_rs_lds((ai) * 128 + wr * 64 + (m) * 16 + fr, fq)
; #define ROWLOOP for (int ai = 0; ai < 2; ++ai) _Pragma("unroll") for (int m = 0; m < 4; ++m)
; __device__ __forceinline__ float row_rs_lds(int rt, int fq) {
;     extern __shared__ __attribute__((aligned(16))) unsigned char lds_raw_[];
;     const f32x4 v = *(const LAS f32x4*)((LAS unsigned char*)lds_raw_ + RS_OFF + rt * 64 + fq * 16);
;     float s = (v[0] + v[1]) + (v[2] + v[3]);
;     s = red4_sum(s);
;     return __builtin_amdgcn_rsqf(s * (1.0f / D) + EPS);
;     __device__ __forceinline__ void operator()(const Acc& acc, const Unit& u, int wr, int wc, int fr, int fq) const {
;     ...
;         if (pn < 2 || pn >= 10) {
;             bf16_t* o = pn < 2 ? GB : V; const int ct = (pn < 2 ? pn : pn - 10) * 256;
; #pragma unroll
;             ROWLOOP { const int row = ROW_OF(u, ai, m); const float rs = ROW_RS(u, ai, m);
; #pragma unroll
;                 for (int bj = 0; bj < 2; ++bj) *(u32x4*)(o + (size_t)row * CW + ct + bj * 128 + wc * 32 + fq * 8) = pack8(acc[ai][bj][m][0] * rs, acc[ai][bj][m][1] * rs); }
.LBB0_455:
	s_lshl_b32 s4, s33, 8
	s_add_i32 s25, s4, 0xfffff600
	s_cmp_lt_i32 s33, 2
	s_cselect_b32 s27, s64, 0x16100000
	s_cselect_b32 s36, s4, s25
	s_add_u32 s4, s6, s27
	s_addc_u32 s25, s7, 0
	s_ashr_i32 s37, s36, 31
	v_add_u32_e32 v154, v172, v170
	v_lshl_add_u32 v150, s34, 8, v139
	s_lshl_b64 s[34:35], s[36:37], 1
	ds_read_b128 v[156:159], v154
	s_add_u32 s4, s4, s34
	s_addc_u32 s25, s25, s35
	s_lshl_b32 s27, s56, 1
	s_add_u32 s34, s4, s27
	s_addc_u32 s35, s25, 0
	v_lshlrev_b32_e32 v136, 1, v138
	v_lshl_add_u64 v[152:153], s[34:35], 0, v[136:137]
	s_waitcnt lgkmcnt(0)
	v_add_f32_e32 v136, v156, v157
	v_add_f32_e32 v151, v158, v159
	v_add_f32_e32 v136, v136, v151
	v_mov_b32_e32 v151, v136
	s_nop 1
	v_permlane16_swap_b32_e32 v136, v151
	v_add_f32_e32 v136, v136, v151
	v_mov_b32_e32 v151, v136
	s_nop 1
	v_permlane32_swap_b32_e32 v136, v151
	v_add_f32_e32 v136, v136, v151
	v_fmamk_f32 v136, v136, 0x3a800000, v174
	v_rsq_f32_e32 v136, v136
	v_ashrrev_i32_e32 v151, 31, v150
	v_lshlrev_b64 v[156:157], 10, v[150:151]
	v_lshl_add_u64 v[156:157], v[152:153], 0, v[156:157]
	v_pk_mul_f32 v[126:127], v[126:127], v[136:137] op_sel_hi:[1,0]
	v_pk_mul_f32 v[124:125], v[124:125], v[136:137] op_sel_hi:[1,0]
	v_pk_mul_f32 v[158:159], v[122:123], v[136:137] op_sel_hi:[1,0]
	v_pk_mul_f32 v[122:123], v[120:121], v[136:137] op_sel_hi:[1,0]
	v_cvt_pk_bf16_f32 v120, v124, v125
	v_cvt_pk_bf16_f32 v121, v126, v127
	v_pk_mul_f32 v[118:119], v[118:119], v[136:137] op_sel_hi:[1,0]
	v_cvt_pk_bf16_f32 v122, v122, v123
	v_cvt_pk_bf16_f32 v123, v158, v159
	global_store_dwordx4 v[156:157], v[120:123], off sc1
	v_pk_mul_f32 v[116:117], v[116:117], v[136:137] op_sel_hi:[1,0]
	s_nop 0
	v_pk_mul_f32 v[120:121], v[114:115], v[136:137] op_sel_hi:[1,0]
	v_pk_mul_f32 v[114:115], v[112:113], v[136:137] op_sel_hi:[1,0]
	v_cvt_pk_bf16_f32 v112, v116, v117
	v_cvt_pk_bf16_f32 v113, v118, v119
	s_nop 0
	v_cvt_pk_bf16_f32 v114, v114, v115
	v_cvt_pk_bf16_f32 v115, v120, v121
	ds_read_b128 v[116:119], v154 offset:1024
	global_store_dwordx4 v[156:157], v[112:115], off offset:256 sc1
	s_nop 1
	v_or_b32_e32 v112, 16, v150
	s_waitcnt lgkmcnt(0)
	v_add_f32_e32 v113, v116, v117
	v_add_f32_e32 v114, v118, v119
	v_add_f32_e32 v113, v113, v114
	v_mov_b32_e32 v114, v113
	s_nop 1
	v_permlane16_swap_b32_e32 v113, v114
	v_add_f32_e32 v113, v113, v114
	v_mov_b32_e32 v114, v113
	s_nop 1
	v_permlane32_swap_b32_e32 v113, v114
	v_add_f32_e32 v113, v113, v114
	v_fmamk_f32 v113, v113, 0x3a800000, v174
	v_rsq_f32_e32 v114, v113
	v_ashrrev_i32_e32 v113, 31, v112
	v_lshlrev_b64 v[112:113], 10, v[112:113]
	v_lshl_add_u64 v[112:113], v[152:153], 0, v[112:113]
	v_pk_mul_f32 v[110:111], v[110:111], v[114:115] op_sel_hi:[1,0]
	v_pk_mul_f32 v[108:109], v[108:109], v[114:115] op_sel_hi:[1,0]
	v_pk_mul_f32 v[116:117], v[106:107], v[114:115] op_sel_hi:[1,0]
	v_pk_mul_f32 v[106:107], v[104:105], v[114:115] op_sel_hi:[1,0]
	v_cvt_pk_bf16_f32 v104, v108, v109
	v_cvt_pk_bf16_f32 v105, v110, v111
	v_pk_mul_f32 v[102:103], v[102:103], v[114:115] op_sel_hi:[1,0]
	v_cvt_pk_bf16_f32 v106, v106, v107
	v_cvt_pk_bf16_f32 v107, v116, v117
	global_store_dwordx4 v[112:113], v[104:107], off sc1
	v_pk_mul_f32 v[100:101], v[100:101], v[114:115] op_sel_hi:[1,0]
	s_nop 0
	v_pk_mul_f32 v[104:105], v[98:99], v[114:115] op_sel_hi:[1,0]
	v_pk_mul_f32 v[98:99], v[96:97], v[114:115] op_sel_hi:[1,0]
	v_cvt_pk_bf16_f32 v96, v100, v101
	v_cvt_pk_bf16_f32 v97, v102, v103
	s_nop 0
	v_cvt_pk_bf16_f32 v98, v98, v99
	v_cvt_pk_bf16_f32 v99, v104, v105
	ds_read_b128 v[100:103], v154 offset:2048
	global_store_dwordx4 v[112:113], v[96:99], off offset:256 sc1
	s_nop 1
	v_or_b32_e32 v96, 32, v150
	s_waitcnt lgkmcnt(0)
	v_add_f32_e32 v97, v100, v101
	v_add_f32_e32 v98, v102, v103
	v_add_f32_e32 v97, v97, v98
	v_mov_b32_e32 v98, v97
	s_nop 1
	v_permlane16_swap_b32_e32 v97, v98
	v_add_f32_e32 v97, v97, v98
	v_mov_b32_e32 v98, v97
	s_nop 1
	v_permlane32_swap_b32_e32 v97, v98
	v_add_f32_e32 v97, v97, v98
	v_fmamk_f32 v97, v97, 0x3a800000, v174
	v_rsq_f32_e32 v98, v97
	v_ashrrev_i32_e32 v97, 31, v96
	v_lshlrev_b64 v[96:97], 10, v[96:97]
	v_lshl_add_u64 v[96:97], v[152:153], 0, v[96:97]
	v_pk_mul_f32 v[94:95], v[94:95], v[98:99] op_sel_hi:[1,0]
	v_pk_mul_f32 v[92:93], v[92:93], v[98:99] op_sel_hi:[1,0]
	v_pk_mul_f32 v[100:101], v[90:91], v[98:99] op_sel_hi:[1,0]
	v_pk_mul_f32 v[90:91], v[88:89], v[98:99] op_sel_hi:[1,0]
	v_cvt_pk_bf16_f32 v88, v92, v93
	v_cvt_pk_bf16_f32 v89, v94, v95
	v_pk_mul_f32 v[86:87], v[86:87], v[98:99] op_sel_hi:[1,0]
	v_cvt_pk_bf16_f32 v90, v90, v91
	v_cvt_pk_bf16_f32 v91, v100, v101
	global_store_dwordx4 v[96:97], v[88:91], off sc1
	v_pk_mul_f32 v[84:85], v[84:85], v[98:99] op_sel_hi:[1,0]
	s_nop 0
	v_pk_mul_f32 v[88:89], v[82:83], v[98:99] op_sel_hi:[1,0]
	v_pk_mul_f32 v[82:83], v[80:81], v[98:99] op_sel_hi:[1,0]
	v_cvt_pk_bf16_f32 v80, v84, v85
	v_cvt_pk_bf16_f32 v81, v86, v87
	s_nop 0
	v_cvt_pk_bf16_f32 v82, v82, v83
	v_cvt_pk_bf16_f32 v83, v88, v89
	ds_read_b128 v[84:87], v154 offset:3072
	global_store_dwordx4 v[96:97], v[80:83], off offset:256 sc1
	s_nop 1
	v_or_b32_e32 v80, 48, v150
	s_waitcnt lgkmcnt(0)
; #define ROW_RS(u, ai, m) row_rs_lds((ai) * 128 + wr * 64 + (m) * 16 + fr, fq)
; #define ROWLOOP for (int ai = 0; ai < 2; ++ai) _Pragma("unroll") for (int m = 0; m < 4; ++m)
;     __device__ __forceinline__ void operator()(const Acc& acc, const Unit& u, int wr, int wc, int fr, int fq) const {
;     ...
;             ROWLOOP { const int row = ROW_OF(u, ai, m); const float rs = ROW_RS(u, ai, m);
; #pragma unroll
;                 for (int bj = 0; bj < 2; ++bj) *(u32x4*)(o + (size_t)row * CW + ct + bj * 128 + wc * 32 + fq * 8) = pack8(acc[ai][bj][m][0] * rs, acc[ai][bj][m][1] * rs); }
	v_add_f32_e32 v81, v84, v85
	v_add_f32_e32 v82, v86, v87
	v_add_f32_e32 v81, v81, v82
	v_mov_b32_e32 v82, v81
	s_nop 1
	v_permlane16_swap_b32_e32 v81, v82
	v_add_f32_e32 v81, v81, v82
	v_mov_b32_e32 v82, v81
	s_nop 1
	v_permlane32_swap_b32_e32 v81, v82
	v_add_f32_e32 v81, v81, v82
	v_fmamk_f32 v81, v81, 0x3a800000, v174
	v_rsq_f32_e32 v82, v81
	v_ashrrev_i32_e32 v81, 31, v80
	v_lshlrev_b64 v[80:81], 10, v[80:81]
	v_lshl_add_u64 v[80:81], v[152:153], 0, v[80:81]
	v_pk_mul_f32 v[78:79], v[78:79], v[82:83] op_sel_hi:[1,0]
	v_pk_mul_f32 v[76:77], v[76:77], v[82:83] op_sel_hi:[1,0]
	v_pk_mul_f32 v[84:85], v[74:75], v[82:83] op_sel_hi:[1,0]
	v_pk_mul_f32 v[74:75], v[72:73], v[82:83] op_sel_hi:[1,0]
	v_cvt_pk_bf16_f32 v72, v76, v77
	v_cvt_pk_bf16_f32 v73, v78, v79
	v_pk_mul_f32 v[70:71], v[70:71], v[82:83] op_sel_hi:[1,0]
	v_cvt_pk_bf16_f32 v74, v74, v75
	v_cvt_pk_bf16_f32 v75, v84, v85
	global_store_dwordx4 v[80:81], v[72:75], off sc1
	v_pk_mul_f32 v[68:69], v[68:69], v[82:83] op_sel_hi:[1,0]
	s_nop 0
	v_pk_mul_f32 v[72:73], v[66:67], v[82:83] op_sel_hi:[1,0]
	v_pk_mul_f32 v[66:67], v[64:65], v[82:83] op_sel_hi:[1,0]
	v_cvt_pk_bf16_f32 v64, v68, v69
	v_cvt_pk_bf16_f32 v65, v70, v71
	s_nop 0
	v_cvt_pk_bf16_f32 v66, v66, v67
	v_cvt_pk_bf16_f32 v67, v72, v73
	ds_read_b128 v[68:71], v154 offset:8192
	global_store_dwordx4 v[80:81], v[64:67], off offset:256 sc1
	s_nop 1
	v_add_u32_e32 v64, 0x80, v150
	s_waitcnt lgkmcnt(0)
	v_add_f32_e32 v65, v68, v69
	v_add_f32_e32 v66, v70, v71
	v_add_f32_e32 v65, v65, v66
	v_mov_b32_e32 v66, v65
	s_nop 1
	v_permlane16_swap_b32_e32 v65, v66
	v_add_f32_e32 v65, v65, v66
	v_mov_b32_e32 v66, v65
	s_nop 1
	v_permlane32_swap_b32_e32 v65, v66
	v_add_f32_e32 v65, v65, v66
	v_fmamk_f32 v65, v65, 0x3a800000, v174
	v_rsq_f32_e32 v66, v65
	v_ashrrev_i32_e32 v65, 31, v64
	v_lshlrev_b64 v[64:65], 10, v[64:65]
	v_lshl_add_u64 v[64:65], v[152:153], 0, v[64:65]
	v_pk_mul_f32 v[62:63], v[62:63], v[66:67] op_sel_hi:[1,0]
	v_pk_mul_f32 v[60:61], v[60:61], v[66:67] op_sel_hi:[1,0]
	v_pk_mul_f32 v[68:69], v[58:59], v[66:67] op_sel_hi:[1,0]
	v_pk_mul_f32 v[58:59], v[56:57], v[66:67] op_sel_hi:[1,0]
	v_cvt_pk_bf16_f32 v56, v60, v61
	v_cvt_pk_bf16_f32 v57, v62, v63
	v_pk_mul_f32 v[54:55], v[54:55], v[66:67] op_sel_hi:[1,0]
	v_cvt_pk_bf16_f32 v58, v58, v59
	v_cvt_pk_bf16_f32 v59, v68, v69
	global_store_dwordx4 v[64:65], v[56:59], off sc1
	v_pk_mul_f32 v[52:53], v[52:53], v[66:67] op_sel_hi:[1,0]
	s_nop 0
	v_pk_mul_f32 v[56:57], v[50:51], v[66:67] op_sel_hi:[1,0]
	v_pk_mul_f32 v[50:51], v[48:49], v[66:67] op_sel_hi:[1,0]
	v_cvt_pk_bf16_f32 v48, v52, v53
	v_cvt_pk_bf16_f32 v49, v54, v55
	s_nop 0
	v_cvt_pk_bf16_f32 v50, v50, v51
	v_cvt_pk_bf16_f32 v51, v56, v57
	ds_read_b128 v[52:55], v154 offset:9216
	global_store_dwordx4 v[64:65], v[48:51], off offset:256 sc1
	s_nop 1
	v_add_u32_e32 v48, 0x90, v150
	s_waitcnt lgkmcnt(0)
; #define ROW_RS(u, ai, m) row_rs_lds((ai) * 128 + wr * 64 + (m) * 16 + fr, fq)
; #define ROWLOOP for (int ai = 0; ai < 2; ++ai) _Pragma("unroll") for (int m = 0; m < 4; ++m)
;     __device__ __forceinline__ void operator()(const Acc& acc, const Unit& u, int wr, int wc, int fr, int fq) const {
;     ...
;             ROWLOOP { const int row = ROW_OF(u, ai, m); const float rs = ROW_RS(u, ai, m);
; #pragma unroll
;                 for (int bj = 0; bj < 2; ++bj) *(u32x4*)(o + (size_t)row * CW + ct + bj * 128 + wc * 32 + fq * 8) = pack8(acc[ai][bj][m][0] * rs, acc[ai][bj][m][1] * rs); }
	v_add_f32_e32 v49, v52, v53
	v_add_f32_e32 v50, v54, v55
	v_add_f32_e32 v49, v49, v50
	v_mov_b32_e32 v50, v49
	s_nop 1
	v_permlane16_swap_b32_e32 v49, v50
	v_add_f32_e32 v49, v49, v50
	v_mov_b32_e32 v50, v49
	s_nop 1
	v_permlane32_swap_b32_e32 v49, v50
	v_add_f32_e32 v49, v49, v50
	v_fmamk_f32 v49, v49, 0x3a800000, v174
	v_rsq_f32_e32 v50, v49
	v_ashrrev_i32_e32 v49, 31, v48
	v_lshlrev_b64 v[48:49], 10, v[48:49]
	v_lshl_add_u64 v[48:49], v[152:153], 0, v[48:49]
	v_pk_mul_f32 v[46:47], v[46:47], v[50:51] op_sel_hi:[1,0]
	v_pk_mul_f32 v[44:45], v[44:45], v[50:51] op_sel_hi:[1,0]
	v_pk_mul_f32 v[52:53], v[42:43], v[50:51] op_sel_hi:[1,0]
	v_pk_mul_f32 v[42:43], v[40:41], v[50:51] op_sel_hi:[1,0]
	v_cvt_pk_bf16_f32 v40, v44, v45
	v_cvt_pk_bf16_f32 v41, v46, v47
	v_pk_mul_f32 v[38:39], v[38:39], v[50:51] op_sel_hi:[1,0]
	v_cvt_pk_bf16_f32 v42, v42, v43
	v_cvt_pk_bf16_f32 v43, v52, v53
	global_store_dwordx4 v[48:49], v[40:43], off sc1
	v_pk_mul_f32 v[36:37], v[36:37], v[50:51] op_sel_hi:[1,0]
	s_nop 0
	v_pk_mul_f32 v[40:41], v[34:35], v[50:51] op_sel_hi:[1,0]
	v_pk_mul_f32 v[34:35], v[32:33], v[50:51] op_sel_hi:[1,0]
	v_cvt_pk_bf16_f32 v32, v36, v37
	v_cvt_pk_bf16_f32 v33, v38, v39
	s_nop 0
	v_cvt_pk_bf16_f32 v34, v34, v35
	v_cvt_pk_bf16_f32 v35, v40, v41
	ds_read_b128 v[36:39], v154 offset:10240
	global_store_dwordx4 v[48:49], v[32:35], off offset:256 sc1
	s_nop 1
	v_add_u32_e32 v32, 0xa0, v150
	s_waitcnt lgkmcnt(0)
	v_add_f32_e32 v33, v36, v37
	v_add_f32_e32 v34, v38, v39
	v_add_f32_e32 v33, v33, v34
	v_mov_b32_e32 v34, v33
	s_nop 1
	v_permlane16_swap_b32_e32 v33, v34
	v_add_f32_e32 v33, v33, v34
	v_mov_b32_e32 v34, v33
	s_nop 1
	v_permlane32_swap_b32_e32 v33, v34
	v_add_f32_e32 v33, v33, v34
	v_fmamk_f32 v33, v33, 0x3a800000, v174
	v_rsq_f32_e32 v34, v33
	v_ashrrev_i32_e32 v33, 31, v32
	v_lshlrev_b64 v[32:33], 10, v[32:33]
	v_lshl_add_u64 v[32:33], v[152:153], 0, v[32:33]
	v_pk_mul_f32 v[30:31], v[30:31], v[34:35] op_sel_hi:[1,0]
	v_pk_mul_f32 v[28:29], v[28:29], v[34:35] op_sel_hi:[1,0]
	v_pk_mul_f32 v[36:37], v[26:27], v[34:35] op_sel_hi:[1,0]
	v_pk_mul_f32 v[26:27], v[24:25], v[34:35] op_sel_hi:[1,0]
	v_cvt_pk_bf16_f32 v24, v28, v29
	v_cvt_pk_bf16_f32 v25, v30, v31
	v_pk_mul_f32 v[22:23], v[22:23], v[34:35] op_sel_hi:[1,0]
	v_cvt_pk_bf16_f32 v26, v26, v27
	v_cvt_pk_bf16_f32 v27, v36, v37
	global_store_dwordx4 v[32:33], v[24:27], off sc1
	v_pk_mul_f32 v[20:21], v[20:21], v[34:35] op_sel_hi:[1,0]
	s_nop 0
	v_pk_mul_f32 v[24:25], v[18:19], v[34:35] op_sel_hi:[1,0]
	v_pk_mul_f32 v[18:19], v[16:17], v[34:35] op_sel_hi:[1,0]
	v_cvt_pk_bf16_f32 v16, v20, v21
	v_cvt_pk_bf16_f32 v17, v22, v23
	s_nop 0
	v_cvt_pk_bf16_f32 v18, v18, v19
	v_cvt_pk_bf16_f32 v19, v24, v25
	ds_read_b128 v[20:23], v154 offset:11264
	global_store_dwordx4 v[32:33], v[16:19], off offset:256 sc1
	s_nop 1
	v_add_u32_e32 v16, 0xb0, v150
	s_waitcnt lgkmcnt(0)
	v_add_f32_e32 v17, v20, v21
	v_add_f32_e32 v18, v22, v23
	v_add_f32_e32 v17, v17, v18
	v_mov_b32_e32 v18, v17
	s_nop 1
	v_permlane16_swap_b32_e32 v17, v18
	v_add_f32_e32 v17, v17, v18
	v_mov_b32_e32 v18, v17
	s_nop 1
	v_permlane32_swap_b32_e32 v17, v18
	v_add_f32_e32 v17, v17, v18
	v_fmamk_f32 v17, v17, 0x3a800000, v174
	v_rsq_f32_e32 v18, v17
	v_ashrrev_i32_e32 v17, 31, v16
	v_lshlrev_b64 v[16:17], 10, v[16:17]
	v_lshl_add_u64 v[16:17], v[152:153], 0, v[16:17]
	v_pk_mul_f32 v[14:15], v[14:15], v[18:19] op_sel_hi:[1,0]
	v_pk_mul_f32 v[12:13], v[12:13], v[18:19] op_sel_hi:[1,0]
	v_pk_mul_f32 v[20:21], v[10:11], v[18:19] op_sel_hi:[1,0]
	v_pk_mul_f32 v[10:11], v[8:9], v[18:19] op_sel_hi:[1,0]
	v_cvt_pk_bf16_f32 v8, v12, v13
	v_cvt_pk_bf16_f32 v9, v14, v15
	v_pk_mul_f32 v[6:7], v[6:7], v[18:19] op_sel_hi:[1,0]
	v_cvt_pk_bf16_f32 v10, v10, v11
	v_cvt_pk_bf16_f32 v11, v20, v21
	global_store_dwordx4 v[16:17], v[8:11], off sc1
	v_pk_mul_f32 v[4:5], v[4:5], v[18:19] op_sel_hi:[1,0]
	s_nop 0
	v_pk_mul_f32 v[8:9], v[2:3], v[18:19] op_sel_hi:[1,0]
	v_pk_mul_f32 v[2:3], v[0:1], v[18:19] op_sel_hi:[1,0]
	v_cvt_pk_bf16_f32 v0, v4, v5
	v_cvt_pk_bf16_f32 v1, v6, v7
	s_nop 0
	v_cvt_pk_bf16_f32 v2, v2, v3
	v_cvt_pk_bf16_f32 v3, v8, v9
	global_store_dwordx4 v[16:17], v[0:3], off offset:256 sc1
	s_andn2_b64 vcc, exec, s[2:3]
	s_mov_b64 s[2:3], -1
	s_cbranch_vccnz .LBB0_437

.LBB0_534:
	s_ashr_i32 s13, s12, 31
	s_lshl_b64 s[22:23], s[12:13], 25
	s_add_u32 s22, s88, s22
	s_addc_u32 s23, s89, s23
	v_lshlrev_b64 v[68:69], 10, v[48:49]
	v_lshl_add_u64 v[68:69], s[22:23], 0, v[68:69]
	s_lshl_b32 s22, s14, 6
	s_ashr_i32 s23, s22, 31
	v_lshl_add_u64 v[68:69], s[22:23], 1, v[68:69]
	v_lshl_add_u64 v[68:69], v[68:69], 0, v[44:45]
	v_cvt_pk_bf16_f32 v64, v64, v65
	v_cvt_pk_bf16_f32 v65, v62, v63
	global_store_dwordx2 v[68:69], v[64:65], off sc1
	v_cvt_pk_bf16_f32 v60, v60, v61
	v_cvt_pk_bf16_f32 v61, v58, v59
	global_store_dwordx2 v[68:69], v[60:61], off offset:32 sc1
	v_cvt_pk_bf16_f32 v56, v56, v57
	v_cvt_pk_bf16_f32 v57, v54, v55
	global_store_dwordx2 v[68:69], v[56:57], off offset:64 sc1
	v_cvt_pk_bf16_f32 v52, v52, v53
	v_cvt_pk_bf16_f32 v53, v50, v51
	global_store_dwordx2 v[68:69], v[52:53], off offset:96 sc1
	s_and_saveexec_b64 s[22:23], s[86:87]
	s_cbranch_execz .LBB0_536
	s_lshl_b64 s[12:13], s[12:13], 20
	s_add_u32 s12, s43, s12
	s_addc_u32 s13, s91, s13
	v_lshlrev_b64 v[48:49], 5, v[48:49]
	v_lshl_add_u64 v[48:49], s[12:13], 0, v[48:49]
	s_ashr_i32 s15, s14, 31
	v_lshl_add_u64 v[48:49], s[14:15], 2, v[48:49]
	global_store_dword v[48:49], v66, off sc1

; #define ATT_FLUSH() do { if (have_prev) { bf16_t* op_ = OB + (size_t)pg * T * CW + ptok * CW + ph * 64 + 4 * fq; \
;         _Pragma("unroll") for (int dt = 0; dt < 4; ++dt) { u32x2 wv; wv.x = cvt_pk_bf16(po[dt][0], po[dt][1]); wv.y = cvt_pk_bf16(po[dt][2], po[dt][3]); *(u32x2*)(op_ + 16 * dt) = wv; } \
;         if (fq == 0) LSE[(size_t)pg * T * NH + ptok * NH + ph] = plse; } } while (0)
; __device__ __forceinline__ void attn_phase(LAS unsigned char* lds, int tid, int vcu, int G, const bf16_t* Q, const bf16_t* Kb, const bf16_t* V, bf16_t* OB, float* LSE, const float* biasT) {
;     ...
;     ATT_FLUSH();
.LBB0_540:
	s_ashr_i32 s17, s16, 31
	s_lshl_b64 s[2:3], s[16:17], 25
	s_add_u32 s2, s88, s2
	s_addc_u32 s3, s89, s3
	s_waitcnt vmcnt(8)
	v_lshlrev_b64 v[0:1], 10, v[48:49]
	v_lshl_add_u64 v[0:1], s[2:3], 0, v[0:1]
	s_lshl_b32 s2, s90, 6
	s_ashr_i32 s3, s2, 31
	v_lshl_add_u64 v[0:1], s[2:3], 1, v[0:1]
	v_mov_b32_e32 v45, 0
	v_lshl_add_u64 v[0:1], v[0:1], 0, v[44:45]
	v_cvt_pk_bf16_f32 v2, v64, v65
	v_cvt_pk_bf16_f32 v3, v62, v63
	global_store_dwordx2 v[0:1], v[2:3], off sc1
	v_cvt_pk_bf16_f32 v2, v60, v61
	v_cvt_pk_bf16_f32 v3, v58, v59
	global_store_dwordx2 v[0:1], v[2:3], off offset:32 sc1
	v_cvt_pk_bf16_f32 v2, v56, v57
	v_cvt_pk_bf16_f32 v3, v54, v55
	global_store_dwordx2 v[0:1], v[2:3], off offset:64 sc1
	v_cvt_pk_bf16_f32 v2, v52, v53
	v_cvt_pk_bf16_f32 v3, v50, v51
	global_store_dwordx2 v[0:1], v[2:3], off offset:96 sc1
	s_and_saveexec_b64 s[2:3], s[86:87]
	s_cbranch_execz .LBB0_542
	s_lshl_b64 s[4:5], s[16:17], 20
	s_add_u32 s4, s43, s4
	s_addc_u32 s5, s91, s5
	v_lshlrev_b64 v[0:1], 5, v[48:49]
	v_lshl_add_u64 v[0:1], s[4:5], 0, v[0:1]
	s_ashr_i32 s91, s90, 31
	v_lshl_add_u64 v[0:1], s[90:91], 2, v[0:1]
	global_store_dword v[0:1], v66, off sc1

; __device__ __forceinline__ f32x4 bf4_lo(const u32x4 w) { return (f32x4){bf_lo(w.x), bf_hi(w.x), bf_lo(w.y), bf_hi(w.y)}; }
; __device__ __forceinline__ f32x4 bf4_hi(const u32x4 w) { return (f32x4){bf_lo(w.z), bf_hi(w.z), bf_lo(w.w), bf_hi(w.w)}; }
; template <int L> __device__ __forceinline__ void layer_body(const Args& args, LAS unsigned char* lds, const int G, const int lo, const int hi, const int wave_s, unsigned& nbar) {
;     ...
;                         for (int q = 0; q < 4; ++q) { const int t = tb + q * tstride; if (t < T) {
;                             const float mxl = fmaxf(lv[q][0], fmaxf(lv[q][1], lv[q][2]));
;                             float w0 = __builtin_amdgcn_exp2f(lv[q][0] - mxl), w1 = __builtin_amdgcn_exp2f(lv[q][1] - mxl), w2 = __builtin_amdgcn_exp2f(lv[q][2] - mxl);
;                             const float inv = __builtin_amdgcn_rcpf(w0 + w1 + w2); w0 *= inv; w1 *= inv; w2 *= inv;
;                             const f32x4 y0 = bf4_lo(ow[q][0]) * w0 + bf4_lo(ow[q][1]) * w1 + bf4_lo(ow[q][2]) * w2, y1 = bf4_hi(ow[q][0]) * w0 + bf4_hi(ow[q][1]) * w1 + bf4_hi(ow[q][2]) * w2;
;                             *(u32x4*)(YC + (size_t)t * D + c8) = pack8(y0, y1); } }
.LBB0_611:
	s_or_b64 exec, exec, s[18:19]
	s_waitcnt vmcnt(1)
	v_max3_f32 v55, v71, v72, v73
	v_sub_f32_e32 v57, v71, v55
	v_sub_f32_e32 v59, v72, v55
	v_exp_f32_e32 v57, v57
	v_exp_f32_e32 v59, v59
	v_sub_f32_e32 v55, v73, v55
	v_exp_f32_e32 v55, v55
	v_lshlrev_b32_e32 v80, 16, v44
	v_add_f32_e32 v71, v57, v59
	v_and_b32_e32 v81, 0xffff0000, v44
	v_add_f32_e32 v71, v55, v71
	v_rcp_f32_e32 v71, v71
	v_lshlrev_b32_e32 v44, 16, v45
	v_and_b32_e32 v45, 0xffff0000, v45
	v_lshlrev_b32_e32 v78, 16, v36
	v_mul_f32_e32 v74, v59, v71
	v_mul_f32_e32 v72, v57, v71
	v_and_b32_e32 v79, 0xffff0000, v36
	v_lshlrev_b32_e32 v36, 16, v37
	v_and_b32_e32 v37, 0xffff0000, v37
	v_pk_mul_f32 v[44:45], v[74:75], v[44:45] op_sel_hi:[0,1]
	v_pk_mul_f32 v[80:81], v[74:75], v[80:81] op_sel_hi:[0,1]
	v_mul_f32_e32 v76, v55, v71
	v_pk_fma_f32 v[78:79], v[72:73], v[78:79], v[80:81] op_sel_hi:[0,1,1]
	v_pk_fma_f32 v[36:37], v[72:73], v[36:37], v[44:45] op_sel_hi:[0,1,1]
	s_waitcnt vmcnt(0)
	v_lshlrev_b32_e32 v44, 16, v40
	v_and_b32_e32 v45, 0xffff0000, v40
	v_lshlrev_b32_e32 v40, 16, v41
	v_and_b32_e32 v41, 0xffff0000, v41
	v_pk_fma_f32 v[40:41], v[76:77], v[40:41], v[36:37] op_sel_hi:[0,1,1]
	v_pk_fma_f32 v[36:37], v[76:77], v[44:45], v[78:79] op_sel_hi:[0,1,1]
	v_lshlrev_b32_e32 v78, 16, v46
	v_and_b32_e32 v79, 0xffff0000, v46
	v_lshlrev_b32_e32 v46, 16, v47
	v_and_b32_e32 v47, 0xffff0000, v47
	v_lshlrev_b32_e32 v44, 16, v38
	v_and_b32_e32 v45, 0xffff0000, v38
	v_lshlrev_b32_e32 v38, 16, v39
	v_and_b32_e32 v39, 0xffff0000, v39
	v_pk_mul_f32 v[46:47], v[74:75], v[46:47] op_sel_hi:[0,1]
	v_pk_mul_f32 v[74:75], v[74:75], v[78:79] op_sel_hi:[0,1]
	v_pk_fma_f32 v[44:45], v[72:73], v[44:45], v[74:75] op_sel_hi:[0,1,1]
	v_pk_fma_f32 v[38:39], v[72:73], v[38:39], v[46:47] op_sel_hi:[0,1,1]
	v_lshlrev_b32_e32 v46, 16, v42
	v_and_b32_e32 v47, 0xffff0000, v42
	v_lshlrev_b32_e32 v42, 16, v43
	v_and_b32_e32 v43, 0xffff0000, v43
	v_cvt_pk_bf16_f32 v36, v36, v37
	v_cvt_pk_bf16_f32 v37, v40, v41
	v_lshlrev_b64 v[40:41], 11, v[60:61]
	v_pk_fma_f32 v[42:43], v[76:77], v[42:43], v[38:39] op_sel_hi:[0,1,1]
	v_pk_fma_f32 v[38:39], v[76:77], v[46:47], v[44:45] op_sel_hi:[0,1,1]
	v_lshl_add_u64 v[40:41], v[52:53], 0, v[40:41]
	v_cvt_pk_bf16_f32 v38, v38, v39
	v_cvt_pk_bf16_f32 v39, v42, v43
	global_store_dwordx4 v[40:41], v[36:39], off sc1
	s_and_saveexec_b64 s[18:19], s[6:7]
	s_cbranch_execnz .LBB0_614
	s_or_b64 exec, exec, s[18:19]
	s_and_saveexec_b64 s[6:7], s[4:5]
	s_cbranch_execnz .LBB0_615

; __device__ __forceinline__ f32x4 bf4_lo(const u32x4 w) { return (f32x4){bf_lo(w.x), bf_hi(w.x), bf_lo(w.y), bf_hi(w.y)}; }
; __device__ __forceinline__ f32x4 bf4_hi(const u32x4 w) { return (f32x4){bf_lo(w.z), bf_hi(w.z), bf_lo(w.w), bf_hi(w.w)}; }
; template <int L> __device__ __forceinline__ void layer_body(const Args& args, LAS unsigned char* lds, const int G, const int lo, const int hi, const int wave_s, unsigned& nbar) {
;     ...
;                         for (int q = 0; q < 4; ++q) { const int t = tb + q * tstride; if (t < T) {
;                             const float mxl = fmaxf(lv[q][0], fmaxf(lv[q][1], lv[q][2]));
;                             float w0 = __builtin_amdgcn_exp2f(lv[q][0] - mxl), w1 = __builtin_amdgcn_exp2f(lv[q][1] - mxl), w2 = __builtin_amdgcn_exp2f(lv[q][2] - mxl);
;                             const float inv = __builtin_amdgcn_rcpf(w0 + w1 + w2); w0 *= inv; w1 *= inv; w2 *= inv;
;                             const f32x4 y0 = bf4_lo(ow[q][0]) * w0 + bf4_lo(ow[q][1]) * w1 + bf4_lo(ow[q][2]) * w2, y1 = bf4_hi(ow[q][0]) * w0 + bf4_hi(ow[q][1]) * w1 + bf4_hi(ow[q][2]) * w2;
;                             *(u32x4*)(YC + (size_t)t * D + c8) = pack8(y0, y1); } }
.LBB0_614:
	v_max3_f32 v36, v64, v67, v70
	v_sub_f32_e32 v37, v64, v36
	v_sub_f32_e32 v38, v67, v36
	v_exp_f32_e32 v37, v37
	v_exp_f32_e32 v38, v38
	v_sub_f32_e32 v36, v70, v36
	v_exp_f32_e32 v39, v36
	v_lshlrev_b32_e32 v46, 16, v20
	v_add_f32_e32 v36, v37, v38
	v_and_b32_e32 v47, 0xffff0000, v20
	v_add_f32_e32 v36, v39, v36
	v_rcp_f32_e32 v40, v36
	v_lshlrev_b32_e32 v60, 16, v21
	v_and_b32_e32 v61, 0xffff0000, v21
	v_lshlrev_b32_e32 v42, 16, v8
	v_mul_f32_e32 v38, v38, v40
	v_mul_f32_e32 v36, v37, v40
	v_and_b32_e32 v43, 0xffff0000, v8
	v_lshlrev_b32_e32 v44, 16, v9
	v_and_b32_e32 v45, 0xffff0000, v9
	v_pk_mul_f32 v[60:61], v[38:39], v[60:61] op_sel_hi:[0,1]
	v_pk_mul_f32 v[46:47], v[38:39], v[46:47] op_sel_hi:[0,1]
	v_mul_f32_e32 v40, v39, v40
	v_pk_fma_f32 v[42:43], v[36:37], v[42:43], v[46:47] op_sel_hi:[0,1,1]
	v_pk_fma_f32 v[44:45], v[36:37], v[44:45], v[60:61] op_sel_hi:[0,1,1]
	v_lshlrev_b32_e32 v46, 16, v32
	v_and_b32_e32 v47, 0xffff0000, v32
	v_lshlrev_b32_e32 v60, 16, v33
	v_and_b32_e32 v61, 0xffff0000, v33
	v_lshlrev_b32_e32 v72, 16, v22
	v_and_b32_e32 v73, 0xffff0000, v22
	v_lshlrev_b32_e32 v74, 16, v23
	v_and_b32_e32 v75, 0xffff0000, v23
	v_pk_fma_f32 v[44:45], v[40:41], v[60:61], v[44:45] op_sel_hi:[0,1,1]
	v_pk_fma_f32 v[42:43], v[40:41], v[46:47], v[42:43] op_sel_hi:[0,1,1]
	v_lshlrev_b32_e32 v46, 16, v10
	v_and_b32_e32 v47, 0xffff0000, v10
	v_lshlrev_b32_e32 v60, 16, v11
	v_and_b32_e32 v61, 0xffff0000, v11
	v_pk_mul_f32 v[74:75], v[38:39], v[74:75] op_sel_hi:[0,1]
	v_pk_mul_f32 v[38:39], v[38:39], v[72:73] op_sel_hi:[0,1]
	v_pk_fma_f32 v[38:39], v[36:37], v[46:47], v[38:39] op_sel_hi:[0,1,1]
	v_pk_fma_f32 v[36:37], v[36:37], v[60:61], v[74:75] op_sel_hi:[0,1,1]
	v_lshlrev_b32_e32 v46, 16, v34
	v_and_b32_e32 v47, 0xffff0000, v34
	v_lshlrev_b32_e32 v60, 16, v35
	v_and_b32_e32 v61, 0xffff0000, v35
	v_ashrrev_i32_e32 v55, 31, v54
	v_pk_fma_f32 v[60:61], v[40:41], v[60:61], v[36:37] op_sel_hi:[0,1,1]
	v_pk_fma_f32 v[38:39], v[40:41], v[46:47], v[38:39] op_sel_hi:[0,1,1]
	v_lshlrev_b64 v[40:41], 11, v[54:55]
	v_lshl_add_u64 v[40:41], v[52:53], 0, v[40:41]
	v_cvt_pk_bf16_f32 v36, v42, v43
	v_cvt_pk_bf16_f32 v37, v44, v45
	v_cvt_pk_bf16_f32 v38, v38, v39
	v_cvt_pk_bf16_f32 v39, v60, v61
	global_store_dwordx4 v[40:41], v[36:39], off sc1
	s_or_b64 exec, exec, s[18:19]
	s_and_saveexec_b64 s[6:7], s[4:5]
	s_cbranch_execz .LBB0_613
; __device__ __forceinline__ f32x4 bf4_lo(const u32x4 w) { return (f32x4){bf_lo(w.x), bf_hi(w.x), bf_lo(w.y), bf_hi(w.y)}; }
; __device__ __forceinline__ f32x4 bf4_hi(const u32x4 w) { return (f32x4){bf_lo(w.z), bf_hi(w.z), bf_lo(w.w), bf_hi(w.w)}; }
; template <int L> __device__ __forceinline__ void layer_body(const Args& args, LAS unsigned char* lds, const int G, const int lo, const int hi, const int wave_s, unsigned& nbar) {
;     ...
;                         for (int q = 0; q < 4; ++q) { const int t = tb + q * tstride; if (t < T) {
;                             const float mxl = fmaxf(lv[q][0], fmaxf(lv[q][1], lv[q][2]));
;                             float w0 = __builtin_amdgcn_exp2f(lv[q][0] - mxl), w1 = __builtin_amdgcn_exp2f(lv[q][1] - mxl), w2 = __builtin_amdgcn_exp2f(lv[q][2] - mxl);
;                             const float inv = __builtin_amdgcn_rcpf(w0 + w1 + w2); w0 *= inv; w1 *= inv; w2 *= inv;
;                             const f32x4 y0 = bf4_lo(ow[q][0]) * w0 + bf4_lo(ow[q][1]) * w1 + bf4_lo(ow[q][2]) * w2, y1 = bf4_hi(ow[q][0]) * w0 + bf4_hi(ow[q][1]) * w1 + bf4_hi(ow[q][2]) * w2;
;                             *(u32x4*)(YC + (size_t)t * D + c8) = pack8(y0, y1); } }
.LBB0_615:
	v_max3_f32 v36, v63, v66, v69
	v_sub_f32_e32 v37, v63, v36
	v_sub_f32_e32 v38, v66, v36
	v_exp_f32_e32 v37, v37
	v_exp_f32_e32 v38, v38
	v_sub_f32_e32 v36, v69, v36
	v_exp_f32_e32 v39, v36
	v_lshlrev_b32_e32 v46, 16, v16
	v_add_f32_e32 v36, v37, v38
	v_and_b32_e32 v47, 0xffff0000, v16
	v_add_f32_e32 v36, v39, v36
	v_rcp_f32_e32 v40, v36
	v_lshlrev_b32_e32 v60, 16, v17
	v_and_b32_e32 v61, 0xffff0000, v17
	v_lshlrev_b32_e32 v42, 16, v4
	v_mul_f32_e32 v38, v38, v40
	v_mul_f32_e32 v36, v37, v40
	v_and_b32_e32 v43, 0xffff0000, v4
	v_lshlrev_b32_e32 v44, 16, v5
	v_and_b32_e32 v45, 0xffff0000, v5
	v_pk_mul_f32 v[60:61], v[38:39], v[60:61] op_sel_hi:[0,1]
	v_pk_mul_f32 v[46:47], v[38:39], v[46:47] op_sel_hi:[0,1]
	v_mul_f32_e32 v40, v39, v40
	v_pk_fma_f32 v[42:43], v[36:37], v[42:43], v[46:47] op_sel_hi:[0,1,1]
	v_pk_fma_f32 v[44:45], v[36:37], v[44:45], v[60:61] op_sel_hi:[0,1,1]
	v_lshlrev_b32_e32 v46, 16, v28
	v_and_b32_e32 v47, 0xffff0000, v28
	v_lshlrev_b32_e32 v60, 16, v29
	v_and_b32_e32 v61, 0xffff0000, v29
	v_lshlrev_b32_e32 v72, 16, v18
	v_and_b32_e32 v73, 0xffff0000, v18
	v_lshlrev_b32_e32 v74, 16, v19
	v_and_b32_e32 v75, 0xffff0000, v19
	v_pk_fma_f32 v[44:45], v[40:41], v[60:61], v[44:45] op_sel_hi:[0,1,1]
	v_pk_fma_f32 v[42:43], v[40:41], v[46:47], v[42:43] op_sel_hi:[0,1,1]
	v_lshlrev_b32_e32 v46, 16, v6
	v_and_b32_e32 v47, 0xffff0000, v6
	v_lshlrev_b32_e32 v60, 16, v7
	v_and_b32_e32 v61, 0xffff0000, v7
	v_pk_mul_f32 v[74:75], v[38:39], v[74:75] op_sel_hi:[0,1]
	v_pk_mul_f32 v[38:39], v[38:39], v[72:73] op_sel_hi:[0,1]
	v_pk_fma_f32 v[38:39], v[36:37], v[46:47], v[38:39] op_sel_hi:[0,1,1]
	v_pk_fma_f32 v[36:37], v[36:37], v[60:61], v[74:75] op_sel_hi:[0,1,1]
	v_lshlrev_b32_e32 v46, 16, v30
	v_and_b32_e32 v47, 0xffff0000, v30
	v_lshlrev_b32_e32 v60, 16, v31
	v_and_b32_e32 v61, 0xffff0000, v31
	v_ashrrev_i32_e32 v59, 31, v58
	v_pk_fma_f32 v[60:61], v[40:41], v[60:61], v[36:37] op_sel_hi:[0,1,1]
	v_pk_fma_f32 v[38:39], v[40:41], v[46:47], v[38:39] op_sel_hi:[0,1,1]
	v_lshlrev_b64 v[40:41], 11, v[58:59]
	v_lshl_add_u64 v[40:41], v[52:53], 0, v[40:41]
	v_cvt_pk_bf16_f32 v36, v42, v43
	v_cvt_pk_bf16_f32 v37, v44, v45
	v_cvt_pk_bf16_f32 v38, v38, v39
	v_cvt_pk_bf16_f32 v39, v60, v61
	global_store_dwordx4 v[40:41], v[36:39], off sc1
	s_or_b64 exec, exec, s[6:7]
	s_and_saveexec_b64 s[4:5], s[2:3]
	s_cbranch_execz .LBB0_604
.LBB0_616:
	v_max3_f32 v36, v62, v65, v68
	v_sub_f32_e32 v37, v62, v36
	v_sub_f32_e32 v38, v65, v36
	v_exp_f32_e32 v37, v37
	v_exp_f32_e32 v38, v38
	v_sub_f32_e32 v36, v68, v36
	v_exp_f32_e32 v39, v36
	v_lshlrev_b32_e32 v46, 16, v12
	v_add_f32_e32 v36, v37, v38
	v_and_b32_e32 v47, 0xffff0000, v12
	v_add_f32_e32 v36, v39, v36
	v_rcp_f32_e32 v40, v36
	v_lshlrev_b32_e32 v58, 16, v13
	v_and_b32_e32 v59, 0xffff0000, v13
	v_lshlrev_b32_e32 v42, 16, v0
	v_mul_f32_e32 v38, v38, v40
	v_mul_f32_e32 v36, v37, v40
	v_and_b32_e32 v43, 0xffff0000, v0
	v_lshlrev_b32_e32 v44, 16, v1
	v_and_b32_e32 v45, 0xffff0000, v1
	v_pk_mul_f32 v[58:59], v[38:39], v[58:59] op_sel_hi:[0,1]
	v_pk_mul_f32 v[46:47], v[38:39], v[46:47] op_sel_hi:[0,1]
	v_mul_f32_e32 v40, v39, v40
	v_pk_fma_f32 v[42:43], v[36:37], v[42:43], v[46:47] op_sel_hi:[0,1,1]
	v_pk_fma_f32 v[44:45], v[36:37], v[44:45], v[58:59] op_sel_hi:[0,1,1]
	v_lshlrev_b32_e32 v46, 16, v24
	v_and_b32_e32 v47, 0xffff0000, v24
	v_lshlrev_b32_e32 v58, 16, v25
	v_and_b32_e32 v59, 0xffff0000, v25
	v_lshlrev_b32_e32 v60, 16, v14
	v_and_b32_e32 v61, 0xffff0000, v14
	v_lshlrev_b32_e32 v72, 16, v15
	v_and_b32_e32 v73, 0xffff0000, v15
	v_pk_fma_f32 v[44:45], v[40:41], v[58:59], v[44:45] op_sel_hi:[0,1,1]
	v_pk_fma_f32 v[42:43], v[40:41], v[46:47], v[42:43] op_sel_hi:[0,1,1]
	v_lshlrev_b32_e32 v46, 16, v2
	v_and_b32_e32 v47, 0xffff0000, v2
	v_lshlrev_b32_e32 v58, 16, v3
	v_and_b32_e32 v59, 0xffff0000, v3
	v_pk_mul_f32 v[72:73], v[38:39], v[72:73] op_sel_hi:[0,1]
	v_pk_mul_f32 v[38:39], v[38:39], v[60:61] op_sel_hi:[0,1]
	v_pk_fma_f32 v[38:39], v[36:37], v[46:47], v[38:39] op_sel_hi:[0,1,1]
	v_pk_fma_f32 v[36:37], v[36:37], v[58:59], v[72:73] op_sel_hi:[0,1,1]
	v_lshlrev_b32_e32 v46, 16, v26
	v_and_b32_e32 v47, 0xffff0000, v26
	v_lshlrev_b32_e32 v58, 16, v27
	v_and_b32_e32 v59, 0xffff0000, v27
	v_ashrrev_i32_e32 v57, 31, v56
	v_pk_fma_f32 v[58:59], v[40:41], v[58:59], v[36:37] op_sel_hi:[0,1,1]
	v_pk_fma_f32 v[38:39], v[40:41], v[46:47], v[38:39] op_sel_hi:[0,1,1]
	v_lshlrev_b64 v[40:41], 11, v[56:57]
	v_lshl_add_u64 v[40:41], v[52:53], 0, v[40:41]
	v_cvt_pk_bf16_f32 v36, v42, v43
	v_cvt_pk_bf16_f32 v37, v44, v45
	v_cvt_pk_bf16_f32 v38, v38, v39
	v_cvt_pk_bf16_f32 v39, v58, v59
	global_store_dwordx4 v[40:41], v[36:39], off sc1
	s_branch .LBB0_604

; __device__ __forceinline__ f32x4 bf4_lo(const u32x4 w) { return (f32x4){bf_lo(w.x), bf_hi(w.x), bf_lo(w.y), bf_hi(w.y)}; }
; __device__ __forceinline__ f32x4 bf4_hi(const u32x4 w) { return (f32x4){bf_lo(w.z), bf_hi(w.z), bf_lo(w.w), bf_hi(w.w)}; }
; template <int L> __device__ __forceinline__ void layer_body(const Args& args, LAS unsigned char* lds, const int G, const int lo, const int hi, const int wave_s, unsigned& nbar) {
;     ...
;                         for (int q = 0; q < 4; ++q) { const int t = tb + q * tstride; if (t < T) {
;                             f32x4 y0 = {0.f, 0.f, 0.f, 0.f}, y1 = y0;
; #pragma unroll
;                             for (int j = 0; j < 3; ++j) { y0 += wt[j][0] * bf4_lo(uw[q][j]); y1 += wt[j][1] * bf4_hi(uw[q][j]); }
;                             y0 *= bf4_lo(gw_[q]); y1 *= bf4_hi(gw_[q]);
;                             *(u32x4*)(YC + (size_t)t * D + c8) = pack8(y0, y1); } }
.LBB0_644:
	s_or_b64 exec, exec, s[14:15]
	s_waitcnt vmcnt(2)
	v_lshlrev_b32_e32 v102, 16, v76
	v_and_b32_e32 v103, 0xffff0000, v76
	v_lshlrev_b32_e32 v76, 16, v77
	v_and_b32_e32 v77, 0xffff0000, v77
	v_pk_fma_f32 v[102:103], v[4:5], v[102:103], 0 op_sel_hi:[1,1,0]
	v_pk_fma_f32 v[76:77], v[6:7], v[76:77], 0 op_sel_hi:[1,1,0]
	v_lshlrev_b32_e32 v104, 16, v78
	v_and_b32_e32 v105, 0xffff0000, v78
	v_lshlrev_b32_e32 v78, 16, v79
	v_and_b32_e32 v79, 0xffff0000, v79
	v_lshlrev_b32_e32 v106, 16, v80
	v_and_b32_e32 v107, 0xffff0000, v80
	v_lshlrev_b32_e32 v80, 16, v81
	v_and_b32_e32 v81, 0xffff0000, v81
	v_pk_fma_f32 v[104:105], v[0:1], v[104:105], 0 op_sel_hi:[1,1,0]
	v_pk_fma_f32 v[78:79], v[2:3], v[78:79], 0 op_sel_hi:[1,1,0]
	v_pk_fma_f32 v[76:77], v[14:15], v[80:81], v[76:77]
	v_pk_fma_f32 v[80:81], v[12:13], v[106:107], v[102:103]
	v_lshlrev_b32_e32 v102, 16, v82
	v_and_b32_e32 v103, 0xffff0000, v82
	v_lshlrev_b32_e32 v82, 16, v83
	v_and_b32_e32 v83, 0xffff0000, v83
	v_pk_fma_f32 v[78:79], v[10:11], v[82:83], v[78:79]
	v_pk_fma_f32 v[82:83], v[8:9], v[102:103], v[104:105]
	s_waitcnt vmcnt(1)
	v_lshlrev_b32_e32 v102, 16, v84
	v_and_b32_e32 v103, 0xffff0000, v84
	v_lshlrev_b32_e32 v84, 16, v85
	v_and_b32_e32 v85, 0xffff0000, v85
	v_pk_fma_f32 v[76:77], v[18:19], v[84:85], v[76:77]
	v_lshlrev_b32_e32 v84, 16, v86
	v_and_b32_e32 v85, 0xffff0000, v86
	v_pk_fma_f32 v[80:81], v[16:17], v[102:103], v[80:81]
	v_pk_fma_f32 v[82:83], v[20:21], v[84:85], v[82:83]
	s_waitcnt vmcnt(0)
	v_lshlrev_b32_e32 v84, 16, v72
	v_and_b32_e32 v85, 0xffff0000, v72
	v_lshlrev_b32_e32 v72, 16, v73
	v_and_b32_e32 v73, 0xffff0000, v73
	v_lshlrev_b32_e32 v86, 16, v87
	v_and_b32_e32 v87, 0xffff0000, v87
	v_pk_mul_f32 v[76:77], v[76:77], v[72:73]
	v_pk_mul_f32 v[72:73], v[80:81], v[84:85]
	v_pk_fma_f32 v[78:79], v[22:23], v[86:87], v[78:79]
	v_lshlrev_b32_e32 v80, 16, v74
	v_and_b32_e32 v81, 0xffff0000, v74
	v_lshlrev_b32_e32 v74, 16, v75
	v_and_b32_e32 v75, 0xffff0000, v75
	v_cvt_pk_bf16_f32 v72, v72, v73
	v_cvt_pk_bf16_f32 v73, v76, v77
	v_lshlrev_b64 v[76:77], 11, v[96:97]
	v_pk_mul_f32 v[78:79], v[78:79], v[74:75]
	v_pk_mul_f32 v[74:75], v[82:83], v[80:81]
	v_lshl_add_u64 v[76:77], v[92:93], 0, v[76:77]
	v_cvt_pk_bf16_f32 v74, v74, v75
	v_cvt_pk_bf16_f32 v75, v78, v79
	global_store_dwordx4 v[76:77], v[72:75], off sc1
	s_and_saveexec_b64 s[6:7], vcc
	s_cbranch_execnz .LBB0_647
	s_or_b64 exec, exec, s[6:7]
	s_and_saveexec_b64 s[6:7], s[4:5]
	s_cbranch_execnz .LBB0_648

; __device__ __forceinline__ f32x4 bf4_lo(const u32x4 w) { return (f32x4){bf_lo(w.x), bf_hi(w.x), bf_lo(w.y), bf_hi(w.y)}; }
; __device__ __forceinline__ f32x4 bf4_hi(const u32x4 w) { return (f32x4){bf_lo(w.z), bf_hi(w.z), bf_lo(w.w), bf_hi(w.w)}; }
; template <int L> __device__ __forceinline__ void layer_body(const Args& args, LAS unsigned char* lds, const int G, const int lo, const int hi, const int wave_s, unsigned& nbar) {
;     ...
;                         for (int q = 0; q < 4; ++q) { const int t = tb + q * tstride; if (t < T) {
;                             f32x4 y0 = {0.f, 0.f, 0.f, 0.f}, y1 = y0;
; #pragma unroll
;                             for (int j = 0; j < 3; ++j) { y0 += wt[j][0] * bf4_lo(uw[q][j]); y1 += wt[j][1] * bf4_hi(uw[q][j]); }
;                             y0 *= bf4_lo(gw_[q]); y1 *= bf4_hi(gw_[q]);
;                             *(u32x4*)(YC + (size_t)t * D + c8) = pack8(y0, y1); } }
.LBB0_647:
	v_lshlrev_b32_e32 v72, 16, v44
	v_and_b32_e32 v73, 0xffff0000, v44
	v_lshlrev_b32_e32 v74, 16, v45
	v_and_b32_e32 v75, 0xffff0000, v45
	v_pk_fma_f32 v[72:73], v[4:5], v[72:73], 0 op_sel_hi:[1,1,0]
	v_lshlrev_b32_e32 v76, 16, v46
	v_and_b32_e32 v77, 0xffff0000, v46
	v_lshlrev_b32_e32 v80, 16, v40
	v_and_b32_e32 v81, 0xffff0000, v40
	v_pk_fma_f32 v[74:75], v[6:7], v[74:75], 0 op_sel_hi:[1,1,0]
	v_lshlrev_b32_e32 v78, 16, v47
	v_and_b32_e32 v79, 0xffff0000, v47
	v_pk_fma_f32 v[76:77], v[0:1], v[76:77], 0 op_sel_hi:[1,1,0]
	v_lshlrev_b32_e32 v82, 16, v41
	v_and_b32_e32 v83, 0xffff0000, v41
	v_pk_fma_f32 v[72:73], v[12:13], v[80:81], v[72:73]
	v_lshlrev_b32_e32 v80, 16, v42
	v_and_b32_e32 v81, 0xffff0000, v42
	v_pk_fma_f32 v[78:79], v[2:3], v[78:79], 0 op_sel_hi:[1,1,0]
	v_pk_fma_f32 v[74:75], v[14:15], v[82:83], v[74:75]
	v_lshlrev_b32_e32 v82, 16, v43
	v_and_b32_e32 v83, 0xffff0000, v43
	v_pk_fma_f32 v[76:77], v[8:9], v[80:81], v[76:77]
	v_lshlrev_b32_e32 v80, 16, v56
	v_and_b32_e32 v81, 0xffff0000, v56
	v_pk_fma_f32 v[78:79], v[10:11], v[82:83], v[78:79]
	v_lshlrev_b32_e32 v82, 16, v57
	v_and_b32_e32 v83, 0xffff0000, v57
	v_pk_fma_f32 v[72:73], v[16:17], v[80:81], v[72:73]
	v_lshlrev_b32_e32 v80, 16, v58
	v_and_b32_e32 v81, 0xffff0000, v58
	v_pk_fma_f32 v[74:75], v[18:19], v[82:83], v[74:75]
	v_lshlrev_b32_e32 v82, 16, v59
	v_and_b32_e32 v83, 0xffff0000, v59
	v_pk_fma_f32 v[76:77], v[20:21], v[80:81], v[76:77]
	v_lshlrev_b32_e32 v80, 16, v68
	v_and_b32_e32 v81, 0xffff0000, v68
	v_pk_fma_f32 v[78:79], v[22:23], v[82:83], v[78:79]
	v_lshlrev_b32_e32 v82, 16, v69
	v_and_b32_e32 v83, 0xffff0000, v69
	v_pk_mul_f32 v[72:73], v[72:73], v[80:81]
	v_lshlrev_b32_e32 v80, 16, v70
	v_and_b32_e32 v81, 0xffff0000, v70
	v_pk_mul_f32 v[74:75], v[74:75], v[82:83]
	v_pk_mul_f32 v[76:77], v[76:77], v[80:81]
	v_ashrrev_i32_e32 v95, 31, v94
	v_cvt_pk_bf16_f32 v72, v72, v73
	v_cvt_pk_bf16_f32 v73, v74, v75
	v_cvt_pk_bf16_f32 v74, v76, v77
	v_lshlrev_b64 v[76:77], 11, v[94:95]
	v_lshlrev_b32_e32 v82, 16, v71
	v_and_b32_e32 v83, 0xffff0000, v71
	v_lshl_add_u64 v[76:77], v[92:93], 0, v[76:77]
	v_pk_mul_f32 v[78:79], v[78:79], v[82:83]
	s_nop 0
	v_cvt_pk_bf16_f32 v75, v78, v79
	global_store_dwordx4 v[76:77], v[72:75], off sc1
	s_or_b64 exec, exec, s[6:7]
	s_and_saveexec_b64 s[6:7], s[4:5]
	s_cbranch_execz .LBB0_646
.LBB0_648:
	v_lshlrev_b32_e32 v72, 16, v36
	v_and_b32_e32 v73, 0xffff0000, v36
	v_lshlrev_b32_e32 v74, 16, v37
	v_and_b32_e32 v75, 0xffff0000, v37
	v_pk_fma_f32 v[72:73], v[4:5], v[72:73], 0 op_sel_hi:[1,1,0]
	v_lshlrev_b32_e32 v76, 16, v38
	v_and_b32_e32 v77, 0xffff0000, v38
	v_lshlrev_b32_e32 v80, 16, v32
	v_and_b32_e32 v81, 0xffff0000, v32
	v_pk_fma_f32 v[74:75], v[6:7], v[74:75], 0 op_sel_hi:[1,1,0]
	v_lshlrev_b32_e32 v78, 16, v39
	v_and_b32_e32 v79, 0xffff0000, v39
	v_pk_fma_f32 v[76:77], v[0:1], v[76:77], 0 op_sel_hi:[1,1,0]
	v_lshlrev_b32_e32 v82, 16, v33
	v_and_b32_e32 v83, 0xffff0000, v33
	v_pk_fma_f32 v[72:73], v[12:13], v[80:81], v[72:73]
	v_lshlrev_b32_e32 v80, 16, v34
	v_and_b32_e32 v81, 0xffff0000, v34
	v_pk_fma_f32 v[78:79], v[2:3], v[78:79], 0 op_sel_hi:[1,1,0]
	v_pk_fma_f32 v[74:75], v[14:15], v[82:83], v[74:75]
	v_lshlrev_b32_e32 v82, 16, v35
	v_and_b32_e32 v83, 0xffff0000, v35
	v_pk_fma_f32 v[76:77], v[8:9], v[80:81], v[76:77]
	v_lshlrev_b32_e32 v80, 16, v52
	v_and_b32_e32 v81, 0xffff0000, v52
	v_pk_fma_f32 v[78:79], v[10:11], v[82:83], v[78:79]
	v_lshlrev_b32_e32 v82, 16, v53
	v_and_b32_e32 v83, 0xffff0000, v53
	v_pk_fma_f32 v[72:73], v[16:17], v[80:81], v[72:73]
	v_lshlrev_b32_e32 v80, 16, v54
	v_and_b32_e32 v81, 0xffff0000, v54
	v_pk_fma_f32 v[74:75], v[18:19], v[82:83], v[74:75]
	v_lshlrev_b32_e32 v82, 16, v55
	v_and_b32_e32 v83, 0xffff0000, v55
	v_pk_fma_f32 v[76:77], v[20:21], v[80:81], v[76:77]
	v_lshlrev_b32_e32 v80, 16, v64
	v_and_b32_e32 v81, 0xffff0000, v64
	v_pk_fma_f32 v[78:79], v[22:23], v[82:83], v[78:79]
	v_lshlrev_b32_e32 v82, 16, v65
	v_and_b32_e32 v83, 0xffff0000, v65
	v_pk_mul_f32 v[72:73], v[72:73], v[80:81]
	v_lshlrev_b32_e32 v80, 16, v66
	v_and_b32_e32 v81, 0xffff0000, v66
	v_pk_mul_f32 v[74:75], v[74:75], v[82:83]
	v_pk_mul_f32 v[76:77], v[76:77], v[80:81]
	v_ashrrev_i32_e32 v101, 31, v100
	v_cvt_pk_bf16_f32 v72, v72, v73
	v_cvt_pk_bf16_f32 v73, v74, v75
	v_cvt_pk_bf16_f32 v74, v76, v77
	v_lshlrev_b64 v[76:77], 11, v[100:101]
	v_lshlrev_b32_e32 v82, 16, v67
	v_and_b32_e32 v83, 0xffff0000, v67
	v_lshl_add_u64 v[76:77], v[92:93], 0, v[76:77]
	v_pk_mul_f32 v[78:79], v[78:79], v[82:83]
	s_nop 0
	v_cvt_pk_bf16_f32 v75, v78, v79
	global_store_dwordx4 v[76:77], v[72:75], off sc1
	s_or_b64 exec, exec, s[6:7]
	s_and_saveexec_b64 s[4:5], s[2:3]
	s_cbranch_execz .LBB0_621
.LBB0_649:
	v_lshlrev_b32_e32 v72, 16, v28
	v_and_b32_e32 v73, 0xffff0000, v28
	v_lshlrev_b32_e32 v74, 16, v29
	v_and_b32_e32 v75, 0xffff0000, v29
	v_pk_fma_f32 v[72:73], v[4:5], v[72:73], 0 op_sel_hi:[1,1,0]
	v_lshlrev_b32_e32 v76, 16, v30
	v_and_b32_e32 v77, 0xffff0000, v30
	v_lshlrev_b32_e32 v80, 16, v24
	v_and_b32_e32 v81, 0xffff0000, v24
	v_pk_fma_f32 v[74:75], v[6:7], v[74:75], 0 op_sel_hi:[1,1,0]
	v_lshlrev_b32_e32 v78, 16, v31
	v_and_b32_e32 v79, 0xffff0000, v31
	v_pk_fma_f32 v[76:77], v[0:1], v[76:77], 0 op_sel_hi:[1,1,0]
	v_lshlrev_b32_e32 v82, 16, v25
	v_and_b32_e32 v83, 0xffff0000, v25
	v_pk_fma_f32 v[72:73], v[12:13], v[80:81], v[72:73]
	v_lshlrev_b32_e32 v80, 16, v26
	v_and_b32_e32 v81, 0xffff0000, v26
	v_pk_fma_f32 v[78:79], v[2:3], v[78:79], 0 op_sel_hi:[1,1,0]
	v_pk_fma_f32 v[74:75], v[14:15], v[82:83], v[74:75]
	v_lshlrev_b32_e32 v82, 16, v27
	v_and_b32_e32 v83, 0xffff0000, v27
	v_pk_fma_f32 v[76:77], v[8:9], v[80:81], v[76:77]
	v_lshlrev_b32_e32 v80, 16, v48
	v_and_b32_e32 v81, 0xffff0000, v48
	v_pk_fma_f32 v[78:79], v[10:11], v[82:83], v[78:79]
	v_lshlrev_b32_e32 v82, 16, v49
	v_and_b32_e32 v83, 0xffff0000, v49
	v_pk_fma_f32 v[72:73], v[16:17], v[80:81], v[72:73]
	v_lshlrev_b32_e32 v80, 16, v50
	v_and_b32_e32 v81, 0xffff0000, v50
	v_pk_fma_f32 v[74:75], v[18:19], v[82:83], v[74:75]
	v_lshlrev_b32_e32 v82, 16, v51
	v_and_b32_e32 v83, 0xffff0000, v51
	v_pk_fma_f32 v[76:77], v[20:21], v[80:81], v[76:77]
	v_lshlrev_b32_e32 v80, 16, v60
	v_and_b32_e32 v81, 0xffff0000, v60
	v_pk_fma_f32 v[78:79], v[22:23], v[82:83], v[78:79]
	v_lshlrev_b32_e32 v82, 16, v61
	v_and_b32_e32 v83, 0xffff0000, v61
	v_pk_mul_f32 v[72:73], v[72:73], v[80:81]
	v_lshlrev_b32_e32 v80, 16, v62
	v_and_b32_e32 v81, 0xffff0000, v62
	v_pk_mul_f32 v[74:75], v[74:75], v[82:83]
	v_pk_mul_f32 v[76:77], v[76:77], v[80:81]
	v_ashrrev_i32_e32 v99, 31, v98
	v_cvt_pk_bf16_f32 v72, v72, v73
	v_cvt_pk_bf16_f32 v73, v74, v75
	v_cvt_pk_bf16_f32 v74, v76, v77
	v_lshlrev_b64 v[76:77], 11, v[98:99]
	v_lshlrev_b32_e32 v82, 16, v63
	v_and_b32_e32 v83, 0xffff0000, v63
	v_lshl_add_u64 v[76:77], v[92:93], 0, v[76:77]
	v_pk_mul_f32 v[78:79], v[78:79], v[82:83]
	s_nop 0
	v_cvt_pk_bf16_f32 v75, v78, v79
	global_store_dwordx4 v[76:77], v[72:75], off sc1
	s_branch .LBB0_621

; __device__ __forceinline__ float fast_sigmoid(float x) { return __builtin_amdgcn_rcpf(1.0f + __builtin_amdgcn_exp2f(-x * LOG2E)); }
; #define ROW_RS(u, ai, m) row_rs_lds((ai) * 128 + wr * 64 + (m) * 16 + fr, fq)
; #define ROWLOOP for (int ai = 0; ai < 2; ++ai) _Pragma("unroll") for (int m = 0; m < 4; ++m)
;     __device__ __forceinline__ void operator()(const Acc& acc, const Unit& u, int wr, int wc, int fr, int fq) const {
;         const bool isx = u.pn < 4; bf16_t* o = isx ? XB : GY; const int ct = (u.pn & 3) * 256;
; #pragma unroll
;         ROWLOOP { const int row = ROW_OF(u, ai, m); const float rs = ROW_RS(u, ai, m);
; #pragma unroll
;             for (int bj = 0; bj < 2; ++bj) {
;                 f32x4 v0 = acc[ai][bj][m][0] * rs, v1 = acc[ai][bj][m][1] * rs;
;                 if (!isx) {
; #pragma unroll
;                     for (int e = 0; e < 4; ++e) { float x = v0[e]; v0[e] = x * fast_sigmoid(1.5957691216f * (x + 0.044715f * x * x * x)); x = v1[e]; v1[e] = x * fast_sigmoid(1.5957691216f * (x + 0.044715f * x * x * x)); }
;                 }
;                 *(u32x4*)(o + (size_t)row * D + ct + bj * 128 + wc * 32 + fq * 8) = pack8(v0, v1);
;             } }
.LBB0_1319:
	s_and_b64 s[30:31], exec, s[30:31]
	s_cselect_b32 s5, s54, 0x19100000
	s_add_u32 s5, s6, s5
	s_addc_u32 s19, s7, 0
	v_lshl_add_u32 v120, s4, 8, v156
	s_lshl_b32 s4, s26, 9
	s_and_b32 s4, s4, 0x600
	s_add_u32 s4, s5, s4
	s_addc_u32 s5, s19, 0
	s_add_u32 s4, s4, s55
	s_addc_u32 s5, s5, 0
	v_ashrrev_i32_e32 v121, 31, v120
	v_mov_b32_e32 v149, v148
	v_lshl_add_u64 v[122:123], s[4:5], 0, v[136:137]
	v_lshlrev_b64 v[124:125], 11, v[120:121]
	v_cvt_pk_bf16_f32 v152, v152, v153
	v_cvt_pk_bf16_f32 v153, v126, v127
	v_mov_b32_e32 v126, v148
	v_mov_b32_e32 v127, v148
	v_cndmask_b32_e64 v121, 0, 1, s[28:29]
	v_lshl_add_u64 v[124:125], v[122:123], 0, v[124:125]
	v_pk_mul_f32 v[118:119], v[118:119], v[126:127]
	v_pk_mul_f32 v[116:117], v[116:117], v[148:149]
	v_pk_mul_f32 v[114:115], v[114:115], v[126:127]
	v_cmp_ne_u32_e64 s[4:5], 1, v121
	s_andn2_b64 vcc, exec, s[28:29]
	v_pk_mul_f32 v[112:113], v[112:113], v[148:149]
	v_cvt_pk_bf16_f32 v154, v154, v155
	v_cvt_pk_bf16_f32 v155, v150, v151
	global_store_dwordx4 v[124:125], v[152:155], off sc1
	s_cbranch_vccnz .LBB0_1321
	v_mul_f32_e32 v126, 0x3d372713, v112
	v_mul_f32_e32 v126, v112, v126
	v_fma_f32 v126, v112, v126, v112
	v_mul_f32_e32 v121, 0x3d372713, v116
	v_mul_f32_e32 v126, 0x3fcc422a, v126
	v_mul_f32_e32 v121, v116, v121
	v_mul_f32_e32 v126, 0xbfb8aa3b, v126
	v_fma_f32 v121, v116, v121, v116
	v_exp_f32_e32 v127, v126
	v_mul_f32_e32 v126, 0x3d372713, v117
	v_mul_f32_e32 v121, 0x3fcc422a, v121
	v_mul_f32_e32 v126, v117, v126
	v_mov_b32_e32 v148, v117
	v_mul_f32_e32 v121, 0xbfb8aa3b, v121
	v_fmac_f32_e32 v148, v148, v126
	v_exp_f32_e32 v121, v121
	v_mul_f32_e32 v126, 0x3fcc422a, v148
	v_mul_f32_e32 v126, 0xbfb8aa3b, v126
	v_exp_f32_e32 v149, v126
	v_add_f32_e32 v121, 1.0, v121
	v_rcp_f32_e32 v126, v121
	v_add_f32_e32 v121, 1.0, v127
	v_rcp_f32_e32 v148, v121
	v_add_f32_e32 v121, 1.0, v149
	v_rcp_f32_e32 v127, v121
	v_mul_f32_e32 v121, 0x3d372713, v113
	v_mul_f32_e32 v121, v113, v121
	v_mov_b32_e32 v149, v113
	v_fmac_f32_e32 v149, v149, v121
	v_mul_f32_e32 v121, 0x3fcc422a, v149
	v_mul_f32_e32 v149, 0x3d372713, v118
	v_mul_f32_e32 v149, v118, v149
	v_mul_f32_e32 v150, 0x3d372713, v114
	v_fma_f32 v149, v118, v149, v118
	v_mul_f32_e32 v150, v114, v150
	v_mul_f32_e32 v149, 0x3fcc422a, v149
	v_fma_f32 v150, v114, v150, v114
	v_mul_f32_e32 v149, 0xbfb8aa3b, v149
	v_mul_f32_e32 v150, 0x3fcc422a, v150
	v_exp_f32_e32 v149, v149
	v_mul_f32_e32 v150, 0xbfb8aa3b, v150
	v_exp_f32_e32 v151, v150
	v_mul_f32_e32 v152, 0x3d372713, v115
	v_add_f32_e32 v149, 1.0, v149
	v_rcp_f32_e32 v150, v149
	v_add_f32_e32 v149, 1.0, v151
	v_mul_f32_e32 v151, 0x3d372713, v119
	v_mul_f32_e32 v151, v119, v151
	v_fma_f32 v151, v119, v151, v119
	v_mul_f32_e32 v152, v115, v152
	v_mul_f32_e32 v151, 0x3fcc422a, v151
	v_fma_f32 v152, v115, v152, v115
	v_mul_f32_e32 v151, 0xbfb8aa3b, v151
	v_mul_f32_e32 v152, 0x3fcc422a, v152
	v_mul_f32_e32 v121, 0xbfb8aa3b, v121
	v_exp_f32_e32 v151, v151
	v_mul_f32_e32 v152, 0xbfb8aa3b, v152
	v_exp_f32_e32 v121, v121
	v_exp_f32_e32 v153, v152
	v_rcp_f32_e32 v152, v149
	v_add_f32_e32 v149, 1.0, v151
	v_add_f32_e32 v121, 1.0, v121
	v_rcp_f32_e32 v151, v149
	v_add_f32_e32 v149, 1.0, v153
	v_rcp_f32_e32 v153, v149
	v_rcp_f32_e32 v149, v121
	v_pk_mul_f32 v[118:119], v[118:119], v[150:151]
	v_pk_mul_f32 v[116:117], v[116:117], v[126:127]
	v_pk_mul_f32 v[114:115], v[114:115], v[152:153]
	v_pk_mul_f32 v[112:113], v[112:113], v[148:149]
.LBB0_1321:
	v_cvt_pk_bf16_f32 v116, v116, v117
	v_cvt_pk_bf16_f32 v117, v118, v119
	s_nop 0
	v_cvt_pk_bf16_f32 v118, v112, v113
	v_cvt_pk_bf16_f32 v119, v114, v115
	ds_read_b128 v[112:115], v160 offset:1024
	s_and_b64 vcc, exec, s[4:5]
	global_store_dwordx4 v[124:125], v[116:119], off offset:256 sc1
	s_waitcnt lgkmcnt(0)
	v_add_f32_e32 v112, v112, v113
	v_add_f32_e32 v113, v114, v115
	v_add_f32_e32 v112, v112, v113
	v_mov_b32_e32 v113, v112
	s_nop 1
	v_permlane16_swap_b32_e32 v112, v113
	v_add_f32_e32 v112, v112, v113
	v_mov_b32_e32 v113, v112
	s_nop 1
	v_permlane32_swap_b32_e32 v112, v113
	v_add_f32_e32 v112, v112, v113
	v_fmamk_f32 v112, v112, 0x3a800000, v159
	v_rsq_f32_e32 v112, v112
	s_nop 0
	v_pk_mul_f32 v[110:111], v[110:111], v[112:113] op_sel_hi:[1,0]
	v_pk_mul_f32 v[108:109], v[108:109], v[112:113] op_sel_hi:[1,0]
	v_pk_mul_f32 v[106:107], v[106:107], v[112:113] op_sel_hi:[1,0]
	v_pk_mul_f32 v[114:115], v[104:105], v[112:113] op_sel_hi:[1,0]
	s_cbranch_vccnz .LBB0_1323
	v_mul_f32_e32 v105, 0x3d372713, v114
	v_mul_f32_e32 v105, v114, v105
	v_mul_f32_e32 v113, 0x3d372713, v109
	v_fma_f32 v105, v114, v105, v114
	v_mul_f32_e32 v113, v109, v113
	v_mov_b32_e32 v116, v109
	v_mul_f32_e32 v105, 0x3fcc422a, v105
	v_fmac_f32_e32 v116, v116, v113
	v_mul_f32_e32 v105, 0xbfb8aa3b, v105
	v_mul_f32_e32 v113, 0x3fcc422a, v116
	v_exp_f32_e32 v105, v105
	v_mul_f32_e32 v113, 0xbfb8aa3b, v113
	v_exp_f32_e32 v113, v113
	v_mov_b32_e32 v117, v115
	v_add_f32_e32 v105, 1.0, v105
	v_rcp_f32_e32 v116, v105
	v_add_f32_e32 v105, 1.0, v113
	v_mul_f32_e32 v113, 0x3d372713, v115
	v_mul_f32_e32 v113, v115, v113
	v_fmac_f32_e32 v117, v117, v113
	v_mul_f32_e32 v113, 0x3fcc422a, v117
	v_mul_f32_e32 v117, 0x3d372713, v110
	v_mul_f32_e32 v117, v110, v117
	v_mul_f32_e32 v118, 0x3d372713, v106
	v_fma_f32 v117, v110, v117, v110
	v_mul_f32_e32 v118, v106, v118
	v_mul_f32_e32 v117, 0x3fcc422a, v117
	v_fma_f32 v118, v106, v118, v106
	v_mul_f32_e32 v117, 0xbfb8aa3b, v117
	v_mul_f32_e32 v118, 0x3fcc422a, v118
	v_exp_f32_e32 v117, v117
	v_mul_f32_e32 v118, 0xbfb8aa3b, v118
	v_exp_f32_e32 v119, v118
	v_mul_f32_e32 v104, 0x3d372713, v108
	v_add_f32_e32 v117, 1.0, v117
	v_rcp_f32_e32 v118, v117
	v_add_f32_e32 v117, 1.0, v119
	v_mul_f32_e32 v119, 0x3d372713, v111
	v_mul_f32_e32 v119, v111, v119
	v_mul_f32_e32 v121, 0x3d372713, v107
	v_mul_f32_e32 v104, v108, v104
	v_fma_f32 v119, v111, v119, v111
	v_mul_f32_e32 v121, v107, v121
	v_fma_f32 v104, v108, v104, v108
	v_mul_f32_e32 v119, 0x3fcc422a, v119
	v_fma_f32 v121, v107, v121, v107
	v_mul_f32_e32 v104, 0x3fcc422a, v104
	v_mul_f32_e32 v119, 0xbfb8aa3b, v119
	v_mul_f32_e32 v121, 0x3fcc422a, v121
	v_mul_f32_e32 v104, 0xbfb8aa3b, v104
	v_mul_f32_e32 v113, 0xbfb8aa3b, v113
	v_exp_f32_e32 v119, v119
	v_mul_f32_e32 v121, 0xbfb8aa3b, v121
	v_exp_f32_e32 v104, v104
	v_exp_f32_e32 v113, v113
	v_exp_f32_e32 v121, v121
	v_rcp_f32_e32 v124, v117
	v_add_f32_e32 v117, 1.0, v119
	v_add_f32_e32 v104, 1.0, v104
	v_add_f32_e32 v113, 1.0, v113
	v_rcp_f32_e32 v119, v117
	v_add_f32_e32 v117, 1.0, v121
	v_rcp_f32_e32 v104, v104
	v_rcp_f32_e32 v105, v105
	v_rcp_f32_e32 v125, v117
	v_rcp_f32_e32 v117, v113
	v_pk_mul_f32 v[110:111], v[110:111], v[118:119]
	v_pk_mul_f32 v[108:109], v[108:109], v[104:105]
	v_pk_mul_f32 v[106:107], v[106:107], v[124:125]
	v_pk_mul_f32 v[114:115], v[114:115], v[116:117]
; __device__ __forceinline__ float fast_sigmoid(float x) { return __builtin_amdgcn_rcpf(1.0f + __builtin_amdgcn_exp2f(-x * LOG2E)); }
; #define ROW_RS(u, ai, m) row_rs_lds((ai) * 128 + wr * 64 + (m) * 16 + fr, fq)
; #define ROWLOOP for (int ai = 0; ai < 2; ++ai) _Pragma("unroll") for (int m = 0; m < 4; ++m)
;     __device__ __forceinline__ void operator()(const Acc& acc, const Unit& u, int wr, int wc, int fr, int fq) const {
;     ...
;         ROWLOOP { const int row = ROW_OF(u, ai, m); const float rs = ROW_RS(u, ai, m);
; #pragma unroll
;             for (int bj = 0; bj < 2; ++bj) {
;                 f32x4 v0 = acc[ai][bj][m][0] * rs, v1 = acc[ai][bj][m][1] * rs;
;                 if (!isx) {
; #pragma unroll
;                     for (int e = 0; e < 4; ++e) { float x = v0[e]; v0[e] = x * fast_sigmoid(1.5957691216f * (x + 0.044715f * x * x * x)); x = v1[e]; v1[e] = x * fast_sigmoid(1.5957691216f * (x + 0.044715f * x * x * x)); }
;                 }
;                 *(u32x4*)(o + (size_t)row * D + ct + bj * 128 + wc * 32 + fq * 8) = pack8(v0, v1);
;             } }
.LBB0_1323:
	v_or_b32_e32 v104, 16, v120
	v_ashrrev_i32_e32 v105, 31, v104
	v_mov_b32_e32 v113, v112
	v_lshlrev_b64 v[104:105], 11, v[104:105]
	v_cvt_pk_bf16_f32 v108, v108, v109
	v_cvt_pk_bf16_f32 v109, v110, v111
	v_cvt_pk_bf16_f32 v110, v114, v115
	v_cvt_pk_bf16_f32 v111, v106, v107
	v_mov_b32_e32 v106, v112
	v_mov_b32_e32 v107, v112
	v_lshl_add_u64 v[104:105], v[122:123], 0, v[104:105]
	v_pk_mul_f32 v[102:103], v[102:103], v[106:107]
	v_pk_mul_f32 v[100:101], v[100:101], v[112:113]
	v_pk_mul_f32 v[98:99], v[98:99], v[106:107]
	s_and_b64 vcc, exec, s[4:5]
	v_pk_mul_f32 v[96:97], v[96:97], v[112:113]
	global_store_dwordx4 v[104:105], v[108:111], off sc1
	s_cbranch_vccnz .LBB0_1325
	v_mul_f32_e32 v107, 0x3d372713, v96
	v_mul_f32_e32 v107, v96, v107
	v_mul_f32_e32 v108, 0x3d372713, v101
	v_fma_f32 v107, v96, v107, v96
	v_mul_f32_e32 v108, v101, v108
	v_mov_b32_e32 v109, v101
	v_mul_f32_e32 v107, 0x3fcc422a, v107
	v_fmac_f32_e32 v109, v109, v108
	v_mul_f32_e32 v107, 0xbfb8aa3b, v107
	v_mul_f32_e32 v108, 0x3fcc422a, v109
	v_exp_f32_e32 v107, v107
	v_mul_f32_e32 v108, 0xbfb8aa3b, v108
	v_exp_f32_e32 v109, v108
	v_mul_f32_e32 v112, 0x3d372713, v103
	v_add_f32_e32 v107, 1.0, v107
	v_mul_f32_e32 v112, v103, v112
	v_rcp_f32_e32 v108, v107
	v_add_f32_e32 v107, 1.0, v109
	v_mul_f32_e32 v109, 0x3d372713, v97
	v_fma_f32 v112, v103, v112, v103
	v_mul_f32_e32 v109, v97, v109
	v_mov_b32_e32 v110, v97
	v_mul_f32_e32 v112, 0x3fcc422a, v112
	v_fmac_f32_e32 v110, v110, v109
	v_mul_f32_e32 v111, 0x3d372713, v98
	v_mul_f32_e32 v112, 0xbfb8aa3b, v112
	v_mul_f32_e32 v106, 0x3d372713, v100
	v_mul_f32_e32 v109, 0x3fcc422a, v110
	v_mul_f32_e32 v110, 0x3d372713, v102
	v_mul_f32_e32 v111, v98, v111
	v_exp_f32_e32 v113, v112
	v_mul_f32_e32 v112, 0x3d372713, v99
	v_mul_f32_e32 v106, v100, v106
	v_mul_f32_e32 v110, v102, v110
	v_fma_f32 v111, v98, v111, v98
	v_mul_f32_e32 v112, v99, v112
	v_fma_f32 v106, v100, v106, v100
	v_fma_f32 v110, v102, v110, v102
	v_mul_f32_e32 v111, 0x3fcc422a, v111
	v_fma_f32 v112, v99, v112, v99
	v_mul_f32_e32 v106, 0x3fcc422a, v106
	v_mul_f32_e32 v110, 0x3fcc422a, v110
	v_mul_f32_e32 v111, 0xbfb8aa3b, v111
	v_mul_f32_e32 v112, 0x3fcc422a, v112
	v_mul_f32_e32 v106, 0xbfb8aa3b, v106
	v_mul_f32_e32 v109, 0xbfb8aa3b, v109
	v_mul_f32_e32 v110, 0xbfb8aa3b, v110
	v_exp_f32_e32 v111, v111
	v_mul_f32_e32 v112, 0xbfb8aa3b, v112
	v_exp_f32_e32 v106, v106
	v_exp_f32_e32 v109, v109
	v_exp_f32_e32 v110, v110
	v_exp_f32_e32 v114, v112
	v_add_f32_e32 v111, 1.0, v111
	v_add_f32_e32 v106, 1.0, v106
	v_add_f32_e32 v109, 1.0, v109
	v_add_f32_e32 v110, 1.0, v110
	v_rcp_f32_e32 v112, v111
	v_add_f32_e32 v111, 1.0, v113
	v_add_f32_e32 v113, 1.0, v114
	v_rcp_f32_e32 v106, v106
	v_rcp_f32_e32 v107, v107
	v_rcp_f32_e32 v110, v110
	v_rcp_f32_e32 v111, v111
	v_rcp_f32_e32 v113, v113
	v_rcp_f32_e32 v109, v109
	v_pk_mul_f32 v[100:101], v[100:101], v[106:107]
	v_pk_mul_f32 v[102:103], v[102:103], v[110:111]
	v_pk_mul_f32 v[98:99], v[98:99], v[112:113]
	v_pk_mul_f32 v[96:97], v[96:97], v[108:109]
.LBB0_1325:
	v_cvt_pk_bf16_f32 v100, v100, v101
	v_cvt_pk_bf16_f32 v101, v102, v103
	s_nop 0
	v_cvt_pk_bf16_f32 v102, v96, v97
	v_cvt_pk_bf16_f32 v103, v98, v99
	ds_read_b128 v[96:99], v160 offset:2048
	s_and_b64 vcc, exec, s[4:5]
	global_store_dwordx4 v[104:105], v[100:103], off offset:256 sc1
	s_waitcnt lgkmcnt(0)
	v_add_f32_e32 v96, v96, v97
	v_add_f32_e32 v97, v98, v99
	v_add_f32_e32 v96, v96, v97
	v_mov_b32_e32 v97, v96
	s_nop 1
	v_permlane16_swap_b32_e32 v96, v97
	v_add_f32_e32 v96, v96, v97
	v_mov_b32_e32 v97, v96
	s_nop 1
	v_permlane32_swap_b32_e32 v96, v97
	v_add_f32_e32 v96, v96, v97
	v_fmamk_f32 v96, v96, 0x3a800000, v159
	v_rsq_f32_e32 v96, v96
	s_nop 0
	v_pk_mul_f32 v[94:95], v[94:95], v[96:97] op_sel_hi:[1,0]
	v_pk_mul_f32 v[92:93], v[92:93], v[96:97] op_sel_hi:[1,0]
	v_pk_mul_f32 v[90:91], v[90:91], v[96:97] op_sel_hi:[1,0]
	v_pk_mul_f32 v[98:99], v[88:89], v[96:97] op_sel_hi:[1,0]
	s_cbranch_vccnz .LBB0_1327
	v_mul_f32_e32 v89, 0x3d372713, v98
	v_mul_f32_e32 v89, v98, v89
	v_mul_f32_e32 v97, 0x3d372713, v93
	v_fma_f32 v89, v98, v89, v98
	v_mul_f32_e32 v97, v93, v97
	v_mov_b32_e32 v100, v93
	v_mul_f32_e32 v89, 0x3fcc422a, v89
	v_fmac_f32_e32 v100, v100, v97
	v_mul_f32_e32 v89, 0xbfb8aa3b, v89
	v_mul_f32_e32 v97, 0x3fcc422a, v100
	v_exp_f32_e32 v89, v89
	v_mul_f32_e32 v97, 0xbfb8aa3b, v97
	v_exp_f32_e32 v97, v97
	v_mov_b32_e32 v101, v99
	v_add_f32_e32 v89, 1.0, v89
	v_rcp_f32_e32 v100, v89
	v_add_f32_e32 v89, 1.0, v97
	v_mul_f32_e32 v97, 0x3d372713, v99
	v_mul_f32_e32 v97, v99, v97
	v_fmac_f32_e32 v101, v101, v97
	v_mul_f32_e32 v97, 0x3fcc422a, v101
	v_mul_f32_e32 v101, 0x3d372713, v94
	v_mul_f32_e32 v101, v94, v101
	v_mul_f32_e32 v102, 0x3d372713, v90
	v_fma_f32 v101, v94, v101, v94
	v_mul_f32_e32 v102, v90, v102
	v_mul_f32_e32 v101, 0x3fcc422a, v101
	v_fma_f32 v102, v90, v102, v90
	v_mul_f32_e32 v101, 0xbfb8aa3b, v101
	v_mul_f32_e32 v102, 0x3fcc422a, v102
	v_exp_f32_e32 v101, v101
	v_mul_f32_e32 v102, 0xbfb8aa3b, v102
	v_exp_f32_e32 v103, v102
	v_mul_f32_e32 v88, 0x3d372713, v92
	v_add_f32_e32 v101, 1.0, v101
	v_rcp_f32_e32 v102, v101
	v_add_f32_e32 v101, 1.0, v103
	v_mul_f32_e32 v103, 0x3d372713, v95
	v_mul_f32_e32 v103, v95, v103
	v_mul_f32_e32 v104, 0x3d372713, v91
	v_mul_f32_e32 v88, v92, v88
	v_fma_f32 v103, v95, v103, v95
	v_mul_f32_e32 v104, v91, v104
	v_fma_f32 v88, v92, v88, v92
	v_mul_f32_e32 v103, 0x3fcc422a, v103
	v_fma_f32 v104, v91, v104, v91
	v_mul_f32_e32 v88, 0x3fcc422a, v88
	v_mul_f32_e32 v103, 0xbfb8aa3b, v103
	v_mul_f32_e32 v104, 0x3fcc422a, v104
	v_mul_f32_e32 v88, 0xbfb8aa3b, v88
	v_mul_f32_e32 v97, 0xbfb8aa3b, v97
	v_exp_f32_e32 v103, v103
	v_mul_f32_e32 v104, 0xbfb8aa3b, v104
	v_exp_f32_e32 v88, v88
	v_exp_f32_e32 v97, v97
	v_exp_f32_e32 v105, v104
	v_rcp_f32_e32 v104, v101
	v_add_f32_e32 v101, 1.0, v103
	v_add_f32_e32 v88, 1.0, v88
	v_add_f32_e32 v97, 1.0, v97
	v_rcp_f32_e32 v103, v101
	v_add_f32_e32 v101, 1.0, v105
	v_rcp_f32_e32 v88, v88
	v_rcp_f32_e32 v89, v89
	v_rcp_f32_e32 v105, v101
	v_rcp_f32_e32 v101, v97
	v_pk_mul_f32 v[94:95], v[94:95], v[102:103]
	v_pk_mul_f32 v[92:93], v[92:93], v[88:89]
	v_pk_mul_f32 v[90:91], v[90:91], v[104:105]
	v_pk_mul_f32 v[98:99], v[98:99], v[100:101]
; #define LAS __attribute__((address_space(3)))
; __device__ __forceinline__ float fast_sigmoid(float x) { return __builtin_amdgcn_rcpf(1.0f + __builtin_amdgcn_exp2f(-x * LOG2E)); }
; #define ROW_RS(u, ai, m) row_rs_lds((ai) * 128 + wr * 64 + (m) * 16 + fr, fq)
; #define ROWLOOP for (int ai = 0; ai < 2; ++ai) _Pragma("unroll") for (int m = 0; m < 4; ++m)
; __device__ __forceinline__ float row_rs_lds(int rt, int fq) {
;     ...
;     const f32x4 v = *(const LAS f32x4*)((LAS unsigned char*)lds_raw_ + RS_OFF + rt * 64 + fq * 16);
;     float s = (v[0] + v[1]) + (v[2] + v[3]);
;     s = red4_sum(s);
;     return __builtin_amdgcn_rsqf(s * (1.0f / D) + EPS);
;     __device__ __forceinline__ void operator()(const Acc& acc, const Unit& u, int wr, int wc, int fr, int fq) const {
;     ...
;         ROWLOOP { const int row = ROW_OF(u, ai, m); const float rs = ROW_RS(u, ai, m);
; #pragma unroll
;             for (int bj = 0; bj < 2; ++bj) {
;                 f32x4 v0 = acc[ai][bj][m][0] * rs, v1 = acc[ai][bj][m][1] * rs;
;                 if (!isx) {
; #pragma unroll
;                     for (int e = 0; e < 4; ++e) { float x = v0[e]; v0[e] = x * fast_sigmoid(1.5957691216f * (x + 0.044715f * x * x * x)); x = v1[e]; v1[e] = x * fast_sigmoid(1.5957691216f * (x + 0.044715f * x * x * x)); }
;                 }
;                 *(u32x4*)(o + (size_t)row * D + ct + bj * 128 + wc * 32 + fq * 8) = pack8(v0, v1);
.LBB0_1327:
	v_or_b32_e32 v88, 32, v120
	v_ashrrev_i32_e32 v89, 31, v88
	v_mov_b32_e32 v97, v96
	v_lshlrev_b64 v[88:89], 11, v[88:89]
	v_cvt_pk_bf16_f32 v92, v92, v93
	v_cvt_pk_bf16_f32 v93, v94, v95
	v_cvt_pk_bf16_f32 v94, v98, v99
	v_cvt_pk_bf16_f32 v95, v90, v91
	v_mov_b32_e32 v90, v96
	v_mov_b32_e32 v91, v96
	v_lshl_add_u64 v[88:89], v[122:123], 0, v[88:89]
	v_pk_mul_f32 v[86:87], v[86:87], v[90:91]
	v_pk_mul_f32 v[84:85], v[84:85], v[96:97]
	v_pk_mul_f32 v[82:83], v[82:83], v[90:91]
	s_and_b64 vcc, exec, s[4:5]
	v_pk_mul_f32 v[80:81], v[80:81], v[96:97]
	global_store_dwordx4 v[88:89], v[92:95], off sc1
	s_cbranch_vccnz .LBB0_1329
	v_mul_f32_e32 v91, 0x3d372713, v80
	v_mul_f32_e32 v91, v80, v91
	v_mul_f32_e32 v92, 0x3d372713, v85
	v_fma_f32 v91, v80, v91, v80
	v_mul_f32_e32 v92, v85, v92
	v_mov_b32_e32 v93, v85
	v_mul_f32_e32 v91, 0x3fcc422a, v91
	v_fmac_f32_e32 v93, v93, v92
	v_mul_f32_e32 v91, 0xbfb8aa3b, v91
	v_mul_f32_e32 v92, 0x3fcc422a, v93
	v_exp_f32_e32 v91, v91
	v_mul_f32_e32 v92, 0xbfb8aa3b, v92
	v_exp_f32_e32 v93, v92
	v_mul_f32_e32 v96, 0x3d372713, v87
	v_add_f32_e32 v91, 1.0, v91
	v_mul_f32_e32 v96, v87, v96
	v_rcp_f32_e32 v92, v91
	v_add_f32_e32 v91, 1.0, v93
	v_mul_f32_e32 v93, 0x3d372713, v81
	v_fma_f32 v96, v87, v96, v87
	v_mul_f32_e32 v93, v81, v93
	v_mov_b32_e32 v94, v81
	v_mul_f32_e32 v96, 0x3fcc422a, v96
	v_fmac_f32_e32 v94, v94, v93
	v_mul_f32_e32 v95, 0x3d372713, v82
	v_mul_f32_e32 v96, 0xbfb8aa3b, v96
	v_mul_f32_e32 v90, 0x3d372713, v84
	v_mul_f32_e32 v93, 0x3fcc422a, v94
	v_mul_f32_e32 v94, 0x3d372713, v86
	v_mul_f32_e32 v95, v82, v95
	v_exp_f32_e32 v97, v96
	v_mul_f32_e32 v96, 0x3d372713, v83
	v_mul_f32_e32 v90, v84, v90
	v_mul_f32_e32 v94, v86, v94
	v_fma_f32 v95, v82, v95, v82
	v_mul_f32_e32 v96, v83, v96
	v_fma_f32 v90, v84, v90, v84
	v_fma_f32 v94, v86, v94, v86
	v_mul_f32_e32 v95, 0x3fcc422a, v95
	v_fma_f32 v96, v83, v96, v83
	v_mul_f32_e32 v90, 0x3fcc422a, v90
	v_mul_f32_e32 v94, 0x3fcc422a, v94
	v_mul_f32_e32 v95, 0xbfb8aa3b, v95
	v_mul_f32_e32 v96, 0x3fcc422a, v96
	v_mul_f32_e32 v90, 0xbfb8aa3b, v90
	v_mul_f32_e32 v93, 0xbfb8aa3b, v93
	v_mul_f32_e32 v94, 0xbfb8aa3b, v94
	v_exp_f32_e32 v95, v95
	v_mul_f32_e32 v96, 0xbfb8aa3b, v96
	v_exp_f32_e32 v90, v90
	v_exp_f32_e32 v93, v93
	v_exp_f32_e32 v94, v94
	v_exp_f32_e32 v98, v96
	v_add_f32_e32 v95, 1.0, v95
	v_add_f32_e32 v90, 1.0, v90
	v_add_f32_e32 v93, 1.0, v93
	v_add_f32_e32 v94, 1.0, v94
	v_rcp_f32_e32 v96, v95
	v_add_f32_e32 v95, 1.0, v97
	v_add_f32_e32 v97, 1.0, v98
	v_rcp_f32_e32 v90, v90
	v_rcp_f32_e32 v91, v91
	v_rcp_f32_e32 v94, v94
	v_rcp_f32_e32 v95, v95
	v_rcp_f32_e32 v97, v97
	v_rcp_f32_e32 v93, v93
	v_pk_mul_f32 v[84:85], v[84:85], v[90:91]
	v_pk_mul_f32 v[86:87], v[86:87], v[94:95]
	v_pk_mul_f32 v[82:83], v[82:83], v[96:97]
	v_pk_mul_f32 v[80:81], v[80:81], v[92:93]
.LBB0_1329:
	v_cvt_pk_bf16_f32 v84, v84, v85
	v_cvt_pk_bf16_f32 v85, v86, v87
	s_nop 0
	v_cvt_pk_bf16_f32 v86, v80, v81
	v_cvt_pk_bf16_f32 v87, v82, v83
	ds_read_b128 v[80:83], v160 offset:3072
	s_and_b64 vcc, exec, s[4:5]
	global_store_dwordx4 v[88:89], v[84:87], off offset:256 sc1
	s_waitcnt lgkmcnt(0)
	v_add_f32_e32 v80, v80, v81
	v_add_f32_e32 v81, v82, v83
	v_add_f32_e32 v80, v80, v81
	v_mov_b32_e32 v81, v80
	s_nop 1
	v_permlane16_swap_b32_e32 v80, v81
	v_add_f32_e32 v80, v80, v81
	v_mov_b32_e32 v81, v80
	s_nop 1
	v_permlane32_swap_b32_e32 v80, v81
	v_add_f32_e32 v80, v80, v81
	v_fmamk_f32 v80, v80, 0x3a800000, v159
	v_rsq_f32_e32 v80, v80
	s_nop 0
	v_pk_mul_f32 v[78:79], v[78:79], v[80:81] op_sel_hi:[1,0]
	v_pk_mul_f32 v[76:77], v[76:77], v[80:81] op_sel_hi:[1,0]
	v_pk_mul_f32 v[74:75], v[74:75], v[80:81] op_sel_hi:[1,0]
	v_pk_mul_f32 v[82:83], v[72:73], v[80:81] op_sel_hi:[1,0]
	s_cbranch_vccnz .LBB0_1331
	v_mul_f32_e32 v73, 0x3d372713, v82
	v_mul_f32_e32 v73, v82, v73
	v_mul_f32_e32 v81, 0x3d372713, v77
	v_fma_f32 v73, v82, v73, v82
	v_mul_f32_e32 v81, v77, v81
	v_mov_b32_e32 v84, v77
	v_mul_f32_e32 v73, 0x3fcc422a, v73
	v_fmac_f32_e32 v84, v84, v81
	v_mul_f32_e32 v73, 0xbfb8aa3b, v73
	v_mul_f32_e32 v81, 0x3fcc422a, v84
	v_exp_f32_e32 v73, v73
	v_mul_f32_e32 v81, 0xbfb8aa3b, v81
	v_exp_f32_e32 v81, v81
	v_mov_b32_e32 v85, v83
	v_add_f32_e32 v73, 1.0, v73
	v_rcp_f32_e32 v84, v73
	v_add_f32_e32 v73, 1.0, v81
	v_mul_f32_e32 v81, 0x3d372713, v83
	v_mul_f32_e32 v81, v83, v81
	v_fmac_f32_e32 v85, v85, v81
	v_mul_f32_e32 v81, 0x3fcc422a, v85
	v_mul_f32_e32 v85, 0x3d372713, v78
	v_mul_f32_e32 v85, v78, v85
	v_mul_f32_e32 v86, 0x3d372713, v74
	v_fma_f32 v85, v78, v85, v78
	v_mul_f32_e32 v86, v74, v86
	v_mul_f32_e32 v85, 0x3fcc422a, v85
	v_fma_f32 v86, v74, v86, v74
	v_mul_f32_e32 v85, 0xbfb8aa3b, v85
	v_mul_f32_e32 v86, 0x3fcc422a, v86
	v_exp_f32_e32 v85, v85
	v_mul_f32_e32 v86, 0xbfb8aa3b, v86
	v_exp_f32_e32 v87, v86
	v_mul_f32_e32 v72, 0x3d372713, v76
	v_add_f32_e32 v85, 1.0, v85
	v_rcp_f32_e32 v86, v85
	v_add_f32_e32 v85, 1.0, v87
	v_mul_f32_e32 v87, 0x3d372713, v79
	v_mul_f32_e32 v87, v79, v87
	v_mul_f32_e32 v88, 0x3d372713, v75
	v_mul_f32_e32 v72, v76, v72
	v_fma_f32 v87, v79, v87, v79
	v_mul_f32_e32 v88, v75, v88
	v_fma_f32 v72, v76, v72, v76
	v_mul_f32_e32 v87, 0x3fcc422a, v87
	v_fma_f32 v88, v75, v88, v75
	v_mul_f32_e32 v72, 0x3fcc422a, v72
	v_mul_f32_e32 v87, 0xbfb8aa3b, v87
	v_mul_f32_e32 v88, 0x3fcc422a, v88
	v_mul_f32_e32 v72, 0xbfb8aa3b, v72
	v_mul_f32_e32 v81, 0xbfb8aa3b, v81
	v_exp_f32_e32 v87, v87
	v_mul_f32_e32 v88, 0xbfb8aa3b, v88
	v_exp_f32_e32 v72, v72
	v_exp_f32_e32 v81, v81
	v_exp_f32_e32 v89, v88
	v_rcp_f32_e32 v88, v85
	v_add_f32_e32 v85, 1.0, v87
	v_add_f32_e32 v72, 1.0, v72
	v_add_f32_e32 v81, 1.0, v81
	v_rcp_f32_e32 v87, v85
	v_add_f32_e32 v85, 1.0, v89
	v_rcp_f32_e32 v72, v72
	v_rcp_f32_e32 v73, v73
	v_rcp_f32_e32 v89, v85
	v_rcp_f32_e32 v85, v81
	v_pk_mul_f32 v[78:79], v[78:79], v[86:87]
	v_pk_mul_f32 v[76:77], v[76:77], v[72:73]
	v_pk_mul_f32 v[74:75], v[74:75], v[88:89]
	v_pk_mul_f32 v[82:83], v[82:83], v[84:85]
; #define LAS __attribute__((address_space(3)))
; __device__ __forceinline__ float fast_sigmoid(float x) { return __builtin_amdgcn_rcpf(1.0f + __builtin_amdgcn_exp2f(-x * LOG2E)); }
; #define ROW_RS(u, ai, m) row_rs_lds((ai) * 128 + wr * 64 + (m) * 16 + fr, fq)
; #define ROWLOOP for (int ai = 0; ai < 2; ++ai) _Pragma("unroll") for (int m = 0; m < 4; ++m)
; __device__ __forceinline__ float row_rs_lds(int rt, int fq) {
;     ...
;     const f32x4 v = *(const LAS f32x4*)((LAS unsigned char*)lds_raw_ + RS_OFF + rt * 64 + fq * 16);
;     float s = (v[0] + v[1]) + (v[2] + v[3]);
;     s = red4_sum(s);
;     return __builtin_amdgcn_rsqf(s * (1.0f / D) + EPS);
;     __device__ __forceinline__ void operator()(const Acc& acc, const Unit& u, int wr, int wc, int fr, int fq) const {
;     ...
;         ROWLOOP { const int row = ROW_OF(u, ai, m); const float rs = ROW_RS(u, ai, m);
; #pragma unroll
;             for (int bj = 0; bj < 2; ++bj) {
;                 f32x4 v0 = acc[ai][bj][m][0] * rs, v1 = acc[ai][bj][m][1] * rs;
;                 if (!isx) {
; #pragma unroll
;                     for (int e = 0; e < 4; ++e) { float x = v0[e]; v0[e] = x * fast_sigmoid(1.5957691216f * (x + 0.044715f * x * x * x)); x = v1[e]; v1[e] = x * fast_sigmoid(1.5957691216f * (x + 0.044715f * x * x * x)); }
;                 }
;                 *(u32x4*)(o + (size_t)row * D + ct + bj * 128 + wc * 32 + fq * 8) = pack8(v0, v1);
.LBB0_1331:
	v_or_b32_e32 v72, 48, v120
	v_ashrrev_i32_e32 v73, 31, v72
	v_mov_b32_e32 v81, v80
	v_lshlrev_b64 v[72:73], 11, v[72:73]
	v_cvt_pk_bf16_f32 v76, v76, v77
	v_cvt_pk_bf16_f32 v77, v78, v79
	v_cvt_pk_bf16_f32 v78, v82, v83
	v_cvt_pk_bf16_f32 v79, v74, v75
	v_mov_b32_e32 v74, v80
	v_mov_b32_e32 v75, v80
	v_lshl_add_u64 v[72:73], v[122:123], 0, v[72:73]
	v_pk_mul_f32 v[70:71], v[70:71], v[74:75]
	v_pk_mul_f32 v[68:69], v[68:69], v[80:81]
	v_pk_mul_f32 v[66:67], v[66:67], v[74:75]
	s_and_b64 vcc, exec, s[4:5]
	v_pk_mul_f32 v[64:65], v[64:65], v[80:81]
	global_store_dwordx4 v[72:73], v[76:79], off sc1
	s_cbranch_vccnz .LBB0_1333
	v_mul_f32_e32 v75, 0x3d372713, v64
	v_mul_f32_e32 v75, v64, v75
	v_mul_f32_e32 v76, 0x3d372713, v69
	v_fma_f32 v75, v64, v75, v64
	v_mul_f32_e32 v76, v69, v76
	v_mov_b32_e32 v77, v69
	v_mul_f32_e32 v75, 0x3fcc422a, v75
	v_fmac_f32_e32 v77, v77, v76
	v_mul_f32_e32 v75, 0xbfb8aa3b, v75
	v_mul_f32_e32 v76, 0x3fcc422a, v77
	v_exp_f32_e32 v75, v75
	v_mul_f32_e32 v76, 0xbfb8aa3b, v76
	v_exp_f32_e32 v77, v76
	v_mul_f32_e32 v80, 0x3d372713, v71
	v_add_f32_e32 v75, 1.0, v75
	v_mul_f32_e32 v80, v71, v80
	v_rcp_f32_e32 v76, v75
	v_add_f32_e32 v75, 1.0, v77
	v_mul_f32_e32 v77, 0x3d372713, v65
	v_fma_f32 v80, v71, v80, v71
	v_mul_f32_e32 v77, v65, v77
	v_mov_b32_e32 v78, v65
	v_mul_f32_e32 v80, 0x3fcc422a, v80
	v_fmac_f32_e32 v78, v78, v77
	v_mul_f32_e32 v79, 0x3d372713, v66
	v_mul_f32_e32 v80, 0xbfb8aa3b, v80
	v_mul_f32_e32 v74, 0x3d372713, v68
	v_mul_f32_e32 v77, 0x3fcc422a, v78
	v_mul_f32_e32 v78, 0x3d372713, v70
	v_mul_f32_e32 v79, v66, v79
	v_exp_f32_e32 v81, v80
	v_mul_f32_e32 v80, 0x3d372713, v67
	v_mul_f32_e32 v74, v68, v74
	v_mul_f32_e32 v78, v70, v78
	v_fma_f32 v79, v66, v79, v66
	v_mul_f32_e32 v80, v67, v80
	v_fma_f32 v74, v68, v74, v68
	v_fma_f32 v78, v70, v78, v70
	v_mul_f32_e32 v79, 0x3fcc422a, v79
	v_fma_f32 v80, v67, v80, v67
	v_mul_f32_e32 v74, 0x3fcc422a, v74
	v_mul_f32_e32 v78, 0x3fcc422a, v78
	v_mul_f32_e32 v79, 0xbfb8aa3b, v79
	v_mul_f32_e32 v80, 0x3fcc422a, v80
	v_mul_f32_e32 v74, 0xbfb8aa3b, v74
	v_mul_f32_e32 v77, 0xbfb8aa3b, v77
	v_mul_f32_e32 v78, 0xbfb8aa3b, v78
	v_exp_f32_e32 v79, v79
	v_mul_f32_e32 v80, 0xbfb8aa3b, v80
	v_exp_f32_e32 v74, v74
	v_exp_f32_e32 v77, v77
	v_exp_f32_e32 v78, v78
	v_exp_f32_e32 v82, v80
	v_add_f32_e32 v79, 1.0, v79
	v_add_f32_e32 v74, 1.0, v74
	v_add_f32_e32 v77, 1.0, v77
	v_add_f32_e32 v78, 1.0, v78
	v_rcp_f32_e32 v80, v79
	v_add_f32_e32 v79, 1.0, v81
	v_add_f32_e32 v81, 1.0, v82
	v_rcp_f32_e32 v74, v74
	v_rcp_f32_e32 v75, v75
	v_rcp_f32_e32 v78, v78
	v_rcp_f32_e32 v79, v79
	v_rcp_f32_e32 v81, v81
	v_rcp_f32_e32 v77, v77
	v_pk_mul_f32 v[68:69], v[68:69], v[74:75]
	v_pk_mul_f32 v[70:71], v[70:71], v[78:79]
	v_pk_mul_f32 v[66:67], v[66:67], v[80:81]
	v_pk_mul_f32 v[64:65], v[64:65], v[76:77]
.LBB0_1333:
	v_cvt_pk_bf16_f32 v68, v68, v69
	v_cvt_pk_bf16_f32 v69, v70, v71
	s_nop 0
	v_cvt_pk_bf16_f32 v70, v64, v65
	v_cvt_pk_bf16_f32 v71, v66, v67
	ds_read_b128 v[64:67], v160 offset:8192
	s_and_b64 vcc, exec, s[4:5]
	global_store_dwordx4 v[72:73], v[68:71], off offset:256 sc1
	s_waitcnt lgkmcnt(0)
	v_add_f32_e32 v64, v64, v65
	v_add_f32_e32 v65, v66, v67
	v_add_f32_e32 v64, v64, v65
	v_mov_b32_e32 v65, v64
	s_nop 1
	v_permlane16_swap_b32_e32 v64, v65
	v_add_f32_e32 v64, v64, v65
	v_mov_b32_e32 v65, v64
	s_nop 1
	v_permlane32_swap_b32_e32 v64, v65
	v_add_f32_e32 v64, v64, v65
	v_fmamk_f32 v64, v64, 0x3a800000, v159
	v_rsq_f32_e32 v64, v64
	s_nop 0
	v_pk_mul_f32 v[62:63], v[62:63], v[64:65] op_sel_hi:[1,0]
	v_pk_mul_f32 v[60:61], v[60:61], v[64:65] op_sel_hi:[1,0]
	v_pk_mul_f32 v[58:59], v[58:59], v[64:65] op_sel_hi:[1,0]
	v_pk_mul_f32 v[66:67], v[56:57], v[64:65] op_sel_hi:[1,0]
	s_cbranch_vccnz .LBB0_1335
	v_mul_f32_e32 v57, 0x3d372713, v66
	v_mul_f32_e32 v57, v66, v57
	v_mul_f32_e32 v65, 0x3d372713, v61
	v_fma_f32 v57, v66, v57, v66
	v_mul_f32_e32 v65, v61, v65
	v_mov_b32_e32 v68, v61
	v_mul_f32_e32 v57, 0x3fcc422a, v57
	v_fmac_f32_e32 v68, v68, v65
	v_mul_f32_e32 v57, 0xbfb8aa3b, v57
	v_mul_f32_e32 v65, 0x3fcc422a, v68
	v_exp_f32_e32 v57, v57
	v_mul_f32_e32 v65, 0xbfb8aa3b, v65
	v_exp_f32_e32 v65, v65
	v_mov_b32_e32 v69, v67
	v_add_f32_e32 v57, 1.0, v57
	v_rcp_f32_e32 v68, v57
	v_add_f32_e32 v57, 1.0, v65
	v_mul_f32_e32 v65, 0x3d372713, v67
	v_mul_f32_e32 v65, v67, v65
	v_fmac_f32_e32 v69, v69, v65
	v_mul_f32_e32 v65, 0x3fcc422a, v69
	v_mul_f32_e32 v69, 0x3d372713, v62
	v_mul_f32_e32 v69, v62, v69
	v_mul_f32_e32 v70, 0x3d372713, v58
	v_fma_f32 v69, v62, v69, v62
	v_mul_f32_e32 v70, v58, v70
	v_mul_f32_e32 v69, 0x3fcc422a, v69
	v_fma_f32 v70, v58, v70, v58
	v_mul_f32_e32 v69, 0xbfb8aa3b, v69
	v_mul_f32_e32 v70, 0x3fcc422a, v70
	v_exp_f32_e32 v69, v69
	v_mul_f32_e32 v70, 0xbfb8aa3b, v70
	v_exp_f32_e32 v71, v70
	v_mul_f32_e32 v56, 0x3d372713, v60
	v_add_f32_e32 v69, 1.0, v69
	v_rcp_f32_e32 v70, v69
	v_add_f32_e32 v69, 1.0, v71
	v_mul_f32_e32 v71, 0x3d372713, v63
	v_mul_f32_e32 v71, v63, v71
	v_mul_f32_e32 v72, 0x3d372713, v59
	v_mul_f32_e32 v56, v60, v56
	v_fma_f32 v71, v63, v71, v63
	v_mul_f32_e32 v72, v59, v72
	v_fma_f32 v56, v60, v56, v60
	v_mul_f32_e32 v71, 0x3fcc422a, v71
	v_fma_f32 v72, v59, v72, v59
	v_mul_f32_e32 v56, 0x3fcc422a, v56
	v_mul_f32_e32 v71, 0xbfb8aa3b, v71
	v_mul_f32_e32 v72, 0x3fcc422a, v72
	v_mul_f32_e32 v56, 0xbfb8aa3b, v56
	v_mul_f32_e32 v65, 0xbfb8aa3b, v65
	v_exp_f32_e32 v71, v71
	v_mul_f32_e32 v72, 0xbfb8aa3b, v72
	v_exp_f32_e32 v56, v56
	v_exp_f32_e32 v65, v65
	v_exp_f32_e32 v73, v72
	v_rcp_f32_e32 v72, v69
	v_add_f32_e32 v69, 1.0, v71
	v_add_f32_e32 v56, 1.0, v56
	v_add_f32_e32 v65, 1.0, v65
	v_rcp_f32_e32 v71, v69
	v_add_f32_e32 v69, 1.0, v73
	v_rcp_f32_e32 v56, v56
	v_rcp_f32_e32 v57, v57
	v_rcp_f32_e32 v73, v69
	v_rcp_f32_e32 v69, v65
	v_pk_mul_f32 v[62:63], v[62:63], v[70:71]
	v_pk_mul_f32 v[60:61], v[60:61], v[56:57]
	v_pk_mul_f32 v[58:59], v[58:59], v[72:73]
	v_pk_mul_f32 v[66:67], v[66:67], v[68:69]
; #define LAS __attribute__((address_space(3)))
; __device__ __forceinline__ float fast_sigmoid(float x) { return __builtin_amdgcn_rcpf(1.0f + __builtin_amdgcn_exp2f(-x * LOG2E)); }
; #define ROW_RS(u, ai, m) row_rs_lds((ai) * 128 + wr * 64 + (m) * 16 + fr, fq)
; #define ROWLOOP for (int ai = 0; ai < 2; ++ai) _Pragma("unroll") for (int m = 0; m < 4; ++m)
; __device__ __forceinline__ float row_rs_lds(int rt, int fq) {
;     ...
;     const f32x4 v = *(const LAS f32x4*)((LAS unsigned char*)lds_raw_ + RS_OFF + rt * 64 + fq * 16);
;     float s = (v[0] + v[1]) + (v[2] + v[3]);
;     s = red4_sum(s);
;     return __builtin_amdgcn_rsqf(s * (1.0f / D) + EPS);
;     __device__ __forceinline__ void operator()(const Acc& acc, const Unit& u, int wr, int wc, int fr, int fq) const {
;     ...
;         ROWLOOP { const int row = ROW_OF(u, ai, m); const float rs = ROW_RS(u, ai, m);
; #pragma unroll
;             for (int bj = 0; bj < 2; ++bj) {
;                 f32x4 v0 = acc[ai][bj][m][0] * rs, v1 = acc[ai][bj][m][1] * rs;
;                 if (!isx) {
; #pragma unroll
;                     for (int e = 0; e < 4; ++e) { float x = v0[e]; v0[e] = x * fast_sigmoid(1.5957691216f * (x + 0.044715f * x * x * x)); x = v1[e]; v1[e] = x * fast_sigmoid(1.5957691216f * (x + 0.044715f * x * x * x)); }
;                 }
;                 *(u32x4*)(o + (size_t)row * D + ct + bj * 128 + wc * 32 + fq * 8) = pack8(v0, v1);
.LBB0_1335:
	v_add_u32_e32 v56, 0x80, v120
	v_ashrrev_i32_e32 v57, 31, v56
	v_mov_b32_e32 v65, v64
	v_lshlrev_b64 v[56:57], 11, v[56:57]
	v_cvt_pk_bf16_f32 v60, v60, v61
	v_cvt_pk_bf16_f32 v61, v62, v63
	v_cvt_pk_bf16_f32 v62, v66, v67
	v_cvt_pk_bf16_f32 v63, v58, v59
	v_mov_b32_e32 v58, v64
	v_mov_b32_e32 v59, v64
	v_lshl_add_u64 v[56:57], v[122:123], 0, v[56:57]
	v_pk_mul_f32 v[54:55], v[54:55], v[58:59]
	v_pk_mul_f32 v[52:53], v[52:53], v[64:65]
	v_pk_mul_f32 v[50:51], v[50:51], v[58:59]
	s_and_b64 vcc, exec, s[4:5]
	v_pk_mul_f32 v[48:49], v[48:49], v[64:65]
	global_store_dwordx4 v[56:57], v[60:63], off sc1
	s_cbranch_vccnz .LBB0_1337
	v_mul_f32_e32 v59, 0x3d372713, v48
	v_mul_f32_e32 v59, v48, v59
	v_mul_f32_e32 v60, 0x3d372713, v53
	v_fma_f32 v59, v48, v59, v48
	v_mul_f32_e32 v60, v53, v60
	v_mov_b32_e32 v61, v53
	v_mul_f32_e32 v59, 0x3fcc422a, v59
	v_fmac_f32_e32 v61, v61, v60
	v_mul_f32_e32 v59, 0xbfb8aa3b, v59
	v_mul_f32_e32 v60, 0x3fcc422a, v61
	v_exp_f32_e32 v59, v59
	v_mul_f32_e32 v60, 0xbfb8aa3b, v60
	v_exp_f32_e32 v61, v60
	v_mul_f32_e32 v64, 0x3d372713, v55
	v_add_f32_e32 v59, 1.0, v59
	v_mul_f32_e32 v64, v55, v64
	v_rcp_f32_e32 v60, v59
	v_add_f32_e32 v59, 1.0, v61
	v_mul_f32_e32 v61, 0x3d372713, v49
	v_fma_f32 v64, v55, v64, v55
	v_mul_f32_e32 v61, v49, v61
	v_mov_b32_e32 v62, v49
	v_mul_f32_e32 v64, 0x3fcc422a, v64
	v_fmac_f32_e32 v62, v62, v61
	v_mul_f32_e32 v63, 0x3d372713, v50
	v_mul_f32_e32 v64, 0xbfb8aa3b, v64
	v_mul_f32_e32 v58, 0x3d372713, v52
	v_mul_f32_e32 v61, 0x3fcc422a, v62
	v_mul_f32_e32 v62, 0x3d372713, v54
	v_mul_f32_e32 v63, v50, v63
	v_exp_f32_e32 v65, v64
	v_mul_f32_e32 v64, 0x3d372713, v51
	v_mul_f32_e32 v58, v52, v58
	v_mul_f32_e32 v62, v54, v62
	v_fma_f32 v63, v50, v63, v50
	v_mul_f32_e32 v64, v51, v64
	v_fma_f32 v58, v52, v58, v52
	v_fma_f32 v62, v54, v62, v54
	v_mul_f32_e32 v63, 0x3fcc422a, v63
	v_fma_f32 v64, v51, v64, v51
	v_mul_f32_e32 v58, 0x3fcc422a, v58
	v_mul_f32_e32 v62, 0x3fcc422a, v62
	v_mul_f32_e32 v63, 0xbfb8aa3b, v63
	v_mul_f32_e32 v64, 0x3fcc422a, v64
	v_mul_f32_e32 v58, 0xbfb8aa3b, v58
	v_mul_f32_e32 v61, 0xbfb8aa3b, v61
	v_mul_f32_e32 v62, 0xbfb8aa3b, v62
	v_exp_f32_e32 v63, v63
	v_mul_f32_e32 v64, 0xbfb8aa3b, v64
	v_exp_f32_e32 v58, v58
	v_exp_f32_e32 v61, v61
	v_exp_f32_e32 v62, v62
	v_exp_f32_e32 v66, v64
	v_add_f32_e32 v63, 1.0, v63
	v_add_f32_e32 v58, 1.0, v58
	v_add_f32_e32 v61, 1.0, v61
	v_add_f32_e32 v62, 1.0, v62
	v_rcp_f32_e32 v64, v63
	v_add_f32_e32 v63, 1.0, v65
	v_add_f32_e32 v65, 1.0, v66
	v_rcp_f32_e32 v58, v58
	v_rcp_f32_e32 v59, v59
	v_rcp_f32_e32 v62, v62
	v_rcp_f32_e32 v63, v63
	v_rcp_f32_e32 v65, v65
	v_rcp_f32_e32 v61, v61
	v_pk_mul_f32 v[52:53], v[52:53], v[58:59]
	v_pk_mul_f32 v[54:55], v[54:55], v[62:63]
	v_pk_mul_f32 v[50:51], v[50:51], v[64:65]
	v_pk_mul_f32 v[48:49], v[48:49], v[60:61]
.LBB0_1337:
	v_cvt_pk_bf16_f32 v52, v52, v53
	v_cvt_pk_bf16_f32 v53, v54, v55
	s_nop 0
	v_cvt_pk_bf16_f32 v54, v48, v49
	v_cvt_pk_bf16_f32 v55, v50, v51
	ds_read_b128 v[48:51], v160 offset:9216
	s_and_b64 vcc, exec, s[4:5]
	global_store_dwordx4 v[56:57], v[52:55], off offset:256 sc1
	s_waitcnt lgkmcnt(0)
	v_add_f32_e32 v48, v48, v49
	v_add_f32_e32 v49, v50, v51
	v_add_f32_e32 v48, v48, v49
	v_mov_b32_e32 v49, v48
	s_nop 1
	v_permlane16_swap_b32_e32 v48, v49
	v_add_f32_e32 v48, v48, v49
	v_mov_b32_e32 v49, v48
	s_nop 1
	v_permlane32_swap_b32_e32 v48, v49
	v_add_f32_e32 v48, v48, v49
	v_fmamk_f32 v48, v48, 0x3a800000, v159
	v_rsq_f32_e32 v48, v48
	s_nop 0
	v_pk_mul_f32 v[46:47], v[46:47], v[48:49] op_sel_hi:[1,0]
	v_pk_mul_f32 v[44:45], v[44:45], v[48:49] op_sel_hi:[1,0]
	v_pk_mul_f32 v[42:43], v[42:43], v[48:49] op_sel_hi:[1,0]
	v_pk_mul_f32 v[50:51], v[40:41], v[48:49] op_sel_hi:[1,0]
	s_cbranch_vccnz .LBB0_1339
	v_mul_f32_e32 v41, 0x3d372713, v50
	v_mul_f32_e32 v41, v50, v41
	v_mul_f32_e32 v49, 0x3d372713, v45
	v_fma_f32 v41, v50, v41, v50
	v_mul_f32_e32 v49, v45, v49
	v_mov_b32_e32 v52, v45
	v_mul_f32_e32 v41, 0x3fcc422a, v41
	v_fmac_f32_e32 v52, v52, v49
	v_mul_f32_e32 v41, 0xbfb8aa3b, v41
	v_mul_f32_e32 v49, 0x3fcc422a, v52
	v_exp_f32_e32 v41, v41
	v_mul_f32_e32 v49, 0xbfb8aa3b, v49
	v_exp_f32_e32 v49, v49
	v_mov_b32_e32 v53, v51
	v_add_f32_e32 v41, 1.0, v41
	v_rcp_f32_e32 v52, v41
	v_add_f32_e32 v41, 1.0, v49
	v_mul_f32_e32 v49, 0x3d372713, v51
	v_mul_f32_e32 v49, v51, v49
	v_fmac_f32_e32 v53, v53, v49
	v_mul_f32_e32 v49, 0x3fcc422a, v53
	v_mul_f32_e32 v53, 0x3d372713, v46
	v_mul_f32_e32 v53, v46, v53
	v_mul_f32_e32 v54, 0x3d372713, v42
	v_fma_f32 v53, v46, v53, v46
	v_mul_f32_e32 v54, v42, v54
	v_mul_f32_e32 v53, 0x3fcc422a, v53
	v_fma_f32 v54, v42, v54, v42
	v_mul_f32_e32 v53, 0xbfb8aa3b, v53
	v_mul_f32_e32 v54, 0x3fcc422a, v54
	v_exp_f32_e32 v53, v53
	v_mul_f32_e32 v54, 0xbfb8aa3b, v54
	v_exp_f32_e32 v55, v54
	v_mul_f32_e32 v40, 0x3d372713, v44
	v_add_f32_e32 v53, 1.0, v53
	v_rcp_f32_e32 v54, v53
	v_add_f32_e32 v53, 1.0, v55
	v_mul_f32_e32 v55, 0x3d372713, v47
	v_mul_f32_e32 v55, v47, v55
	v_mul_f32_e32 v56, 0x3d372713, v43
	v_mul_f32_e32 v40, v44, v40
	v_fma_f32 v55, v47, v55, v47
	v_mul_f32_e32 v56, v43, v56
	v_fma_f32 v40, v44, v40, v44
	v_mul_f32_e32 v55, 0x3fcc422a, v55
	v_fma_f32 v56, v43, v56, v43
	v_mul_f32_e32 v40, 0x3fcc422a, v40
	v_mul_f32_e32 v55, 0xbfb8aa3b, v55
	v_mul_f32_e32 v56, 0x3fcc422a, v56
	v_mul_f32_e32 v40, 0xbfb8aa3b, v40
	v_mul_f32_e32 v49, 0xbfb8aa3b, v49
	v_exp_f32_e32 v55, v55
	v_mul_f32_e32 v56, 0xbfb8aa3b, v56
	v_exp_f32_e32 v40, v40
	v_exp_f32_e32 v49, v49
	v_exp_f32_e32 v57, v56
	v_rcp_f32_e32 v56, v53
	v_add_f32_e32 v53, 1.0, v55
	v_add_f32_e32 v40, 1.0, v40
	v_add_f32_e32 v49, 1.0, v49
	v_rcp_f32_e32 v55, v53
	v_add_f32_e32 v53, 1.0, v57
	v_rcp_f32_e32 v40, v40
	v_rcp_f32_e32 v41, v41
	v_rcp_f32_e32 v57, v53
	v_rcp_f32_e32 v53, v49
	v_pk_mul_f32 v[46:47], v[46:47], v[54:55]
	v_pk_mul_f32 v[44:45], v[44:45], v[40:41]
	v_pk_mul_f32 v[42:43], v[42:43], v[56:57]
	v_pk_mul_f32 v[50:51], v[50:51], v[52:53]
; #define LAS __attribute__((address_space(3)))
; __device__ __forceinline__ float fast_sigmoid(float x) { return __builtin_amdgcn_rcpf(1.0f + __builtin_amdgcn_exp2f(-x * LOG2E)); }
; #define ROW_RS(u, ai, m) row_rs_lds((ai) * 128 + wr * 64 + (m) * 16 + fr, fq)
; #define ROWLOOP for (int ai = 0; ai < 2; ++ai) _Pragma("unroll") for (int m = 0; m < 4; ++m)
; __device__ __forceinline__ float row_rs_lds(int rt, int fq) {
;     ...
;     const f32x4 v = *(const LAS f32x4*)((LAS unsigned char*)lds_raw_ + RS_OFF + rt * 64 + fq * 16);
;     float s = (v[0] + v[1]) + (v[2] + v[3]);
;     s = red4_sum(s);
;     return __builtin_amdgcn_rsqf(s * (1.0f / D) + EPS);
;     __device__ __forceinline__ void operator()(const Acc& acc, const Unit& u, int wr, int wc, int fr, int fq) const {
;     ...
;         ROWLOOP { const int row = ROW_OF(u, ai, m); const float rs = ROW_RS(u, ai, m);
; #pragma unroll
;             for (int bj = 0; bj < 2; ++bj) {
;                 f32x4 v0 = acc[ai][bj][m][0] * rs, v1 = acc[ai][bj][m][1] * rs;
;                 if (!isx) {
; #pragma unroll
;                     for (int e = 0; e < 4; ++e) { float x = v0[e]; v0[e] = x * fast_sigmoid(1.5957691216f * (x + 0.044715f * x * x * x)); x = v1[e]; v1[e] = x * fast_sigmoid(1.5957691216f * (x + 0.044715f * x * x * x)); }
;                 }
;                 *(u32x4*)(o + (size_t)row * D + ct + bj * 128 + wc * 32 + fq * 8) = pack8(v0, v1);
.LBB0_1339:
	v_add_u32_e32 v40, 0x90, v120
	v_ashrrev_i32_e32 v41, 31, v40
	v_mov_b32_e32 v49, v48
	v_lshlrev_b64 v[40:41], 11, v[40:41]
	v_cvt_pk_bf16_f32 v44, v44, v45
	v_cvt_pk_bf16_f32 v45, v46, v47
	v_cvt_pk_bf16_f32 v46, v50, v51
	v_cvt_pk_bf16_f32 v47, v42, v43
	v_mov_b32_e32 v42, v48
	v_mov_b32_e32 v43, v48
	v_lshl_add_u64 v[40:41], v[122:123], 0, v[40:41]
	v_pk_mul_f32 v[38:39], v[38:39], v[42:43]
	v_pk_mul_f32 v[36:37], v[36:37], v[48:49]
	v_pk_mul_f32 v[34:35], v[34:35], v[42:43]
	s_and_b64 vcc, exec, s[4:5]
	v_pk_mul_f32 v[32:33], v[32:33], v[48:49]
	global_store_dwordx4 v[40:41], v[44:47], off sc1
	s_cbranch_vccnz .LBB0_1341
	v_mul_f32_e32 v43, 0x3d372713, v32
	v_mul_f32_e32 v43, v32, v43
	v_mul_f32_e32 v44, 0x3d372713, v37
	v_fma_f32 v43, v32, v43, v32
	v_mul_f32_e32 v44, v37, v44
	v_mov_b32_e32 v45, v37
	v_mul_f32_e32 v43, 0x3fcc422a, v43
	v_fmac_f32_e32 v45, v45, v44
	v_mul_f32_e32 v43, 0xbfb8aa3b, v43
	v_mul_f32_e32 v44, 0x3fcc422a, v45
	v_exp_f32_e32 v43, v43
	v_mul_f32_e32 v44, 0xbfb8aa3b, v44
	v_exp_f32_e32 v45, v44
	v_mul_f32_e32 v48, 0x3d372713, v39
	v_add_f32_e32 v43, 1.0, v43
	v_mul_f32_e32 v48, v39, v48
	v_rcp_f32_e32 v44, v43
	v_add_f32_e32 v43, 1.0, v45
	v_mul_f32_e32 v45, 0x3d372713, v33
	v_fma_f32 v48, v39, v48, v39
	v_mul_f32_e32 v45, v33, v45
	v_mov_b32_e32 v46, v33
	v_mul_f32_e32 v48, 0x3fcc422a, v48
	v_fmac_f32_e32 v46, v46, v45
	v_mul_f32_e32 v47, 0x3d372713, v34
	v_mul_f32_e32 v48, 0xbfb8aa3b, v48
	v_mul_f32_e32 v42, 0x3d372713, v36
	v_mul_f32_e32 v45, 0x3fcc422a, v46
	v_mul_f32_e32 v46, 0x3d372713, v38
	v_mul_f32_e32 v47, v34, v47
	v_exp_f32_e32 v49, v48
	v_mul_f32_e32 v48, 0x3d372713, v35
	v_mul_f32_e32 v42, v36, v42
	v_mul_f32_e32 v46, v38, v46
	v_fma_f32 v47, v34, v47, v34
	v_mul_f32_e32 v48, v35, v48
	v_fma_f32 v42, v36, v42, v36
	v_fma_f32 v46, v38, v46, v38
	v_mul_f32_e32 v47, 0x3fcc422a, v47
	v_fma_f32 v48, v35, v48, v35
	v_mul_f32_e32 v42, 0x3fcc422a, v42
	v_mul_f32_e32 v46, 0x3fcc422a, v46
	v_mul_f32_e32 v47, 0xbfb8aa3b, v47
	v_mul_f32_e32 v48, 0x3fcc422a, v48
	v_mul_f32_e32 v42, 0xbfb8aa3b, v42
	v_mul_f32_e32 v45, 0xbfb8aa3b, v45
	v_mul_f32_e32 v46, 0xbfb8aa3b, v46
	v_exp_f32_e32 v47, v47
	v_mul_f32_e32 v48, 0xbfb8aa3b, v48
	v_exp_f32_e32 v42, v42
	v_exp_f32_e32 v45, v45
	v_exp_f32_e32 v46, v46
	v_exp_f32_e32 v50, v48
	v_add_f32_e32 v47, 1.0, v47
	v_add_f32_e32 v42, 1.0, v42
	v_add_f32_e32 v45, 1.0, v45
	v_add_f32_e32 v46, 1.0, v46
	v_rcp_f32_e32 v48, v47
	v_add_f32_e32 v47, 1.0, v49
	v_add_f32_e32 v49, 1.0, v50
	v_rcp_f32_e32 v42, v42
	v_rcp_f32_e32 v43, v43
	v_rcp_f32_e32 v46, v46
	v_rcp_f32_e32 v47, v47
	v_rcp_f32_e32 v49, v49
	v_rcp_f32_e32 v45, v45
	v_pk_mul_f32 v[36:37], v[36:37], v[42:43]
	v_pk_mul_f32 v[38:39], v[38:39], v[46:47]
	v_pk_mul_f32 v[34:35], v[34:35], v[48:49]
	v_pk_mul_f32 v[32:33], v[32:33], v[44:45]
.LBB0_1341:
	v_cvt_pk_bf16_f32 v36, v36, v37
	v_cvt_pk_bf16_f32 v37, v38, v39
	s_nop 0
	v_cvt_pk_bf16_f32 v38, v32, v33
	v_cvt_pk_bf16_f32 v39, v34, v35
	ds_read_b128 v[32:35], v160 offset:10240
	s_and_b64 vcc, exec, s[4:5]
	global_store_dwordx4 v[40:41], v[36:39], off offset:256 sc1
	s_waitcnt lgkmcnt(0)
	v_add_f32_e32 v32, v32, v33
	v_add_f32_e32 v33, v34, v35
	v_add_f32_e32 v32, v32, v33
	v_mov_b32_e32 v33, v32
	s_nop 1
	v_permlane16_swap_b32_e32 v32, v33
	v_add_f32_e32 v32, v32, v33
	v_mov_b32_e32 v33, v32
	s_nop 1
	v_permlane32_swap_b32_e32 v32, v33
	v_add_f32_e32 v32, v32, v33
	v_fmamk_f32 v32, v32, 0x3a800000, v159
	v_rsq_f32_e32 v32, v32
	s_nop 0
	v_pk_mul_f32 v[30:31], v[30:31], v[32:33] op_sel_hi:[1,0]
	v_pk_mul_f32 v[28:29], v[28:29], v[32:33] op_sel_hi:[1,0]
	v_pk_mul_f32 v[26:27], v[26:27], v[32:33] op_sel_hi:[1,0]
	v_pk_mul_f32 v[34:35], v[24:25], v[32:33] op_sel_hi:[1,0]
	s_cbranch_vccnz .LBB0_1343
	v_mul_f32_e32 v25, 0x3d372713, v34
	v_mul_f32_e32 v25, v34, v25
	v_mul_f32_e32 v33, 0x3d372713, v29
	v_fma_f32 v25, v34, v25, v34
	v_mul_f32_e32 v33, v29, v33
	v_mov_b32_e32 v36, v29
	v_mul_f32_e32 v25, 0x3fcc422a, v25
	v_fmac_f32_e32 v36, v36, v33
	v_mul_f32_e32 v25, 0xbfb8aa3b, v25
	v_mul_f32_e32 v33, 0x3fcc422a, v36
	v_exp_f32_e32 v25, v25
	v_mul_f32_e32 v33, 0xbfb8aa3b, v33
	v_exp_f32_e32 v33, v33
	v_mov_b32_e32 v37, v35
	v_add_f32_e32 v25, 1.0, v25
	v_rcp_f32_e32 v36, v25
	v_add_f32_e32 v25, 1.0, v33
	v_mul_f32_e32 v33, 0x3d372713, v35
	v_mul_f32_e32 v33, v35, v33
	v_fmac_f32_e32 v37, v37, v33
	v_mul_f32_e32 v33, 0x3fcc422a, v37
	v_mul_f32_e32 v37, 0x3d372713, v30
	v_mul_f32_e32 v37, v30, v37
	v_mul_f32_e32 v38, 0x3d372713, v26
	v_fma_f32 v37, v30, v37, v30
	v_mul_f32_e32 v38, v26, v38
	v_mul_f32_e32 v37, 0x3fcc422a, v37
	v_fma_f32 v38, v26, v38, v26
	v_mul_f32_e32 v37, 0xbfb8aa3b, v37
	v_mul_f32_e32 v38, 0x3fcc422a, v38
	v_exp_f32_e32 v37, v37
	v_mul_f32_e32 v38, 0xbfb8aa3b, v38
	v_exp_f32_e32 v39, v38
	v_mul_f32_e32 v24, 0x3d372713, v28
	v_add_f32_e32 v37, 1.0, v37
	v_rcp_f32_e32 v38, v37
	v_add_f32_e32 v37, 1.0, v39
	v_mul_f32_e32 v39, 0x3d372713, v31
	v_mul_f32_e32 v39, v31, v39
	v_mul_f32_e32 v40, 0x3d372713, v27
	v_mul_f32_e32 v24, v28, v24
	v_fma_f32 v39, v31, v39, v31
	v_mul_f32_e32 v40, v27, v40
	v_fma_f32 v24, v28, v24, v28
	v_mul_f32_e32 v39, 0x3fcc422a, v39
	v_fma_f32 v40, v27, v40, v27
	v_mul_f32_e32 v24, 0x3fcc422a, v24
	v_mul_f32_e32 v39, 0xbfb8aa3b, v39
	v_mul_f32_e32 v40, 0x3fcc422a, v40
	v_mul_f32_e32 v24, 0xbfb8aa3b, v24
	v_mul_f32_e32 v33, 0xbfb8aa3b, v33
	v_exp_f32_e32 v39, v39
	v_mul_f32_e32 v40, 0xbfb8aa3b, v40
	v_exp_f32_e32 v24, v24
	v_exp_f32_e32 v33, v33
	v_exp_f32_e32 v41, v40
	v_rcp_f32_e32 v40, v37
	v_add_f32_e32 v37, 1.0, v39
	v_add_f32_e32 v24, 1.0, v24
	v_add_f32_e32 v33, 1.0, v33
	v_rcp_f32_e32 v39, v37
	v_add_f32_e32 v37, 1.0, v41
	v_rcp_f32_e32 v24, v24
	v_rcp_f32_e32 v25, v25
	v_rcp_f32_e32 v41, v37
	v_rcp_f32_e32 v37, v33
	v_pk_mul_f32 v[30:31], v[30:31], v[38:39]
	v_pk_mul_f32 v[28:29], v[28:29], v[24:25]
	v_pk_mul_f32 v[26:27], v[26:27], v[40:41]
	v_pk_mul_f32 v[34:35], v[34:35], v[36:37]
; #define LAS __attribute__((address_space(3)))
; __device__ __forceinline__ float fast_sigmoid(float x) { return __builtin_amdgcn_rcpf(1.0f + __builtin_amdgcn_exp2f(-x * LOG2E)); }
; #define ROW_RS(u, ai, m) row_rs_lds((ai) * 128 + wr * 64 + (m) * 16 + fr, fq)
; #define ROWLOOP for (int ai = 0; ai < 2; ++ai) _Pragma("unroll") for (int m = 0; m < 4; ++m)
; __device__ __forceinline__ float row_rs_lds(int rt, int fq) {
;     ...
;     const f32x4 v = *(const LAS f32x4*)((LAS unsigned char*)lds_raw_ + RS_OFF + rt * 64 + fq * 16);
;     float s = (v[0] + v[1]) + (v[2] + v[3]);
;     s = red4_sum(s);
;     return __builtin_amdgcn_rsqf(s * (1.0f / D) + EPS);
;     __device__ __forceinline__ void operator()(const Acc& acc, const Unit& u, int wr, int wc, int fr, int fq) const {
;     ...
;         ROWLOOP { const int row = ROW_OF(u, ai, m); const float rs = ROW_RS(u, ai, m);
; #pragma unroll
;             for (int bj = 0; bj < 2; ++bj) {
;                 f32x4 v0 = acc[ai][bj][m][0] * rs, v1 = acc[ai][bj][m][1] * rs;
;                 if (!isx) {
; #pragma unroll
;                     for (int e = 0; e < 4; ++e) { float x = v0[e]; v0[e] = x * fast_sigmoid(1.5957691216f * (x + 0.044715f * x * x * x)); x = v1[e]; v1[e] = x * fast_sigmoid(1.5957691216f * (x + 0.044715f * x * x * x)); }
;                 }
;                 *(u32x4*)(o + (size_t)row * D + ct + bj * 128 + wc * 32 + fq * 8) = pack8(v0, v1);
.LBB0_1343:
	v_add_u32_e32 v24, 0xa0, v120
	v_ashrrev_i32_e32 v25, 31, v24
	v_mov_b32_e32 v33, v32
	v_lshlrev_b64 v[24:25], 11, v[24:25]
	v_cvt_pk_bf16_f32 v28, v28, v29
	v_cvt_pk_bf16_f32 v29, v30, v31
	v_cvt_pk_bf16_f32 v30, v34, v35
	v_cvt_pk_bf16_f32 v31, v26, v27
	v_mov_b32_e32 v26, v32
	v_mov_b32_e32 v27, v32
	v_lshl_add_u64 v[24:25], v[122:123], 0, v[24:25]
	v_pk_mul_f32 v[22:23], v[22:23], v[26:27]
	v_pk_mul_f32 v[20:21], v[20:21], v[32:33]
	v_pk_mul_f32 v[18:19], v[18:19], v[26:27]
	s_and_b64 vcc, exec, s[4:5]
	v_pk_mul_f32 v[16:17], v[16:17], v[32:33]
	global_store_dwordx4 v[24:25], v[28:31], off sc1
	s_cbranch_vccnz .LBB0_1345
	v_mul_f32_e32 v27, 0x3d372713, v16
	v_mul_f32_e32 v27, v16, v27
	v_mul_f32_e32 v28, 0x3d372713, v21
	v_fma_f32 v27, v16, v27, v16
	v_mul_f32_e32 v28, v21, v28
	v_mov_b32_e32 v29, v21
	v_mul_f32_e32 v27, 0x3fcc422a, v27
	v_fmac_f32_e32 v29, v29, v28
	v_mul_f32_e32 v27, 0xbfb8aa3b, v27
	v_mul_f32_e32 v28, 0x3fcc422a, v29
	v_exp_f32_e32 v27, v27
	v_mul_f32_e32 v28, 0xbfb8aa3b, v28
	v_exp_f32_e32 v29, v28
	v_mul_f32_e32 v32, 0x3d372713, v23
	v_add_f32_e32 v27, 1.0, v27
	v_mul_f32_e32 v32, v23, v32
	v_rcp_f32_e32 v28, v27
	v_add_f32_e32 v27, 1.0, v29
	v_mul_f32_e32 v29, 0x3d372713, v17
	v_fma_f32 v32, v23, v32, v23
	v_mul_f32_e32 v29, v17, v29
	v_mov_b32_e32 v30, v17
	v_mul_f32_e32 v32, 0x3fcc422a, v32
	v_fmac_f32_e32 v30, v30, v29
	v_mul_f32_e32 v31, 0x3d372713, v18
	v_mul_f32_e32 v32, 0xbfb8aa3b, v32
	v_mul_f32_e32 v26, 0x3d372713, v20
	v_mul_f32_e32 v29, 0x3fcc422a, v30
	v_mul_f32_e32 v30, 0x3d372713, v22
	v_mul_f32_e32 v31, v18, v31
	v_exp_f32_e32 v33, v32
	v_mul_f32_e32 v32, 0x3d372713, v19
	v_mul_f32_e32 v26, v20, v26
	v_mul_f32_e32 v30, v22, v30
	v_fma_f32 v31, v18, v31, v18
	v_mul_f32_e32 v32, v19, v32
	v_fma_f32 v26, v20, v26, v20
	v_fma_f32 v30, v22, v30, v22
	v_mul_f32_e32 v31, 0x3fcc422a, v31
	v_fma_f32 v32, v19, v32, v19
	v_mul_f32_e32 v26, 0x3fcc422a, v26
	v_mul_f32_e32 v30, 0x3fcc422a, v30
	v_mul_f32_e32 v31, 0xbfb8aa3b, v31
	v_mul_f32_e32 v32, 0x3fcc422a, v32
	v_mul_f32_e32 v26, 0xbfb8aa3b, v26
	v_mul_f32_e32 v29, 0xbfb8aa3b, v29
	v_mul_f32_e32 v30, 0xbfb8aa3b, v30
	v_exp_f32_e32 v31, v31
	v_mul_f32_e32 v32, 0xbfb8aa3b, v32
	v_exp_f32_e32 v26, v26
	v_exp_f32_e32 v29, v29
	v_exp_f32_e32 v30, v30
	v_exp_f32_e32 v34, v32
	v_add_f32_e32 v31, 1.0, v31
	v_add_f32_e32 v26, 1.0, v26
	v_add_f32_e32 v29, 1.0, v29
	v_add_f32_e32 v30, 1.0, v30
	v_rcp_f32_e32 v32, v31
	v_add_f32_e32 v31, 1.0, v33
	v_add_f32_e32 v33, 1.0, v34
	v_rcp_f32_e32 v26, v26
	v_rcp_f32_e32 v27, v27
	v_rcp_f32_e32 v30, v30
	v_rcp_f32_e32 v31, v31
	v_rcp_f32_e32 v33, v33
	v_rcp_f32_e32 v29, v29
	v_pk_mul_f32 v[20:21], v[20:21], v[26:27]
	v_pk_mul_f32 v[22:23], v[22:23], v[30:31]
	v_pk_mul_f32 v[18:19], v[18:19], v[32:33]
	v_pk_mul_f32 v[16:17], v[16:17], v[28:29]
.LBB0_1345:
	v_cvt_pk_bf16_f32 v20, v20, v21
	v_cvt_pk_bf16_f32 v21, v22, v23
	s_nop 0
	v_cvt_pk_bf16_f32 v22, v16, v17
	v_cvt_pk_bf16_f32 v23, v18, v19
	ds_read_b128 v[16:19], v160 offset:11264
	s_and_b64 vcc, exec, s[4:5]
	global_store_dwordx4 v[24:25], v[20:23], off offset:256 sc1
	s_waitcnt lgkmcnt(0)
	v_add_f32_e32 v16, v16, v17
	v_add_f32_e32 v17, v18, v19
	v_add_f32_e32 v16, v16, v17
	v_mov_b32_e32 v17, v16
	s_nop 1
	v_permlane16_swap_b32_e32 v16, v17
	v_add_f32_e32 v16, v16, v17
	v_mov_b32_e32 v17, v16
	s_nop 1
	v_permlane32_swap_b32_e32 v16, v17
	v_add_f32_e32 v16, v16, v17
	v_fmamk_f32 v16, v16, 0x3a800000, v159
	v_rsq_f32_e32 v16, v16
	s_nop 0
	v_pk_mul_f32 v[14:15], v[14:15], v[16:17] op_sel_hi:[1,0]
	v_pk_mul_f32 v[12:13], v[12:13], v[16:17] op_sel_hi:[1,0]
	v_pk_mul_f32 v[10:11], v[10:11], v[16:17] op_sel_hi:[1,0]
	v_pk_mul_f32 v[18:19], v[8:9], v[16:17] op_sel_hi:[1,0]
	s_cbranch_vccnz .LBB0_1347
	v_mul_f32_e32 v9, 0x3d372713, v18
	v_mul_f32_e32 v9, v18, v9
	v_mul_f32_e32 v17, 0x3d372713, v13
	v_fma_f32 v9, v18, v9, v18
	v_mul_f32_e32 v17, v13, v17
	v_mov_b32_e32 v20, v13
	v_mul_f32_e32 v9, 0x3fcc422a, v9
	v_fmac_f32_e32 v20, v20, v17
	v_mul_f32_e32 v9, 0xbfb8aa3b, v9
	v_mul_f32_e32 v17, 0x3fcc422a, v20
	v_exp_f32_e32 v9, v9
	v_mul_f32_e32 v17, 0xbfb8aa3b, v17
	v_exp_f32_e32 v17, v17
	v_mov_b32_e32 v21, v19
	v_add_f32_e32 v9, 1.0, v9
	v_rcp_f32_e32 v20, v9
	v_add_f32_e32 v9, 1.0, v17
	v_mul_f32_e32 v17, 0x3d372713, v19
	v_mul_f32_e32 v17, v19, v17
	v_fmac_f32_e32 v21, v21, v17
	v_mul_f32_e32 v17, 0x3fcc422a, v21
	v_mul_f32_e32 v21, 0x3d372713, v14
	v_mul_f32_e32 v21, v14, v21
	v_mul_f32_e32 v22, 0x3d372713, v10
	v_fma_f32 v21, v14, v21, v14
	v_mul_f32_e32 v22, v10, v22
	v_mul_f32_e32 v21, 0x3fcc422a, v21
	v_fma_f32 v22, v10, v22, v10
	v_mul_f32_e32 v21, 0xbfb8aa3b, v21
	v_mul_f32_e32 v22, 0x3fcc422a, v22
	v_exp_f32_e32 v21, v21
	v_mul_f32_e32 v22, 0xbfb8aa3b, v22
	v_exp_f32_e32 v23, v22
	v_mul_f32_e32 v8, 0x3d372713, v12
	v_add_f32_e32 v21, 1.0, v21
	v_rcp_f32_e32 v22, v21
	v_add_f32_e32 v21, 1.0, v23
	v_mul_f32_e32 v23, 0x3d372713, v15
	v_mul_f32_e32 v23, v15, v23
	v_mul_f32_e32 v24, 0x3d372713, v11
	v_mul_f32_e32 v8, v12, v8
	v_fma_f32 v23, v15, v23, v15
	v_mul_f32_e32 v24, v11, v24
	v_fma_f32 v8, v12, v8, v12
	v_mul_f32_e32 v23, 0x3fcc422a, v23
	v_fma_f32 v24, v11, v24, v11
	v_mul_f32_e32 v8, 0x3fcc422a, v8
	v_mul_f32_e32 v23, 0xbfb8aa3b, v23
	v_mul_f32_e32 v24, 0x3fcc422a, v24
	v_mul_f32_e32 v8, 0xbfb8aa3b, v8
	v_mul_f32_e32 v17, 0xbfb8aa3b, v17
	v_exp_f32_e32 v23, v23
	v_mul_f32_e32 v24, 0xbfb8aa3b, v24
	v_exp_f32_e32 v8, v8
	v_exp_f32_e32 v17, v17
	v_exp_f32_e32 v25, v24
	v_rcp_f32_e32 v24, v21
	v_add_f32_e32 v21, 1.0, v23
	v_add_f32_e32 v8, 1.0, v8
	v_add_f32_e32 v17, 1.0, v17
	v_rcp_f32_e32 v23, v21
	v_add_f32_e32 v21, 1.0, v25
	v_rcp_f32_e32 v8, v8
	v_rcp_f32_e32 v9, v9
	v_rcp_f32_e32 v25, v21
	v_rcp_f32_e32 v21, v17
	v_pk_mul_f32 v[14:15], v[14:15], v[22:23]
	v_pk_mul_f32 v[12:13], v[12:13], v[8:9]
	v_pk_mul_f32 v[10:11], v[10:11], v[24:25]
	v_pk_mul_f32 v[18:19], v[18:19], v[20:21]
; __device__ __forceinline__ float fast_sigmoid(float x) { return __builtin_amdgcn_rcpf(1.0f + __builtin_amdgcn_exp2f(-x * LOG2E)); }
; #define ROW_RS(u, ai, m) row_rs_lds((ai) * 128 + wr * 64 + (m) * 16 + fr, fq)
; #define ROWLOOP for (int ai = 0; ai < 2; ++ai) _Pragma("unroll") for (int m = 0; m < 4; ++m)
;     __device__ __forceinline__ void operator()(const Acc& acc, const Unit& u, int wr, int wc, int fr, int fq) const {
;     ...
;         ROWLOOP { const int row = ROW_OF(u, ai, m); const float rs = ROW_RS(u, ai, m);
; #pragma unroll
;             for (int bj = 0; bj < 2; ++bj) {
;                 f32x4 v0 = acc[ai][bj][m][0] * rs, v1 = acc[ai][bj][m][1] * rs;
;                 if (!isx) {
; #pragma unroll
;                     for (int e = 0; e < 4; ++e) { float x = v0[e]; v0[e] = x * fast_sigmoid(1.5957691216f * (x + 0.044715f * x * x * x)); x = v1[e]; v1[e] = x * fast_sigmoid(1.5957691216f * (x + 0.044715f * x * x * x)); }
;                 }
;                 *(u32x4*)(o + (size_t)row * D + ct + bj * 128 + wc * 32 + fq * 8) = pack8(v0, v1);
.LBB0_1347:
	v_add_u32_e32 v8, 0xb0, v120
	v_ashrrev_i32_e32 v9, 31, v8
	v_mov_b32_e32 v17, v16
	v_lshlrev_b64 v[8:9], 11, v[8:9]
	v_cvt_pk_bf16_f32 v12, v12, v13
	v_cvt_pk_bf16_f32 v13, v14, v15
	v_cvt_pk_bf16_f32 v14, v18, v19
	v_cvt_pk_bf16_f32 v15, v10, v11
	v_mov_b32_e32 v10, v16
	v_mov_b32_e32 v11, v16
	v_lshl_add_u64 v[8:9], v[122:123], 0, v[8:9]
	v_pk_mul_f32 v[6:7], v[6:7], v[10:11]
	v_pk_mul_f32 v[4:5], v[4:5], v[16:17]
	v_pk_mul_f32 v[2:3], v[2:3], v[10:11]
	s_and_b64 vcc, exec, s[4:5]
	v_pk_mul_f32 v[0:1], v[0:1], v[16:17]
	global_store_dwordx4 v[8:9], v[12:15], off sc1
	s_cbranch_vccnz .LBB0_1349
	v_mul_f32_e32 v11, 0x3d372713, v0
	v_mul_f32_e32 v11, v0, v11
	v_mul_f32_e32 v12, 0x3d372713, v5
	v_fma_f32 v11, v0, v11, v0
	v_mul_f32_e32 v12, v5, v12
	v_mov_b32_e32 v13, v5
	v_mul_f32_e32 v11, 0x3fcc422a, v11
	v_fmac_f32_e32 v13, v13, v12
	v_mul_f32_e32 v11, 0xbfb8aa3b, v11
	v_mul_f32_e32 v12, 0x3fcc422a, v13
	v_exp_f32_e32 v11, v11
	v_mul_f32_e32 v12, 0xbfb8aa3b, v12
	v_exp_f32_e32 v13, v12
	v_mul_f32_e32 v16, 0x3d372713, v7
	v_add_f32_e32 v11, 1.0, v11
	v_mul_f32_e32 v16, v7, v16
	v_rcp_f32_e32 v12, v11
	v_add_f32_e32 v11, 1.0, v13
	v_mul_f32_e32 v13, 0x3d372713, v1
	v_fma_f32 v16, v7, v16, v7
	v_mul_f32_e32 v13, v1, v13
	v_mov_b32_e32 v14, v1
	v_mul_f32_e32 v16, 0x3fcc422a, v16
	v_fmac_f32_e32 v14, v14, v13
	v_mul_f32_e32 v15, 0x3d372713, v2
	v_mul_f32_e32 v16, 0xbfb8aa3b, v16
	v_mul_f32_e32 v10, 0x3d372713, v4
	v_mul_f32_e32 v13, 0x3fcc422a, v14
	v_mul_f32_e32 v14, 0x3d372713, v6
	v_mul_f32_e32 v15, v2, v15
	v_exp_f32_e32 v17, v16
	v_mul_f32_e32 v16, 0x3d372713, v3
	v_mul_f32_e32 v10, v4, v10
	v_mul_f32_e32 v14, v6, v14
	v_fma_f32 v15, v2, v15, v2
	v_mul_f32_e32 v16, v3, v16
	v_fma_f32 v10, v4, v10, v4
	v_fma_f32 v14, v6, v14, v6
	v_mul_f32_e32 v15, 0x3fcc422a, v15
	v_fma_f32 v16, v3, v16, v3
	v_mul_f32_e32 v10, 0x3fcc422a, v10
	v_mul_f32_e32 v14, 0x3fcc422a, v14
	v_mul_f32_e32 v15, 0xbfb8aa3b, v15
	v_mul_f32_e32 v16, 0x3fcc422a, v16
	v_mul_f32_e32 v10, 0xbfb8aa3b, v10
	v_mul_f32_e32 v13, 0xbfb8aa3b, v13
	v_mul_f32_e32 v14, 0xbfb8aa3b, v14
	v_exp_f32_e32 v15, v15
	v_mul_f32_e32 v16, 0xbfb8aa3b, v16
	v_exp_f32_e32 v10, v10
	v_exp_f32_e32 v13, v13
	v_exp_f32_e32 v14, v14
	v_exp_f32_e32 v18, v16
	v_add_f32_e32 v15, 1.0, v15
	v_add_f32_e32 v10, 1.0, v10
	v_add_f32_e32 v13, 1.0, v13
	v_add_f32_e32 v14, 1.0, v14
	v_rcp_f32_e32 v16, v15
	v_add_f32_e32 v15, 1.0, v17
	v_add_f32_e32 v17, 1.0, v18
	v_rcp_f32_e32 v10, v10
	v_rcp_f32_e32 v11, v11
	v_rcp_f32_e32 v14, v14
	v_rcp_f32_e32 v15, v15
	v_rcp_f32_e32 v17, v17
	v_rcp_f32_e32 v13, v13
	v_pk_mul_f32 v[4:5], v[4:5], v[10:11]
	v_pk_mul_f32 v[6:7], v[6:7], v[14:15]
	v_pk_mul_f32 v[2:3], v[2:3], v[16:17]
	v_pk_mul_f32 v[0:1], v[0:1], v[12:13]
.LBB0_1349:
	s_andn2_b64 vcc, exec, s[2:3]
	s_mov_b64 s[2:3], -1
	v_cvt_pk_bf16_f32 v4, v4, v5
	v_cvt_pk_bf16_f32 v5, v6, v7
	v_cvt_pk_bf16_f32 v6, v0, v1
	v_cvt_pk_bf16_f32 v7, v2, v3
	global_store_dwordx4 v[8:9], v[4:7], off offset:256 sc1
	s_cbranch_vccnz .LBB0_1303
	s_andn2_b64 vcc, exec, s[8:9]
	s_cbranch_vccnz .LBB0_1302
	s_barrier
	s_branch .LBB0_1302

; __device__ __forceinline__ f32x4 bf4_lo(const u32x4 w) { return (f32x4){bf_lo(w.x), bf_hi(w.x), bf_lo(w.y), bf_hi(w.y)}; }
; __device__ __forceinline__ f32x4 bf4_hi(const u32x4 w) { return (f32x4){bf_lo(w.z), bf_hi(w.z), bf_lo(w.w), bf_hi(w.w)}; }
; template <int L> __device__ __forceinline__ void layer_body(const Args& args, LAS unsigned char* lds, const int G, const int lo, const int hi, const int wave_s, unsigned& nbar) {
;     ...
;                     for (int q = 0; q < 4; ++q) { const int t = tb + q * tstride; if (t < T) {
;                         f32x4 y0 = bs[0], y1 = bs[1];
; #pragma unroll
;                         for (int j = 0; j < 4; ++j) { y0 += wt[j][0] * bf4_lo(xw[q][j]); y1 += wt[j][1] * bf4_hi(xw[q][j]); }
;                         *(u32x4*)(XC + (size_t)t * D + c8) = pack8(y0, y1); } }
.LBB0_1444:
	s_or_b64 exec, exec, s[10:11]
	s_waitcnt vmcnt(1)
	v_lshlrev_b32_e32 v116, 16, v92
	v_and_b32_e32 v117, 0xffff0000, v92
	v_lshlrev_b32_e32 v92, 16, v93
	v_and_b32_e32 v93, 0xffff0000, v93
	v_pk_fma_f32 v[116:117], v[32:33], v[116:117], v[36:37]
	v_pk_fma_f32 v[92:93], v[34:35], v[92:93], v[38:39]
	v_lshlrev_b32_e32 v118, 16, v94
	v_and_b32_e32 v119, 0xffff0000, v94
	v_lshlrev_b32_e32 v94, 16, v95
	v_and_b32_e32 v95, 0xffff0000, v95
	v_lshlrev_b32_e32 v120, 16, v96
	v_and_b32_e32 v121, 0xffff0000, v96
	v_lshlrev_b32_e32 v96, 16, v97
	v_and_b32_e32 v97, 0xffff0000, v97
	v_pk_fma_f32 v[118:119], v[24:25], v[118:119], v[28:29]
	v_pk_fma_f32 v[94:95], v[26:27], v[94:95], v[30:31]
	v_pk_fma_f32 v[92:93], v[2:3], v[96:97], v[92:93]
	v_pk_fma_f32 v[96:97], v[0:1], v[120:121], v[116:117]
	v_lshlrev_b32_e32 v116, 16, v98
	v_and_b32_e32 v117, 0xffff0000, v98
	v_lshlrev_b32_e32 v98, 16, v99
	v_and_b32_e32 v99, 0xffff0000, v99
	v_pk_fma_f32 v[94:95], v[10:11], v[98:99], v[94:95]
	v_pk_fma_f32 v[98:99], v[8:9], v[116:117], v[118:119]
	v_lshlrev_b32_e32 v116, 16, v88
	v_and_b32_e32 v117, 0xffff0000, v88
	v_lshlrev_b32_e32 v88, 16, v89
	v_and_b32_e32 v89, 0xffff0000, v89
	v_pk_fma_f32 v[88:89], v[6:7], v[88:89], v[92:93]
	v_lshlrev_b32_e32 v92, 16, v90
	v_and_b32_e32 v93, 0xffff0000, v90
	v_lshlrev_b32_e32 v90, 16, v91
	v_and_b32_e32 v91, 0xffff0000, v91
	v_pk_fma_f32 v[96:97], v[4:5], v[116:117], v[96:97]
	v_pk_fma_f32 v[92:93], v[12:13], v[92:93], v[98:99]
	v_pk_fma_f32 v[90:91], v[14:15], v[90:91], v[94:95]
	s_waitcnt vmcnt(0)
	v_lshlrev_b32_e32 v94, 16, v100
	v_and_b32_e32 v95, 0xffff0000, v100
	v_lshlrev_b32_e32 v98, 16, v101
	v_and_b32_e32 v99, 0xffff0000, v101
	v_pk_fma_f32 v[98:99], v[18:19], v[98:99], v[88:89]
	v_pk_fma_f32 v[88:89], v[16:17], v[94:95], v[96:97]
	v_lshlrev_b32_e32 v94, 16, v102
	v_and_b32_e32 v95, 0xffff0000, v102
	v_lshlrev_b32_e32 v96, 16, v103
	v_and_b32_e32 v97, 0xffff0000, v103
	v_pk_fma_f32 v[96:97], v[22:23], v[96:97], v[90:91]
	v_pk_fma_f32 v[90:91], v[20:21], v[94:95], v[92:93]
	v_lshl_add_u64 v[92:93], v[106:107], 0, v[114:115]
	v_cvt_pk_bf16_f32 v88, v88, v89
	v_cvt_pk_bf16_f32 v89, v98, v99
	v_cvt_pk_bf16_f32 v90, v90, v91
	v_cvt_pk_bf16_f32 v91, v96, v97
	global_store_dwordx4 v[92:93], v[88:91], off sc1
	s_and_saveexec_b64 s[6:7], vcc
	s_cbranch_execnz .LBB0_1447
	s_or_b64 exec, exec, s[6:7]
	s_and_saveexec_b64 s[6:7], s[2:3]
	s_cbranch_execnz .LBB0_1448

; __device__ __forceinline__ f32x4 bf4_lo(const u32x4 w) { return (f32x4){bf_lo(w.x), bf_hi(w.x), bf_lo(w.y), bf_hi(w.y)}; }
; __device__ __forceinline__ f32x4 bf4_hi(const u32x4 w) { return (f32x4){bf_lo(w.z), bf_hi(w.z), bf_lo(w.w), bf_hi(w.w)}; }
; template <int L> __device__ __forceinline__ void layer_body(const Args& args, LAS unsigned char* lds, const int G, const int lo, const int hi, const int wave_s, unsigned& nbar) {
;     ...
;                     for (int q = 0; q < 4; ++q) { const int t = tb + q * tstride; if (t < T) {
;                         f32x4 y0 = bs[0], y1 = bs[1];
; #pragma unroll
;                         for (int j = 0; j < 4; ++j) { y0 += wt[j][0] * bf4_lo(xw[q][j]); y1 += wt[j][1] * bf4_hi(xw[q][j]); }
;                         *(u32x4*)(XC + (size_t)t * D + c8) = pack8(y0, y1); } }
.LBB0_1447:
	v_lshlrev_b32_e32 v88, 16, v60
	v_and_b32_e32 v89, 0xffff0000, v60
	v_lshlrev_b32_e32 v90, 16, v61
	v_and_b32_e32 v91, 0xffff0000, v61
	v_pk_fma_f32 v[88:89], v[32:33], v[88:89], v[36:37]
	v_lshlrev_b32_e32 v92, 16, v62
	v_and_b32_e32 v93, 0xffff0000, v62
	v_lshlrev_b32_e32 v96, 16, v56
	v_and_b32_e32 v97, 0xffff0000, v56
	v_pk_fma_f32 v[90:91], v[34:35], v[90:91], v[38:39]
	v_lshlrev_b32_e32 v94, 16, v63
	v_and_b32_e32 v95, 0xffff0000, v63
	v_pk_fma_f32 v[92:93], v[24:25], v[92:93], v[28:29]
	v_lshlrev_b32_e32 v98, 16, v57
	v_and_b32_e32 v99, 0xffff0000, v57
	v_pk_fma_f32 v[88:89], v[0:1], v[96:97], v[88:89]
	v_lshlrev_b32_e32 v96, 16, v58
	v_and_b32_e32 v97, 0xffff0000, v58
	v_pk_fma_f32 v[94:95], v[26:27], v[94:95], v[30:31]
	v_pk_fma_f32 v[90:91], v[2:3], v[98:99], v[90:91]
	v_lshlrev_b32_e32 v98, 16, v59
	v_and_b32_e32 v99, 0xffff0000, v59
	v_pk_fma_f32 v[92:93], v[8:9], v[96:97], v[92:93]
	v_lshlrev_b32_e32 v96, 16, v72
	v_and_b32_e32 v97, 0xffff0000, v72
	v_pk_fma_f32 v[94:95], v[10:11], v[98:99], v[94:95]
	v_lshlrev_b32_e32 v98, 16, v73
	v_and_b32_e32 v99, 0xffff0000, v73
	v_pk_fma_f32 v[88:89], v[4:5], v[96:97], v[88:89]
	v_lshlrev_b32_e32 v96, 16, v74
	v_and_b32_e32 v97, 0xffff0000, v74
	v_pk_fma_f32 v[90:91], v[6:7], v[98:99], v[90:91]
	v_lshlrev_b32_e32 v98, 16, v75
	v_and_b32_e32 v99, 0xffff0000, v75
	v_pk_fma_f32 v[92:93], v[12:13], v[96:97], v[92:93]
	v_lshlrev_b32_e32 v96, 16, v84
	v_and_b32_e32 v97, 0xffff0000, v84
	v_pk_fma_f32 v[94:95], v[14:15], v[98:99], v[94:95]
	v_lshlrev_b32_e32 v98, 16, v85
	v_and_b32_e32 v99, 0xffff0000, v85
	v_pk_fma_f32 v[88:89], v[16:17], v[96:97], v[88:89]
	v_lshlrev_b32_e32 v96, 16, v86
	v_and_b32_e32 v97, 0xffff0000, v86
	v_pk_fma_f32 v[90:91], v[18:19], v[98:99], v[90:91]
	v_pk_fma_f32 v[92:93], v[20:21], v[96:97], v[92:93]
	v_ashrrev_i32_e32 v109, 31, v108
	v_cvt_pk_bf16_f32 v88, v88, v89
	v_cvt_pk_bf16_f32 v89, v90, v91
	v_cvt_pk_bf16_f32 v90, v92, v93
	v_lshlrev_b64 v[92:93], 11, v[108:109]
	v_lshlrev_b32_e32 v98, 16, v87
	v_and_b32_e32 v99, 0xffff0000, v87
	v_lshl_add_u64 v[92:93], v[106:107], 0, v[92:93]
	v_pk_fma_f32 v[94:95], v[22:23], v[98:99], v[94:95]
	s_nop 0
	v_cvt_pk_bf16_f32 v91, v94, v95
	global_store_dwordx4 v[92:93], v[88:91], off sc1
	s_or_b64 exec, exec, s[6:7]
	s_and_saveexec_b64 s[6:7], s[2:3]
	s_cbranch_execz .LBB0_1446
.LBB0_1448:
	v_lshlrev_b32_e32 v88, 16, v52
	v_and_b32_e32 v89, 0xffff0000, v52
	v_lshlrev_b32_e32 v90, 16, v53
	v_and_b32_e32 v91, 0xffff0000, v53
	v_pk_fma_f32 v[88:89], v[32:33], v[88:89], v[36:37]
	v_lshlrev_b32_e32 v92, 16, v54
	v_and_b32_e32 v93, 0xffff0000, v54
	v_lshlrev_b32_e32 v96, 16, v48
	v_and_b32_e32 v97, 0xffff0000, v48
	v_pk_fma_f32 v[90:91], v[34:35], v[90:91], v[38:39]
	v_lshlrev_b32_e32 v94, 16, v55
	v_and_b32_e32 v95, 0xffff0000, v55
	v_pk_fma_f32 v[92:93], v[24:25], v[92:93], v[28:29]
	v_lshlrev_b32_e32 v98, 16, v49
	v_and_b32_e32 v99, 0xffff0000, v49
	v_pk_fma_f32 v[88:89], v[0:1], v[96:97], v[88:89]
	v_lshlrev_b32_e32 v96, 16, v50
	v_and_b32_e32 v97, 0xffff0000, v50
	v_pk_fma_f32 v[94:95], v[26:27], v[94:95], v[30:31]
	v_pk_fma_f32 v[90:91], v[2:3], v[98:99], v[90:91]
	v_lshlrev_b32_e32 v98, 16, v51
	v_and_b32_e32 v99, 0xffff0000, v51
	v_pk_fma_f32 v[92:93], v[8:9], v[96:97], v[92:93]
	v_lshlrev_b32_e32 v96, 16, v68
	v_and_b32_e32 v97, 0xffff0000, v68
	v_pk_fma_f32 v[94:95], v[10:11], v[98:99], v[94:95]
	v_lshlrev_b32_e32 v98, 16, v69
	v_and_b32_e32 v99, 0xffff0000, v69
	v_pk_fma_f32 v[88:89], v[4:5], v[96:97], v[88:89]
	v_lshlrev_b32_e32 v96, 16, v70
	v_and_b32_e32 v97, 0xffff0000, v70
	v_pk_fma_f32 v[90:91], v[6:7], v[98:99], v[90:91]
	v_lshlrev_b32_e32 v98, 16, v71
	v_and_b32_e32 v99, 0xffff0000, v71
	v_pk_fma_f32 v[92:93], v[12:13], v[96:97], v[92:93]
	v_lshlrev_b32_e32 v96, 16, v80
	v_and_b32_e32 v97, 0xffff0000, v80
	v_pk_fma_f32 v[94:95], v[14:15], v[98:99], v[94:95]
	v_lshlrev_b32_e32 v98, 16, v81
	v_and_b32_e32 v99, 0xffff0000, v81
	v_pk_fma_f32 v[88:89], v[16:17], v[96:97], v[88:89]
	v_lshlrev_b32_e32 v96, 16, v82
	v_and_b32_e32 v97, 0xffff0000, v82
	v_pk_fma_f32 v[90:91], v[18:19], v[98:99], v[90:91]
	v_pk_fma_f32 v[92:93], v[20:21], v[96:97], v[92:93]
	v_ashrrev_i32_e32 v111, 31, v110
	v_cvt_pk_bf16_f32 v88, v88, v89
	v_cvt_pk_bf16_f32 v89, v90, v91
	v_cvt_pk_bf16_f32 v90, v92, v93
	v_lshlrev_b64 v[92:93], 11, v[110:111]
	v_lshlrev_b32_e32 v98, 16, v83
	v_and_b32_e32 v99, 0xffff0000, v83
	v_lshl_add_u64 v[92:93], v[106:107], 0, v[92:93]
	v_pk_fma_f32 v[94:95], v[22:23], v[98:99], v[94:95]
	s_nop 0
	v_cvt_pk_bf16_f32 v91, v94, v95
	global_store_dwordx4 v[92:93], v[88:91], off sc1
	s_or_b64 exec, exec, s[6:7]
	s_and_saveexec_b64 s[2:3], s[4:5]
	s_cbranch_execz .LBB0_1413
.LBB0_1449:
	v_lshlrev_b32_e32 v88, 16, v44
	v_and_b32_e32 v89, 0xffff0000, v44
	v_lshlrev_b32_e32 v90, 16, v45
	v_and_b32_e32 v91, 0xffff0000, v45
	v_pk_fma_f32 v[88:89], v[32:33], v[88:89], v[36:37]
	v_lshlrev_b32_e32 v92, 16, v46
	v_and_b32_e32 v93, 0xffff0000, v46
	v_lshlrev_b32_e32 v96, 16, v40
	v_and_b32_e32 v97, 0xffff0000, v40
	v_pk_fma_f32 v[90:91], v[34:35], v[90:91], v[38:39]
	v_lshlrev_b32_e32 v94, 16, v47
	v_and_b32_e32 v95, 0xffff0000, v47
	v_pk_fma_f32 v[92:93], v[24:25], v[92:93], v[28:29]
	v_lshlrev_b32_e32 v98, 16, v41
	v_and_b32_e32 v99, 0xffff0000, v41
	v_pk_fma_f32 v[88:89], v[0:1], v[96:97], v[88:89]
	v_lshlrev_b32_e32 v96, 16, v42
	v_and_b32_e32 v97, 0xffff0000, v42
	v_pk_fma_f32 v[94:95], v[26:27], v[94:95], v[30:31]
	v_pk_fma_f32 v[90:91], v[2:3], v[98:99], v[90:91]
	v_lshlrev_b32_e32 v98, 16, v43
	v_and_b32_e32 v99, 0xffff0000, v43
	v_pk_fma_f32 v[92:93], v[8:9], v[96:97], v[92:93]
	v_lshlrev_b32_e32 v96, 16, v64
	v_and_b32_e32 v97, 0xffff0000, v64
	v_pk_fma_f32 v[94:95], v[10:11], v[98:99], v[94:95]
	v_lshlrev_b32_e32 v98, 16, v65
	v_and_b32_e32 v99, 0xffff0000, v65
	v_pk_fma_f32 v[88:89], v[4:5], v[96:97], v[88:89]
	v_lshlrev_b32_e32 v96, 16, v66
	v_and_b32_e32 v97, 0xffff0000, v66
	v_pk_fma_f32 v[90:91], v[6:7], v[98:99], v[90:91]
	v_lshlrev_b32_e32 v98, 16, v67
	v_and_b32_e32 v99, 0xffff0000, v67
	v_pk_fma_f32 v[92:93], v[12:13], v[96:97], v[92:93]
	v_lshlrev_b32_e32 v96, 16, v76
	v_and_b32_e32 v97, 0xffff0000, v76
	v_pk_fma_f32 v[94:95], v[14:15], v[98:99], v[94:95]
	v_lshlrev_b32_e32 v98, 16, v77
	v_and_b32_e32 v99, 0xffff0000, v77
	v_pk_fma_f32 v[88:89], v[16:17], v[96:97], v[88:89]
	v_lshlrev_b32_e32 v96, 16, v78
	v_and_b32_e32 v97, 0xffff0000, v78
	v_pk_fma_f32 v[90:91], v[18:19], v[98:99], v[90:91]
	v_pk_fma_f32 v[92:93], v[20:21], v[96:97], v[92:93]
	v_ashrrev_i32_e32 v113, 31, v112
	v_cvt_pk_bf16_f32 v88, v88, v89
	v_cvt_pk_bf16_f32 v89, v90, v91
	v_cvt_pk_bf16_f32 v90, v92, v93
	v_lshlrev_b64 v[92:93], 11, v[112:113]
	v_lshlrev_b32_e32 v98, 16, v79
	v_and_b32_e32 v99, 0xffff0000, v79
	v_lshl_add_u64 v[92:93], v[106:107], 0, v[92:93]
	v_pk_fma_f32 v[94:95], v[22:23], v[98:99], v[94:95]
	s_nop 0
	v_cvt_pk_bf16_f32 v91, v94, v95
	global_store_dwordx4 v[92:93], v[88:91], off sc1
	s_branch .LBB0_1413

; __device__ __forceinline__ float bf_lo(unsigned w) { return __uint_as_float(w << 16); }
; __device__ __forceinline__ float bf_hi(unsigned w) { return __uint_as_float(w & 0xffff0000u); }
; template <int L> __device__ __forceinline__ void layer_body(const Args& args, LAS unsigned char* lds, const int G, const int lo, const int hi, const int wave_s, unsigned& nbar) {
;     ...
;                     for (int t = 0; t < 16; ++t) { lw[0][t] = *(const unsigned*)(LA + (t0 + t) * D + 2 * tid); uw[0][t] = *(const unsigned*)(UU + (t0 + t) * D + 2 * tid); }
; #pragma unroll
;                     for (int tbi = 0; tbi < 8; ++tbi) { const int cb = tbi & 1, nb = cb ^ 1;
;                         if (tbi < 7) {
; #pragma unroll
;                             for (int t = 0; t < 16; ++t) { lw[nb][t] = *(const unsigned*)(LA + (t0 + (tbi + 1) * 16 + t) * D + 2 * tid); uw[nb][t] = *(const unsigned*)(UU + (t0 + (tbi + 1) * 16 + t) * D + 2 * tid); } }
; #pragma unroll
;                         for (int t = 0; t < 16; ++t) { const f32x2 l2 = {bf_lo(lw[cb][t]), bf_hi(lw[cb][t])}; const f32x2 a = {__builtin_amdgcn_exp2f(l2[0]), __builtin_amdgcn_exp2f(l2[1])};
;                             Ls += l2; Up = a * Up + (f32x2){bf_lo(uw[cb][t]), bf_hi(uw[cb][t])}; }
.LBB0_1592:
	s_ashr_i32 s3, s2, 31
	s_lshl_b64 s[4:5], s[2:3], 18
	v_lshl_add_u64 v[6:7], v[0:1], 0, s[4:5]
	v_lshl_add_u64 v[8:9], v[2:3], 0, s[4:5]
	global_load_dword v11, v[6:7], off
	global_load_dword v22, v[6:7], off offset:2048
	global_load_dword v19, v[8:9], off
	global_load_dword v26, v[8:9], off offset:2048
	s_or_b32 s6, s4, 0x1000
	s_mov_b32 s7, s5
	v_lshl_add_u64 v[6:7], v[0:1], 0, s[6:7]
	global_load_dword v27, v[6:7], off
	v_lshl_add_u64 v[6:7], v[2:3], 0, s[6:7]
	s_or_b32 s6, s4, 0x1800
	global_load_dword v30, v[6:7], off
	v_lshl_add_u64 v[6:7], v[0:1], 0, s[6:7]
	global_load_dword v31, v[6:7], off
	v_lshl_add_u64 v[6:7], v[2:3], 0, s[6:7]
	s_or_b32 s6, s4, 0x2000
	global_load_dword v32, v[6:7], off
	v_lshl_add_u64 v[6:7], v[0:1], 0, s[6:7]
	global_load_dword v33, v[6:7], off
	v_lshl_add_u64 v[6:7], v[2:3], 0, s[6:7]
	s_or_b32 s6, s4, 0x2800
	global_load_dword v34, v[6:7], off
	v_lshl_add_u64 v[6:7], v[0:1], 0, s[6:7]
	global_load_dword v35, v[6:7], off
	v_lshl_add_u64 v[6:7], v[2:3], 0, s[6:7]
	s_or_b32 s6, s4, 0x3000
	global_load_dword v36, v[6:7], off
	v_lshl_add_u64 v[6:7], v[0:1], 0, s[6:7]
	global_load_dword v37, v[6:7], off
	v_lshl_add_u64 v[6:7], v[2:3], 0, s[6:7]
	s_or_b32 s6, s4, 0x3800
	global_load_dword v38, v[6:7], off
	v_lshl_add_u64 v[6:7], v[0:1], 0, s[6:7]
	global_load_dword v39, v[6:7], off
	v_lshl_add_u64 v[6:7], v[2:3], 0, s[6:7]
	s_or_b32 s6, s4, 0x4000
	global_load_dword v40, v[6:7], off
	v_lshl_add_u64 v[6:7], v[0:1], 0, s[6:7]
	global_load_dword v41, v[6:7], off
	v_lshl_add_u64 v[6:7], v[2:3], 0, s[6:7]
	s_or_b32 s6, s4, 0x4800
	global_load_dword v42, v[6:7], off
	v_lshl_add_u64 v[6:7], v[0:1], 0, s[6:7]
	global_load_dword v43, v[6:7], off
	v_lshl_add_u64 v[6:7], v[2:3], 0, s[6:7]
	s_or_b32 s6, s4, 0x5000
	global_load_dword v44, v[6:7], off
	v_lshl_add_u64 v[6:7], v[0:1], 0, s[6:7]
	global_load_dword v45, v[6:7], off
	v_lshl_add_u64 v[6:7], v[2:3], 0, s[6:7]
	s_or_b32 s6, s4, 0x5800
	global_load_dword v46, v[6:7], off
	v_lshl_add_u64 v[6:7], v[0:1], 0, s[6:7]
	global_load_dword v47, v[6:7], off
	v_lshl_add_u64 v[6:7], v[2:3], 0, s[6:7]
	s_or_b32 s6, s4, 0x6000
	global_load_dword v48, v[6:7], off
	v_lshl_add_u64 v[6:7], v[0:1], 0, s[6:7]
	global_load_dword v49, v[6:7], off
	v_lshl_add_u64 v[6:7], v[2:3], 0, s[6:7]
	s_or_b32 s6, s4, 0x6800
	global_load_dword v50, v[6:7], off
	v_lshl_add_u64 v[6:7], v[0:1], 0, s[6:7]
	global_load_dword v51, v[6:7], off
	v_lshl_add_u64 v[6:7], v[2:3], 0, s[6:7]
	s_or_b32 s6, s4, 0x7000
	global_load_dword v52, v[6:7], off
	v_lshl_add_u64 v[6:7], v[0:1], 0, s[6:7]
	global_load_dword v53, v[6:7], off
	v_lshl_add_u64 v[6:7], v[2:3], 0, s[6:7]
	s_or_b32 s6, s4, 0x7800
	global_load_dword v54, v[6:7], off
	v_lshl_add_u64 v[6:7], v[0:1], 0, s[6:7]
	global_load_dword v55, v[6:7], off
	v_lshl_add_u64 v[6:7], v[2:3], 0, s[6:7]
	global_load_dword v56, v[6:7], off
	s_or_b32 s6, s4, 0x8000
	v_lshl_add_u64 v[6:7], v[0:1], 0, s[6:7]
	global_load_dword v57, v[6:7], off
	v_lshl_add_u64 v[6:7], v[2:3], 0, s[6:7]
	s_or_b32 s6, s4, 0x8800
	s_waitcnt vmcnt(32)
	v_lshlrev_b32_e32 v10, 16, v11
	v_and_b32_e32 v11, 0xffff0000, v11
	v_exp_f32_e32 v14, v10
	v_exp_f32_e32 v15, v11
	s_waitcnt vmcnt(30)
	v_lshlrev_b32_e32 v18, 16, v19
	v_and_b32_e32 v19, 0xffff0000, v19
	v_pk_add_f32 v[10:11], v[10:11], 0 op_sel_hi:[1,0]
	v_pk_fma_f32 v[14:15], v[14:15], 0, v[18:19] op_sel_hi:[1,0,1]
	v_lshlrev_b32_e32 v18, 16, v22
	v_and_b32_e32 v19, 0xffff0000, v22
	v_exp_f32_e32 v22, v18
	v_exp_f32_e32 v23, v19
	v_pk_add_f32 v[10:11], v[10:11], v[18:19]
	s_waitcnt vmcnt(29)
	v_lshlrev_b32_e32 v18, 16, v26
	v_and_b32_e32 v19, 0xffff0000, v26
	v_pk_fma_f32 v[14:15], v[14:15], v[22:23], v[18:19]
	s_waitcnt vmcnt(28)
	v_lshlrev_b32_e32 v18, 16, v27
	v_and_b32_e32 v19, 0xffff0000, v27
	v_exp_f32_e32 v22, v18
	v_exp_f32_e32 v23, v19
	v_pk_add_f32 v[10:11], v[10:11], v[18:19]
	s_waitcnt vmcnt(27)
	v_lshlrev_b32_e32 v18, 16, v30
	v_and_b32_e32 v19, 0xffff0000, v30
	v_pk_fma_f32 v[14:15], v[14:15], v[22:23], v[18:19]
	s_waitcnt vmcnt(26)
	v_lshlrev_b32_e32 v18, 16, v31
	v_and_b32_e32 v19, 0xffff0000, v31
	v_exp_f32_e32 v22, v18
	v_exp_f32_e32 v23, v19
	v_pk_add_f32 v[10:11], v[10:11], v[18:19]
	s_waitcnt vmcnt(25)
	v_lshlrev_b32_e32 v18, 16, v32
	v_and_b32_e32 v19, 0xffff0000, v32
	v_pk_fma_f32 v[14:15], v[14:15], v[22:23], v[18:19]
	s_waitcnt vmcnt(24)
	v_lshlrev_b32_e32 v18, 16, v33
	v_and_b32_e32 v19, 0xffff0000, v33
	v_exp_f32_e32 v22, v18
	v_exp_f32_e32 v23, v19
	v_pk_add_f32 v[10:11], v[10:11], v[18:19]
	s_waitcnt vmcnt(23)
	v_lshlrev_b32_e32 v18, 16, v34
	v_and_b32_e32 v19, 0xffff0000, v34
	v_pk_fma_f32 v[14:15], v[14:15], v[22:23], v[18:19]
	s_waitcnt vmcnt(22)
	v_lshlrev_b32_e32 v18, 16, v35
	v_and_b32_e32 v19, 0xffff0000, v35
	v_exp_f32_e32 v22, v18
	v_exp_f32_e32 v23, v19
	v_pk_add_f32 v[10:11], v[10:11], v[18:19]
	s_waitcnt vmcnt(21)
	v_lshlrev_b32_e32 v18, 16, v36
	v_and_b32_e32 v19, 0xffff0000, v36
	v_pk_fma_f32 v[14:15], v[14:15], v[22:23], v[18:19]
	s_waitcnt vmcnt(20)
	v_lshlrev_b32_e32 v18, 16, v37
	v_and_b32_e32 v19, 0xffff0000, v37
	v_exp_f32_e32 v22, v18
	v_exp_f32_e32 v23, v19
	v_pk_add_f32 v[10:11], v[10:11], v[18:19]
	s_waitcnt vmcnt(19)
	v_lshlrev_b32_e32 v18, 16, v38
	v_and_b32_e32 v19, 0xffff0000, v38
	v_pk_fma_f32 v[14:15], v[14:15], v[22:23], v[18:19]
	s_waitcnt vmcnt(18)
	v_lshlrev_b32_e32 v18, 16, v39
	v_and_b32_e32 v19, 0xffff0000, v39
	global_load_dword v58, v[6:7], off
	v_lshl_add_u64 v[6:7], v[0:1], 0, s[6:7]
	v_exp_f32_e32 v22, v18
	v_exp_f32_e32 v23, v19
	global_load_dword v59, v[6:7], off
	v_pk_add_f32 v[10:11], v[10:11], v[18:19]
	s_waitcnt vmcnt(19)
; __device__ __forceinline__ float bf_lo(unsigned w) { return __uint_as_float(w << 16); }
; __device__ __forceinline__ float bf_hi(unsigned w) { return __uint_as_float(w & 0xffff0000u); }
; template <int L> __device__ __forceinline__ void layer_body(const Args& args, LAS unsigned char* lds, const int G, const int lo, const int hi, const int wave_s, unsigned& nbar) {
;     ...
;                     for (int t = 0; t < 16; ++t) { lw[0][t] = *(const unsigned*)(LA + (t0 + t) * D + 2 * tid); uw[0][t] = *(const unsigned*)(UU + (t0 + t) * D + 2 * tid); }
; #pragma unroll
;                     for (int tbi = 0; tbi < 8; ++tbi) { const int cb = tbi & 1, nb = cb ^ 1;
;                         if (tbi < 7) {
; #pragma unroll
;                             for (int t = 0; t < 16; ++t) { lw[nb][t] = *(const unsigned*)(LA + (t0 + (tbi + 1) * 16 + t) * D + 2 * tid); uw[nb][t] = *(const unsigned*)(UU + (t0 + (tbi + 1) * 16 + t) * D + 2 * tid); } }
; #pragma unroll
;                         for (int t = 0; t < 16; ++t) { const f32x2 l2 = {bf_lo(lw[cb][t]), bf_hi(lw[cb][t])}; const f32x2 a = {__builtin_amdgcn_exp2f(l2[0]), __builtin_amdgcn_exp2f(l2[1])};
;                             Ls += l2; Up = a * Up + (f32x2){bf_lo(uw[cb][t]), bf_hi(uw[cb][t])}; }
	v_lshlrev_b32_e32 v18, 16, v40
	v_and_b32_e32 v19, 0xffff0000, v40
	v_lshl_add_u64 v[6:7], v[2:3], 0, s[6:7]
	s_or_b32 s6, s4, 0x9000
	v_pk_fma_f32 v[14:15], v[14:15], v[22:23], v[18:19]
	s_waitcnt vmcnt(18)
	v_lshlrev_b32_e32 v18, 16, v41
	v_and_b32_e32 v19, 0xffff0000, v41
	global_load_dword v60, v[6:7], off
	v_lshl_add_u64 v[6:7], v[0:1], 0, s[6:7]
	v_exp_f32_e32 v22, v18
	v_exp_f32_e32 v23, v19
	global_load_dword v61, v[6:7], off
	v_pk_add_f32 v[10:11], v[10:11], v[18:19]
	s_waitcnt vmcnt(19)
	v_lshlrev_b32_e32 v18, 16, v42
	v_and_b32_e32 v19, 0xffff0000, v42
	v_lshl_add_u64 v[6:7], v[2:3], 0, s[6:7]
	s_or_b32 s6, s4, 0x9800
	v_pk_fma_f32 v[14:15], v[14:15], v[22:23], v[18:19]
	s_waitcnt vmcnt(18)
	v_lshlrev_b32_e32 v18, 16, v43
	v_and_b32_e32 v19, 0xffff0000, v43
	global_load_dword v62, v[6:7], off
	v_lshl_add_u64 v[6:7], v[0:1], 0, s[6:7]
	v_exp_f32_e32 v22, v18
	v_exp_f32_e32 v23, v19
	global_load_dword v63, v[6:7], off
	v_pk_add_f32 v[10:11], v[10:11], v[18:19]
	s_waitcnt vmcnt(19)
	v_lshlrev_b32_e32 v18, 16, v44
	v_and_b32_e32 v19, 0xffff0000, v44
	v_lshl_add_u64 v[6:7], v[2:3], 0, s[6:7]
	s_or_b32 s6, s4, 0xa000
	v_pk_fma_f32 v[14:15], v[14:15], v[22:23], v[18:19]
	s_waitcnt vmcnt(18)
	v_lshlrev_b32_e32 v18, 16, v45
	v_and_b32_e32 v19, 0xffff0000, v45
	global_load_dword v64, v[6:7], off
	v_lshl_add_u64 v[6:7], v[0:1], 0, s[6:7]
	v_exp_f32_e32 v22, v18
	v_exp_f32_e32 v23, v19
	global_load_dword v65, v[6:7], off
	v_pk_add_f32 v[10:11], v[10:11], v[18:19]
	s_waitcnt vmcnt(19)
	v_lshlrev_b32_e32 v18, 16, v46
	v_and_b32_e32 v19, 0xffff0000, v46
	v_lshl_add_u64 v[6:7], v[2:3], 0, s[6:7]
	s_or_b32 s6, s4, 0xa800
	v_pk_fma_f32 v[14:15], v[14:15], v[22:23], v[18:19]
	s_waitcnt vmcnt(18)
	v_lshlrev_b32_e32 v18, 16, v47
	v_and_b32_e32 v19, 0xffff0000, v47
	global_load_dword v66, v[6:7], off
	v_lshl_add_u64 v[6:7], v[0:1], 0, s[6:7]
	v_exp_f32_e32 v22, v18
	v_exp_f32_e32 v23, v19
	global_load_dword v67, v[6:7], off
	v_lshl_add_u64 v[6:7], v[2:3], 0, s[6:7]
	s_or_b32 s6, s4, 0xb000
	v_pk_add_f32 v[10:11], v[10:11], v[18:19]
	s_waitcnt vmcnt(19)
	v_lshlrev_b32_e32 v18, 16, v48
	v_and_b32_e32 v19, 0xffff0000, v48
	global_load_dword v68, v[6:7], off
	v_lshl_add_u64 v[6:7], v[0:1], 0, s[6:7]
	v_pk_fma_f32 v[14:15], v[14:15], v[22:23], v[18:19]
	s_waitcnt vmcnt(19)
	v_lshlrev_b32_e32 v18, 16, v49
	v_and_b32_e32 v19, 0xffff0000, v49
	global_load_dword v69, v[6:7], off
	v_lshl_add_u64 v[6:7], v[2:3], 0, s[6:7]
	s_or_b32 s6, s4, 0xb800
	v_exp_f32_e32 v22, v18
	v_exp_f32_e32 v23, v19
	global_load_dword v70, v[6:7], off
	v_lshl_add_u64 v[6:7], v[0:1], 0, s[6:7]
	global_load_dword v71, v[6:7], off
	v_lshl_add_u64 v[6:7], v[2:3], 0, s[6:7]
	s_or_b32 s6, s4, 0xc000
	global_load_dword v72, v[6:7], off
	v_lshl_add_u64 v[6:7], v[0:1], 0, s[6:7]
	v_pk_add_f32 v[10:11], v[10:11], v[18:19]
	s_waitcnt vmcnt(22)
	v_lshlrev_b32_e32 v18, 16, v50
	v_and_b32_e32 v19, 0xffff0000, v50
	global_load_dword v73, v[6:7], off
	v_lshl_add_u64 v[6:7], v[2:3], 0, s[6:7]
	s_or_b32 s6, s4, 0xc800
	v_pk_fma_f32 v[14:15], v[14:15], v[22:23], v[18:19]
	s_waitcnt vmcnt(22)
	v_lshlrev_b32_e32 v18, 16, v51
	v_and_b32_e32 v19, 0xffff0000, v51
	global_load_dword v74, v[6:7], off
	v_lshl_add_u64 v[6:7], v[0:1], 0, s[6:7]
	v_exp_f32_e32 v22, v18
	v_exp_f32_e32 v23, v19
	global_load_dword v75, v[6:7], off
	v_lshl_add_u64 v[6:7], v[2:3], 0, s[6:7]
	s_or_b32 s6, s4, 0xd000
	global_load_dword v28, v[6:7], off
	v_lshl_add_u64 v[6:7], v[0:1], 0, s[6:7]
	global_load_dword v29, v[6:7], off
	v_lshl_add_u64 v[6:7], v[2:3], 0, s[6:7]
	s_or_b32 s6, s4, 0xd800
	v_pk_add_f32 v[10:11], v[10:11], v[18:19]
	s_waitcnt vmcnt(25)
	v_lshlrev_b32_e32 v18, 16, v52
	v_and_b32_e32 v19, 0xffff0000, v52
	global_load_dword v24, v[6:7], off
	v_lshl_add_u64 v[6:7], v[0:1], 0, s[6:7]
	v_pk_fma_f32 v[14:15], v[14:15], v[22:23], v[18:19]
	s_waitcnt vmcnt(25)
	v_lshlrev_b32_e32 v18, 16, v53
	v_and_b32_e32 v19, 0xffff0000, v53
	global_load_dword v25, v[6:7], off
	v_lshl_add_u64 v[6:7], v[2:3], 0, s[6:7]
	s_or_b32 s6, s4, 0xe000
	v_exp_f32_e32 v22, v18
	v_exp_f32_e32 v23, v19
	global_load_dword v20, v[6:7], off
	v_lshl_add_u64 v[6:7], v[0:1], 0, s[6:7]
	global_load_dword v21, v[6:7], off
	v_lshl_add_u64 v[6:7], v[2:3], 0, s[6:7]
	s_or_b32 s6, s4, 0xe800
	global_load_dword v16, v[6:7], off
	v_lshl_add_u64 v[6:7], v[0:1], 0, s[6:7]
	v_pk_add_f32 v[10:11], v[10:11], v[18:19]
	s_waitcnt vmcnt(28)
	v_lshlrev_b32_e32 v18, 16, v54
	v_and_b32_e32 v19, 0xffff0000, v54
	global_load_dword v17, v[6:7], off
	v_lshl_add_u64 v[6:7], v[2:3], 0, s[6:7]
	s_or_b32 s6, s4, 0xf000
	v_pk_fma_f32 v[14:15], v[14:15], v[22:23], v[18:19]
	s_waitcnt vmcnt(28)
	v_lshlrev_b32_e32 v18, 16, v55
	v_and_b32_e32 v19, 0xffff0000, v55
	global_load_dword v12, v[6:7], off
	v_lshl_add_u64 v[6:7], v[0:1], 0, s[6:7]
	v_exp_f32_e32 v22, v18
	v_exp_f32_e32 v23, v19
	global_load_dword v13, v[6:7], off
	v_lshl_add_u64 v[6:7], v[2:3], 0, s[6:7]
	s_or_b32 s6, s4, 0xf800
	global_load_dword v8, v[6:7], off
	v_lshl_add_u64 v[6:7], v[0:1], 0, s[6:7]
	global_load_dword v9, v[6:7], off
	v_lshl_add_u64 v[6:7], v[2:3], 0, s[6:7]
	v_pk_add_f32 v[32:33], v[10:11], v[18:19]
	s_waitcnt vmcnt(31)
; __device__ __forceinline__ float bf_lo(unsigned w) { return __uint_as_float(w << 16); }
; __device__ __forceinline__ float bf_hi(unsigned w) { return __uint_as_float(w & 0xffff0000u); }
; template <int L> __device__ __forceinline__ void layer_body(const Args& args, LAS unsigned char* lds, const int G, const int lo, const int hi, const int wave_s, unsigned& nbar) {
;     ...
;                     for (int t = 0; t < 16; ++t) { lw[0][t] = *(const unsigned*)(LA + (t0 + t) * D + 2 * tid); uw[0][t] = *(const unsigned*)(UU + (t0 + t) * D + 2 * tid); }
; #pragma unroll
;                     for (int tbi = 0; tbi < 8; ++tbi) { const int cb = tbi & 1, nb = cb ^ 1;
;                         if (tbi < 7) {
; #pragma unroll
;                             for (int t = 0; t < 16; ++t) { lw[nb][t] = *(const unsigned*)(LA + (t0 + (tbi + 1) * 16 + t) * D + 2 * tid); uw[nb][t] = *(const unsigned*)(UU + (t0 + (tbi + 1) * 16 + t) * D + 2 * tid); } }
; #pragma unroll
;                         for (int t = 0; t < 16; ++t) { const f32x2 l2 = {bf_lo(lw[cb][t]), bf_hi(lw[cb][t])}; const f32x2 a = {__builtin_amdgcn_exp2f(l2[0]), __builtin_amdgcn_exp2f(l2[1])};
;                             Ls += l2; Up = a * Up + (f32x2){bf_lo(uw[cb][t]), bf_hi(uw[cb][t])}; }
	v_lshlrev_b32_e32 v10, 16, v56
	v_and_b32_e32 v11, 0xffff0000, v56
	s_or_b32 s6, s4, 0x10000
	global_load_dword v6, v[6:7], off
	v_pk_fma_f32 v[34:35], v[14:15], v[22:23], v[10:11]
	v_lshl_add_u64 v[10:11], v[0:1], 0, s[6:7]
	global_load_dword v40, v[10:11], off
	v_lshl_add_u64 v[10:11], v[2:3], 0, s[6:7]
	s_or_b32 s6, s4, 0x10800
	global_load_dword v41, v[10:11], off
	v_lshl_add_u64 v[10:11], v[0:1], 0, s[6:7]
	global_load_dword v42, v[10:11], off
	v_lshl_add_u64 v[10:11], v[2:3], 0, s[6:7]
	s_or_b32 s6, s4, 0x11000
	global_load_dword v43, v[10:11], off
	v_lshl_add_u64 v[10:11], v[0:1], 0, s[6:7]
	global_load_dword v44, v[10:11], off
	v_lshl_add_u64 v[10:11], v[2:3], 0, s[6:7]
	s_or_b32 s6, s4, 0x11800
	global_load_dword v45, v[10:11], off
	v_lshl_add_u64 v[10:11], v[0:1], 0, s[6:7]
	global_load_dword v46, v[10:11], off
	v_lshl_add_u64 v[10:11], v[2:3], 0, s[6:7]
	s_or_b32 s6, s4, 0x12000
	global_load_dword v47, v[10:11], off
	v_lshl_add_u64 v[10:11], v[0:1], 0, s[6:7]
	global_load_dword v48, v[10:11], off
	v_lshl_add_u64 v[10:11], v[2:3], 0, s[6:7]
	s_or_b32 s6, s4, 0x12800
	global_load_dword v49, v[10:11], off
	v_lshl_add_u64 v[10:11], v[0:1], 0, s[6:7]
	global_load_dword v50, v[10:11], off
	v_lshl_add_u64 v[10:11], v[2:3], 0, s[6:7]
	s_or_b32 s6, s4, 0x13000
	global_load_dword v51, v[10:11], off
	v_lshl_add_u64 v[10:11], v[0:1], 0, s[6:7]
	global_load_dword v52, v[10:11], off
	v_lshl_add_u64 v[10:11], v[2:3], 0, s[6:7]
	s_or_b32 s6, s4, 0x13800
	global_load_dword v53, v[10:11], off
	v_lshl_add_u64 v[10:11], v[0:1], 0, s[6:7]
	global_load_dword v54, v[10:11], off
	v_lshl_add_u64 v[10:11], v[2:3], 0, s[6:7]
	s_or_b32 s6, s4, 0x14000
	global_load_dword v55, v[10:11], off
	v_lshl_add_u64 v[10:11], v[0:1], 0, s[6:7]
	global_load_dword v56, v[10:11], off
	v_lshl_add_u64 v[10:11], v[2:3], 0, s[6:7]
	s_or_b32 s6, s4, 0x14800
	global_load_dword v76, v[10:11], off
	v_lshl_add_u64 v[10:11], v[0:1], 0, s[6:7]
	global_load_dword v77, v[10:11], off
	v_lshl_add_u64 v[10:11], v[2:3], 0, s[6:7]
	s_or_b32 s6, s4, 0x15000
	global_load_dword v30, v[10:11], off
	v_lshl_add_u64 v[10:11], v[0:1], 0, s[6:7]
	global_load_dword v31, v[10:11], off
	v_lshl_add_u64 v[10:11], v[2:3], 0, s[6:7]
	s_or_b32 s6, s4, 0x15800
	global_load_dword v26, v[10:11], off
	v_lshl_add_u64 v[10:11], v[0:1], 0, s[6:7]
	global_load_dword v27, v[10:11], off
	v_lshl_add_u64 v[10:11], v[2:3], 0, s[6:7]
	s_or_b32 s6, s4, 0x16000
	global_load_dword v22, v[10:11], off
	v_lshl_add_u64 v[10:11], v[0:1], 0, s[6:7]
	global_load_dword v23, v[10:11], off
	v_lshl_add_u64 v[10:11], v[2:3], 0, s[6:7]
	s_or_b32 s6, s4, 0x16800
	global_load_dword v18, v[10:11], off
	v_lshl_add_u64 v[10:11], v[0:1], 0, s[6:7]
	global_load_dword v19, v[10:11], off
	v_lshl_add_u64 v[10:11], v[2:3], 0, s[6:7]
	s_or_b32 s6, s4, 0x17000
	global_load_dword v14, v[10:11], off
	v_lshl_add_u64 v[10:11], v[0:1], 0, s[6:7]
	global_load_dword v15, v[10:11], off
	v_lshl_add_u64 v[10:11], v[2:3], 0, s[6:7]
	s_or_b32 s6, s4, 0x17800
	v_lshl_add_u64 v[36:37], v[0:1], 0, s[6:7]
	global_load_dword v10, v[10:11], off
	s_nop 0
	global_load_dword v11, v[36:37], off
	v_lshl_add_u64 v[36:37], v[2:3], 0, s[6:7]
	global_load_dword v7, v[36:37], off
	s_waitcnt vmcnt(62)
	v_lshlrev_b32_e32 v36, 16, v57
	v_and_b32_e32 v37, 0xffff0000, v57
	v_exp_f32_e32 v38, v36
	v_exp_f32_e32 v39, v37
	v_pk_add_f32 v[32:33], v[32:33], v[36:37]
	v_lshlrev_b32_e32 v36, 16, v58
	v_and_b32_e32 v37, 0xffff0000, v58
	v_pk_fma_f32 v[34:35], v[34:35], v[38:39], v[36:37]
	s_waitcnt vmcnt(61)
	v_lshlrev_b32_e32 v36, 16, v59
	v_and_b32_e32 v37, 0xffff0000, v59
	v_exp_f32_e32 v38, v36
	v_exp_f32_e32 v39, v37
	v_pk_add_f32 v[32:33], v[32:33], v[36:37]
	s_waitcnt vmcnt(60)
	v_lshlrev_b32_e32 v36, 16, v60
	v_and_b32_e32 v37, 0xffff0000, v60
	v_pk_fma_f32 v[34:35], v[34:35], v[38:39], v[36:37]
	s_waitcnt vmcnt(59)
	v_lshlrev_b32_e32 v36, 16, v61
	v_and_b32_e32 v37, 0xffff0000, v61
	v_exp_f32_e32 v38, v36
	v_exp_f32_e32 v39, v37
	v_pk_add_f32 v[32:33], v[32:33], v[36:37]
	s_waitcnt vmcnt(58)
	v_lshlrev_b32_e32 v36, 16, v62
	v_and_b32_e32 v37, 0xffff0000, v62
	v_pk_fma_f32 v[34:35], v[34:35], v[38:39], v[36:37]
	s_waitcnt vmcnt(57)
	v_lshlrev_b32_e32 v36, 16, v63
	v_and_b32_e32 v37, 0xffff0000, v63
	v_exp_f32_e32 v38, v36
	v_exp_f32_e32 v39, v37
	v_pk_add_f32 v[32:33], v[32:33], v[36:37]
	s_waitcnt vmcnt(56)
	v_lshlrev_b32_e32 v36, 16, v64
	v_and_b32_e32 v37, 0xffff0000, v64
	v_pk_fma_f32 v[34:35], v[34:35], v[38:39], v[36:37]
	s_waitcnt vmcnt(55)
	v_lshlrev_b32_e32 v36, 16, v65
	v_and_b32_e32 v37, 0xffff0000, v65
	v_exp_f32_e32 v38, v36
	v_exp_f32_e32 v39, v37
	v_pk_add_f32 v[32:33], v[32:33], v[36:37]
	s_waitcnt vmcnt(54)
	v_lshlrev_b32_e32 v36, 16, v66
	v_and_b32_e32 v37, 0xffff0000, v66
	v_pk_fma_f32 v[34:35], v[34:35], v[38:39], v[36:37]
	s_waitcnt vmcnt(53)
	v_lshlrev_b32_e32 v36, 16, v67
	v_and_b32_e32 v37, 0xffff0000, v67
	v_exp_f32_e32 v38, v36
	v_exp_f32_e32 v39, v37
	v_pk_add_f32 v[32:33], v[32:33], v[36:37]
	s_waitcnt vmcnt(52)
	v_lshlrev_b32_e32 v36, 16, v68
	v_and_b32_e32 v37, 0xffff0000, v68
	v_pk_fma_f32 v[34:35], v[34:35], v[38:39], v[36:37]
	s_waitcnt vmcnt(51)
	v_lshlrev_b32_e32 v36, 16, v69
	v_and_b32_e32 v37, 0xffff0000, v69
	v_exp_f32_e32 v38, v36
	v_exp_f32_e32 v39, v37
	v_pk_add_f32 v[32:33], v[32:33], v[36:37]
	s_waitcnt vmcnt(50)
	v_lshlrev_b32_e32 v36, 16, v70
	v_and_b32_e32 v37, 0xffff0000, v70
	v_pk_fma_f32 v[34:35], v[34:35], v[38:39], v[36:37]
	s_waitcnt vmcnt(49)
	v_lshlrev_b32_e32 v36, 16, v71
	v_and_b32_e32 v37, 0xffff0000, v71
	v_exp_f32_e32 v38, v36
	v_exp_f32_e32 v39, v37
	v_pk_add_f32 v[32:33], v[32:33], v[36:37]
	s_waitcnt vmcnt(48)
; __device__ __forceinline__ float bf_lo(unsigned w) { return __uint_as_float(w << 16); }
; __device__ __forceinline__ float bf_hi(unsigned w) { return __uint_as_float(w & 0xffff0000u); }
; template <int L> __device__ __forceinline__ void layer_body(const Args& args, LAS unsigned char* lds, const int G, const int lo, const int hi, const int wave_s, unsigned& nbar) {
;     ...
;                     for (int t = 0; t < 16; ++t) { lw[0][t] = *(const unsigned*)(LA + (t0 + t) * D + 2 * tid); uw[0][t] = *(const unsigned*)(UU + (t0 + t) * D + 2 * tid); }
; #pragma unroll
;                     for (int tbi = 0; tbi < 8; ++tbi) { const int cb = tbi & 1, nb = cb ^ 1;
;                         if (tbi < 7) {
; #pragma unroll
;                             for (int t = 0; t < 16; ++t) { lw[nb][t] = *(const unsigned*)(LA + (t0 + (tbi + 1) * 16 + t) * D + 2 * tid); uw[nb][t] = *(const unsigned*)(UU + (t0 + (tbi + 1) * 16 + t) * D + 2 * tid); } }
; #pragma unroll
;                         for (int t = 0; t < 16; ++t) { const f32x2 l2 = {bf_lo(lw[cb][t]), bf_hi(lw[cb][t])}; const f32x2 a = {__builtin_amdgcn_exp2f(l2[0]), __builtin_amdgcn_exp2f(l2[1])};
;                             Ls += l2; Up = a * Up + (f32x2){bf_lo(uw[cb][t]), bf_hi(uw[cb][t])}; }
	v_lshlrev_b32_e32 v36, 16, v72
	v_and_b32_e32 v37, 0xffff0000, v72
	v_pk_fma_f32 v[34:35], v[34:35], v[38:39], v[36:37]
	s_waitcnt vmcnt(47)
	v_lshlrev_b32_e32 v36, 16, v73
	v_and_b32_e32 v37, 0xffff0000, v73
	v_exp_f32_e32 v38, v36
	v_exp_f32_e32 v39, v37
	v_pk_add_f32 v[32:33], v[32:33], v[36:37]
	s_waitcnt vmcnt(46)
	v_lshlrev_b32_e32 v36, 16, v74
	v_and_b32_e32 v37, 0xffff0000, v74
	v_pk_fma_f32 v[34:35], v[34:35], v[38:39], v[36:37]
	s_waitcnt vmcnt(45)
	v_lshlrev_b32_e32 v36, 16, v75
	v_and_b32_e32 v37, 0xffff0000, v75
	v_exp_f32_e32 v38, v36
	v_exp_f32_e32 v39, v37
	v_pk_add_f32 v[32:33], v[32:33], v[36:37]
	s_waitcnt vmcnt(44)
	v_lshlrev_b32_e32 v36, 16, v28
	v_and_b32_e32 v37, 0xffff0000, v28
	s_waitcnt vmcnt(43)
	v_lshlrev_b32_e32 v28, 16, v29
	v_and_b32_e32 v29, 0xffff0000, v29
	v_pk_fma_f32 v[34:35], v[34:35], v[38:39], v[36:37]
	v_exp_f32_e32 v36, v28
	v_exp_f32_e32 v37, v29
	v_pk_add_f32 v[28:29], v[32:33], v[28:29]
	s_waitcnt vmcnt(42)
	v_lshlrev_b32_e32 v32, 16, v24
	v_and_b32_e32 v33, 0xffff0000, v24
	s_waitcnt vmcnt(41)
	v_lshlrev_b32_e32 v24, 16, v25
	v_and_b32_e32 v25, 0xffff0000, v25
	v_pk_fma_f32 v[32:33], v[34:35], v[36:37], v[32:33]
	v_exp_f32_e32 v34, v24
	v_exp_f32_e32 v35, v25
	v_pk_add_f32 v[24:25], v[28:29], v[24:25]
	s_waitcnt vmcnt(40)
	v_lshlrev_b32_e32 v28, 16, v20
	v_and_b32_e32 v29, 0xffff0000, v20
	s_waitcnt vmcnt(39)
	v_lshlrev_b32_e32 v20, 16, v21
	v_and_b32_e32 v21, 0xffff0000, v21
	v_pk_fma_f32 v[28:29], v[32:33], v[34:35], v[28:29]
	v_exp_f32_e32 v32, v20
	v_exp_f32_e32 v33, v21
	v_pk_add_f32 v[20:21], v[24:25], v[20:21]
	s_waitcnt vmcnt(38)
	v_lshlrev_b32_e32 v24, 16, v16
	v_and_b32_e32 v25, 0xffff0000, v16
	s_waitcnt vmcnt(37)
	v_lshlrev_b32_e32 v16, 16, v17
	v_and_b32_e32 v17, 0xffff0000, v17
	v_pk_fma_f32 v[24:25], v[28:29], v[32:33], v[24:25]
	v_exp_f32_e32 v28, v16
	v_exp_f32_e32 v29, v17
	v_pk_add_f32 v[16:17], v[20:21], v[16:17]
	s_waitcnt vmcnt(36)
	v_lshlrev_b32_e32 v20, 16, v12
	v_and_b32_e32 v21, 0xffff0000, v12
	s_waitcnt vmcnt(35)
	v_lshlrev_b32_e32 v12, 16, v13
	v_and_b32_e32 v13, 0xffff0000, v13
	v_pk_fma_f32 v[20:21], v[24:25], v[28:29], v[20:21]
	v_exp_f32_e32 v24, v12
	v_exp_f32_e32 v25, v13
	v_pk_add_f32 v[12:13], v[16:17], v[12:13]
	s_waitcnt vmcnt(34)
	v_lshlrev_b32_e32 v16, 16, v8
	v_and_b32_e32 v17, 0xffff0000, v8
	s_waitcnt vmcnt(33)
	v_lshlrev_b32_e32 v8, 16, v9
	v_and_b32_e32 v9, 0xffff0000, v9
	v_pk_fma_f32 v[16:17], v[20:21], v[24:25], v[16:17]
	v_exp_f32_e32 v20, v8
	v_exp_f32_e32 v21, v9
	v_pk_add_f32 v[32:33], v[12:13], v[8:9]
	s_waitcnt vmcnt(32)
	v_lshlrev_b32_e32 v8, 16, v6
	v_and_b32_e32 v9, 0xffff0000, v6
	s_or_b32 s6, s4, 0x18000
	v_pk_fma_f32 v[34:35], v[16:17], v[20:21], v[8:9]
	v_lshl_add_u64 v[8:9], v[0:1], 0, s[6:7]
	global_load_dword v57, v[8:9], off
	v_lshl_add_u64 v[8:9], v[2:3], 0, s[6:7]
	s_or_b32 s6, s4, 0x18800
	global_load_dword v58, v[8:9], off
	v_lshl_add_u64 v[8:9], v[0:1], 0, s[6:7]
	global_load_dword v59, v[8:9], off
	v_lshl_add_u64 v[8:9], v[2:3], 0, s[6:7]
	s_or_b32 s6, s4, 0x19000
	global_load_dword v60, v[8:9], off
	v_lshl_add_u64 v[8:9], v[0:1], 0, s[6:7]
	global_load_dword v61, v[8:9], off
	v_lshl_add_u64 v[8:9], v[2:3], 0, s[6:7]
	s_or_b32 s6, s4, 0x19800
	global_load_dword v62, v[8:9], off
	v_lshl_add_u64 v[8:9], v[0:1], 0, s[6:7]
	global_load_dword v63, v[8:9], off
	v_lshl_add_u64 v[8:9], v[2:3], 0, s[6:7]
	s_or_b32 s6, s4, 0x1a000
	global_load_dword v64, v[8:9], off
	v_lshl_add_u64 v[8:9], v[0:1], 0, s[6:7]
	global_load_dword v65, v[8:9], off
	v_lshl_add_u64 v[8:9], v[2:3], 0, s[6:7]
	s_or_b32 s6, s4, 0x1a800
	global_load_dword v66, v[8:9], off
	v_lshl_add_u64 v[8:9], v[0:1], 0, s[6:7]
	global_load_dword v67, v[8:9], off
	v_lshl_add_u64 v[8:9], v[2:3], 0, s[6:7]
	s_or_b32 s6, s4, 0x1b000
	global_load_dword v68, v[8:9], off
	v_lshl_add_u64 v[8:9], v[0:1], 0, s[6:7]
	global_load_dword v69, v[8:9], off
	v_lshl_add_u64 v[8:9], v[2:3], 0, s[6:7]
	s_or_b32 s6, s4, 0x1b800
	global_load_dword v70, v[8:9], off
	v_lshl_add_u64 v[8:9], v[0:1], 0, s[6:7]
	global_load_dword v71, v[8:9], off
	v_lshl_add_u64 v[8:9], v[2:3], 0, s[6:7]
	s_or_b32 s6, s4, 0x1c000
	global_load_dword v72, v[8:9], off
	v_lshl_add_u64 v[8:9], v[0:1], 0, s[6:7]
	global_load_dword v73, v[8:9], off
	v_lshl_add_u64 v[8:9], v[2:3], 0, s[6:7]
	s_or_b32 s6, s4, 0x1c800
	global_load_dword v74, v[8:9], off
	v_lshl_add_u64 v[8:9], v[0:1], 0, s[6:7]
	global_load_dword v75, v[8:9], off
	v_lshl_add_u64 v[8:9], v[2:3], 0, s[6:7]
	s_or_b32 s6, s4, 0x1d000
	global_load_dword v28, v[8:9], off
	v_lshl_add_u64 v[8:9], v[0:1], 0, s[6:7]
	global_load_dword v29, v[8:9], off
	v_lshl_add_u64 v[8:9], v[2:3], 0, s[6:7]
	s_or_b32 s6, s4, 0x1d800
	global_load_dword v24, v[8:9], off
	v_lshl_add_u64 v[8:9], v[0:1], 0, s[6:7]
	global_load_dword v25, v[8:9], off
	v_lshl_add_u64 v[8:9], v[2:3], 0, s[6:7]
	s_or_b32 s6, s4, 0x1e000
	global_load_dword v20, v[8:9], off
	v_lshl_add_u64 v[8:9], v[0:1], 0, s[6:7]
	global_load_dword v21, v[8:9], off
	v_lshl_add_u64 v[8:9], v[2:3], 0, s[6:7]
	s_or_b32 s6, s4, 0x1e800
	global_load_dword v16, v[8:9], off
	v_lshl_add_u64 v[8:9], v[0:1], 0, s[6:7]
	global_load_dword v17, v[8:9], off
	v_lshl_add_u64 v[8:9], v[2:3], 0, s[6:7]
	s_or_b32 s6, s4, 0x1f000
	global_load_dword v12, v[8:9], off
	v_lshl_add_u64 v[8:9], v[0:1], 0, s[6:7]
	global_load_dword v13, v[8:9], off
	v_lshl_add_u64 v[8:9], v[2:3], 0, s[6:7]
	s_or_b32 s6, s4, 0x1f800
	v_lshl_add_u64 v[36:37], v[0:1], 0, s[6:7]
	global_load_dword v8, v[8:9], off
	s_nop 0
	global_load_dword v9, v[36:37], off
	v_lshl_add_u64 v[36:37], v[2:3], 0, s[6:7]
	global_load_dword v6, v[36:37], off
	s_waitcnt vmcnt(62)
; __device__ __forceinline__ float bf_lo(unsigned w) { return __uint_as_float(w << 16); }
; __device__ __forceinline__ float bf_hi(unsigned w) { return __uint_as_float(w & 0xffff0000u); }
; template <int L> __device__ __forceinline__ void layer_body(const Args& args, LAS unsigned char* lds, const int G, const int lo, const int hi, const int wave_s, unsigned& nbar) {
;     ...
;                     for (int t = 0; t < 16; ++t) { lw[0][t] = *(const unsigned*)(LA + (t0 + t) * D + 2 * tid); uw[0][t] = *(const unsigned*)(UU + (t0 + t) * D + 2 * tid); }
; #pragma unroll
;                     for (int tbi = 0; tbi < 8; ++tbi) { const int cb = tbi & 1, nb = cb ^ 1;
;                         if (tbi < 7) {
; #pragma unroll
;                             for (int t = 0; t < 16; ++t) { lw[nb][t] = *(const unsigned*)(LA + (t0 + (tbi + 1) * 16 + t) * D + 2 * tid); uw[nb][t] = *(const unsigned*)(UU + (t0 + (tbi + 1) * 16 + t) * D + 2 * tid); } }
; #pragma unroll
;                         for (int t = 0; t < 16; ++t) { const f32x2 l2 = {bf_lo(lw[cb][t]), bf_hi(lw[cb][t])}; const f32x2 a = {__builtin_amdgcn_exp2f(l2[0]), __builtin_amdgcn_exp2f(l2[1])};
;                             Ls += l2; Up = a * Up + (f32x2){bf_lo(uw[cb][t]), bf_hi(uw[cb][t])}; }
	v_lshlrev_b32_e32 v36, 16, v40
	v_and_b32_e32 v37, 0xffff0000, v40
	v_exp_f32_e32 v38, v36
	v_exp_f32_e32 v39, v37
	v_pk_add_f32 v[32:33], v[32:33], v[36:37]
	v_lshlrev_b32_e32 v36, 16, v41
	v_and_b32_e32 v37, 0xffff0000, v41
	v_pk_fma_f32 v[34:35], v[34:35], v[38:39], v[36:37]
	s_waitcnt vmcnt(61)
	v_lshlrev_b32_e32 v36, 16, v42
	v_and_b32_e32 v37, 0xffff0000, v42
	v_exp_f32_e32 v38, v36
	v_exp_f32_e32 v39, v37
	v_pk_add_f32 v[32:33], v[32:33], v[36:37]
	s_waitcnt vmcnt(60)
	v_lshlrev_b32_e32 v36, 16, v43
	v_and_b32_e32 v37, 0xffff0000, v43
	v_pk_fma_f32 v[34:35], v[34:35], v[38:39], v[36:37]
	s_waitcnt vmcnt(59)
	v_lshlrev_b32_e32 v36, 16, v44
	v_and_b32_e32 v37, 0xffff0000, v44
	v_exp_f32_e32 v38, v36
	v_exp_f32_e32 v39, v37
	v_pk_add_f32 v[32:33], v[32:33], v[36:37]
	s_waitcnt vmcnt(58)
	v_lshlrev_b32_e32 v36, 16, v45
	v_and_b32_e32 v37, 0xffff0000, v45
	v_pk_fma_f32 v[34:35], v[34:35], v[38:39], v[36:37]
	s_waitcnt vmcnt(57)
	v_lshlrev_b32_e32 v36, 16, v46
	v_and_b32_e32 v37, 0xffff0000, v46
	v_exp_f32_e32 v38, v36
	v_exp_f32_e32 v39, v37
	v_pk_add_f32 v[32:33], v[32:33], v[36:37]
	s_waitcnt vmcnt(56)
	v_lshlrev_b32_e32 v36, 16, v47
	v_and_b32_e32 v37, 0xffff0000, v47
	v_pk_fma_f32 v[34:35], v[34:35], v[38:39], v[36:37]
	s_waitcnt vmcnt(55)
	v_lshlrev_b32_e32 v36, 16, v48
	v_and_b32_e32 v37, 0xffff0000, v48
	v_exp_f32_e32 v38, v36
	v_exp_f32_e32 v39, v37
	v_pk_add_f32 v[32:33], v[32:33], v[36:37]
	s_waitcnt vmcnt(54)
	v_lshlrev_b32_e32 v36, 16, v49
	v_and_b32_e32 v37, 0xffff0000, v49
	v_pk_fma_f32 v[34:35], v[34:35], v[38:39], v[36:37]
	s_waitcnt vmcnt(53)
	v_lshlrev_b32_e32 v36, 16, v50
	v_and_b32_e32 v37, 0xffff0000, v50
	v_exp_f32_e32 v38, v36
	v_exp_f32_e32 v39, v37
	v_pk_add_f32 v[32:33], v[32:33], v[36:37]
	s_waitcnt vmcnt(52)
	v_lshlrev_b32_e32 v36, 16, v51
	v_and_b32_e32 v37, 0xffff0000, v51
	v_pk_fma_f32 v[34:35], v[34:35], v[38:39], v[36:37]
	s_waitcnt vmcnt(51)
	v_lshlrev_b32_e32 v36, 16, v52
	v_and_b32_e32 v37, 0xffff0000, v52
	v_exp_f32_e32 v38, v36
	v_exp_f32_e32 v39, v37
	v_pk_add_f32 v[32:33], v[32:33], v[36:37]
	s_waitcnt vmcnt(50)
	v_lshlrev_b32_e32 v36, 16, v53
	v_and_b32_e32 v37, 0xffff0000, v53
	v_pk_fma_f32 v[34:35], v[34:35], v[38:39], v[36:37]
	s_waitcnt vmcnt(49)
	v_lshlrev_b32_e32 v36, 16, v54
	v_and_b32_e32 v37, 0xffff0000, v54
	v_exp_f32_e32 v38, v36
	v_exp_f32_e32 v39, v37
	v_pk_add_f32 v[32:33], v[32:33], v[36:37]
	s_waitcnt vmcnt(48)
	v_lshlrev_b32_e32 v36, 16, v55
	v_and_b32_e32 v37, 0xffff0000, v55
	v_pk_fma_f32 v[34:35], v[34:35], v[38:39], v[36:37]
	s_waitcnt vmcnt(47)
	v_lshlrev_b32_e32 v36, 16, v56
	v_and_b32_e32 v37, 0xffff0000, v56
	v_exp_f32_e32 v38, v36
	v_exp_f32_e32 v39, v37
	v_pk_add_f32 v[32:33], v[32:33], v[36:37]
	s_waitcnt vmcnt(46)
	v_lshlrev_b32_e32 v36, 16, v76
	v_and_b32_e32 v37, 0xffff0000, v76
	v_pk_fma_f32 v[34:35], v[34:35], v[38:39], v[36:37]
	s_waitcnt vmcnt(45)
	v_lshlrev_b32_e32 v36, 16, v77
	v_and_b32_e32 v37, 0xffff0000, v77
	v_exp_f32_e32 v38, v36
	v_exp_f32_e32 v39, v37
	v_pk_add_f32 v[32:33], v[32:33], v[36:37]
	s_waitcnt vmcnt(44)
	v_lshlrev_b32_e32 v36, 16, v30
	v_and_b32_e32 v37, 0xffff0000, v30
	s_waitcnt vmcnt(43)
	v_lshlrev_b32_e32 v30, 16, v31
	v_and_b32_e32 v31, 0xffff0000, v31
	v_pk_fma_f32 v[34:35], v[34:35], v[38:39], v[36:37]
	v_exp_f32_e32 v36, v30
	v_exp_f32_e32 v37, v31
	v_pk_add_f32 v[30:31], v[32:33], v[30:31]
	s_waitcnt vmcnt(42)
	v_lshlrev_b32_e32 v32, 16, v26
	v_and_b32_e32 v33, 0xffff0000, v26
	s_waitcnt vmcnt(41)
	v_lshlrev_b32_e32 v26, 16, v27
	v_and_b32_e32 v27, 0xffff0000, v27
	v_pk_fma_f32 v[32:33], v[34:35], v[36:37], v[32:33]
	v_exp_f32_e32 v34, v26
	v_exp_f32_e32 v35, v27
	v_pk_add_f32 v[26:27], v[30:31], v[26:27]
	s_waitcnt vmcnt(40)
	v_lshlrev_b32_e32 v30, 16, v22
	v_and_b32_e32 v31, 0xffff0000, v22
	s_waitcnt vmcnt(39)
	v_lshlrev_b32_e32 v22, 16, v23
	v_and_b32_e32 v23, 0xffff0000, v23
	v_pk_fma_f32 v[30:31], v[32:33], v[34:35], v[30:31]
	v_exp_f32_e32 v32, v22
	v_exp_f32_e32 v33, v23
	v_pk_add_f32 v[22:23], v[26:27], v[22:23]
	s_waitcnt vmcnt(38)
	v_lshlrev_b32_e32 v26, 16, v18
	v_and_b32_e32 v27, 0xffff0000, v18
	s_waitcnt vmcnt(37)
	v_lshlrev_b32_e32 v18, 16, v19
	v_and_b32_e32 v19, 0xffff0000, v19
	v_pk_fma_f32 v[26:27], v[30:31], v[32:33], v[26:27]
	v_exp_f32_e32 v30, v18
	v_exp_f32_e32 v31, v19
	v_pk_add_f32 v[18:19], v[22:23], v[18:19]
	s_waitcnt vmcnt(36)
	v_lshlrev_b32_e32 v22, 16, v14
	v_and_b32_e32 v23, 0xffff0000, v14
	s_waitcnt vmcnt(35)
	v_lshlrev_b32_e32 v14, 16, v15
	v_and_b32_e32 v15, 0xffff0000, v15
	v_pk_fma_f32 v[22:23], v[26:27], v[30:31], v[22:23]
	v_exp_f32_e32 v26, v14
	v_exp_f32_e32 v27, v15
	v_pk_add_f32 v[14:15], v[18:19], v[14:15]
	s_waitcnt vmcnt(34)
	v_lshlrev_b32_e32 v18, 16, v10
	v_and_b32_e32 v19, 0xffff0000, v10
	s_waitcnt vmcnt(33)
	v_lshlrev_b32_e32 v10, 16, v11
	v_and_b32_e32 v11, 0xffff0000, v11
	v_pk_fma_f32 v[18:19], v[22:23], v[26:27], v[18:19]
	v_exp_f32_e32 v22, v10
	v_exp_f32_e32 v23, v11
	v_pk_add_f32 v[32:33], v[14:15], v[10:11]
	s_waitcnt vmcnt(32)
; __device__ __forceinline__ float bf_lo(unsigned w) { return __uint_as_float(w << 16); }
; __device__ __forceinline__ float bf_hi(unsigned w) { return __uint_as_float(w & 0xffff0000u); }
; template <int L> __device__ __forceinline__ void layer_body(const Args& args, LAS unsigned char* lds, const int G, const int lo, const int hi, const int wave_s, unsigned& nbar) {
;     ...
;                     for (int t = 0; t < 16; ++t) { lw[0][t] = *(const unsigned*)(LA + (t0 + t) * D + 2 * tid); uw[0][t] = *(const unsigned*)(UU + (t0 + t) * D + 2 * tid); }
; #pragma unroll
;                     for (int tbi = 0; tbi < 8; ++tbi) { const int cb = tbi & 1, nb = cb ^ 1;
;                         if (tbi < 7) {
; #pragma unroll
;                             for (int t = 0; t < 16; ++t) { lw[nb][t] = *(const unsigned*)(LA + (t0 + (tbi + 1) * 16 + t) * D + 2 * tid); uw[nb][t] = *(const unsigned*)(UU + (t0 + (tbi + 1) * 16 + t) * D + 2 * tid); } }
; #pragma unroll
;                         for (int t = 0; t < 16; ++t) { const f32x2 l2 = {bf_lo(lw[cb][t]), bf_hi(lw[cb][t])}; const f32x2 a = {__builtin_amdgcn_exp2f(l2[0]), __builtin_amdgcn_exp2f(l2[1])};
;                             Ls += l2; Up = a * Up + (f32x2){bf_lo(uw[cb][t]), bf_hi(uw[cb][t])}; }
	v_lshlrev_b32_e32 v10, 16, v7
	v_and_b32_e32 v11, 0xffff0000, v7
	s_or_b32 s6, s4, 0x20000
	v_pk_fma_f32 v[34:35], v[18:19], v[22:23], v[10:11]
	v_lshl_add_u64 v[10:11], v[0:1], 0, s[6:7]
	global_load_dword v40, v[10:11], off
	v_lshl_add_u64 v[10:11], v[2:3], 0, s[6:7]
	s_or_b32 s6, s4, 0x20800
	global_load_dword v42, v[10:11], off
	v_lshl_add_u64 v[10:11], v[0:1], 0, s[6:7]
	global_load_dword v43, v[10:11], off
	v_lshl_add_u64 v[10:11], v[2:3], 0, s[6:7]
	s_or_b32 s6, s4, 0x21000
	global_load_dword v44, v[10:11], off
	v_lshl_add_u64 v[10:11], v[0:1], 0, s[6:7]
	global_load_dword v45, v[10:11], off
	v_lshl_add_u64 v[10:11], v[2:3], 0, s[6:7]
	s_or_b32 s6, s4, 0x21800
	global_load_dword v46, v[10:11], off
	v_lshl_add_u64 v[10:11], v[0:1], 0, s[6:7]
	global_load_dword v47, v[10:11], off
	v_lshl_add_u64 v[10:11], v[2:3], 0, s[6:7]
	s_or_b32 s6, s4, 0x22000
	global_load_dword v48, v[10:11], off
	v_lshl_add_u64 v[10:11], v[0:1], 0, s[6:7]
	global_load_dword v49, v[10:11], off
	v_lshl_add_u64 v[10:11], v[2:3], 0, s[6:7]
	s_or_b32 s6, s4, 0x22800
	global_load_dword v50, v[10:11], off
	v_lshl_add_u64 v[10:11], v[0:1], 0, s[6:7]
	global_load_dword v51, v[10:11], off
	v_lshl_add_u64 v[10:11], v[2:3], 0, s[6:7]
	s_or_b32 s6, s4, 0x23000
	global_load_dword v52, v[10:11], off
	v_lshl_add_u64 v[10:11], v[0:1], 0, s[6:7]
	global_load_dword v53, v[10:11], off
	v_lshl_add_u64 v[10:11], v[2:3], 0, s[6:7]
	s_or_b32 s6, s4, 0x23800
	global_load_dword v54, v[10:11], off
	v_lshl_add_u64 v[10:11], v[0:1], 0, s[6:7]
	global_load_dword v55, v[10:11], off
	v_lshl_add_u64 v[10:11], v[2:3], 0, s[6:7]
	s_or_b32 s6, s4, 0x24000
	global_load_dword v56, v[10:11], off
	v_lshl_add_u64 v[10:11], v[0:1], 0, s[6:7]
	global_load_dword v76, v[10:11], off
	v_lshl_add_u64 v[10:11], v[2:3], 0, s[6:7]
	s_or_b32 s6, s4, 0x24800
	global_load_dword v77, v[10:11], off
	v_lshl_add_u64 v[10:11], v[0:1], 0, s[6:7]
	global_load_dword v78, v[10:11], off
	v_lshl_add_u64 v[10:11], v[2:3], 0, s[6:7]
	s_or_b32 s6, s4, 0x25000
	global_load_dword v30, v[10:11], off
	v_lshl_add_u64 v[10:11], v[0:1], 0, s[6:7]
	global_load_dword v31, v[10:11], off
	v_lshl_add_u64 v[10:11], v[2:3], 0, s[6:7]
	s_or_b32 s6, s4, 0x25800
	global_load_dword v26, v[10:11], off
	v_lshl_add_u64 v[10:11], v[0:1], 0, s[6:7]
	global_load_dword v27, v[10:11], off
	v_lshl_add_u64 v[10:11], v[2:3], 0, s[6:7]
	s_or_b32 s6, s4, 0x26000
	global_load_dword v22, v[10:11], off
	v_lshl_add_u64 v[10:11], v[0:1], 0, s[6:7]
	global_load_dword v23, v[10:11], off
	v_lshl_add_u64 v[10:11], v[2:3], 0, s[6:7]
	s_or_b32 s6, s4, 0x26800
	global_load_dword v18, v[10:11], off
	v_lshl_add_u64 v[10:11], v[0:1], 0, s[6:7]
	global_load_dword v19, v[10:11], off
	v_lshl_add_u64 v[10:11], v[2:3], 0, s[6:7]
	s_or_b32 s6, s4, 0x27000
	global_load_dword v14, v[10:11], off
	v_lshl_add_u64 v[10:11], v[0:1], 0, s[6:7]
	global_load_dword v15, v[10:11], off
	v_lshl_add_u64 v[10:11], v[2:3], 0, s[6:7]
	s_or_b32 s6, s4, 0x27800
	v_lshl_add_u64 v[36:37], v[0:1], 0, s[6:7]
	global_load_dword v10, v[10:11], off
	s_nop 0
	global_load_dword v11, v[36:37], off
	v_lshl_add_u64 v[36:37], v[2:3], 0, s[6:7]
	global_load_dword v7, v[36:37], off
	s_waitcnt vmcnt(62)
	v_lshlrev_b32_e32 v36, 16, v57
	v_and_b32_e32 v37, 0xffff0000, v57
	v_exp_f32_e32 v38, v36
	v_exp_f32_e32 v39, v37
	v_pk_add_f32 v[32:33], v[32:33], v[36:37]
	v_lshlrev_b32_e32 v36, 16, v58
	v_and_b32_e32 v37, 0xffff0000, v58
	v_pk_fma_f32 v[34:35], v[34:35], v[38:39], v[36:37]
	s_waitcnt vmcnt(61)
	v_lshlrev_b32_e32 v36, 16, v59
	v_and_b32_e32 v37, 0xffff0000, v59
	v_exp_f32_e32 v38, v36
	v_exp_f32_e32 v39, v37
	v_pk_add_f32 v[32:33], v[32:33], v[36:37]
	s_waitcnt vmcnt(60)
	v_lshlrev_b32_e32 v36, 16, v60
	v_and_b32_e32 v37, 0xffff0000, v60
	v_pk_fma_f32 v[34:35], v[34:35], v[38:39], v[36:37]
	s_waitcnt vmcnt(59)
	v_lshlrev_b32_e32 v36, 16, v61
	v_and_b32_e32 v37, 0xffff0000, v61
	v_exp_f32_e32 v38, v36
	v_exp_f32_e32 v39, v37
	v_pk_add_f32 v[32:33], v[32:33], v[36:37]
	s_waitcnt vmcnt(58)
	v_lshlrev_b32_e32 v36, 16, v62
	v_and_b32_e32 v37, 0xffff0000, v62
	v_pk_fma_f32 v[34:35], v[34:35], v[38:39], v[36:37]
	s_waitcnt vmcnt(57)
	v_lshlrev_b32_e32 v36, 16, v63
	v_and_b32_e32 v37, 0xffff0000, v63
	v_exp_f32_e32 v38, v36
	v_exp_f32_e32 v39, v37
	v_pk_add_f32 v[32:33], v[32:33], v[36:37]
	s_waitcnt vmcnt(56)
	v_lshlrev_b32_e32 v36, 16, v64
	v_and_b32_e32 v37, 0xffff0000, v64
	v_pk_fma_f32 v[34:35], v[34:35], v[38:39], v[36:37]
	s_waitcnt vmcnt(55)
	v_lshlrev_b32_e32 v36, 16, v65
	v_and_b32_e32 v37, 0xffff0000, v65
	v_exp_f32_e32 v38, v36
	v_exp_f32_e32 v39, v37
	v_pk_add_f32 v[32:33], v[32:33], v[36:37]
	s_waitcnt vmcnt(54)
	v_lshlrev_b32_e32 v36, 16, v66
	v_and_b32_e32 v37, 0xffff0000, v66
	v_pk_fma_f32 v[34:35], v[34:35], v[38:39], v[36:37]
	s_waitcnt vmcnt(53)
	v_lshlrev_b32_e32 v36, 16, v67
	v_and_b32_e32 v37, 0xffff0000, v67
	v_exp_f32_e32 v38, v36
	v_exp_f32_e32 v39, v37
	v_pk_add_f32 v[32:33], v[32:33], v[36:37]
	s_waitcnt vmcnt(52)
	v_lshlrev_b32_e32 v36, 16, v68
	v_and_b32_e32 v37, 0xffff0000, v68
	v_pk_fma_f32 v[34:35], v[34:35], v[38:39], v[36:37]
	s_waitcnt vmcnt(51)
	v_lshlrev_b32_e32 v36, 16, v69
	v_and_b32_e32 v37, 0xffff0000, v69
	v_exp_f32_e32 v38, v36
	v_exp_f32_e32 v39, v37
	v_pk_add_f32 v[32:33], v[32:33], v[36:37]
	s_waitcnt vmcnt(50)
	v_lshlrev_b32_e32 v36, 16, v70
	v_and_b32_e32 v37, 0xffff0000, v70
	v_pk_fma_f32 v[34:35], v[34:35], v[38:39], v[36:37]
	s_waitcnt vmcnt(49)
	v_lshlrev_b32_e32 v36, 16, v71
	v_and_b32_e32 v37, 0xffff0000, v71
	v_exp_f32_e32 v38, v36
	v_exp_f32_e32 v39, v37
	v_pk_add_f32 v[32:33], v[32:33], v[36:37]
	s_waitcnt vmcnt(48)
; __device__ __forceinline__ float bf_lo(unsigned w) { return __uint_as_float(w << 16); }
; __device__ __forceinline__ float bf_hi(unsigned w) { return __uint_as_float(w & 0xffff0000u); }
; template <int L> __device__ __forceinline__ void layer_body(const Args& args, LAS unsigned char* lds, const int G, const int lo, const int hi, const int wave_s, unsigned& nbar) {
;     ...
;                     for (int t = 0; t < 16; ++t) { lw[0][t] = *(const unsigned*)(LA + (t0 + t) * D + 2 * tid); uw[0][t] = *(const unsigned*)(UU + (t0 + t) * D + 2 * tid); }
; #pragma unroll
;                     for (int tbi = 0; tbi < 8; ++tbi) { const int cb = tbi & 1, nb = cb ^ 1;
;                         if (tbi < 7) {
; #pragma unroll
;                             for (int t = 0; t < 16; ++t) { lw[nb][t] = *(const unsigned*)(LA + (t0 + (tbi + 1) * 16 + t) * D + 2 * tid); uw[nb][t] = *(const unsigned*)(UU + (t0 + (tbi + 1) * 16 + t) * D + 2 * tid); } }
; #pragma unroll
;                         for (int t = 0; t < 16; ++t) { const f32x2 l2 = {bf_lo(lw[cb][t]), bf_hi(lw[cb][t])}; const f32x2 a = {__builtin_amdgcn_exp2f(l2[0]), __builtin_amdgcn_exp2f(l2[1])};
;                             Ls += l2; Up = a * Up + (f32x2){bf_lo(uw[cb][t]), bf_hi(uw[cb][t])}; }
	v_lshlrev_b32_e32 v36, 16, v72
	v_and_b32_e32 v37, 0xffff0000, v72
	v_pk_fma_f32 v[34:35], v[34:35], v[38:39], v[36:37]
	s_waitcnt vmcnt(47)
	v_lshlrev_b32_e32 v36, 16, v73
	v_and_b32_e32 v37, 0xffff0000, v73
	v_exp_f32_e32 v38, v36
	v_exp_f32_e32 v39, v37
	v_pk_add_f32 v[32:33], v[32:33], v[36:37]
	s_waitcnt vmcnt(46)
	v_lshlrev_b32_e32 v36, 16, v74
	v_and_b32_e32 v37, 0xffff0000, v74
	v_pk_fma_f32 v[34:35], v[34:35], v[38:39], v[36:37]
	s_waitcnt vmcnt(45)
	v_lshlrev_b32_e32 v36, 16, v75
	v_and_b32_e32 v37, 0xffff0000, v75
	v_exp_f32_e32 v38, v36
	v_exp_f32_e32 v39, v37
	v_pk_add_f32 v[32:33], v[32:33], v[36:37]
	s_waitcnt vmcnt(44)
	v_lshlrev_b32_e32 v36, 16, v28
	v_and_b32_e32 v37, 0xffff0000, v28
	s_waitcnt vmcnt(43)
	v_lshlrev_b32_e32 v28, 16, v29
	v_and_b32_e32 v29, 0xffff0000, v29
	v_pk_fma_f32 v[34:35], v[34:35], v[38:39], v[36:37]
	v_exp_f32_e32 v36, v28
	v_exp_f32_e32 v37, v29
	v_pk_add_f32 v[28:29], v[32:33], v[28:29]
	s_waitcnt vmcnt(42)
	v_lshlrev_b32_e32 v32, 16, v24
	v_and_b32_e32 v33, 0xffff0000, v24
	s_waitcnt vmcnt(41)
	v_lshlrev_b32_e32 v24, 16, v25
	v_and_b32_e32 v25, 0xffff0000, v25
	v_pk_fma_f32 v[32:33], v[34:35], v[36:37], v[32:33]
	v_exp_f32_e32 v34, v24
	v_exp_f32_e32 v35, v25
	v_pk_add_f32 v[24:25], v[28:29], v[24:25]
	s_waitcnt vmcnt(40)
	v_lshlrev_b32_e32 v28, 16, v20
	v_and_b32_e32 v29, 0xffff0000, v20
	s_waitcnt vmcnt(39)
	v_lshlrev_b32_e32 v20, 16, v21
	v_and_b32_e32 v21, 0xffff0000, v21
	v_pk_fma_f32 v[28:29], v[32:33], v[34:35], v[28:29]
	v_exp_f32_e32 v32, v20
	v_exp_f32_e32 v33, v21
	v_pk_add_f32 v[20:21], v[24:25], v[20:21]
	s_waitcnt vmcnt(38)
	v_lshlrev_b32_e32 v24, 16, v16
	v_and_b32_e32 v25, 0xffff0000, v16
	s_waitcnt vmcnt(37)
	v_lshlrev_b32_e32 v16, 16, v17
	v_and_b32_e32 v17, 0xffff0000, v17
	v_pk_fma_f32 v[24:25], v[28:29], v[32:33], v[24:25]
	v_exp_f32_e32 v28, v16
	v_exp_f32_e32 v29, v17
	v_pk_add_f32 v[16:17], v[20:21], v[16:17]
	s_waitcnt vmcnt(36)
	v_lshlrev_b32_e32 v20, 16, v12
	v_and_b32_e32 v21, 0xffff0000, v12
	s_waitcnt vmcnt(35)
	v_lshlrev_b32_e32 v12, 16, v13
	v_and_b32_e32 v13, 0xffff0000, v13
	v_pk_fma_f32 v[20:21], v[24:25], v[28:29], v[20:21]
	v_exp_f32_e32 v24, v12
	v_exp_f32_e32 v25, v13
	v_pk_add_f32 v[12:13], v[16:17], v[12:13]
	s_waitcnt vmcnt(34)
	v_lshlrev_b32_e32 v16, 16, v8
	v_and_b32_e32 v17, 0xffff0000, v8
	s_waitcnt vmcnt(33)
	v_lshlrev_b32_e32 v8, 16, v9
	v_and_b32_e32 v9, 0xffff0000, v9
	v_pk_fma_f32 v[16:17], v[20:21], v[24:25], v[16:17]
	v_exp_f32_e32 v20, v8
	v_exp_f32_e32 v21, v9
	v_pk_add_f32 v[34:35], v[12:13], v[8:9]
	s_waitcnt vmcnt(32)
	v_lshlrev_b32_e32 v8, 16, v6
	v_and_b32_e32 v9, 0xffff0000, v6
	s_or_b32 s6, s4, 0x28000
	v_pk_fma_f32 v[36:37], v[16:17], v[20:21], v[8:9]
	v_lshl_add_u64 v[8:9], v[0:1], 0, s[6:7]
	global_load_dword v33, v[8:9], off
	v_lshl_add_u64 v[8:9], v[2:3], 0, s[6:7]
	s_or_b32 s6, s4, 0x28800
	global_load_dword v57, v[8:9], off
	v_lshl_add_u64 v[8:9], v[0:1], 0, s[6:7]
	global_load_dword v58, v[8:9], off
	v_lshl_add_u64 v[8:9], v[2:3], 0, s[6:7]
	s_or_b32 s6, s4, 0x29000
	global_load_dword v59, v[8:9], off
	v_lshl_add_u64 v[8:9], v[0:1], 0, s[6:7]
	global_load_dword v60, v[8:9], off
	v_lshl_add_u64 v[8:9], v[2:3], 0, s[6:7]
	s_or_b32 s6, s4, 0x29800
	global_load_dword v61, v[8:9], off
	v_lshl_add_u64 v[8:9], v[0:1], 0, s[6:7]
	global_load_dword v62, v[8:9], off
	v_lshl_add_u64 v[8:9], v[2:3], 0, s[6:7]
	s_or_b32 s6, s4, 0x2a000
	global_load_dword v63, v[8:9], off
	v_lshl_add_u64 v[8:9], v[0:1], 0, s[6:7]
	global_load_dword v64, v[8:9], off
	v_lshl_add_u64 v[8:9], v[2:3], 0, s[6:7]
	s_or_b32 s6, s4, 0x2a800
	global_load_dword v65, v[8:9], off
	v_lshl_add_u64 v[8:9], v[0:1], 0, s[6:7]
	global_load_dword v66, v[8:9], off
	v_lshl_add_u64 v[8:9], v[2:3], 0, s[6:7]
	s_or_b32 s6, s4, 0x2b000
	global_load_dword v67, v[8:9], off
	v_lshl_add_u64 v[8:9], v[0:1], 0, s[6:7]
	global_load_dword v68, v[8:9], off
	v_lshl_add_u64 v[8:9], v[2:3], 0, s[6:7]
	s_or_b32 s6, s4, 0x2b800
	global_load_dword v69, v[8:9], off
	v_lshl_add_u64 v[8:9], v[0:1], 0, s[6:7]
	global_load_dword v70, v[8:9], off
	v_lshl_add_u64 v[8:9], v[2:3], 0, s[6:7]
	s_or_b32 s6, s4, 0x2c000
	global_load_dword v71, v[8:9], off
	v_lshl_add_u64 v[8:9], v[0:1], 0, s[6:7]
	global_load_dword v72, v[8:9], off
	v_lshl_add_u64 v[8:9], v[2:3], 0, s[6:7]
	s_or_b32 s6, s4, 0x2c800
	global_load_dword v73, v[8:9], off
	v_lshl_add_u64 v[8:9], v[0:1], 0, s[6:7]
	global_load_dword v74, v[8:9], off
	v_lshl_add_u64 v[8:9], v[2:3], 0, s[6:7]
	s_or_b32 s6, s4, 0x2d000
	global_load_dword v29, v[8:9], off
	v_lshl_add_u64 v[8:9], v[0:1], 0, s[6:7]
	global_load_dword v32, v[8:9], off
	v_lshl_add_u64 v[8:9], v[2:3], 0, s[6:7]
	s_or_b32 s6, s4, 0x2d800
	global_load_dword v25, v[8:9], off
	v_lshl_add_u64 v[8:9], v[0:1], 0, s[6:7]
	global_load_dword v28, v[8:9], off
	v_lshl_add_u64 v[8:9], v[2:3], 0, s[6:7]
	s_or_b32 s6, s4, 0x2e000
	global_load_dword v21, v[8:9], off
	v_lshl_add_u64 v[8:9], v[0:1], 0, s[6:7]
	global_load_dword v24, v[8:9], off
	v_lshl_add_u64 v[8:9], v[2:3], 0, s[6:7]
	s_or_b32 s6, s4, 0x2e800
	global_load_dword v17, v[8:9], off
	v_lshl_add_u64 v[8:9], v[0:1], 0, s[6:7]
	global_load_dword v20, v[8:9], off
	v_lshl_add_u64 v[8:9], v[2:3], 0, s[6:7]
	s_or_b32 s6, s4, 0x2f000
	global_load_dword v12, v[8:9], off
	v_lshl_add_u64 v[8:9], v[0:1], 0, s[6:7]
	global_load_dword v13, v[8:9], off
	v_lshl_add_u64 v[8:9], v[2:3], 0, s[6:7]
	s_or_b32 s6, s4, 0x2f800
	global_load_dword v6, v[8:9], off
	v_lshl_add_u64 v[8:9], v[0:1], 0, s[6:7]
	v_lshl_add_u64 v[38:39], v[2:3], 0, s[6:7]
	global_load_dword v9, v[8:9], off
	s_or_b32 s6, s4, 0x30000
	global_load_dword v8, v[38:39], off
	s_waitcnt vmcnt(62)
; __device__ __forceinline__ float bf_lo(unsigned w) { return __uint_as_float(w << 16); }
; __device__ __forceinline__ float bf_hi(unsigned w) { return __uint_as_float(w & 0xffff0000u); }
; template <int L> __device__ __forceinline__ void layer_body(const Args& args, LAS unsigned char* lds, const int G, const int lo, const int hi, const int wave_s, unsigned& nbar) {
;     ...
;                     for (int t = 0; t < 16; ++t) { lw[0][t] = *(const unsigned*)(LA + (t0 + t) * D + 2 * tid); uw[0][t] = *(const unsigned*)(UU + (t0 + t) * D + 2 * tid); }
; #pragma unroll
;                     for (int tbi = 0; tbi < 8; ++tbi) { const int cb = tbi & 1, nb = cb ^ 1;
;                         if (tbi < 7) {
; #pragma unroll
;                             for (int t = 0; t < 16; ++t) { lw[nb][t] = *(const unsigned*)(LA + (t0 + (tbi + 1) * 16 + t) * D + 2 * tid); uw[nb][t] = *(const unsigned*)(UU + (t0 + (tbi + 1) * 16 + t) * D + 2 * tid); } }
; #pragma unroll
;                         for (int t = 0; t < 16; ++t) { const f32x2 l2 = {bf_lo(lw[cb][t]), bf_hi(lw[cb][t])}; const f32x2 a = {__builtin_amdgcn_exp2f(l2[0]), __builtin_amdgcn_exp2f(l2[1])};
;                             Ls += l2; Up = a * Up + (f32x2){bf_lo(uw[cb][t]), bf_hi(uw[cb][t])}; }
	v_lshlrev_b32_e32 v38, 16, v40
	v_and_b32_e32 v39, 0xffff0000, v40
	v_exp_f32_e32 v40, v38
	v_exp_f32_e32 v41, v39
	v_pk_add_f32 v[34:35], v[34:35], v[38:39]
	v_lshlrev_b32_e32 v38, 16, v42
	v_and_b32_e32 v39, 0xffff0000, v42
	v_pk_fma_f32 v[36:37], v[36:37], v[40:41], v[38:39]
	s_waitcnt vmcnt(61)
	v_lshlrev_b32_e32 v38, 16, v43
	v_and_b32_e32 v39, 0xffff0000, v43
	v_exp_f32_e32 v40, v38
	v_exp_f32_e32 v41, v39
	v_pk_add_f32 v[34:35], v[34:35], v[38:39]
	s_waitcnt vmcnt(60)
	v_lshlrev_b32_e32 v38, 16, v44
	v_and_b32_e32 v39, 0xffff0000, v44
	v_pk_fma_f32 v[36:37], v[36:37], v[40:41], v[38:39]
	s_waitcnt vmcnt(59)
	v_lshlrev_b32_e32 v38, 16, v45
	v_and_b32_e32 v39, 0xffff0000, v45
	v_exp_f32_e32 v40, v38
	v_exp_f32_e32 v41, v39
	v_pk_add_f32 v[34:35], v[34:35], v[38:39]
	s_waitcnt vmcnt(58)
	v_lshlrev_b32_e32 v38, 16, v46
	v_and_b32_e32 v39, 0xffff0000, v46
	v_pk_fma_f32 v[36:37], v[36:37], v[40:41], v[38:39]
	s_waitcnt vmcnt(57)
	v_lshlrev_b32_e32 v38, 16, v47
	v_and_b32_e32 v39, 0xffff0000, v47
	v_exp_f32_e32 v40, v38
	v_exp_f32_e32 v41, v39
	v_pk_add_f32 v[34:35], v[34:35], v[38:39]
	s_waitcnt vmcnt(56)
	v_lshlrev_b32_e32 v38, 16, v48
	v_and_b32_e32 v39, 0xffff0000, v48
	v_pk_fma_f32 v[36:37], v[36:37], v[40:41], v[38:39]
	s_waitcnt vmcnt(55)
	v_lshlrev_b32_e32 v38, 16, v49
	v_and_b32_e32 v39, 0xffff0000, v49
	v_exp_f32_e32 v40, v38
	v_exp_f32_e32 v41, v39
	v_pk_add_f32 v[34:35], v[34:35], v[38:39]
	s_waitcnt vmcnt(54)
	v_lshlrev_b32_e32 v38, 16, v50
	v_and_b32_e32 v39, 0xffff0000, v50
	v_pk_fma_f32 v[36:37], v[36:37], v[40:41], v[38:39]
	s_waitcnt vmcnt(53)
	v_lshlrev_b32_e32 v38, 16, v51
	v_and_b32_e32 v39, 0xffff0000, v51
	v_exp_f32_e32 v40, v38
	v_exp_f32_e32 v41, v39
	v_pk_add_f32 v[34:35], v[34:35], v[38:39]
	s_waitcnt vmcnt(52)
	v_lshlrev_b32_e32 v38, 16, v52
	v_and_b32_e32 v39, 0xffff0000, v52
	v_pk_fma_f32 v[36:37], v[36:37], v[40:41], v[38:39]
	s_waitcnt vmcnt(51)
	v_lshlrev_b32_e32 v38, 16, v53
	v_and_b32_e32 v39, 0xffff0000, v53
	v_exp_f32_e32 v40, v38
	v_exp_f32_e32 v41, v39
	v_pk_add_f32 v[34:35], v[34:35], v[38:39]
	s_waitcnt vmcnt(50)
	v_lshlrev_b32_e32 v38, 16, v54
	v_and_b32_e32 v39, 0xffff0000, v54
	v_pk_fma_f32 v[36:37], v[36:37], v[40:41], v[38:39]
	s_waitcnt vmcnt(49)
	v_lshlrev_b32_e32 v38, 16, v55
	v_and_b32_e32 v39, 0xffff0000, v55
	v_exp_f32_e32 v40, v38
	v_exp_f32_e32 v41, v39
	v_pk_add_f32 v[34:35], v[34:35], v[38:39]
	s_waitcnt vmcnt(48)
	v_lshlrev_b32_e32 v38, 16, v56
	v_and_b32_e32 v39, 0xffff0000, v56
	v_pk_fma_f32 v[36:37], v[36:37], v[40:41], v[38:39]
	s_waitcnt vmcnt(47)
	v_lshlrev_b32_e32 v38, 16, v76
	v_and_b32_e32 v39, 0xffff0000, v76
	v_exp_f32_e32 v40, v38
	v_exp_f32_e32 v41, v39
	v_pk_add_f32 v[34:35], v[34:35], v[38:39]
	s_waitcnt vmcnt(46)
	v_lshlrev_b32_e32 v38, 16, v77
	v_and_b32_e32 v39, 0xffff0000, v77
	v_pk_fma_f32 v[36:37], v[36:37], v[40:41], v[38:39]
	s_waitcnt vmcnt(45)
	v_lshlrev_b32_e32 v38, 16, v78
	v_and_b32_e32 v39, 0xffff0000, v78
	v_exp_f32_e32 v40, v38
	v_exp_f32_e32 v41, v39
	v_pk_add_f32 v[34:35], v[34:35], v[38:39]
	s_waitcnt vmcnt(44)
	v_lshlrev_b32_e32 v38, 16, v30
	v_and_b32_e32 v39, 0xffff0000, v30
	s_waitcnt vmcnt(43)
	v_lshlrev_b32_e32 v30, 16, v31
	v_and_b32_e32 v31, 0xffff0000, v31
	v_pk_fma_f32 v[36:37], v[36:37], v[40:41], v[38:39]
	v_exp_f32_e32 v38, v30
	v_exp_f32_e32 v39, v31
	v_pk_add_f32 v[30:31], v[34:35], v[30:31]
	s_waitcnt vmcnt(42)
	v_lshlrev_b32_e32 v34, 16, v26
	v_and_b32_e32 v35, 0xffff0000, v26
	s_waitcnt vmcnt(41)
	v_lshlrev_b32_e32 v26, 16, v27
	v_and_b32_e32 v27, 0xffff0000, v27
	v_pk_fma_f32 v[34:35], v[36:37], v[38:39], v[34:35]
	v_exp_f32_e32 v36, v26
	v_exp_f32_e32 v37, v27
	v_pk_add_f32 v[26:27], v[30:31], v[26:27]
	s_waitcnt vmcnt(40)
	v_lshlrev_b32_e32 v30, 16, v22
	v_and_b32_e32 v31, 0xffff0000, v22
	s_waitcnt vmcnt(39)
	v_lshlrev_b32_e32 v22, 16, v23
	v_and_b32_e32 v23, 0xffff0000, v23
	v_pk_fma_f32 v[30:31], v[34:35], v[36:37], v[30:31]
	v_exp_f32_e32 v34, v22
	v_exp_f32_e32 v35, v23
	v_pk_add_f32 v[22:23], v[26:27], v[22:23]
	s_waitcnt vmcnt(38)
	v_lshlrev_b32_e32 v26, 16, v18
	v_and_b32_e32 v27, 0xffff0000, v18
	s_waitcnt vmcnt(37)
	v_lshlrev_b32_e32 v18, 16, v19
	v_and_b32_e32 v19, 0xffff0000, v19
	v_pk_fma_f32 v[26:27], v[30:31], v[34:35], v[26:27]
	v_exp_f32_e32 v30, v18
	v_exp_f32_e32 v31, v19
	v_pk_add_f32 v[18:19], v[22:23], v[18:19]
	s_waitcnt vmcnt(36)
	v_lshlrev_b32_e32 v22, 16, v14
	v_and_b32_e32 v23, 0xffff0000, v14
	s_waitcnt vmcnt(35)
	v_lshlrev_b32_e32 v14, 16, v15
	v_and_b32_e32 v15, 0xffff0000, v15
	v_pk_fma_f32 v[22:23], v[26:27], v[30:31], v[22:23]
	v_exp_f32_e32 v26, v14
	v_exp_f32_e32 v27, v15
	v_pk_add_f32 v[14:15], v[18:19], v[14:15]
	s_waitcnt vmcnt(34)
	v_lshlrev_b32_e32 v18, 16, v10
	v_and_b32_e32 v19, 0xffff0000, v10
	s_waitcnt vmcnt(33)
	v_lshlrev_b32_e32 v10, 16, v11
	v_and_b32_e32 v11, 0xffff0000, v11
	v_pk_fma_f32 v[18:19], v[22:23], v[26:27], v[18:19]
	v_exp_f32_e32 v22, v10
	v_exp_f32_e32 v23, v11
	v_pk_add_f32 v[34:35], v[14:15], v[10:11]
	s_waitcnt vmcnt(32)
; __device__ __forceinline__ float bf_lo(unsigned w) { return __uint_as_float(w << 16); }
; __device__ __forceinline__ float bf_hi(unsigned w) { return __uint_as_float(w & 0xffff0000u); }
; template <int L> __device__ __forceinline__ void layer_body(const Args& args, LAS unsigned char* lds, const int G, const int lo, const int hi, const int wave_s, unsigned& nbar) {
;     ...
;                     for (int t = 0; t < 16; ++t) { lw[0][t] = *(const unsigned*)(LA + (t0 + t) * D + 2 * tid); uw[0][t] = *(const unsigned*)(UU + (t0 + t) * D + 2 * tid); }
; #pragma unroll
;                     for (int tbi = 0; tbi < 8; ++tbi) { const int cb = tbi & 1, nb = cb ^ 1;
;                         if (tbi < 7) {
; #pragma unroll
;                             for (int t = 0; t < 16; ++t) { lw[nb][t] = *(const unsigned*)(LA + (t0 + (tbi + 1) * 16 + t) * D + 2 * tid); uw[nb][t] = *(const unsigned*)(UU + (t0 + (tbi + 1) * 16 + t) * D + 2 * tid); } }
; #pragma unroll
;                         for (int t = 0; t < 16; ++t) { const f32x2 l2 = {bf_lo(lw[cb][t]), bf_hi(lw[cb][t])}; const f32x2 a = {__builtin_amdgcn_exp2f(l2[0]), __builtin_amdgcn_exp2f(l2[1])};
;                             Ls += l2; Up = a * Up + (f32x2){bf_lo(uw[cb][t]), bf_hi(uw[cb][t])}; }
	v_lshlrev_b32_e32 v10, 16, v7
	v_and_b32_e32 v11, 0xffff0000, v7
	v_pk_fma_f32 v[36:37], v[18:19], v[22:23], v[10:11]
	v_lshl_add_u64 v[10:11], v[0:1], 0, s[6:7]
	global_load_dword v42, v[10:11], off
	v_lshl_add_u64 v[10:11], v[2:3], 0, s[6:7]
	s_or_b32 s6, s4, 0x30800
	global_load_dword v43, v[10:11], off
	v_lshl_add_u64 v[10:11], v[0:1], 0, s[6:7]
	global_load_dword v44, v[10:11], off
	v_lshl_add_u64 v[10:11], v[2:3], 0, s[6:7]
	s_or_b32 s6, s4, 0x31000
	global_load_dword v45, v[10:11], off
	v_lshl_add_u64 v[10:11], v[0:1], 0, s[6:7]
	global_load_dword v46, v[10:11], off
	v_lshl_add_u64 v[10:11], v[2:3], 0, s[6:7]
	s_or_b32 s6, s4, 0x31800
	global_load_dword v47, v[10:11], off
	v_lshl_add_u64 v[10:11], v[0:1], 0, s[6:7]
	global_load_dword v48, v[10:11], off
	v_lshl_add_u64 v[10:11], v[2:3], 0, s[6:7]
	s_or_b32 s6, s4, 0x32000
	global_load_dword v49, v[10:11], off
	v_lshl_add_u64 v[10:11], v[0:1], 0, s[6:7]
	global_load_dword v50, v[10:11], off
	v_lshl_add_u64 v[10:11], v[2:3], 0, s[6:7]
	s_or_b32 s6, s4, 0x32800
	global_load_dword v51, v[10:11], off
	v_lshl_add_u64 v[10:11], v[0:1], 0, s[6:7]
	global_load_dword v52, v[10:11], off
	v_lshl_add_u64 v[10:11], v[2:3], 0, s[6:7]
	s_or_b32 s6, s4, 0x33000
	global_load_dword v53, v[10:11], off
	v_lshl_add_u64 v[10:11], v[0:1], 0, s[6:7]
	global_load_dword v54, v[10:11], off
	v_lshl_add_u64 v[10:11], v[2:3], 0, s[6:7]
	s_or_b32 s6, s4, 0x33800
	global_load_dword v55, v[10:11], off
	v_lshl_add_u64 v[10:11], v[0:1], 0, s[6:7]
	global_load_dword v56, v[10:11], off
	v_lshl_add_u64 v[10:11], v[2:3], 0, s[6:7]
	s_or_b32 s6, s4, 0x34000
	global_load_dword v75, v[10:11], off
	v_lshl_add_u64 v[10:11], v[0:1], 0, s[6:7]
	global_load_dword v76, v[10:11], off
	v_lshl_add_u64 v[10:11], v[2:3], 0, s[6:7]
	s_or_b32 s6, s4, 0x34800
	global_load_dword v77, v[10:11], off
	v_lshl_add_u64 v[10:11], v[0:1], 0, s[6:7]
	global_load_dword v78, v[10:11], off
	v_lshl_add_u64 v[10:11], v[2:3], 0, s[6:7]
	s_or_b32 s6, s4, 0x35000
	global_load_dword v30, v[10:11], off
	v_lshl_add_u64 v[10:11], v[0:1], 0, s[6:7]
	global_load_dword v31, v[10:11], off
	v_lshl_add_u64 v[10:11], v[2:3], 0, s[6:7]
	s_or_b32 s6, s4, 0x35800
	global_load_dword v26, v[10:11], off
	v_lshl_add_u64 v[10:11], v[0:1], 0, s[6:7]
	global_load_dword v27, v[10:11], off
	v_lshl_add_u64 v[10:11], v[2:3], 0, s[6:7]
	s_or_b32 s6, s4, 0x36000
	global_load_dword v22, v[10:11], off
	v_lshl_add_u64 v[10:11], v[0:1], 0, s[6:7]
	global_load_dword v23, v[10:11], off
	v_lshl_add_u64 v[10:11], v[2:3], 0, s[6:7]
	s_or_b32 s6, s4, 0x36800
	global_load_dword v18, v[10:11], off
	v_lshl_add_u64 v[10:11], v[0:1], 0, s[6:7]
	global_load_dword v19, v[10:11], off
	v_lshl_add_u64 v[10:11], v[2:3], 0, s[6:7]
	s_or_b32 s6, s4, 0x37000
	global_load_dword v15, v[10:11], off
	v_lshl_add_u64 v[10:11], v[0:1], 0, s[6:7]
	global_load_dword v16, v[10:11], off
	v_lshl_add_u64 v[10:11], v[2:3], 0, s[6:7]
	s_or_b32 s6, s4, 0x37800
	v_lshl_add_u64 v[38:39], v[0:1], 0, s[6:7]
	global_load_dword v14, v[38:39], off
	v_lshl_add_u64 v[38:39], v[2:3], 0, s[6:7]
	global_load_dword v11, v[10:11], off
	s_waitcnt vmcnt(32)
	v_and_b32_e32 v7, 0xffff0000, v9
	global_load_dword v10, v[38:39], off
	v_lshlrev_b32_e32 v38, 16, v33
	v_and_b32_e32 v39, 0xffff0000, v33
	v_exp_f32_e32 v40, v38
	v_exp_f32_e32 v41, v39
	v_pk_add_f32 v[34:35], v[34:35], v[38:39]
	v_lshlrev_b32_e32 v38, 16, v57
	v_and_b32_e32 v39, 0xffff0000, v57
	v_pk_fma_f32 v[36:37], v[36:37], v[40:41], v[38:39]
	v_lshlrev_b32_e32 v38, 16, v58
	v_and_b32_e32 v39, 0xffff0000, v58
	v_exp_f32_e32 v40, v38
	v_exp_f32_e32 v41, v39
	v_pk_add_f32 v[34:35], v[34:35], v[38:39]
	v_lshlrev_b32_e32 v38, 16, v59
	v_and_b32_e32 v39, 0xffff0000, v59
	v_pk_fma_f32 v[36:37], v[36:37], v[40:41], v[38:39]
	v_lshlrev_b32_e32 v38, 16, v60
	v_and_b32_e32 v39, 0xffff0000, v60
	v_exp_f32_e32 v40, v38
	v_exp_f32_e32 v41, v39
	v_pk_add_f32 v[34:35], v[34:35], v[38:39]
	v_lshlrev_b32_e32 v38, 16, v61
	v_and_b32_e32 v39, 0xffff0000, v61
	v_pk_fma_f32 v[36:37], v[36:37], v[40:41], v[38:39]
	v_lshlrev_b32_e32 v38, 16, v62
	v_and_b32_e32 v39, 0xffff0000, v62
	v_exp_f32_e32 v40, v38
	v_exp_f32_e32 v41, v39
	v_pk_add_f32 v[34:35], v[34:35], v[38:39]
	v_lshlrev_b32_e32 v38, 16, v63
	v_and_b32_e32 v39, 0xffff0000, v63
	v_pk_fma_f32 v[36:37], v[36:37], v[40:41], v[38:39]
	v_lshlrev_b32_e32 v38, 16, v64
	v_and_b32_e32 v39, 0xffff0000, v64
	v_exp_f32_e32 v40, v38
	v_exp_f32_e32 v41, v39
	v_pk_add_f32 v[34:35], v[34:35], v[38:39]
	v_lshlrev_b32_e32 v38, 16, v65
	v_and_b32_e32 v39, 0xffff0000, v65
	v_pk_fma_f32 v[36:37], v[36:37], v[40:41], v[38:39]
	v_lshlrev_b32_e32 v38, 16, v66
	v_and_b32_e32 v39, 0xffff0000, v66
	v_exp_f32_e32 v40, v38
	v_exp_f32_e32 v41, v39
	v_pk_add_f32 v[34:35], v[34:35], v[38:39]
	v_lshlrev_b32_e32 v38, 16, v67
	v_and_b32_e32 v39, 0xffff0000, v67
	v_pk_fma_f32 v[36:37], v[36:37], v[40:41], v[38:39]
	v_lshlrev_b32_e32 v38, 16, v68
	v_and_b32_e32 v39, 0xffff0000, v68
	v_exp_f32_e32 v40, v38
	v_exp_f32_e32 v41, v39
	v_pk_add_f32 v[34:35], v[34:35], v[38:39]
	v_lshlrev_b32_e32 v38, 16, v69
	v_and_b32_e32 v39, 0xffff0000, v69
	v_pk_fma_f32 v[36:37], v[36:37], v[40:41], v[38:39]
	v_lshlrev_b32_e32 v38, 16, v70
	v_and_b32_e32 v39, 0xffff0000, v70
	v_exp_f32_e32 v40, v38
	v_exp_f32_e32 v41, v39
	v_pk_add_f32 v[34:35], v[34:35], v[38:39]
	v_lshlrev_b32_e32 v38, 16, v71
	v_and_b32_e32 v39, 0xffff0000, v71
	v_pk_fma_f32 v[36:37], v[36:37], v[40:41], v[38:39]
	v_lshlrev_b32_e32 v38, 16, v72
	v_and_b32_e32 v39, 0xffff0000, v72
	v_exp_f32_e32 v40, v38
	v_exp_f32_e32 v41, v39
	v_pk_add_f32 v[34:35], v[34:35], v[38:39]
	v_lshlrev_b32_e32 v38, 16, v73
	v_and_b32_e32 v39, 0xffff0000, v73
; __device__ __forceinline__ float bf_lo(unsigned w) { return __uint_as_float(w << 16); }
; __device__ __forceinline__ float bf_hi(unsigned w) { return __uint_as_float(w & 0xffff0000u); }
; template <int L> __device__ __forceinline__ void layer_body(const Args& args, LAS unsigned char* lds, const int G, const int lo, const int hi, const int wave_s, unsigned& nbar) {
;     ...
;                     for (int t = 0; t < 16; ++t) { lw[0][t] = *(const unsigned*)(LA + (t0 + t) * D + 2 * tid); uw[0][t] = *(const unsigned*)(UU + (t0 + t) * D + 2 * tid); }
; #pragma unroll
;                     for (int tbi = 0; tbi < 8; ++tbi) { const int cb = tbi & 1, nb = cb ^ 1;
;                         if (tbi < 7) {
; #pragma unroll
;                             for (int t = 0; t < 16; ++t) { lw[nb][t] = *(const unsigned*)(LA + (t0 + (tbi + 1) * 16 + t) * D + 2 * tid); uw[nb][t] = *(const unsigned*)(UU + (t0 + (tbi + 1) * 16 + t) * D + 2 * tid); } }
; #pragma unroll
;                         for (int t = 0; t < 16; ++t) { const f32x2 l2 = {bf_lo(lw[cb][t]), bf_hi(lw[cb][t])}; const f32x2 a = {__builtin_amdgcn_exp2f(l2[0]), __builtin_amdgcn_exp2f(l2[1])};
;                             Ls += l2; Up = a * Up + (f32x2){bf_lo(uw[cb][t]), bf_hi(uw[cb][t])}; }
	v_pk_fma_f32 v[36:37], v[36:37], v[40:41], v[38:39]
	v_lshlrev_b32_e32 v38, 16, v74
	v_and_b32_e32 v39, 0xffff0000, v74
	v_exp_f32_e32 v40, v38
	v_exp_f32_e32 v41, v39
	v_pk_add_f32 v[34:35], v[34:35], v[38:39]
	v_lshlrev_b32_e32 v38, 16, v29
	v_and_b32_e32 v39, 0xffff0000, v29
	v_pk_fma_f32 v[36:37], v[36:37], v[40:41], v[38:39]
	v_lshlrev_b32_e32 v38, 16, v32
	v_and_b32_e32 v39, 0xffff0000, v32
	v_exp_f32_e32 v32, v38
	v_exp_f32_e32 v33, v39
	v_pk_add_f32 v[34:35], v[34:35], v[38:39]
	v_lshlrev_b32_e32 v38, 16, v25
	v_and_b32_e32 v39, 0xffff0000, v25
	v_pk_fma_f32 v[32:33], v[36:37], v[32:33], v[38:39]
	v_lshlrev_b32_e32 v36, 16, v28
	v_and_b32_e32 v37, 0xffff0000, v28
	v_exp_f32_e32 v28, v36
	v_exp_f32_e32 v29, v37
	v_pk_add_f32 v[34:35], v[34:35], v[36:37]
	v_lshlrev_b32_e32 v36, 16, v21
	v_and_b32_e32 v37, 0xffff0000, v21
	v_pk_fma_f32 v[28:29], v[32:33], v[28:29], v[36:37]
	v_lshlrev_b32_e32 v32, 16, v24
	v_and_b32_e32 v33, 0xffff0000, v24
	v_exp_f32_e32 v24, v32
	v_exp_f32_e32 v25, v33
	v_pk_add_f32 v[32:33], v[34:35], v[32:33]
	v_lshlrev_b32_e32 v34, 16, v17
	v_and_b32_e32 v35, 0xffff0000, v17
	v_pk_fma_f32 v[24:25], v[28:29], v[24:25], v[34:35]
	v_lshlrev_b32_e32 v28, 16, v20
	v_and_b32_e32 v29, 0xffff0000, v20
	v_exp_f32_e32 v20, v28
	v_exp_f32_e32 v21, v29
	v_pk_add_f32 v[28:29], v[32:33], v[28:29]
	v_lshlrev_b32_e32 v32, 16, v12
	v_and_b32_e32 v33, 0xffff0000, v12
	v_lshlrev_b32_e32 v12, 16, v13
	v_and_b32_e32 v13, 0xffff0000, v13
	v_pk_fma_f32 v[20:21], v[24:25], v[20:21], v[32:33]
	v_exp_f32_e32 v24, v12
	v_exp_f32_e32 v25, v13
	v_pk_add_f32 v[12:13], v[28:29], v[12:13]
	v_lshlrev_b32_e32 v28, 16, v6
	v_and_b32_e32 v29, 0xffff0000, v6
	v_lshlrev_b32_e32 v6, 16, v9
	v_pk_fma_f32 v[20:21], v[20:21], v[24:25], v[28:29]
	v_exp_f32_e32 v24, v6
	v_exp_f32_e32 v25, v7
	v_pk_add_f32 v[6:7], v[12:13], v[6:7]
	s_waitcnt vmcnt(32)
	v_lshlrev_b32_e32 v12, 16, v8
	v_and_b32_e32 v13, 0xffff0000, v8
	s_or_b32 s6, s4, 0x38000
	v_pk_fma_f32 v[8:9], v[20:21], v[24:25], v[12:13]
	v_lshl_add_u64 v[12:13], v[0:1], 0, s[6:7]
	global_load_dword v57, v[12:13], off
	v_lshl_add_u64 v[12:13], v[2:3], 0, s[6:7]
	s_or_b32 s6, s4, 0x38800
	global_load_dword v58, v[12:13], off
	v_lshl_add_u64 v[12:13], v[0:1], 0, s[6:7]
	global_load_dword v59, v[12:13], off
	v_lshl_add_u64 v[12:13], v[2:3], 0, s[6:7]
	s_or_b32 s6, s4, 0x39000
	global_load_dword v60, v[12:13], off
	v_lshl_add_u64 v[12:13], v[0:1], 0, s[6:7]
	global_load_dword v61, v[12:13], off
	v_lshl_add_u64 v[12:13], v[2:3], 0, s[6:7]
	s_or_b32 s6, s4, 0x39800
	global_load_dword v62, v[12:13], off
	v_lshl_add_u64 v[12:13], v[0:1], 0, s[6:7]
	global_load_dword v63, v[12:13], off
	v_lshl_add_u64 v[12:13], v[2:3], 0, s[6:7]
	s_or_b32 s6, s4, 0x3a000
	global_load_dword v64, v[12:13], off
	v_lshl_add_u64 v[12:13], v[0:1], 0, s[6:7]
	global_load_dword v65, v[12:13], off
	v_lshl_add_u64 v[12:13], v[2:3], 0, s[6:7]
	s_or_b32 s6, s4, 0x3a800
	global_load_dword v66, v[12:13], off
	v_lshl_add_u64 v[12:13], v[0:1], 0, s[6:7]
	global_load_dword v67, v[12:13], off
	v_lshl_add_u64 v[12:13], v[2:3], 0, s[6:7]
	s_or_b32 s6, s4, 0x3b000
	global_load_dword v68, v[12:13], off
	v_lshl_add_u64 v[12:13], v[0:1], 0, s[6:7]
	global_load_dword v69, v[12:13], off
	v_lshl_add_u64 v[12:13], v[2:3], 0, s[6:7]
	s_or_b32 s6, s4, 0x3b800
	global_load_dword v70, v[12:13], off
	v_lshl_add_u64 v[12:13], v[0:1], 0, s[6:7]
	global_load_dword v71, v[12:13], off
	v_lshl_add_u64 v[12:13], v[2:3], 0, s[6:7]
	s_or_b32 s6, s4, 0x3c000
	global_load_dword v72, v[12:13], off
	v_lshl_add_u64 v[12:13], v[0:1], 0, s[6:7]
	global_load_dword v73, v[12:13], off
	v_lshl_add_u64 v[12:13], v[2:3], 0, s[6:7]
	s_or_b32 s6, s4, 0x3c800
	global_load_dword v74, v[12:13], off
	v_lshl_add_u64 v[12:13], v[0:1], 0, s[6:7]
	global_load_dword v79, v[12:13], off
	v_lshl_add_u64 v[12:13], v[2:3], 0, s[6:7]
	s_or_b32 s6, s4, 0x3d000
	global_load_dword v80, v[12:13], off
	v_lshl_add_u64 v[12:13], v[0:1], 0, s[6:7]
	global_load_dword v81, v[12:13], off
	v_lshl_add_u64 v[12:13], v[2:3], 0, s[6:7]
	s_or_b32 s6, s4, 0x3d800
	global_load_dword v82, v[12:13], off
	v_lshl_add_u64 v[12:13], v[0:1], 0, s[6:7]
	global_load_dword v83, v[12:13], off
	v_lshl_add_u64 v[12:13], v[2:3], 0, s[6:7]
	s_or_b32 s6, s4, 0x3e000
	global_load_dword v84, v[12:13], off
	v_lshl_add_u64 v[12:13], v[0:1], 0, s[6:7]
	global_load_dword v85, v[12:13], off
	v_lshl_add_u64 v[12:13], v[2:3], 0, s[6:7]
	s_or_b32 s6, s4, 0x3e800
	global_load_dword v86, v[12:13], off
	v_lshl_add_u64 v[12:13], v[0:1], 0, s[6:7]
	global_load_dword v87, v[12:13], off
	v_lshl_add_u64 v[12:13], v[2:3], 0, s[6:7]
	s_or_b32 s6, s4, 0x3f000
	global_load_dword v88, v[12:13], off
	v_lshl_add_u64 v[12:13], v[0:1], 0, s[6:7]
	global_load_dword v89, v[12:13], off
	v_lshl_add_u64 v[12:13], v[2:3], 0, s[6:7]
	s_or_b32 s4, s4, 0x3f800
	global_load_dword v90, v[12:13], off
	v_lshl_add_u64 v[12:13], v[0:1], 0, s[4:5]
	global_load_dword v91, v[12:13], off
	v_lshl_add_u64 v[12:13], v[2:3], 0, s[4:5]
	global_load_dword v92, v[12:13], off
	s_waitcnt vmcnt(62)
	v_lshlrev_b32_e32 v12, 16, v42
	v_and_b32_e32 v13, 0xffff0000, v42
	v_exp_f32_e32 v20, v12
	v_exp_f32_e32 v21, v13
	s_waitcnt vmcnt(61)
	v_lshlrev_b32_e32 v28, 16, v44
	v_and_b32_e32 v29, 0xffff0000, v44
	v_exp_f32_e32 v32, v28
	v_exp_f32_e32 v33, v29
	v_lshlrev_b32_e32 v24, 16, v43
	v_and_b32_e32 v25, 0xffff0000, v43
	v_pk_fma_f32 v[8:9], v[8:9], v[20:21], v[24:25]
	s_waitcnt vmcnt(60)
	v_lshlrev_b32_e32 v20, 16, v45
	v_and_b32_e32 v21, 0xffff0000, v45
	v_pk_fma_f32 v[8:9], v[8:9], v[32:33], v[20:21]
	s_waitcnt vmcnt(59)
; __device__ __forceinline__ float bf_lo(unsigned w) { return __uint_as_float(w << 16); }
; __device__ __forceinline__ float bf_hi(unsigned w) { return __uint_as_float(w & 0xffff0000u); }
; template <int L> __device__ __forceinline__ void layer_body(const Args& args, LAS unsigned char* lds, const int G, const int lo, const int hi, const int wave_s, unsigned& nbar) {
;     ...
;                     for (int t = 0; t < 16; ++t) { lw[0][t] = *(const unsigned*)(LA + (t0 + t) * D + 2 * tid); uw[0][t] = *(const unsigned*)(UU + (t0 + t) * D + 2 * tid); }
; #pragma unroll
;                     for (int tbi = 0; tbi < 8; ++tbi) { const int cb = tbi & 1, nb = cb ^ 1;
;                         if (tbi < 7) {
; #pragma unroll
;                             for (int t = 0; t < 16; ++t) { lw[nb][t] = *(const unsigned*)(LA + (t0 + (tbi + 1) * 16 + t) * D + 2 * tid); uw[nb][t] = *(const unsigned*)(UU + (t0 + (tbi + 1) * 16 + t) * D + 2 * tid); } }
; #pragma unroll
;                         for (int t = 0; t < 16; ++t) { const f32x2 l2 = {bf_lo(lw[cb][t]), bf_hi(lw[cb][t])}; const f32x2 a = {__builtin_amdgcn_exp2f(l2[0]), __builtin_amdgcn_exp2f(l2[1])};
;                             Ls += l2; Up = a * Up + (f32x2){bf_lo(uw[cb][t]), bf_hi(uw[cb][t])}; }
	v_lshlrev_b32_e32 v20, 16, v46
	v_and_b32_e32 v21, 0xffff0000, v46
	v_exp_f32_e32 v24, v20
	v_exp_f32_e32 v25, v21
	s_waitcnt vmcnt(57)
	v_lshlrev_b32_e32 v34, 16, v48
	v_and_b32_e32 v35, 0xffff0000, v48
	v_exp_f32_e32 v36, v34
	v_exp_f32_e32 v37, v35
	v_lshlrev_b32_e32 v32, 16, v47
	v_and_b32_e32 v33, 0xffff0000, v47
	v_pk_fma_f32 v[8:9], v[8:9], v[24:25], v[32:33]
	s_waitcnt vmcnt(56)
	v_lshlrev_b32_e32 v24, 16, v49
	v_and_b32_e32 v25, 0xffff0000, v49
	v_pk_fma_f32 v[8:9], v[8:9], v[36:37], v[24:25]
	s_waitcnt vmcnt(55)
	v_lshlrev_b32_e32 v24, 16, v50
	v_and_b32_e32 v25, 0xffff0000, v50
	v_exp_f32_e32 v32, v24
	v_exp_f32_e32 v33, v25
	s_waitcnt vmcnt(53)
	v_lshlrev_b32_e32 v38, 16, v52
	v_and_b32_e32 v39, 0xffff0000, v52
	v_exp_f32_e32 v40, v38
	v_exp_f32_e32 v41, v39
	v_lshlrev_b32_e32 v36, 16, v51
	v_and_b32_e32 v37, 0xffff0000, v51
	v_pk_fma_f32 v[8:9], v[8:9], v[32:33], v[36:37]
	s_waitcnt vmcnt(52)
	v_lshlrev_b32_e32 v32, 16, v53
	v_and_b32_e32 v33, 0xffff0000, v53
	v_pk_fma_f32 v[8:9], v[8:9], v[40:41], v[32:33]
	s_waitcnt vmcnt(51)
	v_lshlrev_b32_e32 v32, 16, v54
	v_and_b32_e32 v33, 0xffff0000, v54
	v_exp_f32_e32 v36, v32
	v_exp_f32_e32 v37, v33
	s_waitcnt vmcnt(49)
	v_lshlrev_b32_e32 v42, 16, v56
	v_and_b32_e32 v43, 0xffff0000, v56
	v_exp_f32_e32 v44, v42
	v_exp_f32_e32 v45, v43
	v_lshlrev_b32_e32 v40, 16, v55
	v_and_b32_e32 v41, 0xffff0000, v55
	v_pk_fma_f32 v[8:9], v[8:9], v[36:37], v[40:41]
	s_waitcnt vmcnt(48)
	v_lshlrev_b32_e32 v36, 16, v75
	v_and_b32_e32 v37, 0xffff0000, v75
	v_pk_fma_f32 v[8:9], v[8:9], v[44:45], v[36:37]
	s_waitcnt vmcnt(47)
	v_lshlrev_b32_e32 v36, 16, v76
	v_and_b32_e32 v37, 0xffff0000, v76
	v_exp_f32_e32 v40, v36
	v_exp_f32_e32 v41, v37
	s_waitcnt vmcnt(45)
	v_lshlrev_b32_e32 v46, 16, v78
	v_and_b32_e32 v47, 0xffff0000, v78
	v_exp_f32_e32 v48, v46
	v_exp_f32_e32 v49, v47
	v_lshlrev_b32_e32 v44, 16, v77
	v_and_b32_e32 v45, 0xffff0000, v77
	v_pk_fma_f32 v[8:9], v[8:9], v[40:41], v[44:45]
	s_waitcnt vmcnt(44)
	v_lshlrev_b32_e32 v40, 16, v30
	v_and_b32_e32 v41, 0xffff0000, v30
	s_waitcnt vmcnt(43)
	v_lshlrev_b32_e32 v30, 16, v31
	v_and_b32_e32 v31, 0xffff0000, v31
	v_pk_fma_f32 v[8:9], v[8:9], v[48:49], v[40:41]
	v_exp_f32_e32 v40, v30
	v_exp_f32_e32 v41, v31
	s_waitcnt vmcnt(42)
	v_lshlrev_b32_e32 v44, 16, v26
	v_and_b32_e32 v45, 0xffff0000, v26
	s_waitcnt vmcnt(41)
	v_lshlrev_b32_e32 v26, 16, v27
	v_and_b32_e32 v27, 0xffff0000, v27
	v_exp_f32_e32 v48, v26
	v_exp_f32_e32 v49, v27
	v_pk_add_f32 v[6:7], v[6:7], v[12:13]
	v_pk_fma_f32 v[8:9], v[8:9], v[40:41], v[44:45]
	s_waitcnt vmcnt(40)
	v_lshlrev_b32_e32 v40, 16, v22
	v_and_b32_e32 v41, 0xffff0000, v22
	s_waitcnt vmcnt(39)
	v_lshlrev_b32_e32 v22, 16, v23
	v_and_b32_e32 v23, 0xffff0000, v23
	v_pk_add_f32 v[6:7], v[6:7], v[28:29]
	v_pk_fma_f32 v[8:9], v[8:9], v[48:49], v[40:41]
	v_exp_f32_e32 v40, v22
	v_exp_f32_e32 v41, v23
	s_waitcnt vmcnt(38)
	v_lshlrev_b32_e32 v44, 16, v18
	v_and_b32_e32 v45, 0xffff0000, v18
	s_waitcnt vmcnt(37)
	v_lshlrev_b32_e32 v18, 16, v19
	v_and_b32_e32 v19, 0xffff0000, v19
	v_pk_add_f32 v[6:7], v[6:7], v[20:21]
	v_exp_f32_e32 v48, v18
	v_exp_f32_e32 v49, v19
	v_pk_add_f32 v[6:7], v[6:7], v[34:35]
	v_pk_fma_f32 v[8:9], v[8:9], v[40:41], v[44:45]
	v_pk_add_f32 v[6:7], v[6:7], v[24:25]
	s_waitcnt vmcnt(36)
	v_lshlrev_b32_e32 v40, 16, v15
	v_pk_add_f32 v[6:7], v[6:7], v[38:39]
	v_and_b32_e32 v41, 0xffff0000, v15
	v_pk_add_f32 v[6:7], v[6:7], v[32:33]
	v_pk_fma_f32 v[8:9], v[8:9], v[48:49], v[40:41]
	s_waitcnt vmcnt(35)
	v_lshlrev_b32_e32 v40, 16, v16
	v_and_b32_e32 v41, 0xffff0000, v16
	v_pk_add_f32 v[6:7], v[6:7], v[42:43]
	v_exp_f32_e32 v16, v40
	v_exp_f32_e32 v17, v41
	v_pk_add_f32 v[6:7], v[6:7], v[36:37]
	s_waitcnt vmcnt(33)
	v_lshlrev_b32_e32 v44, 16, v11
	v_pk_add_f32 v[6:7], v[6:7], v[46:47]
	v_and_b32_e32 v45, 0xffff0000, v11
	v_pk_add_f32 v[6:7], v[6:7], v[30:31]
	v_lshlrev_b32_e32 v48, 16, v14
	v_and_b32_e32 v49, 0xffff0000, v14
	v_pk_add_f32 v[6:7], v[6:7], v[26:27]
	v_exp_f32_e32 v14, v48
	v_exp_f32_e32 v15, v49
	v_pk_fma_f32 v[8:9], v[8:9], v[16:17], v[44:45]
	s_waitcnt vmcnt(32)
	v_lshlrev_b32_e32 v16, 16, v10
	v_and_b32_e32 v17, 0xffff0000, v10
	v_pk_add_f32 v[6:7], v[6:7], v[22:23]
	s_waitcnt vmcnt(31)
	v_lshlrev_b32_e32 v10, 16, v57
	v_and_b32_e32 v11, 0xffff0000, v57
	v_pk_add_f32 v[6:7], v[6:7], v[18:19]
	v_exp_f32_e32 v12, v10
	v_exp_f32_e32 v13, v11
	v_pk_add_f32 v[6:7], v[6:7], v[40:41]
	v_pk_fma_f32 v[8:9], v[8:9], v[14:15], v[16:17]
	v_pk_add_f32 v[6:7], v[6:7], v[48:49]
	s_lshl_b64 s[4:5], s[2:3], 13
	v_pk_add_f32 v[6:7], v[6:7], v[10:11]
	s_waitcnt vmcnt(30)
	v_lshlrev_b32_e32 v10, 16, v58
	v_and_b32_e32 v11, 0xffff0000, v58
	v_pk_fma_f32 v[8:9], v[8:9], v[12:13], v[10:11]
	s_waitcnt vmcnt(29)
; __device__ __forceinline__ float bf_lo(unsigned w) { return __uint_as_float(w << 16); }
; __device__ __forceinline__ float bf_hi(unsigned w) { return __uint_as_float(w & 0xffff0000u); }
; template <int L> __device__ __forceinline__ void layer_body(const Args& args, LAS unsigned char* lds, const int G, const int lo, const int hi, const int wave_s, unsigned& nbar) {
;     ...
;                         for (int t = 0; t < 16; ++t) { const f32x2 l2 = {bf_lo(lw[cb][t]), bf_hi(lw[cb][t])}; const f32x2 a = {__builtin_amdgcn_exp2f(l2[0]), __builtin_amdgcn_exp2f(l2[1])};
;                             Ls += l2; Up = a * Up + (f32x2){bf_lo(uw[cb][t]), bf_hi(uw[cb][t])}; }
;                         asm volatile("" ::: "memory"); }
;                     *(f32x4*)(AGG + ((size_t)item * D + 2 * tid) * 2) = (f32x4){__builtin_amdgcn_exp2f(Ls[0]), __builtin_amdgcn_exp2f(Ls[1]), Up[0], Up[1]};
	v_lshlrev_b32_e32 v10, 16, v59
	v_and_b32_e32 v11, 0xffff0000, v59
	v_exp_f32_e32 v12, v10
	v_exp_f32_e32 v13, v11
	v_pk_add_f32 v[6:7], v[6:7], v[10:11]
	s_waitcnt vmcnt(28)
	v_lshlrev_b32_e32 v10, 16, v60
	v_and_b32_e32 v11, 0xffff0000, v60
	v_pk_fma_f32 v[8:9], v[8:9], v[12:13], v[10:11]
	s_waitcnt vmcnt(27)
	v_lshlrev_b32_e32 v10, 16, v61
	v_and_b32_e32 v11, 0xffff0000, v61
	v_exp_f32_e32 v12, v10
	v_exp_f32_e32 v13, v11
	v_pk_add_f32 v[6:7], v[6:7], v[10:11]
	s_waitcnt vmcnt(26)
	v_lshlrev_b32_e32 v10, 16, v62
	v_and_b32_e32 v11, 0xffff0000, v62
	v_pk_fma_f32 v[8:9], v[8:9], v[12:13], v[10:11]
	s_waitcnt vmcnt(25)
	v_lshlrev_b32_e32 v10, 16, v63
	v_and_b32_e32 v11, 0xffff0000, v63
	v_exp_f32_e32 v12, v10
	v_exp_f32_e32 v13, v11
	v_pk_add_f32 v[6:7], v[6:7], v[10:11]
	s_waitcnt vmcnt(24)
	v_lshlrev_b32_e32 v10, 16, v64
	v_and_b32_e32 v11, 0xffff0000, v64
	v_pk_fma_f32 v[8:9], v[8:9], v[12:13], v[10:11]
	s_waitcnt vmcnt(23)
	v_lshlrev_b32_e32 v10, 16, v65
	v_and_b32_e32 v11, 0xffff0000, v65
	v_exp_f32_e32 v12, v10
	v_exp_f32_e32 v13, v11
	v_pk_add_f32 v[6:7], v[6:7], v[10:11]
	s_waitcnt vmcnt(22)
	v_lshlrev_b32_e32 v10, 16, v66
	v_and_b32_e32 v11, 0xffff0000, v66
	v_pk_fma_f32 v[8:9], v[8:9], v[12:13], v[10:11]
	s_waitcnt vmcnt(21)
	v_lshlrev_b32_e32 v10, 16, v67
	v_and_b32_e32 v11, 0xffff0000, v67
	v_exp_f32_e32 v12, v10
	v_exp_f32_e32 v13, v11
	v_pk_add_f32 v[6:7], v[6:7], v[10:11]
	s_waitcnt vmcnt(20)
	v_lshlrev_b32_e32 v10, 16, v68
	v_and_b32_e32 v11, 0xffff0000, v68
	v_pk_fma_f32 v[8:9], v[8:9], v[12:13], v[10:11]
	s_waitcnt vmcnt(19)
	v_lshlrev_b32_e32 v10, 16, v69
	v_and_b32_e32 v11, 0xffff0000, v69
	v_exp_f32_e32 v12, v10
	v_exp_f32_e32 v13, v11
	v_pk_add_f32 v[6:7], v[6:7], v[10:11]
	s_waitcnt vmcnt(18)
	v_lshlrev_b32_e32 v10, 16, v70
	v_and_b32_e32 v11, 0xffff0000, v70
	v_pk_fma_f32 v[8:9], v[8:9], v[12:13], v[10:11]
	s_waitcnt vmcnt(17)
	v_lshlrev_b32_e32 v10, 16, v71
	v_and_b32_e32 v11, 0xffff0000, v71
	v_exp_f32_e32 v12, v10
	v_exp_f32_e32 v13, v11
	v_pk_add_f32 v[6:7], v[6:7], v[10:11]
	s_waitcnt vmcnt(16)
	v_lshlrev_b32_e32 v10, 16, v72
	v_and_b32_e32 v11, 0xffff0000, v72
	v_pk_fma_f32 v[8:9], v[8:9], v[12:13], v[10:11]
	s_waitcnt vmcnt(15)
	v_lshlrev_b32_e32 v10, 16, v73
	v_and_b32_e32 v11, 0xffff0000, v73
	v_exp_f32_e32 v12, v10
	v_exp_f32_e32 v13, v11
	v_pk_add_f32 v[6:7], v[6:7], v[10:11]
	s_waitcnt vmcnt(14)
	v_lshlrev_b32_e32 v10, 16, v74
	v_and_b32_e32 v11, 0xffff0000, v74
	v_pk_fma_f32 v[8:9], v[8:9], v[12:13], v[10:11]
	s_waitcnt vmcnt(13)
	v_lshlrev_b32_e32 v10, 16, v79
	v_and_b32_e32 v11, 0xffff0000, v79
	v_exp_f32_e32 v12, v10
	v_exp_f32_e32 v13, v11
	v_pk_add_f32 v[6:7], v[6:7], v[10:11]
	s_waitcnt vmcnt(12)
	v_lshlrev_b32_e32 v10, 16, v80
	v_and_b32_e32 v11, 0xffff0000, v80
	v_pk_fma_f32 v[8:9], v[8:9], v[12:13], v[10:11]
	s_waitcnt vmcnt(11)
	v_lshlrev_b32_e32 v10, 16, v81
	v_and_b32_e32 v11, 0xffff0000, v81
	v_exp_f32_e32 v12, v10
	v_exp_f32_e32 v13, v11
	v_pk_add_f32 v[6:7], v[6:7], v[10:11]
	s_waitcnt vmcnt(10)
	v_lshlrev_b32_e32 v10, 16, v82
	v_and_b32_e32 v11, 0xffff0000, v82
	v_pk_fma_f32 v[8:9], v[8:9], v[12:13], v[10:11]
	s_waitcnt vmcnt(9)
	v_lshlrev_b32_e32 v10, 16, v83
	v_and_b32_e32 v11, 0xffff0000, v83
	v_exp_f32_e32 v12, v10
	v_exp_f32_e32 v13, v11
	v_pk_add_f32 v[6:7], v[6:7], v[10:11]
	s_waitcnt vmcnt(8)
	v_lshlrev_b32_e32 v10, 16, v84
	v_and_b32_e32 v11, 0xffff0000, v84
	v_pk_fma_f32 v[8:9], v[8:9], v[12:13], v[10:11]
	s_waitcnt vmcnt(7)
	v_lshlrev_b32_e32 v10, 16, v85
	v_and_b32_e32 v11, 0xffff0000, v85
	v_exp_f32_e32 v12, v10
	v_exp_f32_e32 v13, v11
	v_pk_add_f32 v[6:7], v[6:7], v[10:11]
	s_waitcnt vmcnt(6)
	v_lshlrev_b32_e32 v10, 16, v86
	v_and_b32_e32 v11, 0xffff0000, v86
	v_pk_fma_f32 v[8:9], v[8:9], v[12:13], v[10:11]
	s_waitcnt vmcnt(5)
	v_lshlrev_b32_e32 v10, 16, v87
	v_and_b32_e32 v11, 0xffff0000, v87
	v_exp_f32_e32 v12, v10
	v_exp_f32_e32 v13, v11
	v_pk_add_f32 v[6:7], v[6:7], v[10:11]
	s_waitcnt vmcnt(4)
	v_lshlrev_b32_e32 v10, 16, v88
	v_and_b32_e32 v11, 0xffff0000, v88
	v_pk_fma_f32 v[8:9], v[8:9], v[12:13], v[10:11]
	s_waitcnt vmcnt(3)
	v_lshlrev_b32_e32 v10, 16, v89
	v_and_b32_e32 v11, 0xffff0000, v89
	v_exp_f32_e32 v12, v10
	v_exp_f32_e32 v13, v11
	v_pk_add_f32 v[6:7], v[6:7], v[10:11]
	s_waitcnt vmcnt(2)
	v_lshlrev_b32_e32 v10, 16, v90
	v_and_b32_e32 v11, 0xffff0000, v90
	v_pk_fma_f32 v[8:9], v[8:9], v[12:13], v[10:11]
	s_waitcnt vmcnt(1)
	v_lshlrev_b32_e32 v10, 16, v91
	v_and_b32_e32 v11, 0xffff0000, v91
	v_exp_f32_e32 v12, v10
	v_exp_f32_e32 v13, v11
	v_pk_add_f32 v[6:7], v[6:7], v[10:11]
	s_waitcnt vmcnt(0)
	v_lshlrev_b32_e32 v10, 16, v92
	v_exp_f32_e32 v6, v6
	v_exp_f32_e32 v7, v7
	v_and_b32_e32 v11, 0xffff0000, v92
	s_add_i32 s2, s2, s92
	v_pk_fma_f32 v[8:9], v[8:9], v[12:13], v[10:11]
	v_lshl_add_u64 v[10:11], v[4:5], 0, s[4:5]
	s_cmpk_lt_i32 s2, 0x100
	global_store_dwordx4 v[10:11], v[6:9], off sc1
	s_cbranch_scc1 .LBB0_1592

; __device__ __forceinline__ f32x4 bf4_lo(const u32x4 w) { return (f32x4){bf_lo(w.x), bf_hi(w.x), bf_lo(w.y), bf_hi(w.y)}; }
; __device__ __forceinline__ f32x4 bf4_hi(const u32x4 w) { return (f32x4){bf_lo(w.z), bf_hi(w.z), bf_lo(w.w), bf_hi(w.w)}; }
;     __device__ __forceinline__ void operator()(const Acc& acc, const Unit& u, int wr, int wc, int fr, int fq) const {
;     ...
;                 for (int m = 0; m < 4; ++m)
; #pragma unroll
;                     for (int bj = 0; bj < 2; ++bj) hw[m][bj] = *(const u32x4*)((const bf16_t*)base + (size_t)ROW_OF(u, ai, m) * D + colb + bj * 128);
; #pragma unroll
;                 for (int m = 0; m < 4; ++m)
; #pragma unroll
;                     for (int bj = 0; bj < 2; ++bj) { hv[m][bj][0] = bf4_lo(hw[m][bj]); hv[m][bj][1] = bf4_hi(hw[m][bj]); }
;             }
; #pragma unroll
;             for (int m = 0; m < 4; ++m) {
;                 const int row = ROW_OF(u, ai, m); float sq = 0.f;
; #pragma unroll
;                 for (int bj = 0; bj < 2; ++bj) {
;                     const size_t off = (size_t)row * D + colb + bj * 128;
;                     const f32x4 h0 = hv[m][bj][0] + acc[ai][bj][m][0] * scale, h1 = hv[m][bj][1] + acc[ai][bj][m][1] * scale;
;                     *(u32x4*)(hb + off) = pack8(h0, h1);
;                     sq += (h0[0] * h0[0] + h0[1] * h0[1]) + (h0[2] * h0[2] + h0[3] * h0[3]) + (h1[0] * h1[0] + h1[1] * h1[1]) + (h1[2] * h1[2] + h1[3] * h1[3]);
;                 }
;                 sq = red4_sum(sq);
;                 if (fq == 0) ss_out[(size_t)row * 16 + u.pn * 4 + wc] = sq;
;             }
.LBB0_1737:
	v_lshl_or_b32 v168, s6, 8, v188
	v_lshl_add_u32 v172, s34, 8, v186
	v_ashrrev_i32_e32 v169, 31, v168
	v_lshlrev_b64 v[200:201], 1, v[168:169]
	v_ashrrev_i32_e32 v173, 31, v172
	v_lshl_add_u64 v[170:171], s[14:15], 0, v[200:201]
	v_lshlrev_b64 v[202:203], 11, v[172:173]
	v_lshl_add_u64 v[128:129], v[170:171], 0, v[202:203]
	global_load_dwordx4 v[192:195], v[128:129], off
	global_load_dwordx4 v[196:199], v[128:129], off offset:256
	v_or_b32_e32 v182, 16, v172
	v_or_b32_e32 v178, 32, v172
	v_or_b32_e32 v174, 48, v172
	v_ashrrev_i32_e32 v183, 31, v182
	v_ashrrev_i32_e32 v179, 31, v178
	v_ashrrev_i32_e32 v175, 31, v174
	v_lshlrev_b64 v[184:185], 11, v[182:183]
	v_lshlrev_b64 v[180:181], 11, v[178:179]
	v_lshlrev_b64 v[176:177], 11, v[174:175]
	v_lshl_add_u64 v[128:129], v[170:171], 0, v[184:185]
	v_lshl_add_u64 v[130:131], v[170:171], 0, v[180:181]
	v_lshl_add_u64 v[204:205], v[170:171], 0, v[176:177]
	global_load_dwordx4 v[148:151], v[128:129], off
	global_load_dwordx4 v[144:147], v[128:129], off offset:256
	global_load_dwordx4 v[140:143], v[130:131], off
	global_load_dwordx4 v[136:139], v[130:131], off offset:256
	global_load_dwordx4 v[132:135], v[204:205], off
	s_nop 0
	global_load_dwordx4 v[128:131], v[204:205], off offset:256
	v_lshl_add_u64 v[202:203], s[16:17], 0, v[202:203]
	v_lshl_add_u64 v[200:201], v[202:203], 0, v[200:201]
	s_lshl_b32 s34, s6, 2
	s_ashr_i32 s35, s34, 31
	s_waitcnt vmcnt(0)
	v_lshlrev_b32_e32 v202, 16, v192
	v_and_b32_e32 v203, 0xffff0000, v192
	v_lshlrev_b32_e32 v192, 16, v193
	v_and_b32_e32 v193, 0xffff0000, v193
	v_lshlrev_b32_e32 v206, 16, v196
	v_and_b32_e32 v207, 0xffff0000, v196
	v_lshlrev_b32_e32 v196, 16, v197
	v_and_b32_e32 v197, 0xffff0000, v197
	v_lshlrev_b32_e32 v204, 16, v194
	v_and_b32_e32 v205, 0xffff0000, v194
	v_lshlrev_b32_e32 v194, 16, v195
	v_and_b32_e32 v195, 0xffff0000, v195
	v_lshlrev_b32_e32 v208, 16, v198
	v_and_b32_e32 v209, 0xffff0000, v198
	v_pk_add_f32 v[122:123], v[122:123], v[192:193]
	v_pk_add_f32 v[120:121], v[120:121], v[202:203]
	v_pk_add_f32 v[118:119], v[118:119], v[196:197]
	v_pk_add_f32 v[116:117], v[116:117], v[206:207]
	v_lshlrev_b32_e32 v198, 16, v199
	v_and_b32_e32 v199, 0xffff0000, v199
	v_pk_add_f32 v[126:127], v[126:127], v[194:195]
	v_pk_add_f32 v[124:125], v[124:125], v[204:205]
	v_pk_add_f32 v[194:195], v[112:113], v[208:209]
	v_cvt_pk_bf16_f32 v112, v120, v121
	v_cvt_pk_bf16_f32 v113, v122, v123
	v_mul_f32_e32 v121, v121, v121
	v_mul_f32_e32 v123, v123, v123
	v_mul_f32_e32 v196, v117, v117
	v_mul_f32_e32 v197, v119, v119
	v_pk_add_f32 v[192:193], v[114:115], v[198:199]
	v_cvt_pk_bf16_f32 v114, v124, v125
	v_cvt_pk_bf16_f32 v115, v126, v127
	v_mul_f32_e32 v125, v125, v125
	v_mul_f32_e32 v198, v195, v195
	global_store_dwordx4 v[200:201], v[112:115], off sc1
	v_fmac_f32_e32 v121, v120, v120
	v_fmac_f32_e32 v123, v122, v122
	v_cvt_pk_bf16_f32 v112, v116, v117
	v_fmac_f32_e32 v196, v116, v116
	v_fmac_f32_e32 v197, v118, v118
	v_mul_f32_e32 v127, v127, v127
	v_mul_f32_e32 v199, v193, v193
	v_fmac_f32_e32 v125, v124, v124
	v_cvt_pk_bf16_f32 v113, v118, v119
	v_cvt_pk_bf16_f32 v114, v194, v195
	v_cvt_pk_bf16_f32 v115, v192, v193
	v_fmac_f32_e32 v198, v194, v194
	v_add_f32_e32 v116, v121, v123
	global_store_dwordx4 v[200:201], v[112:115], off offset:256 sc1
	v_fmac_f32_e32 v127, v126, v126
	v_fmac_f32_e32 v199, v192, v192
	v_add_f32_e32 v112, v196, v197
	v_add_f32_e32 v113, v125, v116
	v_add_f32_e32 v112, v198, v112
	v_add_f32_e32 v113, v127, v113
	v_add_f32_e32 v112, v199, v112
	v_add_f32_e32 v112, v113, v112
	v_mov_b32_e32 v113, v112
	s_nop 1
	v_permlane16_swap_b32_e32 v112, v113
	v_add_f32_e32 v112, v112, v113
	v_mov_b32_e32 v113, v112
	s_nop 1
	v_permlane32_swap_b32_e32 v112, v113
	s_and_saveexec_b64 s[36:37], s[2:3]
	s_cbranch_execz .LBB0_1739
	v_add_f32_e32 v114, v112, v113
	v_lshlrev_b64 v[112:113], 6, v[172:173]
	v_lshl_add_u64 v[112:113], s[10:11], 0, v[112:113]
	v_lshl_add_u64 v[112:113], s[34:35], 2, v[112:113]
	s_lshl_b32 s6, s49, 2
	v_lshl_add_u64 v[112:113], v[112:113], 0, s[6:7]
	global_store_dword v[112:113], v114, off sc1
.LBB0_1739:
	s_or_b64 exec, exec, s[36:37]
	v_lshlrev_b32_e32 v114, 16, v149
	v_and_b32_e32 v115, 0xffff0000, v149
	v_lshlrev_b32_e32 v116, 16, v150
	v_and_b32_e32 v117, 0xffff0000, v150
	v_lshlrev_b32_e32 v112, 16, v148
	v_and_b32_e32 v113, 0xffff0000, v148
	v_pk_add_f32 v[110:111], v[110:111], v[114:115]
	v_pk_add_f32 v[114:115], v[104:105], v[116:117]
	v_lshl_add_u64 v[116:117], s[16:17], 0, v[184:185]
	v_lshlrev_b32_e32 v118, 16, v151
	v_and_b32_e32 v119, 0xffff0000, v151
	v_pk_add_f32 v[108:109], v[108:109], v[112:113]
	v_lshl_add_u64 v[116:117], v[168:169], 1, v[116:117]
	v_cvt_pk_bf16_f32 v104, v108, v109
	v_cvt_pk_bf16_f32 v105, v110, v111
	v_pk_add_f32 v[112:113], v[106:107], v[118:119]
	v_cvt_pk_bf16_f32 v106, v114, v115
	v_lshlrev_b32_e32 v120, 16, v144
	v_cvt_pk_bf16_f32 v107, v112, v113
	global_store_dwordx4 v[116:117], v[104:107], off sc1
	v_and_b32_e32 v121, 0xffff0000, v144
	v_lshlrev_b32_e32 v122, 16, v145
	v_mul_f32_e32 v104, v109, v109
	v_mul_f32_e32 v105, v111, v111
	v_fmac_f32_e32 v104, v108, v108
	v_fmac_f32_e32 v105, v110, v110
	v_add_f32_e32 v104, v104, v105
	v_mul_f32_e32 v105, v115, v115
	v_fmac_f32_e32 v105, v114, v114
	v_and_b32_e32 v123, 0xffff0000, v145
	v_lshlrev_b32_e32 v124, 16, v146
	v_and_b32_e32 v125, 0xffff0000, v146
	v_add_f32_e32 v104, v105, v104
	v_mul_f32_e32 v105, v113, v113
	v_lshlrev_b32_e32 v126, 16, v147
	v_and_b32_e32 v127, 0xffff0000, v147
	v_fmac_f32_e32 v105, v112, v112
	v_pk_add_f32 v[102:103], v[102:103], v[122:123]
	v_pk_add_f32 v[100:101], v[100:101], v[120:121]
	v_pk_add_f32 v[106:107], v[96:97], v[124:125]
	v_cvt_pk_bf16_f32 v96, v100, v101
	v_cvt_pk_bf16_f32 v97, v102, v103
	v_add_f32_e32 v108, v105, v104
	v_pk_add_f32 v[104:105], v[98:99], v[126:127]
	v_cvt_pk_bf16_f32 v98, v106, v107
	s_nop 0
	v_cvt_pk_bf16_f32 v99, v104, v105
	global_store_dwordx4 v[116:117], v[96:99], off offset:256 sc1
	s_nop 1
	v_mul_f32_e32 v96, v101, v101
	v_mul_f32_e32 v97, v103, v103
	v_fmac_f32_e32 v96, v100, v100
	v_fmac_f32_e32 v97, v102, v102
	v_add_f32_e32 v96, v96, v97
	v_mul_f32_e32 v97, v107, v107
	v_fmac_f32_e32 v97, v106, v106
	v_add_f32_e32 v96, v97, v96
	v_mul_f32_e32 v97, v105, v105
	v_fmac_f32_e32 v97, v104, v104
	v_add_f32_e32 v96, v97, v96
	v_add_f32_e32 v96, v108, v96
	v_mov_b32_e32 v97, v96
	s_nop 1
	v_permlane16_swap_b32_e32 v96, v97
	v_add_f32_e32 v96, v96, v97
	v_mov_b32_e32 v97, v96
	s_nop 1
	v_permlane32_swap_b32_e32 v96, v97
	s_and_saveexec_b64 s[36:37], s[2:3]
	s_cbranch_execz .LBB0_1741
	v_add_f32_e32 v98, v96, v97
	v_lshlrev_b64 v[96:97], 6, v[182:183]
	v_lshl_add_u64 v[96:97], s[10:11], 0, v[96:97]
	v_lshl_add_u64 v[96:97], s[34:35], 2, v[96:97]
	s_lshl_b32 s6, s49, 2
	v_lshl_add_u64 v[96:97], v[96:97], 0, s[6:7]
	global_store_dword v[96:97], v98, off sc1
;     __device__ __forceinline__ void operator()(const Acc& acc, const Unit& u, int wr, int wc, int fr, int fq) const {
;     ...
;             for (int m = 0; m < 4; ++m) {
;                 const int row = ROW_OF(u, ai, m); float sq = 0.f;
; #pragma unroll
;                 for (int bj = 0; bj < 2; ++bj) {
;                     const size_t off = (size_t)row * D + colb + bj * 128;
;                     const f32x4 h0 = hv[m][bj][0] + acc[ai][bj][m][0] * scale, h1 = hv[m][bj][1] + acc[ai][bj][m][1] * scale;
;                     *(u32x4*)(hb + off) = pack8(h0, h1);
;                     sq += (h0[0] * h0[0] + h0[1] * h0[1]) + (h0[2] * h0[2] + h0[3] * h0[3]) + (h1[0] * h1[0] + h1[1] * h1[1]) + (h1[2] * h1[2] + h1[3] * h1[3]);
;                 }
;                 sq = red4_sum(sq);
;                 if (fq == 0) ss_out[(size_t)row * 16 + u.pn * 4 + wc] = sq;
;             }
.LBB0_1741:
	s_or_b64 exec, exec, s[36:37]
	v_lshlrev_b32_e32 v98, 16, v141
	v_and_b32_e32 v99, 0xffff0000, v141
	v_lshlrev_b32_e32 v100, 16, v142
	v_and_b32_e32 v101, 0xffff0000, v142
	v_lshlrev_b32_e32 v96, 16, v140
	v_and_b32_e32 v97, 0xffff0000, v140
	v_pk_add_f32 v[94:95], v[94:95], v[98:99]
	v_pk_add_f32 v[98:99], v[88:89], v[100:101]
	v_lshl_add_u64 v[100:101], s[16:17], 0, v[180:181]
	v_lshlrev_b32_e32 v102, 16, v143
	v_and_b32_e32 v103, 0xffff0000, v143
	v_pk_add_f32 v[92:93], v[92:93], v[96:97]
	v_lshl_add_u64 v[100:101], v[168:169], 1, v[100:101]
	v_cvt_pk_bf16_f32 v88, v92, v93
	v_cvt_pk_bf16_f32 v89, v94, v95
	v_pk_add_f32 v[96:97], v[90:91], v[102:103]
	v_cvt_pk_bf16_f32 v90, v98, v99
	v_lshlrev_b32_e32 v104, 16, v136
	v_cvt_pk_bf16_f32 v91, v96, v97
	global_store_dwordx4 v[100:101], v[88:91], off sc1
	v_and_b32_e32 v105, 0xffff0000, v136
	v_lshlrev_b32_e32 v106, 16, v137
	v_mul_f32_e32 v88, v93, v93
	v_mul_f32_e32 v89, v95, v95
	v_fmac_f32_e32 v88, v92, v92
	v_fmac_f32_e32 v89, v94, v94
	v_add_f32_e32 v88, v88, v89
	v_mul_f32_e32 v89, v99, v99
	v_fmac_f32_e32 v89, v98, v98
	v_and_b32_e32 v107, 0xffff0000, v137
	v_lshlrev_b32_e32 v108, 16, v138
	v_and_b32_e32 v109, 0xffff0000, v138
	v_add_f32_e32 v88, v89, v88
	v_mul_f32_e32 v89, v97, v97
	v_lshlrev_b32_e32 v110, 16, v139
	v_and_b32_e32 v111, 0xffff0000, v139
	v_fmac_f32_e32 v89, v96, v96
	v_pk_add_f32 v[86:87], v[86:87], v[106:107]
	v_pk_add_f32 v[84:85], v[84:85], v[104:105]
	v_pk_add_f32 v[90:91], v[80:81], v[108:109]
	v_cvt_pk_bf16_f32 v80, v84, v85
	v_cvt_pk_bf16_f32 v81, v86, v87
	v_add_f32_e32 v92, v89, v88
	v_pk_add_f32 v[88:89], v[82:83], v[110:111]
	v_cvt_pk_bf16_f32 v82, v90, v91
	s_nop 0
	v_cvt_pk_bf16_f32 v83, v88, v89
	global_store_dwordx4 v[100:101], v[80:83], off offset:256 sc1
	s_nop 1
	v_mul_f32_e32 v80, v85, v85
	v_mul_f32_e32 v81, v87, v87
	v_fmac_f32_e32 v80, v84, v84
	v_fmac_f32_e32 v81, v86, v86
	v_add_f32_e32 v80, v80, v81
	v_mul_f32_e32 v81, v91, v91
	v_fmac_f32_e32 v81, v90, v90
	v_add_f32_e32 v80, v81, v80
	v_mul_f32_e32 v81, v89, v89
	v_fmac_f32_e32 v81, v88, v88
	v_add_f32_e32 v80, v81, v80
	v_add_f32_e32 v80, v92, v80
	v_mov_b32_e32 v81, v80
	s_nop 1
	v_permlane16_swap_b32_e32 v80, v81
	v_add_f32_e32 v80, v80, v81
	v_mov_b32_e32 v81, v80
	s_nop 1
	v_permlane32_swap_b32_e32 v80, v81
	s_and_saveexec_b64 s[36:37], s[2:3]
	s_cbranch_execz .LBB0_1743
	v_add_f32_e32 v82, v80, v81
	v_lshlrev_b64 v[80:81], 6, v[178:179]
	v_lshl_add_u64 v[80:81], s[10:11], 0, v[80:81]
	v_lshl_add_u64 v[80:81], s[34:35], 2, v[80:81]
	s_lshl_b32 s6, s49, 2
	v_lshl_add_u64 v[80:81], v[80:81], 0, s[6:7]
	global_store_dword v[80:81], v82, off sc1
.LBB0_1743:
	s_or_b64 exec, exec, s[36:37]
	v_lshlrev_b32_e32 v82, 16, v133
	v_and_b32_e32 v83, 0xffff0000, v133
	v_lshlrev_b32_e32 v84, 16, v134
	v_and_b32_e32 v85, 0xffff0000, v134
	v_lshlrev_b32_e32 v80, 16, v132
	v_and_b32_e32 v81, 0xffff0000, v132
	v_pk_add_f32 v[78:79], v[78:79], v[82:83]
	v_pk_add_f32 v[82:83], v[72:73], v[84:85]
	v_lshl_add_u64 v[84:85], s[16:17], 0, v[176:177]
	v_lshlrev_b32_e32 v86, 16, v135
	v_and_b32_e32 v87, 0xffff0000, v135
	v_pk_add_f32 v[76:77], v[76:77], v[80:81]
	v_lshl_add_u64 v[84:85], v[168:169], 1, v[84:85]
	v_cvt_pk_bf16_f32 v72, v76, v77
	v_cvt_pk_bf16_f32 v73, v78, v79
	v_pk_add_f32 v[80:81], v[74:75], v[86:87]
	v_cvt_pk_bf16_f32 v74, v82, v83
	v_lshlrev_b32_e32 v88, 16, v128
	v_cvt_pk_bf16_f32 v75, v80, v81
	global_store_dwordx4 v[84:85], v[72:75], off sc1
	v_and_b32_e32 v89, 0xffff0000, v128
	v_lshlrev_b32_e32 v90, 16, v129
	v_mul_f32_e32 v72, v77, v77
	v_mul_f32_e32 v73, v79, v79
	v_fmac_f32_e32 v72, v76, v76
	v_fmac_f32_e32 v73, v78, v78
	v_add_f32_e32 v72, v72, v73
	v_mul_f32_e32 v73, v83, v83
	v_fmac_f32_e32 v73, v82, v82
	v_and_b32_e32 v91, 0xffff0000, v129
	v_lshlrev_b32_e32 v92, 16, v130
	v_and_b32_e32 v93, 0xffff0000, v130
	v_add_f32_e32 v72, v73, v72
	v_mul_f32_e32 v73, v81, v81
	v_lshlrev_b32_e32 v94, 16, v131
	v_and_b32_e32 v95, 0xffff0000, v131
	v_fmac_f32_e32 v73, v80, v80
	v_pk_add_f32 v[70:71], v[70:71], v[90:91]
	v_pk_add_f32 v[68:69], v[68:69], v[88:89]
	v_pk_add_f32 v[74:75], v[64:65], v[92:93]
	v_cvt_pk_bf16_f32 v64, v68, v69
	v_cvt_pk_bf16_f32 v65, v70, v71
	v_add_f32_e32 v76, v73, v72
	v_pk_add_f32 v[72:73], v[66:67], v[94:95]
	v_cvt_pk_bf16_f32 v66, v74, v75
	s_nop 0
	v_cvt_pk_bf16_f32 v67, v72, v73
	global_store_dwordx4 v[84:85], v[64:67], off offset:256 sc1
	s_nop 1
	v_mul_f32_e32 v64, v69, v69
	v_mul_f32_e32 v65, v71, v71
	v_fmac_f32_e32 v64, v68, v68
	v_fmac_f32_e32 v65, v70, v70
	v_add_f32_e32 v64, v64, v65
	v_mul_f32_e32 v65, v75, v75
	v_fmac_f32_e32 v65, v74, v74
	v_add_f32_e32 v64, v65, v64
	v_mul_f32_e32 v65, v73, v73
	v_fmac_f32_e32 v65, v72, v72
	v_add_f32_e32 v64, v65, v64
	v_add_f32_e32 v64, v76, v64
	v_mov_b32_e32 v65, v64
	s_nop 1
	v_permlane16_swap_b32_e32 v64, v65
	v_add_f32_e32 v64, v64, v65
	v_mov_b32_e32 v65, v64
	s_nop 1
	v_permlane32_swap_b32_e32 v64, v65
	s_and_saveexec_b64 s[36:37], s[2:3]
	s_cbranch_execz .LBB0_1745
	v_add_f32_e32 v66, v64, v65
	v_lshlrev_b64 v[64:65], 6, v[174:175]
	v_lshl_add_u64 v[64:65], s[10:11], 0, v[64:65]
	v_lshl_add_u64 v[64:65], s[34:35], 2, v[64:65]
	s_lshl_b32 s6, s49, 2
	v_lshl_add_u64 v[64:65], v[64:65], 0, s[6:7]
	global_store_dword v[64:65], v66, off sc1
; __device__ __forceinline__ f32x4 bf4_lo(const u32x4 w) { return (f32x4){bf_lo(w.x), bf_hi(w.x), bf_lo(w.y), bf_hi(w.y)}; }
; __device__ __forceinline__ f32x4 bf4_hi(const u32x4 w) { return (f32x4){bf_lo(w.z), bf_hi(w.z), bf_lo(w.w), bf_hi(w.w)}; }
;     __device__ __forceinline__ void operator()(const Acc& acc, const Unit& u, int wr, int wc, int fr, int fq) const {
;     ...
;                 u32x4 hw[4][2];
; #pragma unroll
;                 for (int m = 0; m < 4; ++m)
; #pragma unroll
;                     for (int bj = 0; bj < 2; ++bj) hw[m][bj] = *(const u32x4*)((const bf16_t*)base + (size_t)ROW_OF(u, ai, m) * D + colb + bj * 128);
; #pragma unroll
;                 for (int m = 0; m < 4; ++m)
; #pragma unroll
;                     for (int bj = 0; bj < 2; ++bj) { hv[m][bj][0] = bf4_lo(hw[m][bj]); hv[m][bj][1] = bf4_hi(hw[m][bj]); }
;             }
; #pragma unroll
;             for (int m = 0; m < 4; ++m) {
;                 const int row = ROW_OF(u, ai, m); float sq = 0.f;
; #pragma unroll
;                 for (int bj = 0; bj < 2; ++bj) {
;                     const size_t off = (size_t)row * D + colb + bj * 128;
;                     const f32x4 h0 = hv[m][bj][0] + acc[ai][bj][m][0] * scale, h1 = hv[m][bj][1] + acc[ai][bj][m][1] * scale;
;                     *(u32x4*)(hb + off) = pack8(h0, h1);
;                     sq += (h0[0] * h0[0] + h0[1] * h0[1]) + (h0[2] * h0[2] + h0[3] * h0[3]) + (h1[0] * h1[0] + h1[1] * h1[1]) + (h1[2] * h1[2] + h1[3] * h1[3]);
;                 }
;                 sq = red4_sum(sq);
;                 if (fq == 0) ss_out[(size_t)row * 16 + u.pn * 4 + wc] = sq;
;             }
.LBB0_1745:
	s_or_b64 exec, exec, s[36:37]
	v_add_u32_e32 v100, 0x80, v172
	v_ashrrev_i32_e32 v101, 31, v100
	v_lshlrev_b64 v[110:111], 11, v[100:101]
	v_lshl_add_u64 v[64:65], v[170:171], 0, v[110:111]
	global_load_dwordx4 v[102:105], v[64:65], off
	global_load_dwordx4 v[106:109], v[64:65], off offset:256
	v_add_u32_e32 v96, 0x90, v172
	v_add_u32_e32 v92, 0xa0, v172
	v_add_u32_e32 v88, 0xb0, v172
	v_ashrrev_i32_e32 v97, 31, v96
	v_ashrrev_i32_e32 v93, 31, v92
	v_ashrrev_i32_e32 v89, 31, v88
	v_lshlrev_b64 v[98:99], 11, v[96:97]
	v_lshlrev_b64 v[94:95], 11, v[92:93]
	v_lshlrev_b64 v[90:91], 11, v[88:89]
	v_lshl_add_u64 v[64:65], v[170:171], 0, v[98:99]
	v_lshl_add_u64 v[66:67], v[170:171], 0, v[94:95]
	v_lshl_add_u64 v[112:113], v[170:171], 0, v[90:91]
	global_load_dwordx4 v[84:87], v[64:65], off
	global_load_dwordx4 v[80:83], v[64:65], off offset:256
	global_load_dwordx4 v[76:79], v[66:67], off
	global_load_dwordx4 v[72:75], v[66:67], off offset:256
	global_load_dwordx4 v[68:71], v[112:113], off
	s_nop 0
	global_load_dwordx4 v[64:67], v[112:113], off offset:256
	v_lshl_add_u64 v[110:111], s[16:17], 0, v[110:111]
	v_lshl_add_u64 v[110:111], v[168:169], 1, v[110:111]
	s_waitcnt vmcnt(0)
	v_lshlrev_b32_e32 v112, 16, v102
	v_and_b32_e32 v113, 0xffff0000, v102
	v_lshlrev_b32_e32 v102, 16, v103
	v_and_b32_e32 v103, 0xffff0000, v103
	v_lshlrev_b32_e32 v116, 16, v106
	v_and_b32_e32 v117, 0xffff0000, v106
	v_lshlrev_b32_e32 v106, 16, v107
	v_and_b32_e32 v107, 0xffff0000, v107
	v_lshlrev_b32_e32 v114, 16, v104
	v_and_b32_e32 v115, 0xffff0000, v104
	v_lshlrev_b32_e32 v104, 16, v105
	v_and_b32_e32 v105, 0xffff0000, v105
	v_lshlrev_b32_e32 v118, 16, v108
	v_and_b32_e32 v119, 0xffff0000, v108
	v_pk_add_f32 v[62:63], v[62:63], v[102:103]
	v_pk_add_f32 v[60:61], v[60:61], v[112:113]
	v_pk_add_f32 v[54:55], v[54:55], v[106:107]
	v_pk_add_f32 v[52:53], v[52:53], v[116:117]
	v_lshlrev_b32_e32 v108, 16, v109
	v_and_b32_e32 v109, 0xffff0000, v109
	v_pk_add_f32 v[58:59], v[58:59], v[104:105]
	v_pk_add_f32 v[56:57], v[56:57], v[114:115]
	v_pk_add_f32 v[104:105], v[48:49], v[118:119]
	v_cvt_pk_bf16_f32 v48, v60, v61
	v_cvt_pk_bf16_f32 v49, v62, v63
	v_mul_f32_e32 v61, v61, v61
	v_mul_f32_e32 v63, v63, v63
	v_mul_f32_e32 v106, v53, v53
	v_mul_f32_e32 v107, v55, v55
	v_pk_add_f32 v[102:103], v[50:51], v[108:109]
	v_cvt_pk_bf16_f32 v50, v56, v57
	v_cvt_pk_bf16_f32 v51, v58, v59
	v_mul_f32_e32 v57, v57, v57
	v_mul_f32_e32 v108, v105, v105
	global_store_dwordx4 v[110:111], v[48:51], off sc1
	v_fmac_f32_e32 v61, v60, v60
	v_fmac_f32_e32 v63, v62, v62
	v_cvt_pk_bf16_f32 v48, v52, v53
	v_fmac_f32_e32 v106, v52, v52
	v_fmac_f32_e32 v107, v54, v54
	v_mul_f32_e32 v59, v59, v59
	v_mul_f32_e32 v109, v103, v103
	v_fmac_f32_e32 v57, v56, v56
	v_cvt_pk_bf16_f32 v49, v54, v55
	v_cvt_pk_bf16_f32 v50, v104, v105
	v_cvt_pk_bf16_f32 v51, v102, v103
	v_fmac_f32_e32 v108, v104, v104
	v_add_f32_e32 v52, v61, v63
	global_store_dwordx4 v[110:111], v[48:51], off offset:256 sc1
	v_fmac_f32_e32 v59, v58, v58
	v_fmac_f32_e32 v109, v102, v102
	v_add_f32_e32 v48, v106, v107
	v_add_f32_e32 v49, v57, v52
	v_add_f32_e32 v48, v108, v48
	v_add_f32_e32 v49, v59, v49
	v_add_f32_e32 v48, v109, v48
	v_add_f32_e32 v48, v49, v48
	v_mov_b32_e32 v49, v48
	s_nop 1
	v_permlane16_swap_b32_e32 v48, v49
	v_add_f32_e32 v48, v48, v49
	v_mov_b32_e32 v49, v48
	s_nop 1
	v_permlane32_swap_b32_e32 v48, v49
	s_and_saveexec_b64 s[36:37], s[2:3]
	s_cbranch_execz .LBB0_1747
	v_add_f32_e32 v50, v48, v49
	v_lshlrev_b64 v[48:49], 6, v[100:101]
	v_lshl_add_u64 v[48:49], s[10:11], 0, v[48:49]
	v_lshl_add_u64 v[48:49], s[34:35], 2, v[48:49]
	s_lshl_b32 s6, s49, 2
	v_lshl_add_u64 v[48:49], v[48:49], 0, s[6:7]
	global_store_dword v[48:49], v50, off sc1
.LBB0_1747:
	s_or_b64 exec, exec, s[36:37]
	v_lshlrev_b32_e32 v50, 16, v85
	v_and_b32_e32 v51, 0xffff0000, v85
	v_lshlrev_b32_e32 v52, 16, v86
	v_and_b32_e32 v53, 0xffff0000, v86
	v_lshlrev_b32_e32 v48, 16, v84
	v_and_b32_e32 v49, 0xffff0000, v84
	v_pk_add_f32 v[46:47], v[46:47], v[50:51]
	v_pk_add_f32 v[50:51], v[40:41], v[52:53]
	v_lshl_add_u64 v[52:53], s[16:17], 0, v[98:99]
	v_lshlrev_b32_e32 v54, 16, v87
	v_and_b32_e32 v55, 0xffff0000, v87
	v_pk_add_f32 v[44:45], v[44:45], v[48:49]
	v_lshl_add_u64 v[52:53], v[168:169], 1, v[52:53]
	v_cvt_pk_bf16_f32 v40, v44, v45
	v_cvt_pk_bf16_f32 v41, v46, v47
	v_pk_add_f32 v[48:49], v[42:43], v[54:55]
	v_cvt_pk_bf16_f32 v42, v50, v51
	v_lshlrev_b32_e32 v56, 16, v80
	v_cvt_pk_bf16_f32 v43, v48, v49
	global_store_dwordx4 v[52:53], v[40:43], off sc1
	v_and_b32_e32 v57, 0xffff0000, v80
	v_lshlrev_b32_e32 v58, 16, v81
	v_mul_f32_e32 v40, v45, v45
	v_mul_f32_e32 v41, v47, v47
	v_fmac_f32_e32 v40, v44, v44
	v_fmac_f32_e32 v41, v46, v46
	v_add_f32_e32 v40, v40, v41
	v_mul_f32_e32 v41, v51, v51
	v_fmac_f32_e32 v41, v50, v50
	v_and_b32_e32 v59, 0xffff0000, v81
	v_lshlrev_b32_e32 v60, 16, v82
	v_and_b32_e32 v61, 0xffff0000, v82
	v_add_f32_e32 v40, v41, v40
	v_mul_f32_e32 v41, v49, v49
	v_lshlrev_b32_e32 v62, 16, v83
	v_and_b32_e32 v63, 0xffff0000, v83
	v_fmac_f32_e32 v41, v48, v48
	v_pk_add_f32 v[38:39], v[38:39], v[58:59]
	v_pk_add_f32 v[36:37], v[36:37], v[56:57]
	v_pk_add_f32 v[42:43], v[32:33], v[60:61]
	v_cvt_pk_bf16_f32 v32, v36, v37
	v_cvt_pk_bf16_f32 v33, v38, v39
	v_add_f32_e32 v44, v41, v40
	v_pk_add_f32 v[40:41], v[34:35], v[62:63]
	v_cvt_pk_bf16_f32 v34, v42, v43
	s_nop 0
	v_cvt_pk_bf16_f32 v35, v40, v41
	global_store_dwordx4 v[52:53], v[32:35], off offset:256 sc1
	s_nop 1
	v_mul_f32_e32 v32, v37, v37
	v_mul_f32_e32 v33, v39, v39
	v_fmac_f32_e32 v32, v36, v36
	v_fmac_f32_e32 v33, v38, v38
	v_add_f32_e32 v32, v32, v33
	v_mul_f32_e32 v33, v43, v43
	v_fmac_f32_e32 v33, v42, v42
	v_add_f32_e32 v32, v33, v32
	v_mul_f32_e32 v33, v41, v41
	v_fmac_f32_e32 v33, v40, v40
	v_add_f32_e32 v32, v33, v32
	v_add_f32_e32 v32, v44, v32
	v_mov_b32_e32 v33, v32
	s_nop 1
	v_permlane16_swap_b32_e32 v32, v33
	v_add_f32_e32 v32, v32, v33
	v_mov_b32_e32 v33, v32
	s_nop 1
	v_permlane32_swap_b32_e32 v32, v33
	s_and_saveexec_b64 s[36:37], s[2:3]
	s_cbranch_execz .LBB0_1749
	v_add_f32_e32 v34, v32, v33
	v_lshlrev_b64 v[32:33], 6, v[96:97]
	v_lshl_add_u64 v[32:33], s[10:11], 0, v[32:33]
	v_lshl_add_u64 v[32:33], s[34:35], 2, v[32:33]
	s_lshl_b32 s6, s49, 2
	v_lshl_add_u64 v[32:33], v[32:33], 0, s[6:7]
	global_store_dword v[32:33], v34, off sc1
; __device__ __forceinline__ f32x4 bf4_lo(const u32x4 w) { return (f32x4){bf_lo(w.x), bf_hi(w.x), bf_lo(w.y), bf_hi(w.y)}; }
; __device__ __forceinline__ f32x4 bf4_hi(const u32x4 w) { return (f32x4){bf_lo(w.z), bf_hi(w.z), bf_lo(w.w), bf_hi(w.w)}; }
;     __device__ __forceinline__ void operator()(const Acc& acc, const Unit& u, int wr, int wc, int fr, int fq) const {
;     ...
;                 u32x4 hw[4][2];
; #pragma unroll
;                 for (int m = 0; m < 4; ++m)
; #pragma unroll
;                     for (int bj = 0; bj < 2; ++bj) hw[m][bj] = *(const u32x4*)((const bf16_t*)base + (size_t)ROW_OF(u, ai, m) * D + colb + bj * 128);
; #pragma unroll
;                 for (int m = 0; m < 4; ++m)
; #pragma unroll
;                     for (int bj = 0; bj < 2; ++bj) { hv[m][bj][0] = bf4_lo(hw[m][bj]); hv[m][bj][1] = bf4_hi(hw[m][bj]); }
;             }
; #pragma unroll
;             for (int m = 0; m < 4; ++m) {
;                 const int row = ROW_OF(u, ai, m); float sq = 0.f;
; #pragma unroll
;                 for (int bj = 0; bj < 2; ++bj) {
;                     const size_t off = (size_t)row * D + colb + bj * 128;
;                     const f32x4 h0 = hv[m][bj][0] + acc[ai][bj][m][0] * scale, h1 = hv[m][bj][1] + acc[ai][bj][m][1] * scale;
;                     *(u32x4*)(hb + off) = pack8(h0, h1);
;                     sq += (h0[0] * h0[0] + h0[1] * h0[1]) + (h0[2] * h0[2] + h0[3] * h0[3]) + (h1[0] * h1[0] + h1[1] * h1[1]) + (h1[2] * h1[2] + h1[3] * h1[3]);
;                 }
;                 sq = red4_sum(sq);
;                 if (fq == 0) ss_out[(size_t)row * 16 + u.pn * 4 + wc] = sq;
;             }
.LBB0_1749:
	s_or_b64 exec, exec, s[36:37]
	v_lshlrev_b32_e32 v34, 16, v77
	v_and_b32_e32 v35, 0xffff0000, v77
	v_lshlrev_b32_e32 v36, 16, v78
	v_and_b32_e32 v37, 0xffff0000, v78
	v_lshlrev_b32_e32 v32, 16, v76
	v_and_b32_e32 v33, 0xffff0000, v76
	v_pk_add_f32 v[30:31], v[30:31], v[34:35]
	v_pk_add_f32 v[34:35], v[24:25], v[36:37]
	v_lshl_add_u64 v[36:37], s[16:17], 0, v[94:95]
	v_lshlrev_b32_e32 v38, 16, v79
	v_and_b32_e32 v39, 0xffff0000, v79
	v_pk_add_f32 v[28:29], v[28:29], v[32:33]
	v_lshl_add_u64 v[36:37], v[168:169], 1, v[36:37]
	v_cvt_pk_bf16_f32 v24, v28, v29
	v_cvt_pk_bf16_f32 v25, v30, v31
	v_pk_add_f32 v[32:33], v[26:27], v[38:39]
	v_cvt_pk_bf16_f32 v26, v34, v35
	v_lshlrev_b32_e32 v40, 16, v72
	v_cvt_pk_bf16_f32 v27, v32, v33
	global_store_dwordx4 v[36:37], v[24:27], off sc1
	v_and_b32_e32 v41, 0xffff0000, v72
	v_lshlrev_b32_e32 v42, 16, v73
	v_mul_f32_e32 v24, v29, v29
	v_mul_f32_e32 v25, v31, v31
	v_fmac_f32_e32 v24, v28, v28
	v_fmac_f32_e32 v25, v30, v30
	v_add_f32_e32 v24, v24, v25
	v_mul_f32_e32 v25, v35, v35
	v_fmac_f32_e32 v25, v34, v34
	v_and_b32_e32 v43, 0xffff0000, v73
	v_lshlrev_b32_e32 v44, 16, v74
	v_and_b32_e32 v45, 0xffff0000, v74
	v_add_f32_e32 v24, v25, v24
	v_mul_f32_e32 v25, v33, v33
	v_lshlrev_b32_e32 v46, 16, v75
	v_and_b32_e32 v47, 0xffff0000, v75
	v_fmac_f32_e32 v25, v32, v32
	v_pk_add_f32 v[22:23], v[22:23], v[42:43]
	v_pk_add_f32 v[20:21], v[20:21], v[40:41]
	v_pk_add_f32 v[26:27], v[16:17], v[44:45]
	v_cvt_pk_bf16_f32 v16, v20, v21
	v_cvt_pk_bf16_f32 v17, v22, v23
	v_add_f32_e32 v28, v25, v24
	v_pk_add_f32 v[24:25], v[18:19], v[46:47]
	v_cvt_pk_bf16_f32 v18, v26, v27
	s_nop 0
	v_cvt_pk_bf16_f32 v19, v24, v25
	global_store_dwordx4 v[36:37], v[16:19], off offset:256 sc1
	s_nop 1
	v_mul_f32_e32 v16, v21, v21
	v_mul_f32_e32 v17, v23, v23
	v_fmac_f32_e32 v16, v20, v20
	v_fmac_f32_e32 v17, v22, v22
	v_add_f32_e32 v16, v16, v17
	v_mul_f32_e32 v17, v27, v27
	v_fmac_f32_e32 v17, v26, v26
	v_add_f32_e32 v16, v17, v16
	v_mul_f32_e32 v17, v25, v25
	v_fmac_f32_e32 v17, v24, v24
	v_add_f32_e32 v16, v17, v16
	v_add_f32_e32 v16, v28, v16
	v_mov_b32_e32 v17, v16
	s_nop 1
	v_permlane16_swap_b32_e32 v16, v17
	v_add_f32_e32 v16, v16, v17
	v_mov_b32_e32 v17, v16
	s_nop 1
	v_permlane32_swap_b32_e32 v16, v17
	s_and_saveexec_b64 s[36:37], s[2:3]
	s_cbranch_execz .LBB0_1751
	v_add_f32_e32 v18, v16, v17
	v_lshlrev_b64 v[16:17], 6, v[92:93]
	v_lshl_add_u64 v[16:17], s[10:11], 0, v[16:17]
	v_lshl_add_u64 v[16:17], s[34:35], 2, v[16:17]
	s_lshl_b32 s6, s49, 2
	v_lshl_add_u64 v[16:17], v[16:17], 0, s[6:7]
	global_store_dword v[16:17], v18, off sc1
.LBB0_1751:
	s_or_b64 exec, exec, s[36:37]
	v_lshlrev_b32_e32 v18, 16, v69
	v_and_b32_e32 v19, 0xffff0000, v69
	v_lshlrev_b32_e32 v20, 16, v70
	v_and_b32_e32 v21, 0xffff0000, v70
	v_lshlrev_b32_e32 v16, 16, v68
	v_and_b32_e32 v17, 0xffff0000, v68
	v_pk_add_f32 v[14:15], v[14:15], v[18:19]
	v_pk_add_f32 v[18:19], v[8:9], v[20:21]
	v_lshl_add_u64 v[20:21], s[16:17], 0, v[90:91]
	v_lshlrev_b32_e32 v22, 16, v71
	v_and_b32_e32 v23, 0xffff0000, v71
	v_pk_add_f32 v[12:13], v[12:13], v[16:17]
	v_lshl_add_u64 v[20:21], v[168:169], 1, v[20:21]
	v_cvt_pk_bf16_f32 v8, v12, v13
	v_cvt_pk_bf16_f32 v9, v14, v15
	v_pk_add_f32 v[16:17], v[10:11], v[22:23]
	v_cvt_pk_bf16_f32 v10, v18, v19
	v_lshlrev_b32_e32 v24, 16, v64
	v_cvt_pk_bf16_f32 v11, v16, v17
	global_store_dwordx4 v[20:21], v[8:11], off sc1
	v_and_b32_e32 v25, 0xffff0000, v64
	v_lshlrev_b32_e32 v26, 16, v65
	v_mul_f32_e32 v8, v13, v13
	v_mul_f32_e32 v9, v15, v15
	v_fmac_f32_e32 v8, v12, v12
	v_fmac_f32_e32 v9, v14, v14
	v_add_f32_e32 v8, v8, v9
	v_mul_f32_e32 v9, v19, v19
	v_fmac_f32_e32 v9, v18, v18
	v_and_b32_e32 v27, 0xffff0000, v65
	v_lshlrev_b32_e32 v28, 16, v66
	v_and_b32_e32 v29, 0xffff0000, v66
	v_add_f32_e32 v8, v9, v8
	v_mul_f32_e32 v9, v17, v17
	v_lshlrev_b32_e32 v30, 16, v67
	v_and_b32_e32 v31, 0xffff0000, v67
	v_fmac_f32_e32 v9, v16, v16
	v_pk_add_f32 v[6:7], v[6:7], v[26:27]
	v_pk_add_f32 v[4:5], v[4:5], v[24:25]
	v_pk_add_f32 v[10:11], v[0:1], v[28:29]
	v_cvt_pk_bf16_f32 v0, v4, v5
	v_cvt_pk_bf16_f32 v1, v6, v7
	v_add_f32_e32 v12, v9, v8
	v_pk_add_f32 v[8:9], v[2:3], v[30:31]
	v_cvt_pk_bf16_f32 v2, v10, v11
	s_nop 0
	v_cvt_pk_bf16_f32 v3, v8, v9
	global_store_dwordx4 v[20:21], v[0:3], off offset:256 sc1
	s_nop 1
	v_mul_f32_e32 v0, v5, v5
	v_mul_f32_e32 v1, v7, v7
	v_fmac_f32_e32 v0, v4, v4
	v_fmac_f32_e32 v1, v6, v6
	v_add_f32_e32 v0, v0, v1
	v_mul_f32_e32 v1, v11, v11
	v_fmac_f32_e32 v1, v10, v10
	v_add_f32_e32 v0, v1, v0
	v_mul_f32_e32 v1, v9, v9
	v_fmac_f32_e32 v1, v8, v8
	v_add_f32_e32 v0, v1, v0
	v_add_f32_e32 v0, v12, v0
	v_mov_b32_e32 v1, v0
	s_nop 1
	v_permlane16_swap_b32_e32 v0, v1
	v_add_f32_e32 v0, v0, v1
	v_mov_b32_e32 v1, v0
	s_nop 1
	v_permlane32_swap_b32_e32 v0, v1
	s_and_saveexec_b64 s[36:37], s[2:3]
	s_cbranch_execz .LBB0_1753
	v_add_f32_e32 v2, v0, v1
	v_lshlrev_b64 v[0:1], 6, v[88:89]
	v_lshl_add_u64 v[0:1], s[10:11], 0, v[0:1]
	v_lshl_add_u64 v[0:1], s[34:35], 2, v[0:1]
	s_lshl_b32 s6, s49, 2
	v_lshl_add_u64 v[0:1], v[0:1], 0, s[6:7]
	global_store_dword v[0:1], v2, off sc1
